# s_sleep 2 at each GEMM K-loop iteration head (pacing) on top of attention reschedule + per-tile pacing
# baseline (speedup 1.0000x reference)
; #define PG8_STAGE(bufoff, gbase, voff) do { _Pragma("unroll") for (int _i = 0; _i < 2; ++_i) \
;         __builtin_amdgcn_global_load_lds((const unsigned*)((const char*)(gbase) + (voff)[_i]), (PG8_LAS unsigned*)(lds + (bufoff) + ldsw + _i * 8192), 16, 0, 0); } while (0)
; #define PG8_LDA(dst, b, h) do { _Pragma("unroll") for (int m = 0; m < 4; ++m) _Pragma("unroll") for (int k = 0; k < 2; ++k) dst[m][k] = *(const PG8_LAS bf16x8*)(lds + PG8_SA(b, h) + aoff + m * 2048 + k * 1024); } while (0)
; #define PG8_LDB(dst, b, h) do { _Pragma("unroll") for (int n = 0; n < 2; ++n) _Pragma("unroll") for (int k = 0; k < 2; ++k) dst[n][k] = *(const PG8_LAS bf16x8*)(lds + PG8_SB(b, h) + boff + n * 2048 + k * 1024); } while (0)
; #define PG8_MMA(ai, bj, At, Bt) do { __builtin_amdgcn_s_setprio(1); _Pragma("unroll") for (int m = 0; m < 4; ++m) _Pragma("unroll") for (int n = 0; n < 2; ++n) _Pragma("unroll") for (int k = 0; k < 2; ++k) \
;         acc[ai][bj][m][n] = __builtin_amdgcn_mfma_f32_16x16x32_bf16(Bt[n][k], At[m][k], acc[ai][bj][m][n], 0, 0, 0); __builtin_amdgcn_s_setprio(0); } while (0)
; #define PG8_WAIT_V(n) asm volatile("s_waitcnt vmcnt(" #n ")" ::: "memory")
; #define PG8_WAIT_L(n) asm volatile("s_waitcnt lgkmcnt(" #n ")" ::: "memory")
; #define PG8_BAR __builtin_amdgcn_s_barrier()
; #define PG8_SCHED __builtin_amdgcn_sched_barrier(0)
; template <class Epi, class Sched, bool ALIGN_EPI = false, bool SP2 = false>
; __device__ __forceinline__ void gemm_phase(PG8_LAS unsigned char* lds, const Gemm g, const Sched& S, const Epi& E) {
;     ...
;             PG8_LDB(B0, 0, 0); PG8_LDB(B1, 0, 1); PG8_SCHED; PG8_LDA(At, 0, 0); PG8_STAGE(PG8_SA(1, 1), a1 + hstep, voffA);
;             PG8_WAIT_V(8); PG8_WAIT_L(0); PG8_BAR; PG8_MMA(0, 0, At, B0); PG8_MMA(0, 1, At, B1); PG8_BAR; PG8_SCHED;
;             PG8_LDA(At, 0, 1); PG8_STAGE(PG8_SB(0, 0), b2, voffB); PG8_STAGE(PG8_SB(0, 1), b2 + hstep, voffB); PG8_STAGE(PG8_SA(0, 0), a2, voffA);
;             PG8_WAIT_V(8); PG8_WAIT_L(0); PG8_BAR; PG8_MMA(1, 0, At, B0); PG8_MMA(1, 1, At, B1); PG8_BAR; PG8_SCHED;
.LBB0_1183:
	s_sleep 2
	ds_read_b128 v[128:131], v165
	ds_read_b128 v[152:155], v165 offset:1024
	ds_read_b128 v[156:159], v165 offset:2048
	ds_read_b128 v[170:173], v165 offset:3072
	ds_read_b128 v[174:177], v166
	ds_read_b128 v[178:181], v166 offset:1024
	ds_read_b128 v[182:185], v166 offset:2048
	ds_read_b128 v[186:189], v166 offset:3072
	s_add_i32 s96, s74, 2
	s_add_u32 vcc_lo, s52, 0x80
	s_addc_u32 s75, s53, 0
	s_cmp_eq_u32 s82, s74
	s_cselect_b32 s74, s8, vcc_lo
	s_cselect_b32 s75, s9, s75
	s_cselect_b32 vcc_hi, s39, s49
	s_cselect_b32 vcc_lo, s38, s20
	v_lshl_add_u64 v[190:191], s[52:53], 0, v[146:147]
	s_add_i32 m0, s70, 0xc000
	ds_read_b128 v[196:199], v167
	ds_read_b128 v[200:203], v167 offset:1024
	ds_read_b128 v[204:207], v167 offset:2048
	ds_read_b128 v[208:211], v167 offset:3072
	ds_read_b128 v[212:215], v167 offset:4096
	ds_read_b128 v[216:219], v167 offset:5120
	ds_read_b128 v[220:223], v167 offset:6144
	ds_read_b128 v[224:227], v167 offset:7168
	global_load_lds_dwordx4 v[190:191], off
	v_lshl_add_u64 v[190:191], s[52:53], 0, v[148:149]
	s_add_i32 m0, s70, 0xe000
	s_nop 0
	global_load_lds_dwordx4 v[190:191], off
	s_waitcnt vmcnt(8)
	s_waitcnt lgkmcnt(0)
	s_barrier
	s_setprio 1
	s_waitcnt lgkmcnt(0)
	v_mfma_f32_16x16x32_bf16 v[124:127], v[128:131], v[196:199], v[124:127]
	v_mfma_f32_16x16x32_bf16 v[120:123], v[156:159], v[196:199], v[120:123]
	v_mfma_f32_16x16x32_bf16 v[108:111], v[128:131], v[204:207], v[108:111]
	v_mfma_f32_16x16x32_bf16 v[104:107], v[156:159], v[204:207], v[104:107]
	v_mfma_f32_16x16x32_bf16 v[92:95], v[128:131], v[212:215], v[92:95]
	v_mfma_f32_16x16x32_bf16 v[88:91], v[156:159], v[212:215], v[88:91]
	v_mfma_f32_16x16x32_bf16 v[76:79], v[128:131], v[220:223], v[76:79]
	v_mfma_f32_16x16x32_bf16 v[72:75], v[156:159], v[220:223], v[72:75]
	v_mfma_f32_16x16x32_bf16 v[124:127], v[152:155], v[200:203], v[124:127]
	v_mfma_f32_16x16x32_bf16 v[120:123], v[170:173], v[200:203], v[120:123]
	v_mfma_f32_16x16x32_bf16 v[108:111], v[152:155], v[208:211], v[108:111]
	v_mfma_f32_16x16x32_bf16 v[104:107], v[170:173], v[208:211], v[104:107]
	v_mfma_f32_16x16x32_bf16 v[92:95], v[152:155], v[216:219], v[92:95]
	v_mfma_f32_16x16x32_bf16 v[88:91], v[170:173], v[216:219], v[88:91]
	v_mfma_f32_16x16x32_bf16 v[76:79], v[152:155], v[224:227], v[76:79]
	v_mfma_f32_16x16x32_bf16 v[72:75], v[170:173], v[224:227], v[72:75]
	s_setprio 0
	s_setprio 1
	v_mfma_f32_16x16x32_bf16 v[116:119], v[174:177], v[196:199], v[116:119]
	v_mfma_f32_16x16x32_bf16 v[112:115], v[182:185], v[196:199], v[112:115]
	v_mfma_f32_16x16x32_bf16 v[100:103], v[174:177], v[204:207], v[100:103]
	v_mfma_f32_16x16x32_bf16 v[96:99], v[182:185], v[204:207], v[96:99]
	v_mfma_f32_16x16x32_bf16 v[84:87], v[174:177], v[212:215], v[84:87]
	v_mfma_f32_16x16x32_bf16 v[80:83], v[182:185], v[212:215], v[80:83]
	v_mfma_f32_16x16x32_bf16 v[68:71], v[174:177], v[220:223], v[68:71]
	v_mfma_f32_16x16x32_bf16 v[64:67], v[182:185], v[220:223], v[64:67]
	v_mfma_f32_16x16x32_bf16 v[116:119], v[178:181], v[200:203], v[116:119]
	v_mfma_f32_16x16x32_bf16 v[112:115], v[186:189], v[200:203], v[112:115]
	v_mfma_f32_16x16x32_bf16 v[100:103], v[178:181], v[208:211], v[100:103]
	v_mfma_f32_16x16x32_bf16 v[96:99], v[186:189], v[208:211], v[96:99]
	v_mfma_f32_16x16x32_bf16 v[84:87], v[178:181], v[216:219], v[84:87]
	v_mfma_f32_16x16x32_bf16 v[80:83], v[186:189], v[216:219], v[80:83]
	v_mfma_f32_16x16x32_bf16 v[68:71], v[178:181], v[224:227], v[68:71]
	v_mfma_f32_16x16x32_bf16 v[64:67], v[186:189], v[224:227], v[64:67]
	s_setprio 0
	s_barrier
	s_add_i32 s85, s90, s67
	v_lshl_add_u64 v[190:191], vcc, 0, v[134:135]
	s_mov_b32 m0, s85
	ds_read_b128 v[196:199], v167 offset:16384
	ds_read_b128 v[200:203], v167 offset:17408
	ds_read_b128 v[204:207], v167 offset:18432
	ds_read_b128 v[208:211], v167 offset:19456
	ds_read_b128 v[212:215], v167 offset:20480
	ds_read_b128 v[216:219], v167 offset:21504
	ds_read_b128 v[220:223], v167 offset:22528
	ds_read_b128 v[224:227], v167 offset:23552
	global_load_lds_dwordx4 v[190:191], off
	s_add_i32 m0, s85, 0x2000
	v_lshl_add_u64 v[228:229], vcc, 0, v[138:139]
	s_add_u32 vcc_lo, vcc_lo, s14
	s_addc_u32 vcc_hi, vcc_hi, s15
	s_add_i32 s85, s91, s67
	global_load_lds_dwordx4 v[228:229], off
	v_lshl_add_u64 v[230:231], vcc, 0, v[134:135]
	s_mov_b32 m0, s85
	v_lshl_add_u64 v[232:233], vcc, 0, v[138:139]
	global_load_lds_dwordx4 v[230:231], off
	s_add_i32 m0, s85, 0x2000
	v_lshl_add_u64 v[234:235], s[74:75], 0, v[132:133]
	global_load_lds_dwordx4 v[232:233], off
	s_mov_b32 m0, s70
	v_lshl_add_u64 v[236:237], s[74:75], 0, v[136:137]
	global_load_lds_dwordx4 v[234:235], off
	s_mov_b32 m0, s71
	s_nop 0
	global_load_lds_dwordx4 v[236:237], off
	s_waitcnt vmcnt(8)
	s_waitcnt lgkmcnt(0)
	s_barrier
; #define PG8_STAGE(bufoff, gbase, voff) do { _Pragma("unroll") for (int _i = 0; _i < 2; ++_i) \
;         __builtin_amdgcn_global_load_lds((const unsigned*)((const char*)(gbase) + (voff)[_i]), (PG8_LAS unsigned*)(lds + (bufoff) + ldsw + _i * 8192), 16, 0, 0); } while (0)
; #define PG8_LDA(dst, b, h) do { _Pragma("unroll") for (int m = 0; m < 4; ++m) _Pragma("unroll") for (int k = 0; k < 2; ++k) dst[m][k] = *(const PG8_LAS bf16x8*)(lds + PG8_SA(b, h) + aoff + m * 2048 + k * 1024); } while (0)
; #define PG8_LDB(dst, b, h) do { _Pragma("unroll") for (int n = 0; n < 2; ++n) _Pragma("unroll") for (int k = 0; k < 2; ++k) dst[n][k] = *(const PG8_LAS bf16x8*)(lds + PG8_SB(b, h) + boff + n * 2048 + k * 1024); } while (0)
; #define PG8_MMA(ai, bj, At, Bt) do { __builtin_amdgcn_s_setprio(1); _Pragma("unroll") for (int m = 0; m < 4; ++m) _Pragma("unroll") for (int n = 0; n < 2; ++n) _Pragma("unroll") for (int k = 0; k < 2; ++k) \
;         acc[ai][bj][m][n] = __builtin_amdgcn_mfma_f32_16x16x32_bf16(Bt[n][k], At[m][k], acc[ai][bj][m][n], 0, 0, 0); __builtin_amdgcn_s_setprio(0); } while (0)
; #define PG8_WAIT_V(n) asm volatile("s_waitcnt vmcnt(" #n ")" ::: "memory")
; #define PG8_WAIT_L(n) asm volatile("s_waitcnt lgkmcnt(" #n ")" ::: "memory")
; #define PG8_BAR __builtin_amdgcn_s_barrier()
; #define PG8_SCHED __builtin_amdgcn_sched_barrier(0)
; template <class Epi, class Sched, bool ALIGN_EPI = false, bool SP2 = false>
; __device__ __forceinline__ void gemm_phase(PG8_LAS unsigned char* lds, const Gemm g, const Sched& S, const Epi& E) {
;     ...
;             PG8_WAIT_V(8); PG8_WAIT_L(0); PG8_BAR; PG8_MMA(1, 0, At, B0); PG8_MMA(1, 1, At, B1); PG8_BAR; PG8_SCHED;
;             PG8_LDB(B0, 1, 0); PG8_LDB(B1, 1, 1); PG8_SCHED; PG8_LDA(At, 1, 0); PG8_STAGE(PG8_SA(0, 1), a2 + hstep, voffA);
;             PG8_WAIT_V(8); PG8_WAIT_L(0); PG8_BAR; PG8_MMA(0, 0, At, B0); PG8_MMA(0, 1, At, B1); PG8_BAR; PG8_SCHED;
	s_setprio 1
	s_waitcnt lgkmcnt(0)
	v_mfma_f32_16x16x32_bf16 v[60:63], v[128:131], v[196:199], v[60:63]
	v_mfma_f32_16x16x32_bf16 v[56:59], v[156:159], v[196:199], v[56:59]
	v_mfma_f32_16x16x32_bf16 v[44:47], v[128:131], v[204:207], v[44:47]
	v_mfma_f32_16x16x32_bf16 v[40:43], v[156:159], v[204:207], v[40:43]
	v_mfma_f32_16x16x32_bf16 v[28:31], v[128:131], v[212:215], v[28:31]
	v_mfma_f32_16x16x32_bf16 v[24:27], v[156:159], v[212:215], v[24:27]
	v_mfma_f32_16x16x32_bf16 v[12:15], v[128:131], v[220:223], v[12:15]
	v_mfma_f32_16x16x32_bf16 v[8:11], v[156:159], v[220:223], v[8:11]
	v_mfma_f32_16x16x32_bf16 v[60:63], v[152:155], v[200:203], v[60:63]
	v_mfma_f32_16x16x32_bf16 v[56:59], v[170:173], v[200:203], v[56:59]
	v_mfma_f32_16x16x32_bf16 v[44:47], v[152:155], v[208:211], v[44:47]
	v_mfma_f32_16x16x32_bf16 v[40:43], v[170:173], v[208:211], v[40:43]
	v_mfma_f32_16x16x32_bf16 v[28:31], v[152:155], v[216:219], v[28:31]
	v_mfma_f32_16x16x32_bf16 v[24:27], v[170:173], v[216:219], v[24:27]
	v_mfma_f32_16x16x32_bf16 v[12:15], v[152:155], v[224:227], v[12:15]
	v_mfma_f32_16x16x32_bf16 v[8:11], v[170:173], v[224:227], v[8:11]
	s_setprio 0
	s_setprio 1
	v_mfma_f32_16x16x32_bf16 v[52:55], v[174:177], v[196:199], v[52:55]
	v_mfma_f32_16x16x32_bf16 v[48:51], v[182:185], v[196:199], v[48:51]
	v_mfma_f32_16x16x32_bf16 v[36:39], v[174:177], v[204:207], v[36:39]
	v_mfma_f32_16x16x32_bf16 v[32:35], v[182:185], v[204:207], v[32:35]
	v_mfma_f32_16x16x32_bf16 v[20:23], v[174:177], v[212:215], v[20:23]
	v_mfma_f32_16x16x32_bf16 v[16:19], v[182:185], v[212:215], v[16:19]
	v_mfma_f32_16x16x32_bf16 v[4:7], v[174:177], v[220:223], v[4:7]
	v_mfma_f32_16x16x32_bf16 v[0:3], v[182:185], v[220:223], v[0:3]
	v_mfma_f32_16x16x32_bf16 v[52:55], v[178:181], v[200:203], v[52:55]
	v_mfma_f32_16x16x32_bf16 v[48:51], v[186:189], v[200:203], v[48:51]
	v_mfma_f32_16x16x32_bf16 v[36:39], v[178:181], v[208:211], v[36:39]
	v_mfma_f32_16x16x32_bf16 v[32:35], v[186:189], v[208:211], v[32:35]
	v_mfma_f32_16x16x32_bf16 v[20:23], v[178:181], v[216:219], v[20:23]
	v_mfma_f32_16x16x32_bf16 v[16:19], v[186:189], v[216:219], v[16:19]
	v_mfma_f32_16x16x32_bf16 v[4:7], v[178:181], v[224:227], v[4:7]
	v_mfma_f32_16x16x32_bf16 v[0:3], v[186:189], v[224:227], v[0:3]
	s_setprio 0
	s_barrier
	s_add_i32 s85, 0, 0x18000
	v_add_u32_e32 v169, s85, v160
	s_add_i32 vcc_lo, 0, 0x1c000
	ds_read_b128 v[128:131], v169
	ds_read_b128 v[152:155], v169 offset:1024
	ds_read_b128 v[156:159], v169 offset:2048
	ds_read_b128 v[170:173], v169 offset:3072
	v_add_u32_e32 v169, vcc_lo, v160
	ds_read_b128 v[174:177], v169
	ds_read_b128 v[178:181], v169 offset:1024
	ds_read_b128 v[182:185], v169 offset:2048
	ds_read_b128 v[186:189], v169 offset:3072
	s_add_u32 s74, s74, s14
	s_addc_u32 s75, s75, s15
	s_mov_b32 m0, s76
	v_lshl_add_u64 v[238:239], s[74:75], 0, v[132:133]
	ds_read_b128 v[196:199], v167 offset:32768
	ds_read_b128 v[200:203], v167 offset:33792
	ds_read_b128 v[204:207], v167 offset:34816
	ds_read_b128 v[208:211], v167 offset:35840
	ds_read_b128 v[212:215], v167 offset:36864
	ds_read_b128 v[216:219], v167 offset:37888
	ds_read_b128 v[220:223], v167 offset:38912
	ds_read_b128 v[224:227], v167 offset:39936
	global_load_lds_dwordx4 v[238:239], off
	v_lshl_add_u64 v[238:239], s[74:75], 0, v[136:137]
	s_mov_b32 m0, s77
	s_nop 0
	global_load_lds_dwordx4 v[238:239], off
	s_waitcnt vmcnt(8)
	s_waitcnt lgkmcnt(0)
	s_barrier
	s_setprio 1
	s_waitcnt lgkmcnt(0)
	v_mfma_f32_16x16x32_bf16 v[124:127], v[128:131], v[196:199], v[124:127]
	v_mfma_f32_16x16x32_bf16 v[120:123], v[156:159], v[196:199], v[120:123]
	v_mfma_f32_16x16x32_bf16 v[108:111], v[128:131], v[204:207], v[108:111]
	v_mfma_f32_16x16x32_bf16 v[104:107], v[156:159], v[204:207], v[104:107]
	v_mfma_f32_16x16x32_bf16 v[92:95], v[128:131], v[212:215], v[92:95]
	v_mfma_f32_16x16x32_bf16 v[88:91], v[156:159], v[212:215], v[88:91]
	v_mfma_f32_16x16x32_bf16 v[76:79], v[128:131], v[220:223], v[76:79]
	v_mfma_f32_16x16x32_bf16 v[72:75], v[156:159], v[220:223], v[72:75]
	v_mfma_f32_16x16x32_bf16 v[124:127], v[152:155], v[200:203], v[124:127]
	v_mfma_f32_16x16x32_bf16 v[120:123], v[170:173], v[200:203], v[120:123]
	v_mfma_f32_16x16x32_bf16 v[108:111], v[152:155], v[208:211], v[108:111]
	v_mfma_f32_16x16x32_bf16 v[104:107], v[170:173], v[208:211], v[104:107]
	v_mfma_f32_16x16x32_bf16 v[92:95], v[152:155], v[216:219], v[92:95]
	v_mfma_f32_16x16x32_bf16 v[88:91], v[170:173], v[216:219], v[88:91]
	v_mfma_f32_16x16x32_bf16 v[76:79], v[152:155], v[224:227], v[76:79]
	v_mfma_f32_16x16x32_bf16 v[72:75], v[170:173], v[224:227], v[72:75]
	s_setprio 0
	s_setprio 1
	v_mfma_f32_16x16x32_bf16 v[116:119], v[174:177], v[196:199], v[116:119]
	v_mfma_f32_16x16x32_bf16 v[112:115], v[182:185], v[196:199], v[112:115]
	v_mfma_f32_16x16x32_bf16 v[100:103], v[174:177], v[204:207], v[100:103]
	v_mfma_f32_16x16x32_bf16 v[96:99], v[182:185], v[204:207], v[96:99]
	v_mfma_f32_16x16x32_bf16 v[84:87], v[174:177], v[212:215], v[84:87]
	v_mfma_f32_16x16x32_bf16 v[80:83], v[182:185], v[212:215], v[80:83]
	v_mfma_f32_16x16x32_bf16 v[68:71], v[174:177], v[220:223], v[68:71]
	v_mfma_f32_16x16x32_bf16 v[64:67], v[182:185], v[220:223], v[64:67]
	v_mfma_f32_16x16x32_bf16 v[116:119], v[178:181], v[200:203], v[116:119]
	v_mfma_f32_16x16x32_bf16 v[112:115], v[186:189], v[200:203], v[112:115]
	v_mfma_f32_16x16x32_bf16 v[100:103], v[178:181], v[208:211], v[100:103]
	v_mfma_f32_16x16x32_bf16 v[96:99], v[186:189], v[208:211], v[96:99]
	v_mfma_f32_16x16x32_bf16 v[84:87], v[178:181], v[216:219], v[84:87]
	v_mfma_f32_16x16x32_bf16 v[80:83], v[186:189], v[216:219], v[80:83]
	v_mfma_f32_16x16x32_bf16 v[68:71], v[178:181], v[224:227], v[68:71]
	v_mfma_f32_16x16x32_bf16 v[64:67], v[186:189], v[224:227], v[64:67]
	s_setprio 0
	s_barrier
; #define PG8_STAGE(bufoff, gbase, voff) do { _Pragma("unroll") for (int _i = 0; _i < 2; ++_i) \
;         __builtin_amdgcn_global_load_lds((const unsigned*)((const char*)(gbase) + (voff)[_i]), (PG8_LAS unsigned*)(lds + (bufoff) + ldsw + _i * 8192), 16, 0, 0); } while (0)
; #define PG8_LDA(dst, b, h) do { _Pragma("unroll") for (int m = 0; m < 4; ++m) _Pragma("unroll") for (int k = 0; k < 2; ++k) dst[m][k] = *(const PG8_LAS bf16x8*)(lds + PG8_SA(b, h) + aoff + m * 2048 + k * 1024); } while (0)
; #define PG8_MMA(ai, bj, At, Bt) do { __builtin_amdgcn_s_setprio(1); _Pragma("unroll") for (int m = 0; m < 4; ++m) _Pragma("unroll") for (int n = 0; n < 2; ++n) _Pragma("unroll") for (int k = 0; k < 2; ++k) \
;         acc[ai][bj][m][n] = __builtin_amdgcn_mfma_f32_16x16x32_bf16(Bt[n][k], At[m][k], acc[ai][bj][m][n], 0, 0, 0); __builtin_amdgcn_s_setprio(0); } while (0)
; #define PG8_WAIT_V(n) asm volatile("s_waitcnt vmcnt(" #n ")" ::: "memory")
; #define PG8_WAIT_L(n) asm volatile("s_waitcnt lgkmcnt(" #n ")" ::: "memory")
; #define PG8_BAR __builtin_amdgcn_s_barrier()
; #define PG8_SCHED __builtin_amdgcn_sched_barrier(0)
; template <class Epi, class Sched, bool ALIGN_EPI = false, bool SP2 = false>
; __device__ __forceinline__ void gemm_phase(PG8_LAS unsigned char* lds, const Gemm g, const Sched& S, const Epi& E) {
;     ...
;         for (int t = 0; t < nt; t += 2) {
;     ...
;             PG8_LDA(At, 1, 1); PG8_STAGE(PG8_SB(1, 0), b3, voffB); PG8_STAGE(PG8_SB(1, 1), b3 + hstep, voffB); PG8_STAGE(PG8_SA(1, 0), a3, voffA);
;             PG8_WAIT_V(8); PG8_WAIT_L(0); PG8_BAR; PG8_MMA(1, 0, At, B0); PG8_MMA(1, 1, At, B1); PG8_BAR; PG8_SCHED;
	s_add_i32 s74, s85, s67
	v_lshl_add_u64 v[190:191], v[190:191], 0, s[24:25]
	s_mov_b32 m0, s74
	ds_read_b128 v[196:199], v167 offset:49152
	ds_read_b128 v[200:203], v167 offset:50176
	ds_read_b128 v[204:207], v167 offset:51200
	ds_read_b128 v[208:211], v167 offset:52224
	ds_read_b128 v[212:215], v167 offset:53248
	ds_read_b128 v[216:219], v167 offset:54272
	ds_read_b128 v[220:223], v167 offset:55296
	ds_read_b128 v[224:227], v167 offset:56320
	global_load_lds_dwordx4 v[190:191], off
	v_lshl_add_u64 v[190:191], v[228:229], 0, s[24:25]
	s_add_i32 m0, s74, 0x2000
	s_add_i32 s74, vcc_lo, s67
	global_load_lds_dwordx4 v[190:191], off
	v_lshl_add_u64 v[190:191], v[230:231], 0, s[24:25]
	s_mov_b32 m0, s74
	s_nop 0
	global_load_lds_dwordx4 v[190:191], off
	v_lshl_add_u64 v[190:191], v[232:233], 0, s[24:25]
	s_add_i32 m0, s74, 0x2000
	s_nop 0
	global_load_lds_dwordx4 v[190:191], off
	v_lshl_add_u64 v[190:191], v[234:235], 0, s[24:25]
	s_mov_b32 m0, s80
	s_nop 0
	global_load_lds_dwordx4 v[190:191], off
	v_lshl_add_u64 v[190:191], v[236:237], 0, s[24:25]
	s_mov_b32 m0, s81
	s_nop 0
	global_load_lds_dwordx4 v[190:191], off
	s_waitcnt vmcnt(8)
	s_waitcnt lgkmcnt(0)
	s_barrier
	s_setprio 1
	s_waitcnt lgkmcnt(0)
	v_mfma_f32_16x16x32_bf16 v[60:63], v[128:131], v[196:199], v[60:63]
	v_mfma_f32_16x16x32_bf16 v[56:59], v[156:159], v[196:199], v[56:59]
	v_mfma_f32_16x16x32_bf16 v[44:47], v[128:131], v[204:207], v[44:47]
	v_mfma_f32_16x16x32_bf16 v[40:43], v[156:159], v[204:207], v[40:43]
	v_mfma_f32_16x16x32_bf16 v[28:31], v[128:131], v[212:215], v[28:31]
	v_mfma_f32_16x16x32_bf16 v[24:27], v[156:159], v[212:215], v[24:27]
	v_mfma_f32_16x16x32_bf16 v[12:15], v[128:131], v[220:223], v[12:15]
	v_mfma_f32_16x16x32_bf16 v[8:11], v[156:159], v[220:223], v[8:11]
	v_mfma_f32_16x16x32_bf16 v[60:63], v[152:155], v[200:203], v[60:63]
	v_mfma_f32_16x16x32_bf16 v[56:59], v[170:173], v[200:203], v[56:59]
	v_mfma_f32_16x16x32_bf16 v[44:47], v[152:155], v[208:211], v[44:47]
	v_mfma_f32_16x16x32_bf16 v[40:43], v[170:173], v[208:211], v[40:43]
	v_mfma_f32_16x16x32_bf16 v[28:31], v[152:155], v[216:219], v[28:31]
	v_mfma_f32_16x16x32_bf16 v[24:27], v[170:173], v[216:219], v[24:27]
	v_mfma_f32_16x16x32_bf16 v[12:15], v[152:155], v[224:227], v[12:15]
	v_mfma_f32_16x16x32_bf16 v[8:11], v[170:173], v[224:227], v[8:11]
	s_setprio 0
	s_setprio 1
	v_mfma_f32_16x16x32_bf16 v[52:55], v[174:177], v[196:199], v[52:55]
	v_mfma_f32_16x16x32_bf16 v[48:51], v[182:185], v[196:199], v[48:51]
	v_mfma_f32_16x16x32_bf16 v[36:39], v[174:177], v[204:207], v[36:39]
	v_mfma_f32_16x16x32_bf16 v[32:35], v[182:185], v[204:207], v[32:35]
	v_mfma_f32_16x16x32_bf16 v[20:23], v[174:177], v[212:215], v[20:23]
	v_mfma_f32_16x16x32_bf16 v[16:19], v[182:185], v[212:215], v[16:19]
	v_mfma_f32_16x16x32_bf16 v[4:7], v[174:177], v[220:223], v[4:7]
	v_mfma_f32_16x16x32_bf16 v[0:3], v[182:185], v[220:223], v[0:3]
	v_mfma_f32_16x16x32_bf16 v[52:55], v[178:181], v[200:203], v[52:55]
	v_mfma_f32_16x16x32_bf16 v[48:51], v[186:189], v[200:203], v[48:51]
	v_mfma_f32_16x16x32_bf16 v[36:39], v[178:181], v[208:211], v[36:39]
	v_mfma_f32_16x16x32_bf16 v[32:35], v[186:189], v[208:211], v[32:35]
	v_mfma_f32_16x16x32_bf16 v[20:23], v[178:181], v[216:219], v[20:23]
	v_mfma_f32_16x16x32_bf16 v[16:19], v[186:189], v[216:219], v[16:19]
	v_mfma_f32_16x16x32_bf16 v[4:7], v[178:181], v[224:227], v[4:7]
	v_mfma_f32_16x16x32_bf16 v[0:3], v[186:189], v[224:227], v[0:3]
	s_setprio 0
	s_barrier
	s_add_u32 s52, s52, 0x100
	s_addc_u32 s53, s53, 0
	s_add_u32 s20, s20, 0x100
	s_addc_u32 s49, s49, 0
	s_cmp_ge_i32 s96, s79
	s_mov_b32 s74, s96
	s_cbranch_scc0 .LBB0_1183

; #define PG8_STAGE(bufoff, gbase, voff) do { _Pragma("unroll") for (int _i = 0; _i < 2; ++_i) \
;         __builtin_amdgcn_global_load_lds((const unsigned*)((const char*)(gbase) + (voff)[_i]), (PG8_LAS unsigned*)(lds + (bufoff) + ldsw + _i * 8192), 16, 0, 0); } while (0)
; #define PG8_LDA(dst, b, h) do { _Pragma("unroll") for (int m = 0; m < 4; ++m) _Pragma("unroll") for (int k = 0; k < 2; ++k) dst[m][k] = *(const PG8_LAS bf16x8*)(lds + PG8_SA(b, h) + aoff + m * 2048 + k * 1024); } while (0)
; #define PG8_LDB(dst, b, h) do { _Pragma("unroll") for (int n = 0; n < 2; ++n) _Pragma("unroll") for (int k = 0; k < 2; ++k) dst[n][k] = *(const PG8_LAS bf16x8*)(lds + PG8_SB(b, h) + boff + n * 2048 + k * 1024); } while (0)
; #define PG8_MMA(ai, bj, At, Bt) do { __builtin_amdgcn_s_setprio(1); _Pragma("unroll") for (int m = 0; m < 4; ++m) _Pragma("unroll") for (int n = 0; n < 2; ++n) _Pragma("unroll") for (int k = 0; k < 2; ++k) \
;         acc[ai][bj][m][n] = __builtin_amdgcn_mfma_f32_16x16x32_bf16(Bt[n][k], At[m][k], acc[ai][bj][m][n], 0, 0, 0); __builtin_amdgcn_s_setprio(0); } while (0)
; #define PG8_WAIT_V(n) asm volatile("s_waitcnt vmcnt(" #n ")" ::: "memory")
; #define PG8_WAIT_L(n) asm volatile("s_waitcnt lgkmcnt(" #n ")" ::: "memory")
; #define PG8_BAR __builtin_amdgcn_s_barrier()
; #define PG8_SCHED __builtin_amdgcn_sched_barrier(0)
; template <class Epi, class Sched, bool ALIGN_EPI = false, bool SP2 = false>
; __device__ __forceinline__ void gemm_phase(PG8_LAS unsigned char* lds, const Gemm g, const Sched& S, const Epi& E) {
;     ...
;             PG8_LDB(B0, 0, 0); PG8_LDB(B1, 0, 1); PG8_SCHED; PG8_LDA(At, 0, 0); PG8_STAGE(PG8_SA(1, 1), a1 + hstep, voffA);
;             PG8_WAIT_V(8); PG8_WAIT_L(0); PG8_BAR; PG8_MMA(0, 0, At, B0); PG8_MMA(0, 1, At, B1); PG8_BAR; PG8_SCHED;
;             PG8_LDA(At, 0, 1); PG8_STAGE(PG8_SB(0, 0), b2, voffB); PG8_STAGE(PG8_SB(0, 1), b2 + hstep, voffB); PG8_STAGE(PG8_SA(0, 0), a2, voffA);
;             PG8_WAIT_V(8); PG8_WAIT_L(0); PG8_BAR; PG8_MMA(1, 0, At, B0); PG8_MMA(1, 1, At, B1); PG8_BAR; PG8_SCHED;
.LBB0_1291:
	s_sleep 2
	ds_read_b128 v[64:67], v203
	ds_read_b128 v[68:71], v203 offset:1024
	ds_read_b128 v[104:107], v203 offset:2048
	ds_read_b128 v[108:111], v203 offset:3072
	ds_read_b128 v[144:147], v212
	ds_read_b128 v[148:151], v212 offset:1024
	ds_read_b128 v[176:179], v212 offset:2048
	ds_read_b128 v[180:183], v212 offset:3072
	s_add_i32 s79, s76, 2
	s_add_u32 s94, s6, 0x80
	s_addc_u32 s77, s7, 0
	s_cmp_eq_u32 s89, s76
	s_cselect_b32 s76, s38, s94
	s_cselect_b32 s77, s39, s77
	s_cselect_b32 vcc_hi, s75, s78
	s_cselect_b32 vcc_lo, s74, s9
	v_lshl_add_u64 v[200:201], s[6:7], 0, v[168:169]
	s_add_i32 m0, s80, 0xc000
	ds_read_b128 v[184:187], v213
	ds_read_b128 v[188:191], v213 offset:1024
	ds_read_b128 v[196:199], v213 offset:2048
	ds_read_b128 v[204:207], v213 offset:3072
	ds_read_b128 v[208:211], v213 offset:4096
	ds_read_b128 v[214:217], v213 offset:5120
	ds_read_b128 v[218:221], v213 offset:6144
	ds_read_b128 v[222:225], v213 offset:7168
	global_load_lds_dwordx4 v[200:201], off
	v_lshl_add_u64 v[200:201], s[6:7], 0, v[170:171]
	s_add_i32 m0, s80, 0xe000
	s_nop 0
	global_load_lds_dwordx4 v[200:201], off
	s_waitcnt vmcnt(8)
	s_waitcnt lgkmcnt(0)
	s_barrier
	s_setprio 1
	s_waitcnt lgkmcnt(0)
	v_mfma_f32_16x16x32_bf16 v[140:143], v[64:67], v[184:187], v[140:143]
	v_mfma_f32_16x16x32_bf16 v[136:139], v[104:107], v[184:187], v[136:139]
	v_mfma_f32_16x16x32_bf16 v[124:127], v[64:67], v[196:199], v[124:127]
	v_mfma_f32_16x16x32_bf16 v[120:123], v[104:107], v[196:199], v[120:123]
	v_mfma_f32_16x16x32_bf16 v[100:103], v[64:67], v[208:211], v[100:103]
	v_mfma_f32_16x16x32_bf16 v[96:99], v[104:107], v[208:211], v[96:99]
	v_mfma_f32_16x16x32_bf16 v[84:87], v[64:67], v[218:221], v[84:87]
	v_mfma_f32_16x16x32_bf16 v[80:83], v[104:107], v[218:221], v[80:83]
	v_mfma_f32_16x16x32_bf16 v[140:143], v[68:71], v[188:191], v[140:143]
	v_mfma_f32_16x16x32_bf16 v[136:139], v[108:111], v[188:191], v[136:139]
	v_mfma_f32_16x16x32_bf16 v[124:127], v[68:71], v[204:207], v[124:127]
	v_mfma_f32_16x16x32_bf16 v[120:123], v[108:111], v[204:207], v[120:123]
	v_mfma_f32_16x16x32_bf16 v[100:103], v[68:71], v[214:217], v[100:103]
	v_mfma_f32_16x16x32_bf16 v[96:99], v[108:111], v[214:217], v[96:99]
	v_mfma_f32_16x16x32_bf16 v[84:87], v[68:71], v[222:225], v[84:87]
	v_mfma_f32_16x16x32_bf16 v[80:83], v[108:111], v[222:225], v[80:83]
	s_setprio 0
	s_setprio 1
	v_mfma_f32_16x16x32_bf16 v[132:135], v[144:147], v[184:187], v[132:135]
	v_mfma_f32_16x16x32_bf16 v[128:131], v[176:179], v[184:187], v[128:131]
	v_mfma_f32_16x16x32_bf16 v[116:119], v[144:147], v[196:199], v[116:119]
	v_mfma_f32_16x16x32_bf16 v[112:115], v[176:179], v[196:199], v[112:115]
	v_mfma_f32_16x16x32_bf16 v[92:95], v[144:147], v[208:211], v[92:95]
	v_mfma_f32_16x16x32_bf16 v[88:91], v[176:179], v[208:211], v[88:91]
	v_mfma_f32_16x16x32_bf16 v[76:79], v[144:147], v[218:221], v[76:79]
	v_mfma_f32_16x16x32_bf16 v[72:75], v[176:179], v[218:221], v[72:75]
	v_mfma_f32_16x16x32_bf16 v[132:135], v[148:151], v[188:191], v[132:135]
	v_mfma_f32_16x16x32_bf16 v[128:131], v[180:183], v[188:191], v[128:131]
	v_mfma_f32_16x16x32_bf16 v[116:119], v[148:151], v[204:207], v[116:119]
	v_mfma_f32_16x16x32_bf16 v[112:115], v[180:183], v[204:207], v[112:115]
	v_mfma_f32_16x16x32_bf16 v[92:95], v[148:151], v[214:217], v[92:95]
	v_mfma_f32_16x16x32_bf16 v[88:91], v[180:183], v[214:217], v[88:91]
	v_mfma_f32_16x16x32_bf16 v[76:79], v[148:151], v[222:225], v[76:79]
	v_mfma_f32_16x16x32_bf16 v[72:75], v[180:183], v[222:225], v[72:75]
	s_setprio 0
	s_barrier
	s_add_i32 s94, s47, s71
	v_lshl_add_u64 v[200:201], vcc, 0, v[154:155]
	s_mov_b32 m0, s94
	ds_read_b128 v[184:187], v213 offset:16384
	ds_read_b128 v[188:191], v213 offset:17408
	ds_read_b128 v[196:199], v213 offset:18432
	ds_read_b128 v[204:207], v213 offset:19456
	ds_read_b128 v[208:211], v213 offset:20480
	ds_read_b128 v[214:217], v213 offset:21504
	ds_read_b128 v[218:221], v213 offset:22528
	ds_read_b128 v[222:225], v213 offset:23552
	global_load_lds_dwordx4 v[200:201], off
	s_add_i32 m0, s94, 0x2000
	v_lshl_add_u64 v[226:227], vcc, 0, v[158:159]
	s_add_u32 vcc_lo, vcc_lo, s14
	s_addc_u32 vcc_hi, vcc_hi, s15
	s_add_i32 s94, s66, s71
	global_load_lds_dwordx4 v[226:227], off
	v_lshl_add_u64 v[228:229], vcc, 0, v[154:155]
	s_mov_b32 m0, s94
	v_lshl_add_u64 v[230:231], vcc, 0, v[158:159]
	global_load_lds_dwordx4 v[228:229], off
	s_add_i32 m0, s94, 0x2000
	v_lshl_add_u64 v[232:233], s[76:77], 0, v[152:153]
	global_load_lds_dwordx4 v[230:231], off
	s_mov_b32 m0, s80
	v_lshl_add_u64 v[234:235], s[76:77], 0, v[156:157]
	global_load_lds_dwordx4 v[232:233], off
	s_mov_b32 m0, s81
	s_nop 0
	global_load_lds_dwordx4 v[234:235], off
	s_waitcnt vmcnt(8)
	s_waitcnt lgkmcnt(0)
	s_barrier
; #define PG8_STAGE(bufoff, gbase, voff) do { _Pragma("unroll") for (int _i = 0; _i < 2; ++_i) \
;         __builtin_amdgcn_global_load_lds((const unsigned*)((const char*)(gbase) + (voff)[_i]), (PG8_LAS unsigned*)(lds + (bufoff) + ldsw + _i * 8192), 16, 0, 0); } while (0)
; #define PG8_LDA(dst, b, h) do { _Pragma("unroll") for (int m = 0; m < 4; ++m) _Pragma("unroll") for (int k = 0; k < 2; ++k) dst[m][k] = *(const PG8_LAS bf16x8*)(lds + PG8_SA(b, h) + aoff + m * 2048 + k * 1024); } while (0)
; #define PG8_LDB(dst, b, h) do { _Pragma("unroll") for (int n = 0; n < 2; ++n) _Pragma("unroll") for (int k = 0; k < 2; ++k) dst[n][k] = *(const PG8_LAS bf16x8*)(lds + PG8_SB(b, h) + boff + n * 2048 + k * 1024); } while (0)
; #define PG8_MMA(ai, bj, At, Bt) do { __builtin_amdgcn_s_setprio(1); _Pragma("unroll") for (int m = 0; m < 4; ++m) _Pragma("unroll") for (int n = 0; n < 2; ++n) _Pragma("unroll") for (int k = 0; k < 2; ++k) \
;         acc[ai][bj][m][n] = __builtin_amdgcn_mfma_f32_16x16x32_bf16(Bt[n][k], At[m][k], acc[ai][bj][m][n], 0, 0, 0); __builtin_amdgcn_s_setprio(0); } while (0)
; #define PG8_WAIT_V(n) asm volatile("s_waitcnt vmcnt(" #n ")" ::: "memory")
; #define PG8_WAIT_L(n) asm volatile("s_waitcnt lgkmcnt(" #n ")" ::: "memory")
; #define PG8_BAR __builtin_amdgcn_s_barrier()
; #define PG8_SCHED __builtin_amdgcn_sched_barrier(0)
; template <class Epi, class Sched, bool ALIGN_EPI = false, bool SP2 = false>
; __device__ __forceinline__ void gemm_phase(PG8_LAS unsigned char* lds, const Gemm g, const Sched& S, const Epi& E) {
;     ...
;             PG8_WAIT_V(8); PG8_WAIT_L(0); PG8_BAR; PG8_MMA(1, 0, At, B0); PG8_MMA(1, 1, At, B1); PG8_BAR; PG8_SCHED;
;             PG8_LDB(B0, 1, 0); PG8_LDB(B1, 1, 1); PG8_SCHED; PG8_LDA(At, 1, 0); PG8_STAGE(PG8_SA(0, 1), a2 + hstep, voffA);
;             PG8_WAIT_V(8); PG8_WAIT_L(0); PG8_BAR; PG8_MMA(0, 0, At, B0); PG8_MMA(0, 1, At, B1); PG8_BAR; PG8_SCHED;
	s_setprio 1
	s_waitcnt lgkmcnt(0)
	v_mfma_f32_16x16x32_bf16 v[60:63], v[64:67], v[184:187], v[60:63]
	v_mfma_f32_16x16x32_bf16 v[56:59], v[104:107], v[184:187], v[56:59]
	v_mfma_f32_16x16x32_bf16 v[44:47], v[64:67], v[196:199], v[44:47]
	v_mfma_f32_16x16x32_bf16 v[40:43], v[104:107], v[196:199], v[40:43]
	v_mfma_f32_16x16x32_bf16 v[28:31], v[64:67], v[208:211], v[28:31]
	v_mfma_f32_16x16x32_bf16 v[24:27], v[104:107], v[208:211], v[24:27]
	v_mfma_f32_16x16x32_bf16 v[12:15], v[64:67], v[218:221], v[12:15]
	v_mfma_f32_16x16x32_bf16 v[8:11], v[104:107], v[218:221], v[8:11]
	v_mfma_f32_16x16x32_bf16 v[60:63], v[68:71], v[188:191], v[60:63]
	v_mfma_f32_16x16x32_bf16 v[56:59], v[108:111], v[188:191], v[56:59]
	v_mfma_f32_16x16x32_bf16 v[44:47], v[68:71], v[204:207], v[44:47]
	v_mfma_f32_16x16x32_bf16 v[40:43], v[108:111], v[204:207], v[40:43]
	v_mfma_f32_16x16x32_bf16 v[28:31], v[68:71], v[214:217], v[28:31]
	v_mfma_f32_16x16x32_bf16 v[24:27], v[108:111], v[214:217], v[24:27]
	v_mfma_f32_16x16x32_bf16 v[12:15], v[68:71], v[222:225], v[12:15]
	v_mfma_f32_16x16x32_bf16 v[8:11], v[108:111], v[222:225], v[8:11]
	s_setprio 0
	s_setprio 1
	v_mfma_f32_16x16x32_bf16 v[52:55], v[144:147], v[184:187], v[52:55]
	v_mfma_f32_16x16x32_bf16 v[48:51], v[176:179], v[184:187], v[48:51]
	v_mfma_f32_16x16x32_bf16 v[36:39], v[144:147], v[196:199], v[36:39]
	v_mfma_f32_16x16x32_bf16 v[32:35], v[176:179], v[196:199], v[32:35]
	v_mfma_f32_16x16x32_bf16 v[20:23], v[144:147], v[208:211], v[20:23]
	v_mfma_f32_16x16x32_bf16 v[16:19], v[176:179], v[208:211], v[16:19]
	v_mfma_f32_16x16x32_bf16 v[4:7], v[144:147], v[218:221], v[4:7]
	v_mfma_f32_16x16x32_bf16 v[0:3], v[176:179], v[218:221], v[0:3]
	v_mfma_f32_16x16x32_bf16 v[52:55], v[148:151], v[188:191], v[52:55]
	v_mfma_f32_16x16x32_bf16 v[48:51], v[180:183], v[188:191], v[48:51]
	v_mfma_f32_16x16x32_bf16 v[36:39], v[148:151], v[204:207], v[36:39]
	v_mfma_f32_16x16x32_bf16 v[32:35], v[180:183], v[204:207], v[32:35]
	v_mfma_f32_16x16x32_bf16 v[20:23], v[148:151], v[214:217], v[20:23]
	v_mfma_f32_16x16x32_bf16 v[16:19], v[180:183], v[214:217], v[16:19]
	v_mfma_f32_16x16x32_bf16 v[4:7], v[148:151], v[222:225], v[4:7]
	v_mfma_f32_16x16x32_bf16 v[0:3], v[180:183], v[222:225], v[0:3]
	s_setprio 0
	s_barrier
	s_add_i32 s94, 0, 0x18000
	s_add_i32 vcc_lo, 0, 0x1c000
	v_add_u32_e32 v108, s94, v163
	v_add_u32_e32 v160, vcc_lo, v163
	ds_read_b128 v[64:67], v108
	ds_read_b128 v[68:71], v108 offset:1024
	ds_read_b128 v[104:107], v108 offset:2048
	ds_read_b128 v[108:111], v108 offset:3072
	ds_read_b128 v[144:147], v160
	ds_read_b128 v[148:151], v160 offset:1024
	ds_read_b128 v[176:179], v160 offset:2048
	ds_read_b128 v[180:183], v160 offset:3072
	s_add_u32 s76, s76, s14
	s_addc_u32 s77, s77, s15
	s_mov_b32 m0, s82
	v_lshl_add_u64 v[236:237], s[76:77], 0, v[152:153]
	ds_read_b128 v[184:187], v213 offset:32768
	ds_read_b128 v[188:191], v213 offset:33792
	ds_read_b128 v[196:199], v213 offset:34816
	ds_read_b128 v[204:207], v213 offset:35840
	ds_read_b128 v[208:211], v213 offset:36864
	ds_read_b128 v[214:217], v213 offset:37888
	ds_read_b128 v[218:221], v213 offset:38912
	ds_read_b128 v[222:225], v213 offset:39936
	global_load_lds_dwordx4 v[236:237], off
	v_lshl_add_u64 v[236:237], s[76:77], 0, v[156:157]
	s_mov_b32 m0, s83
	s_nop 0
	global_load_lds_dwordx4 v[236:237], off
	s_waitcnt vmcnt(8)
	s_waitcnt lgkmcnt(0)
	s_barrier
	s_setprio 1
	s_waitcnt lgkmcnt(0)
	v_mfma_f32_16x16x32_bf16 v[140:143], v[64:67], v[184:187], v[140:143]
	v_mfma_f32_16x16x32_bf16 v[136:139], v[104:107], v[184:187], v[136:139]
	v_mfma_f32_16x16x32_bf16 v[124:127], v[64:67], v[196:199], v[124:127]
	v_mfma_f32_16x16x32_bf16 v[120:123], v[104:107], v[196:199], v[120:123]
	v_mfma_f32_16x16x32_bf16 v[100:103], v[64:67], v[208:211], v[100:103]
	v_mfma_f32_16x16x32_bf16 v[96:99], v[104:107], v[208:211], v[96:99]
	v_mfma_f32_16x16x32_bf16 v[84:87], v[64:67], v[218:221], v[84:87]
	v_mfma_f32_16x16x32_bf16 v[80:83], v[104:107], v[218:221], v[80:83]
	v_mfma_f32_16x16x32_bf16 v[140:143], v[68:71], v[188:191], v[140:143]
	v_mfma_f32_16x16x32_bf16 v[136:139], v[108:111], v[188:191], v[136:139]
	v_mfma_f32_16x16x32_bf16 v[124:127], v[68:71], v[204:207], v[124:127]
	v_mfma_f32_16x16x32_bf16 v[120:123], v[108:111], v[204:207], v[120:123]
	v_mfma_f32_16x16x32_bf16 v[100:103], v[68:71], v[214:217], v[100:103]
	v_mfma_f32_16x16x32_bf16 v[96:99], v[108:111], v[214:217], v[96:99]
	v_mfma_f32_16x16x32_bf16 v[84:87], v[68:71], v[222:225], v[84:87]
	v_mfma_f32_16x16x32_bf16 v[80:83], v[108:111], v[222:225], v[80:83]
	s_setprio 0
	s_setprio 1
	v_mfma_f32_16x16x32_bf16 v[132:135], v[144:147], v[184:187], v[132:135]
	v_mfma_f32_16x16x32_bf16 v[128:131], v[176:179], v[184:187], v[128:131]
	v_mfma_f32_16x16x32_bf16 v[116:119], v[144:147], v[196:199], v[116:119]
	v_mfma_f32_16x16x32_bf16 v[112:115], v[176:179], v[196:199], v[112:115]
	v_mfma_f32_16x16x32_bf16 v[92:95], v[144:147], v[208:211], v[92:95]
	v_mfma_f32_16x16x32_bf16 v[88:91], v[176:179], v[208:211], v[88:91]
	v_mfma_f32_16x16x32_bf16 v[76:79], v[144:147], v[218:221], v[76:79]
	v_mfma_f32_16x16x32_bf16 v[72:75], v[176:179], v[218:221], v[72:75]
	v_mfma_f32_16x16x32_bf16 v[132:135], v[148:151], v[188:191], v[132:135]
	v_mfma_f32_16x16x32_bf16 v[128:131], v[180:183], v[188:191], v[128:131]
	v_mfma_f32_16x16x32_bf16 v[116:119], v[148:151], v[204:207], v[116:119]
	v_mfma_f32_16x16x32_bf16 v[112:115], v[180:183], v[204:207], v[112:115]
	v_mfma_f32_16x16x32_bf16 v[92:95], v[148:151], v[214:217], v[92:95]
	v_mfma_f32_16x16x32_bf16 v[88:91], v[180:183], v[214:217], v[88:91]
	v_mfma_f32_16x16x32_bf16 v[76:79], v[148:151], v[222:225], v[76:79]
	v_mfma_f32_16x16x32_bf16 v[72:75], v[180:183], v[222:225], v[72:75]
	s_setprio 0
	s_barrier
; #define PG8_STAGE(bufoff, gbase, voff) do { _Pragma("unroll") for (int _i = 0; _i < 2; ++_i) \
;         __builtin_amdgcn_global_load_lds((const unsigned*)((const char*)(gbase) + (voff)[_i]), (PG8_LAS unsigned*)(lds + (bufoff) + ldsw + _i * 8192), 16, 0, 0); } while (0)
; #define PG8_LDA(dst, b, h) do { _Pragma("unroll") for (int m = 0; m < 4; ++m) _Pragma("unroll") for (int k = 0; k < 2; ++k) dst[m][k] = *(const PG8_LAS bf16x8*)(lds + PG8_SA(b, h) + aoff + m * 2048 + k * 1024); } while (0)
; #define PG8_MMA(ai, bj, At, Bt) do { __builtin_amdgcn_s_setprio(1); _Pragma("unroll") for (int m = 0; m < 4; ++m) _Pragma("unroll") for (int n = 0; n < 2; ++n) _Pragma("unroll") for (int k = 0; k < 2; ++k) \
;         acc[ai][bj][m][n] = __builtin_amdgcn_mfma_f32_16x16x32_bf16(Bt[n][k], At[m][k], acc[ai][bj][m][n], 0, 0, 0); __builtin_amdgcn_s_setprio(0); } while (0)
; #define PG8_WAIT_V(n) asm volatile("s_waitcnt vmcnt(" #n ")" ::: "memory")
; #define PG8_WAIT_L(n) asm volatile("s_waitcnt lgkmcnt(" #n ")" ::: "memory")
; #define PG8_BAR __builtin_amdgcn_s_barrier()
; #define PG8_SCHED __builtin_amdgcn_sched_barrier(0)
; template <class Epi, class Sched, bool ALIGN_EPI = false, bool SP2 = false>
; __device__ __forceinline__ void gemm_phase(PG8_LAS unsigned char* lds, const Gemm g, const Sched& S, const Epi& E) {
;     ...
;         for (int t = 0; t < nt; t += 2) {
;     ...
;             PG8_LDA(At, 1, 1); PG8_STAGE(PG8_SB(1, 0), b3, voffB); PG8_STAGE(PG8_SB(1, 1), b3 + hstep, voffB); PG8_STAGE(PG8_SA(1, 0), a3, voffA);
;             PG8_WAIT_V(8); PG8_WAIT_L(0); PG8_BAR; PG8_MMA(1, 0, At, B0); PG8_MMA(1, 1, At, B1); PG8_BAR; PG8_SCHED;
	s_add_i32 s76, s94, s71
	v_lshl_add_u64 v[200:201], v[200:201], 0, s[26:27]
	s_mov_b32 m0, s76
	ds_read_b128 v[184:187], v213 offset:49152
	ds_read_b128 v[188:191], v213 offset:50176
	ds_read_b128 v[196:199], v213 offset:51200
	ds_read_b128 v[204:207], v213 offset:52224
	ds_read_b128 v[208:211], v213 offset:53248
	ds_read_b128 v[214:217], v213 offset:54272
	ds_read_b128 v[218:221], v213 offset:55296
	ds_read_b128 v[222:225], v213 offset:56320
	global_load_lds_dwordx4 v[200:201], off
	v_lshl_add_u64 v[200:201], v[226:227], 0, s[26:27]
	s_add_i32 m0, s76, 0x2000
	s_add_i32 s76, vcc_lo, s71
	global_load_lds_dwordx4 v[200:201], off
	v_lshl_add_u64 v[200:201], v[228:229], 0, s[26:27]
	s_mov_b32 m0, s76
	s_nop 0
	global_load_lds_dwordx4 v[200:201], off
	v_lshl_add_u64 v[200:201], v[230:231], 0, s[26:27]
	s_add_i32 m0, s76, 0x2000
	s_nop 0
	global_load_lds_dwordx4 v[200:201], off
	v_lshl_add_u64 v[200:201], v[232:233], 0, s[26:27]
	s_mov_b32 m0, s86
	s_nop 0
	global_load_lds_dwordx4 v[200:201], off
	v_lshl_add_u64 v[200:201], v[234:235], 0, s[26:27]
	s_mov_b32 m0, s87
	s_nop 0
	global_load_lds_dwordx4 v[200:201], off
	s_waitcnt vmcnt(8)
	s_waitcnt lgkmcnt(0)
	s_barrier
	s_setprio 1
	s_waitcnt lgkmcnt(0)
	v_mfma_f32_16x16x32_bf16 v[60:63], v[64:67], v[184:187], v[60:63]
	v_mfma_f32_16x16x32_bf16 v[56:59], v[104:107], v[184:187], v[56:59]
	v_mfma_f32_16x16x32_bf16 v[44:47], v[64:67], v[196:199], v[44:47]
	v_mfma_f32_16x16x32_bf16 v[40:43], v[104:107], v[196:199], v[40:43]
	v_mfma_f32_16x16x32_bf16 v[28:31], v[64:67], v[208:211], v[28:31]
	v_mfma_f32_16x16x32_bf16 v[24:27], v[104:107], v[208:211], v[24:27]
	v_mfma_f32_16x16x32_bf16 v[12:15], v[64:67], v[218:221], v[12:15]
	v_mfma_f32_16x16x32_bf16 v[8:11], v[104:107], v[218:221], v[8:11]
	v_mfma_f32_16x16x32_bf16 v[60:63], v[68:71], v[188:191], v[60:63]
	v_mfma_f32_16x16x32_bf16 v[56:59], v[108:111], v[188:191], v[56:59]
	v_mfma_f32_16x16x32_bf16 v[44:47], v[68:71], v[204:207], v[44:47]
	v_mfma_f32_16x16x32_bf16 v[40:43], v[108:111], v[204:207], v[40:43]
	v_mfma_f32_16x16x32_bf16 v[28:31], v[68:71], v[214:217], v[28:31]
	v_mfma_f32_16x16x32_bf16 v[24:27], v[108:111], v[214:217], v[24:27]
	v_mfma_f32_16x16x32_bf16 v[12:15], v[68:71], v[222:225], v[12:15]
	v_mfma_f32_16x16x32_bf16 v[8:11], v[108:111], v[222:225], v[8:11]
	s_setprio 0
	s_setprio 1
	v_mfma_f32_16x16x32_bf16 v[52:55], v[144:147], v[184:187], v[52:55]
	v_mfma_f32_16x16x32_bf16 v[48:51], v[176:179], v[184:187], v[48:51]
	v_mfma_f32_16x16x32_bf16 v[36:39], v[144:147], v[196:199], v[36:39]
	v_mfma_f32_16x16x32_bf16 v[32:35], v[176:179], v[196:199], v[32:35]
	v_mfma_f32_16x16x32_bf16 v[20:23], v[144:147], v[208:211], v[20:23]
	v_mfma_f32_16x16x32_bf16 v[16:19], v[176:179], v[208:211], v[16:19]
	v_mfma_f32_16x16x32_bf16 v[4:7], v[144:147], v[218:221], v[4:7]
	v_mfma_f32_16x16x32_bf16 v[0:3], v[176:179], v[218:221], v[0:3]
	v_mfma_f32_16x16x32_bf16 v[52:55], v[148:151], v[188:191], v[52:55]
	v_mfma_f32_16x16x32_bf16 v[48:51], v[180:183], v[188:191], v[48:51]
	v_mfma_f32_16x16x32_bf16 v[36:39], v[148:151], v[204:207], v[36:39]
	v_mfma_f32_16x16x32_bf16 v[32:35], v[180:183], v[204:207], v[32:35]
	v_mfma_f32_16x16x32_bf16 v[20:23], v[148:151], v[214:217], v[20:23]
	v_mfma_f32_16x16x32_bf16 v[16:19], v[180:183], v[214:217], v[16:19]
	v_mfma_f32_16x16x32_bf16 v[4:7], v[148:151], v[222:225], v[4:7]
	v_mfma_f32_16x16x32_bf16 v[0:3], v[180:183], v[222:225], v[0:3]
	s_setprio 0
	s_barrier
	s_add_u32 s6, s6, 0x100
	s_addc_u32 s7, s7, 0
	s_add_u32 s9, s9, 0x100
	s_addc_u32 s78, s78, 0
	s_cmp_ge_i32 s79, s84
	s_mov_b32 s76, s79
	s_cbranch_scc0 .LBB0_1291

; #define PG8_STAGE(bufoff, gbase, voff) do { _Pragma("unroll") for (int _i = 0; _i < 2; ++_i) \
;         __builtin_amdgcn_global_load_lds((const unsigned*)((const char*)(gbase) + (voff)[_i]), (PG8_LAS unsigned*)(lds + (bufoff) + ldsw + _i * 8192), 16, 0, 0); } while (0)
; #define PG8_LDA(dst, b, h) do { _Pragma("unroll") for (int m = 0; m < 4; ++m) _Pragma("unroll") for (int k = 0; k < 2; ++k) dst[m][k] = *(const PG8_LAS bf16x8*)(lds + PG8_SA(b, h) + aoff + m * 2048 + k * 1024); } while (0)
; #define PG8_LDB(dst, b, h) do { _Pragma("unroll") for (int n = 0; n < 2; ++n) _Pragma("unroll") for (int k = 0; k < 2; ++k) dst[n][k] = *(const PG8_LAS bf16x8*)(lds + PG8_SB(b, h) + boff + n * 2048 + k * 1024); } while (0)
; #define PG8_MMA(ai, bj, At, Bt) do { __builtin_amdgcn_s_setprio(1); _Pragma("unroll") for (int m = 0; m < 4; ++m) _Pragma("unroll") for (int n = 0; n < 2; ++n) _Pragma("unroll") for (int k = 0; k < 2; ++k) \
;         acc[ai][bj][m][n] = __builtin_amdgcn_mfma_f32_16x16x32_bf16(Bt[n][k], At[m][k], acc[ai][bj][m][n], 0, 0, 0); __builtin_amdgcn_s_setprio(0); } while (0)
; #define PG8_WAIT_V(n) asm volatile("s_waitcnt vmcnt(" #n ")" ::: "memory")
; #define PG8_WAIT_L(n) asm volatile("s_waitcnt lgkmcnt(" #n ")" ::: "memory")
; #define PG8_BAR __builtin_amdgcn_s_barrier()
; #define PG8_SCHED __builtin_amdgcn_sched_barrier(0)
; template <class Epi, class Sched, bool ALIGN_EPI = false, bool SP2 = false>
; __device__ __forceinline__ void gemm_phase(PG8_LAS unsigned char* lds, const Gemm g, const Sched& S, const Epi& E) {
;     ...
;             PG8_LDB(B0, 0, 0); PG8_LDB(B1, 0, 1); PG8_SCHED; PG8_LDA(At, 0, 0); PG8_STAGE(PG8_SA(1, 1), a1 + hstep, voffA);
;             PG8_WAIT_V(8); PG8_WAIT_L(0); PG8_BAR; PG8_MMA(0, 0, At, B0); PG8_MMA(0, 1, At, B1); PG8_BAR; PG8_SCHED;
;             PG8_LDA(At, 0, 1); PG8_STAGE(PG8_SB(0, 0), b2, voffB); PG8_STAGE(PG8_SB(0, 1), b2 + hstep, voffB); PG8_STAGE(PG8_SA(0, 0), a2, voffA);
;             PG8_WAIT_V(8); PG8_WAIT_L(0); PG8_BAR; PG8_MMA(1, 0, At, B0); PG8_MMA(1, 1, At, B1); PG8_BAR; PG8_SCHED;
.LBB0_1352:
	s_sleep 2
	ds_read_b128 v[128:131], v161
	ds_read_b128 v[132:135], v161 offset:1024
	ds_read_b128 v[168:171], v161 offset:2048
	ds_read_b128 v[172:175], v161 offset:3072
	ds_read_b128 v[176:179], v165
	ds_read_b128 v[180:183], v165 offset:1024
	ds_read_b128 v[184:187], v165 offset:2048
	ds_read_b128 v[188:191], v165 offset:3072
	s_add_i32 s75, s38, 2
	s_add_u32 s94, s6, 0x80
	s_addc_u32 s39, s7, 0
	s_cmp_eq_u32 s87, s38
	s_cselect_b32 s38, s30, s94
	s_cselect_b32 s39, s31, s39
	s_cselect_b32 s95, s35, s74
	s_cselect_b32 s94, s34, s37
	v_lshl_add_u64 v[154:155], s[6:7], 0, v[146:147]
	s_add_i32 m0, s79, 0xc000
	ds_read_b128 v[196:199], v167
	ds_read_b128 v[200:203], v167 offset:1024
	ds_read_b128 v[204:207], v167 offset:2048
	ds_read_b128 v[208:211], v167 offset:3072
	ds_read_b128 v[212:215], v167 offset:4096
	ds_read_b128 v[216:219], v167 offset:5120
	ds_read_b128 v[220:223], v167 offset:6144
	ds_read_b128 v[224:227], v167 offset:7168
	global_load_lds_dwordx4 v[154:155], off
	v_lshl_add_u64 v[154:155], s[6:7], 0, v[148:149]
	s_add_i32 m0, s79, 0xe000
	s_nop 0
	global_load_lds_dwordx4 v[154:155], off
	s_waitcnt vmcnt(8)
	s_waitcnt lgkmcnt(0)
	s_barrier
	s_setprio 1
	s_waitcnt lgkmcnt(0)
	v_mfma_f32_16x16x32_bf16 v[124:127], v[128:131], v[196:199], v[124:127]
	v_mfma_f32_16x16x32_bf16 v[120:123], v[168:171], v[196:199], v[120:123]
	v_mfma_f32_16x16x32_bf16 v[108:111], v[128:131], v[204:207], v[108:111]
	v_mfma_f32_16x16x32_bf16 v[104:107], v[168:171], v[204:207], v[104:107]
	v_mfma_f32_16x16x32_bf16 v[92:95], v[128:131], v[212:215], v[92:95]
	v_mfma_f32_16x16x32_bf16 v[88:91], v[168:171], v[212:215], v[88:91]
	v_mfma_f32_16x16x32_bf16 v[76:79], v[128:131], v[220:223], v[76:79]
	v_mfma_f32_16x16x32_bf16 v[72:75], v[168:171], v[220:223], v[72:75]
	v_mfma_f32_16x16x32_bf16 v[124:127], v[132:135], v[200:203], v[124:127]
	v_mfma_f32_16x16x32_bf16 v[120:123], v[172:175], v[200:203], v[120:123]
	v_mfma_f32_16x16x32_bf16 v[108:111], v[132:135], v[208:211], v[108:111]
	v_mfma_f32_16x16x32_bf16 v[104:107], v[172:175], v[208:211], v[104:107]
	v_mfma_f32_16x16x32_bf16 v[92:95], v[132:135], v[216:219], v[92:95]
	v_mfma_f32_16x16x32_bf16 v[88:91], v[172:175], v[216:219], v[88:91]
	v_mfma_f32_16x16x32_bf16 v[76:79], v[132:135], v[224:227], v[76:79]
	v_mfma_f32_16x16x32_bf16 v[72:75], v[172:175], v[224:227], v[72:75]
	s_setprio 0
	s_setprio 1
	v_mfma_f32_16x16x32_bf16 v[116:119], v[176:179], v[196:199], v[116:119]
	v_mfma_f32_16x16x32_bf16 v[112:115], v[184:187], v[196:199], v[112:115]
	v_mfma_f32_16x16x32_bf16 v[100:103], v[176:179], v[204:207], v[100:103]
	v_mfma_f32_16x16x32_bf16 v[96:99], v[184:187], v[204:207], v[96:99]
	v_mfma_f32_16x16x32_bf16 v[84:87], v[176:179], v[212:215], v[84:87]
	v_mfma_f32_16x16x32_bf16 v[80:83], v[184:187], v[212:215], v[80:83]
	v_mfma_f32_16x16x32_bf16 v[68:71], v[176:179], v[220:223], v[68:71]
	v_mfma_f32_16x16x32_bf16 v[64:67], v[184:187], v[220:223], v[64:67]
	v_mfma_f32_16x16x32_bf16 v[116:119], v[180:183], v[200:203], v[116:119]
	v_mfma_f32_16x16x32_bf16 v[112:115], v[188:191], v[200:203], v[112:115]
	v_mfma_f32_16x16x32_bf16 v[100:103], v[180:183], v[208:211], v[100:103]
	v_mfma_f32_16x16x32_bf16 v[96:99], v[188:191], v[208:211], v[96:99]
	v_mfma_f32_16x16x32_bf16 v[84:87], v[180:183], v[216:219], v[84:87]
	v_mfma_f32_16x16x32_bf16 v[80:83], v[188:191], v[216:219], v[80:83]
	v_mfma_f32_16x16x32_bf16 v[68:71], v[180:183], v[224:227], v[68:71]
	v_mfma_f32_16x16x32_bf16 v[64:67], v[188:191], v[224:227], v[64:67]
	s_setprio 0
	s_barrier
	s_add_i32 s96, s88, s66
	v_lshl_add_u64 v[154:155], s[94:95], 0, v[138:139]
	s_mov_b32 m0, s96
	ds_read_b128 v[196:199], v167 offset:16384
	ds_read_b128 v[200:203], v167 offset:17408
	ds_read_b128 v[204:207], v167 offset:18432
	ds_read_b128 v[208:211], v167 offset:19456
	ds_read_b128 v[212:215], v167 offset:20480
	ds_read_b128 v[216:219], v167 offset:21504
	ds_read_b128 v[220:223], v167 offset:22528
	ds_read_b128 v[224:227], v167 offset:23552
	global_load_lds_dwordx4 v[154:155], off
	s_add_i32 m0, s96, 0x2000
	v_lshl_add_u64 v[158:159], s[94:95], 0, v[142:143]
	s_add_u32 s94, s94, s8
	s_addc_u32 s95, s95, s9
	s_add_i32 s96, s89, s66
	global_load_lds_dwordx4 v[158:159], off
	v_lshl_add_u64 v[162:163], s[94:95], 0, v[138:139]
	s_mov_b32 m0, s96
	v_lshl_add_u64 v[228:229], s[94:95], 0, v[142:143]
	global_load_lds_dwordx4 v[162:163], off
	s_add_i32 m0, s96, 0x2000
	v_lshl_add_u64 v[230:231], s[38:39], 0, v[136:137]
	global_load_lds_dwordx4 v[228:229], off
	s_mov_b32 m0, s79
	v_lshl_add_u64 v[232:233], s[38:39], 0, v[140:141]
	global_load_lds_dwordx4 v[230:231], off
	s_mov_b32 m0, s80
	s_nop 0
	global_load_lds_dwordx4 v[232:233], off
	s_waitcnt vmcnt(8)
	s_waitcnt lgkmcnt(0)
	s_barrier
; #define PG8_STAGE(bufoff, gbase, voff) do { _Pragma("unroll") for (int _i = 0; _i < 2; ++_i) \
;         __builtin_amdgcn_global_load_lds((const unsigned*)((const char*)(gbase) + (voff)[_i]), (PG8_LAS unsigned*)(lds + (bufoff) + ldsw + _i * 8192), 16, 0, 0); } while (0)
; #define PG8_LDA(dst, b, h) do { _Pragma("unroll") for (int m = 0; m < 4; ++m) _Pragma("unroll") for (int k = 0; k < 2; ++k) dst[m][k] = *(const PG8_LAS bf16x8*)(lds + PG8_SA(b, h) + aoff + m * 2048 + k * 1024); } while (0)
; #define PG8_LDB(dst, b, h) do { _Pragma("unroll") for (int n = 0; n < 2; ++n) _Pragma("unroll") for (int k = 0; k < 2; ++k) dst[n][k] = *(const PG8_LAS bf16x8*)(lds + PG8_SB(b, h) + boff + n * 2048 + k * 1024); } while (0)
; #define PG8_MMA(ai, bj, At, Bt) do { __builtin_amdgcn_s_setprio(1); _Pragma("unroll") for (int m = 0; m < 4; ++m) _Pragma("unroll") for (int n = 0; n < 2; ++n) _Pragma("unroll") for (int k = 0; k < 2; ++k) \
;         acc[ai][bj][m][n] = __builtin_amdgcn_mfma_f32_16x16x32_bf16(Bt[n][k], At[m][k], acc[ai][bj][m][n], 0, 0, 0); __builtin_amdgcn_s_setprio(0); } while (0)
; #define PG8_WAIT_V(n) asm volatile("s_waitcnt vmcnt(" #n ")" ::: "memory")
; #define PG8_WAIT_L(n) asm volatile("s_waitcnt lgkmcnt(" #n ")" ::: "memory")
; #define PG8_BAR __builtin_amdgcn_s_barrier()
; #define PG8_SCHED __builtin_amdgcn_sched_barrier(0)
; template <class Epi, class Sched, bool ALIGN_EPI = false, bool SP2 = false>
; __device__ __forceinline__ void gemm_phase(PG8_LAS unsigned char* lds, const Gemm g, const Sched& S, const Epi& E) {
;     ...
;             PG8_WAIT_V(8); PG8_WAIT_L(0); PG8_BAR; PG8_MMA(1, 0, At, B0); PG8_MMA(1, 1, At, B1); PG8_BAR; PG8_SCHED;
;             PG8_LDB(B0, 1, 0); PG8_LDB(B1, 1, 1); PG8_SCHED; PG8_LDA(At, 1, 0); PG8_STAGE(PG8_SA(0, 1), a2 + hstep, voffA);
;             PG8_WAIT_V(8); PG8_WAIT_L(0); PG8_BAR; PG8_MMA(0, 0, At, B0); PG8_MMA(0, 1, At, B1); PG8_BAR; PG8_SCHED;
	s_setprio 1
	s_waitcnt lgkmcnt(0)
	v_mfma_f32_16x16x32_bf16 v[60:63], v[128:131], v[196:199], v[60:63]
	v_mfma_f32_16x16x32_bf16 v[56:59], v[168:171], v[196:199], v[56:59]
	v_mfma_f32_16x16x32_bf16 v[44:47], v[128:131], v[204:207], v[44:47]
	v_mfma_f32_16x16x32_bf16 v[40:43], v[168:171], v[204:207], v[40:43]
	v_mfma_f32_16x16x32_bf16 v[28:31], v[128:131], v[212:215], v[28:31]
	v_mfma_f32_16x16x32_bf16 v[24:27], v[168:171], v[212:215], v[24:27]
	v_mfma_f32_16x16x32_bf16 v[12:15], v[128:131], v[220:223], v[12:15]
	v_mfma_f32_16x16x32_bf16 v[8:11], v[168:171], v[220:223], v[8:11]
	v_mfma_f32_16x16x32_bf16 v[60:63], v[132:135], v[200:203], v[60:63]
	v_mfma_f32_16x16x32_bf16 v[56:59], v[172:175], v[200:203], v[56:59]
	v_mfma_f32_16x16x32_bf16 v[44:47], v[132:135], v[208:211], v[44:47]
	v_mfma_f32_16x16x32_bf16 v[40:43], v[172:175], v[208:211], v[40:43]
	v_mfma_f32_16x16x32_bf16 v[28:31], v[132:135], v[216:219], v[28:31]
	v_mfma_f32_16x16x32_bf16 v[24:27], v[172:175], v[216:219], v[24:27]
	v_mfma_f32_16x16x32_bf16 v[12:15], v[132:135], v[224:227], v[12:15]
	v_mfma_f32_16x16x32_bf16 v[8:11], v[172:175], v[224:227], v[8:11]
	s_setprio 0
	s_setprio 1
	v_mfma_f32_16x16x32_bf16 v[52:55], v[176:179], v[196:199], v[52:55]
	v_mfma_f32_16x16x32_bf16 v[48:51], v[184:187], v[196:199], v[48:51]
	v_mfma_f32_16x16x32_bf16 v[36:39], v[176:179], v[204:207], v[36:39]
	v_mfma_f32_16x16x32_bf16 v[32:35], v[184:187], v[204:207], v[32:35]
	v_mfma_f32_16x16x32_bf16 v[20:23], v[176:179], v[212:215], v[20:23]
	v_mfma_f32_16x16x32_bf16 v[16:19], v[184:187], v[212:215], v[16:19]
	v_mfma_f32_16x16x32_bf16 v[4:7], v[176:179], v[220:223], v[4:7]
	v_mfma_f32_16x16x32_bf16 v[0:3], v[184:187], v[220:223], v[0:3]
	v_mfma_f32_16x16x32_bf16 v[52:55], v[180:183], v[200:203], v[52:55]
	v_mfma_f32_16x16x32_bf16 v[48:51], v[188:191], v[200:203], v[48:51]
	v_mfma_f32_16x16x32_bf16 v[36:39], v[180:183], v[208:211], v[36:39]
	v_mfma_f32_16x16x32_bf16 v[32:35], v[188:191], v[208:211], v[32:35]
	v_mfma_f32_16x16x32_bf16 v[20:23], v[180:183], v[216:219], v[20:23]
	v_mfma_f32_16x16x32_bf16 v[16:19], v[188:191], v[216:219], v[16:19]
	v_mfma_f32_16x16x32_bf16 v[4:7], v[180:183], v[224:227], v[4:7]
	v_mfma_f32_16x16x32_bf16 v[0:3], v[188:191], v[224:227], v[0:3]
	s_setprio 0
	s_barrier
	s_add_i32 s94, 0, 0x18000
	v_add_u32_e32 v152, s94, v153
	s_add_i32 s95, 0, 0x1c000
	ds_read_b128 v[128:131], v152
	ds_read_b128 v[132:135], v152 offset:1024
	ds_read_b128 v[168:171], v152 offset:2048
	ds_read_b128 v[172:175], v152 offset:3072
	v_add_u32_e32 v152, s95, v153
	ds_read_b128 v[176:179], v152
	ds_read_b128 v[180:183], v152 offset:1024
	ds_read_b128 v[184:187], v152 offset:2048
	ds_read_b128 v[188:191], v152 offset:3072
	s_add_u32 s38, s38, s8
	s_addc_u32 s39, s39, s9
	s_mov_b32 m0, s81
	v_lshl_add_u64 v[234:235], s[38:39], 0, v[136:137]
	ds_read_b128 v[196:199], v167 offset:32768
	ds_read_b128 v[200:203], v167 offset:33792
	ds_read_b128 v[204:207], v167 offset:34816
	ds_read_b128 v[208:211], v167 offset:35840
	ds_read_b128 v[212:215], v167 offset:36864
	ds_read_b128 v[216:219], v167 offset:37888
	ds_read_b128 v[220:223], v167 offset:38912
	ds_read_b128 v[224:227], v167 offset:39936
	global_load_lds_dwordx4 v[234:235], off
	v_lshl_add_u64 v[234:235], s[38:39], 0, v[140:141]
	s_mov_b32 m0, s82
	s_nop 0
	global_load_lds_dwordx4 v[234:235], off
	s_waitcnt vmcnt(8)
	s_waitcnt lgkmcnt(0)
	s_barrier
	s_setprio 1
	s_waitcnt lgkmcnt(0)
	v_mfma_f32_16x16x32_bf16 v[124:127], v[128:131], v[196:199], v[124:127]
	v_mfma_f32_16x16x32_bf16 v[120:123], v[168:171], v[196:199], v[120:123]
	v_mfma_f32_16x16x32_bf16 v[108:111], v[128:131], v[204:207], v[108:111]
	v_mfma_f32_16x16x32_bf16 v[104:107], v[168:171], v[204:207], v[104:107]
	v_mfma_f32_16x16x32_bf16 v[92:95], v[128:131], v[212:215], v[92:95]
	v_mfma_f32_16x16x32_bf16 v[88:91], v[168:171], v[212:215], v[88:91]
	v_mfma_f32_16x16x32_bf16 v[76:79], v[128:131], v[220:223], v[76:79]
	v_mfma_f32_16x16x32_bf16 v[72:75], v[168:171], v[220:223], v[72:75]
	v_mfma_f32_16x16x32_bf16 v[124:127], v[132:135], v[200:203], v[124:127]
	v_mfma_f32_16x16x32_bf16 v[120:123], v[172:175], v[200:203], v[120:123]
	v_mfma_f32_16x16x32_bf16 v[108:111], v[132:135], v[208:211], v[108:111]
	v_mfma_f32_16x16x32_bf16 v[104:107], v[172:175], v[208:211], v[104:107]
	v_mfma_f32_16x16x32_bf16 v[92:95], v[132:135], v[216:219], v[92:95]
	v_mfma_f32_16x16x32_bf16 v[88:91], v[172:175], v[216:219], v[88:91]
	v_mfma_f32_16x16x32_bf16 v[76:79], v[132:135], v[224:227], v[76:79]
	v_mfma_f32_16x16x32_bf16 v[72:75], v[172:175], v[224:227], v[72:75]
	s_setprio 0
	s_setprio 1
	v_mfma_f32_16x16x32_bf16 v[116:119], v[176:179], v[196:199], v[116:119]
	v_mfma_f32_16x16x32_bf16 v[112:115], v[184:187], v[196:199], v[112:115]
	v_mfma_f32_16x16x32_bf16 v[100:103], v[176:179], v[204:207], v[100:103]
	v_mfma_f32_16x16x32_bf16 v[96:99], v[184:187], v[204:207], v[96:99]
	v_mfma_f32_16x16x32_bf16 v[84:87], v[176:179], v[212:215], v[84:87]
	v_mfma_f32_16x16x32_bf16 v[80:83], v[184:187], v[212:215], v[80:83]
	v_mfma_f32_16x16x32_bf16 v[68:71], v[176:179], v[220:223], v[68:71]
	v_mfma_f32_16x16x32_bf16 v[64:67], v[184:187], v[220:223], v[64:67]
	v_mfma_f32_16x16x32_bf16 v[116:119], v[180:183], v[200:203], v[116:119]
	v_mfma_f32_16x16x32_bf16 v[112:115], v[188:191], v[200:203], v[112:115]
	v_mfma_f32_16x16x32_bf16 v[100:103], v[180:183], v[208:211], v[100:103]
	v_mfma_f32_16x16x32_bf16 v[96:99], v[188:191], v[208:211], v[96:99]
	v_mfma_f32_16x16x32_bf16 v[84:87], v[180:183], v[216:219], v[84:87]
	v_mfma_f32_16x16x32_bf16 v[80:83], v[188:191], v[216:219], v[80:83]
	v_mfma_f32_16x16x32_bf16 v[68:71], v[180:183], v[224:227], v[68:71]
	v_mfma_f32_16x16x32_bf16 v[64:67], v[188:191], v[224:227], v[64:67]
	s_setprio 0
	s_barrier
; #define PG8_STAGE(bufoff, gbase, voff) do { _Pragma("unroll") for (int _i = 0; _i < 2; ++_i) \
;         __builtin_amdgcn_global_load_lds((const unsigned*)((const char*)(gbase) + (voff)[_i]), (PG8_LAS unsigned*)(lds + (bufoff) + ldsw + _i * 8192), 16, 0, 0); } while (0)
; #define PG8_LDA(dst, b, h) do { _Pragma("unroll") for (int m = 0; m < 4; ++m) _Pragma("unroll") for (int k = 0; k < 2; ++k) dst[m][k] = *(const PG8_LAS bf16x8*)(lds + PG8_SA(b, h) + aoff + m * 2048 + k * 1024); } while (0)
; #define PG8_MMA(ai, bj, At, Bt) do { __builtin_amdgcn_s_setprio(1); _Pragma("unroll") for (int m = 0; m < 4; ++m) _Pragma("unroll") for (int n = 0; n < 2; ++n) _Pragma("unroll") for (int k = 0; k < 2; ++k) \
;         acc[ai][bj][m][n] = __builtin_amdgcn_mfma_f32_16x16x32_bf16(Bt[n][k], At[m][k], acc[ai][bj][m][n], 0, 0, 0); __builtin_amdgcn_s_setprio(0); } while (0)
; #define PG8_WAIT_V(n) asm volatile("s_waitcnt vmcnt(" #n ")" ::: "memory")
; #define PG8_WAIT_L(n) asm volatile("s_waitcnt lgkmcnt(" #n ")" ::: "memory")
; #define PG8_BAR __builtin_amdgcn_s_barrier()
; #define PG8_SCHED __builtin_amdgcn_sched_barrier(0)
; template <class Epi, class Sched, bool ALIGN_EPI = false, bool SP2 = false>
; __device__ __forceinline__ void gemm_phase(PG8_LAS unsigned char* lds, const Gemm g, const Sched& S, const Epi& E) {
;     ...
;         for (int t = 0; t < nt; t += 2) {
;     ...
;             PG8_LDA(At, 1, 1); PG8_STAGE(PG8_SB(1, 0), b3, voffB); PG8_STAGE(PG8_SB(1, 1), b3 + hstep, voffB); PG8_STAGE(PG8_SA(1, 0), a3, voffA);
;             PG8_WAIT_V(8); PG8_WAIT_L(0); PG8_BAR; PG8_MMA(1, 0, At, B0); PG8_MMA(1, 1, At, B1); PG8_BAR; PG8_SCHED;
	s_add_i32 s38, s94, s66
	v_lshl_add_u64 v[154:155], v[154:155], 0, s[22:23]
	s_mov_b32 m0, s38
	ds_read_b128 v[196:199], v167 offset:49152
	ds_read_b128 v[200:203], v167 offset:50176
	ds_read_b128 v[204:207], v167 offset:51200
	ds_read_b128 v[208:211], v167 offset:52224
	ds_read_b128 v[212:215], v167 offset:53248
	ds_read_b128 v[216:219], v167 offset:54272
	ds_read_b128 v[220:223], v167 offset:55296
	ds_read_b128 v[224:227], v167 offset:56320
	global_load_lds_dwordx4 v[154:155], off
	v_lshl_add_u64 v[154:155], v[158:159], 0, s[22:23]
	s_add_i32 m0, s38, 0x2000
	s_add_i32 s38, s95, s66
	global_load_lds_dwordx4 v[154:155], off
	v_lshl_add_u64 v[154:155], v[162:163], 0, s[22:23]
	s_mov_b32 m0, s38
	s_nop 0
	global_load_lds_dwordx4 v[154:155], off
	v_lshl_add_u64 v[154:155], v[228:229], 0, s[22:23]
	s_add_i32 m0, s38, 0x2000
	s_nop 0
	global_load_lds_dwordx4 v[154:155], off
	v_lshl_add_u64 v[154:155], v[230:231], 0, s[22:23]
	s_mov_b32 m0, s84
	s_nop 0
	global_load_lds_dwordx4 v[154:155], off
	v_lshl_add_u64 v[154:155], v[232:233], 0, s[22:23]
	s_mov_b32 m0, s85
	s_nop 0
	global_load_lds_dwordx4 v[154:155], off
	s_waitcnt vmcnt(8)
	s_waitcnt lgkmcnt(0)
	s_barrier
	s_setprio 1
	s_waitcnt lgkmcnt(0)
	v_mfma_f32_16x16x32_bf16 v[60:63], v[128:131], v[196:199], v[60:63]
	v_mfma_f32_16x16x32_bf16 v[56:59], v[168:171], v[196:199], v[56:59]
	v_mfma_f32_16x16x32_bf16 v[44:47], v[128:131], v[204:207], v[44:47]
	v_mfma_f32_16x16x32_bf16 v[40:43], v[168:171], v[204:207], v[40:43]
	v_mfma_f32_16x16x32_bf16 v[28:31], v[128:131], v[212:215], v[28:31]
	v_mfma_f32_16x16x32_bf16 v[24:27], v[168:171], v[212:215], v[24:27]
	v_mfma_f32_16x16x32_bf16 v[12:15], v[128:131], v[220:223], v[12:15]
	v_mfma_f32_16x16x32_bf16 v[8:11], v[168:171], v[220:223], v[8:11]
	v_mfma_f32_16x16x32_bf16 v[60:63], v[132:135], v[200:203], v[60:63]
	v_mfma_f32_16x16x32_bf16 v[56:59], v[172:175], v[200:203], v[56:59]
	v_mfma_f32_16x16x32_bf16 v[44:47], v[132:135], v[208:211], v[44:47]
	v_mfma_f32_16x16x32_bf16 v[40:43], v[172:175], v[208:211], v[40:43]
	v_mfma_f32_16x16x32_bf16 v[28:31], v[132:135], v[216:219], v[28:31]
	v_mfma_f32_16x16x32_bf16 v[24:27], v[172:175], v[216:219], v[24:27]
	v_mfma_f32_16x16x32_bf16 v[12:15], v[132:135], v[224:227], v[12:15]
	v_mfma_f32_16x16x32_bf16 v[8:11], v[172:175], v[224:227], v[8:11]
	s_setprio 0
	s_setprio 1
	v_mfma_f32_16x16x32_bf16 v[52:55], v[176:179], v[196:199], v[52:55]
	v_mfma_f32_16x16x32_bf16 v[48:51], v[184:187], v[196:199], v[48:51]
	v_mfma_f32_16x16x32_bf16 v[36:39], v[176:179], v[204:207], v[36:39]
	v_mfma_f32_16x16x32_bf16 v[32:35], v[184:187], v[204:207], v[32:35]
	v_mfma_f32_16x16x32_bf16 v[20:23], v[176:179], v[212:215], v[20:23]
	v_mfma_f32_16x16x32_bf16 v[16:19], v[184:187], v[212:215], v[16:19]
	v_mfma_f32_16x16x32_bf16 v[4:7], v[176:179], v[220:223], v[4:7]
	v_mfma_f32_16x16x32_bf16 v[0:3], v[184:187], v[220:223], v[0:3]
	v_mfma_f32_16x16x32_bf16 v[52:55], v[180:183], v[200:203], v[52:55]
	v_mfma_f32_16x16x32_bf16 v[48:51], v[188:191], v[200:203], v[48:51]
	v_mfma_f32_16x16x32_bf16 v[36:39], v[180:183], v[208:211], v[36:39]
	v_mfma_f32_16x16x32_bf16 v[32:35], v[188:191], v[208:211], v[32:35]
	v_mfma_f32_16x16x32_bf16 v[20:23], v[180:183], v[216:219], v[20:23]
	v_mfma_f32_16x16x32_bf16 v[16:19], v[188:191], v[216:219], v[16:19]
	v_mfma_f32_16x16x32_bf16 v[4:7], v[180:183], v[224:227], v[4:7]
	v_mfma_f32_16x16x32_bf16 v[0:3], v[188:191], v[224:227], v[0:3]
	s_setprio 0
	s_barrier
	s_add_u32 s6, s6, 0x100
	s_addc_u32 s7, s7, 0
	s_add_u32 s37, s37, 0x100
	s_addc_u32 s74, s74, 0
	s_cmp_ge_i32 s75, s86
	s_mov_b32 s38, s75
	s_cbranch_scc0 .LBB0_1352

; #define PG8_STAGE(bufoff, gbase, voff) do { _Pragma("unroll") for (int _i = 0; _i < 2; ++_i) \
;         __builtin_amdgcn_global_load_lds((const unsigned*)((const char*)(gbase) + (voff)[_i]), (PG8_LAS unsigned*)(lds + (bufoff) + ldsw + _i * 8192), 16, 0, 0); } while (0)
; #define PG8_LDA(dst, b, h) do { _Pragma("unroll") for (int m = 0; m < 4; ++m) _Pragma("unroll") for (int k = 0; k < 2; ++k) dst[m][k] = *(const PG8_LAS bf16x8*)(lds + PG8_SA(b, h) + aoff + m * 2048 + k * 1024); } while (0)
; #define PG8_LDB(dst, b, h) do { _Pragma("unroll") for (int n = 0; n < 2; ++n) _Pragma("unroll") for (int k = 0; k < 2; ++k) dst[n][k] = *(const PG8_LAS bf16x8*)(lds + PG8_SB(b, h) + boff + n * 2048 + k * 1024); } while (0)
; #define PG8_MMA(ai, bj, At, Bt) do { __builtin_amdgcn_s_setprio(1); _Pragma("unroll") for (int m = 0; m < 4; ++m) _Pragma("unroll") for (int n = 0; n < 2; ++n) _Pragma("unroll") for (int k = 0; k < 2; ++k) \
;         acc[ai][bj][m][n] = __builtin_amdgcn_mfma_f32_16x16x32_bf16(Bt[n][k], At[m][k], acc[ai][bj][m][n], 0, 0, 0); __builtin_amdgcn_s_setprio(0); } while (0)
; #define PG8_WAIT_V(n) asm volatile("s_waitcnt vmcnt(" #n ")" ::: "memory")
; #define PG8_WAIT_L(n) asm volatile("s_waitcnt lgkmcnt(" #n ")" ::: "memory")
; #define PG8_BAR __builtin_amdgcn_s_barrier()
; #define PG8_SCHED __builtin_amdgcn_sched_barrier(0)
; template <class Epi, class Sched, bool ALIGN_EPI = false, bool SP2 = false>
; __device__ __forceinline__ void gemm_phase(PG8_LAS unsigned char* lds, const Gemm g, const Sched& S, const Epi& E) {
;     ...
;             PG8_LDB(B0, 0, 0); PG8_LDB(B1, 0, 1); PG8_SCHED; PG8_LDA(At, 0, 0); PG8_STAGE(PG8_SA(1, 1), a1 + hstep, voffA);
;             PG8_WAIT_V(8); PG8_WAIT_L(0); PG8_BAR; PG8_MMA(0, 0, At, B0); PG8_MMA(0, 1, At, B1); PG8_BAR; PG8_SCHED;
;             PG8_LDA(At, 0, 1); PG8_STAGE(PG8_SB(0, 0), b2, voffB); PG8_STAGE(PG8_SB(0, 1), b2 + hstep, voffB); PG8_STAGE(PG8_SA(0, 0), a2, voffA);
;             PG8_WAIT_V(8); PG8_WAIT_L(0); PG8_BAR; PG8_MMA(1, 0, At, B0); PG8_MMA(1, 1, At, B1); PG8_BAR; PG8_SCHED;
.LBB0_1381:
	s_sleep 2
	ds_read_b128 v[146:149], v162
	ds_read_b128 v[150:153], v162 offset:1024
	ds_read_b128 v[154:157], v162 offset:2048
	ds_read_b128 v[166:169], v162 offset:3072
	ds_read_b128 v[170:173], v163
	ds_read_b128 v[174:177], v163 offset:1024
	ds_read_b128 v[178:181], v163 offset:2048
	ds_read_b128 v[182:185], v163 offset:3072
	s_add_i32 s75, s38, 2
	s_add_u32 s94, s6, 0x80
	s_addc_u32 s39, s7, 0
	s_cmp_eq_u32 s86, s38
	s_cselect_b32 s38, s30, s94
	s_cselect_b32 s39, s31, s39
	s_cselect_b32 s95, s35, s74
	s_cselect_b32 s94, s34, s37
	v_lshl_add_u64 v[158:159], s[6:7], 0, v[140:141]
	s_add_i32 m0, s77, 0xc000
	ds_read_b128 v[186:189], v164
	ds_read_b128 v[196:199], v164 offset:1024
	ds_read_b128 v[200:203], v164 offset:2048
	ds_read_b128 v[204:207], v164 offset:3072
	ds_read_b128 v[208:211], v164 offset:4096
	ds_read_b128 v[212:215], v164 offset:5120
	ds_read_b128 v[216:219], v164 offset:6144
	ds_read_b128 v[220:223], v164 offset:7168
	global_load_lds_dwordx4 v[158:159], off
	v_lshl_add_u64 v[158:159], s[6:7], 0, v[142:143]
	s_add_i32 m0, s77, 0xe000
	s_nop 0
	global_load_lds_dwordx4 v[158:159], off
	s_waitcnt vmcnt(8)
	s_waitcnt lgkmcnt(0)
	s_barrier
	s_setprio 1
	s_waitcnt lgkmcnt(0)
	v_mfma_f32_16x16x32_bf16 v[124:127], v[146:149], v[186:189], v[124:127]
	v_mfma_f32_16x16x32_bf16 v[120:123], v[154:157], v[186:189], v[120:123]
	v_mfma_f32_16x16x32_bf16 v[116:119], v[146:149], v[200:203], v[116:119]
	v_mfma_f32_16x16x32_bf16 v[112:115], v[154:157], v[200:203], v[112:115]
	v_mfma_f32_16x16x32_bf16 v[108:111], v[146:149], v[208:211], v[108:111]
	v_mfma_f32_16x16x32_bf16 v[104:107], v[154:157], v[208:211], v[104:107]
	v_mfma_f32_16x16x32_bf16 v[100:103], v[146:149], v[216:219], v[100:103]
	v_mfma_f32_16x16x32_bf16 v[96:99], v[154:157], v[216:219], v[96:99]
	v_mfma_f32_16x16x32_bf16 v[124:127], v[150:153], v[196:199], v[124:127]
	v_mfma_f32_16x16x32_bf16 v[120:123], v[166:169], v[196:199], v[120:123]
	v_mfma_f32_16x16x32_bf16 v[116:119], v[150:153], v[204:207], v[116:119]
	v_mfma_f32_16x16x32_bf16 v[112:115], v[166:169], v[204:207], v[112:115]
	v_mfma_f32_16x16x32_bf16 v[108:111], v[150:153], v[212:215], v[108:111]
	v_mfma_f32_16x16x32_bf16 v[104:107], v[166:169], v[212:215], v[104:107]
	v_mfma_f32_16x16x32_bf16 v[100:103], v[150:153], v[220:223], v[100:103]
	v_mfma_f32_16x16x32_bf16 v[96:99], v[166:169], v[220:223], v[96:99]
	s_setprio 0
	s_setprio 1
	v_mfma_f32_16x16x32_bf16 v[60:63], v[170:173], v[186:189], v[60:63]
	v_mfma_f32_16x16x32_bf16 v[56:59], v[178:181], v[186:189], v[56:59]
	v_mfma_f32_16x16x32_bf16 v[52:55], v[170:173], v[200:203], v[52:55]
	v_mfma_f32_16x16x32_bf16 v[48:51], v[178:181], v[200:203], v[48:51]
	v_mfma_f32_16x16x32_bf16 v[44:47], v[170:173], v[208:211], v[44:47]
	v_mfma_f32_16x16x32_bf16 v[40:43], v[178:181], v[208:211], v[40:43]
	v_mfma_f32_16x16x32_bf16 v[36:39], v[170:173], v[216:219], v[36:39]
	v_mfma_f32_16x16x32_bf16 v[32:35], v[178:181], v[216:219], v[32:35]
	v_mfma_f32_16x16x32_bf16 v[60:63], v[174:177], v[196:199], v[60:63]
	v_mfma_f32_16x16x32_bf16 v[56:59], v[182:185], v[196:199], v[56:59]
	v_mfma_f32_16x16x32_bf16 v[52:55], v[174:177], v[204:207], v[52:55]
	v_mfma_f32_16x16x32_bf16 v[48:51], v[182:185], v[204:207], v[48:51]
	v_mfma_f32_16x16x32_bf16 v[44:47], v[174:177], v[212:215], v[44:47]
	v_mfma_f32_16x16x32_bf16 v[40:43], v[182:185], v[212:215], v[40:43]
	v_mfma_f32_16x16x32_bf16 v[36:39], v[174:177], v[220:223], v[36:39]
	v_mfma_f32_16x16x32_bf16 v[32:35], v[182:185], v[220:223], v[32:35]
	s_setprio 0
	s_barrier
	s_add_i32 s96, s87, s46
	v_lshl_add_u64 v[158:159], s[94:95], 0, v[130:131]
	s_mov_b32 m0, s96
	ds_read_b128 v[186:189], v164 offset:16384
	ds_read_b128 v[196:199], v164 offset:17408
	ds_read_b128 v[200:203], v164 offset:18432
	ds_read_b128 v[204:207], v164 offset:19456
	ds_read_b128 v[208:211], v164 offset:20480
	ds_read_b128 v[212:215], v164 offset:21504
	ds_read_b128 v[216:219], v164 offset:22528
	ds_read_b128 v[220:223], v164 offset:23552
	global_load_lds_dwordx4 v[158:159], off
	s_add_i32 m0, s96, 0x2000
	v_lshl_add_u64 v[190:191], s[94:95], 0, v[134:135]
	s_add_u32 s94, s94, s8
	s_addc_u32 s95, s95, s9
	s_add_i32 s96, s88, s46
	global_load_lds_dwordx4 v[190:191], off
	v_lshl_add_u64 v[224:225], s[94:95], 0, v[130:131]
	s_mov_b32 m0, s96
	v_lshl_add_u64 v[226:227], s[94:95], 0, v[134:135]
	global_load_lds_dwordx4 v[224:225], off
	s_add_i32 m0, s96, 0x2000
	v_lshl_add_u64 v[228:229], s[38:39], 0, v[128:129]
	global_load_lds_dwordx4 v[226:227], off
	s_mov_b32 m0, s77
	v_lshl_add_u64 v[230:231], s[38:39], 0, v[132:133]
	global_load_lds_dwordx4 v[228:229], off
	s_mov_b32 m0, s78
	s_nop 0
	global_load_lds_dwordx4 v[230:231], off
	s_waitcnt vmcnt(8)
	s_waitcnt lgkmcnt(0)
	s_barrier
; #define PG8_STAGE(bufoff, gbase, voff) do { _Pragma("unroll") for (int _i = 0; _i < 2; ++_i) \
;         __builtin_amdgcn_global_load_lds((const unsigned*)((const char*)(gbase) + (voff)[_i]), (PG8_LAS unsigned*)(lds + (bufoff) + ldsw + _i * 8192), 16, 0, 0); } while (0)
; #define PG8_LDA(dst, b, h) do { _Pragma("unroll") for (int m = 0; m < 4; ++m) _Pragma("unroll") for (int k = 0; k < 2; ++k) dst[m][k] = *(const PG8_LAS bf16x8*)(lds + PG8_SA(b, h) + aoff + m * 2048 + k * 1024); } while (0)
; #define PG8_LDB(dst, b, h) do { _Pragma("unroll") for (int n = 0; n < 2; ++n) _Pragma("unroll") for (int k = 0; k < 2; ++k) dst[n][k] = *(const PG8_LAS bf16x8*)(lds + PG8_SB(b, h) + boff + n * 2048 + k * 1024); } while (0)
; #define PG8_MMA(ai, bj, At, Bt) do { __builtin_amdgcn_s_setprio(1); _Pragma("unroll") for (int m = 0; m < 4; ++m) _Pragma("unroll") for (int n = 0; n < 2; ++n) _Pragma("unroll") for (int k = 0; k < 2; ++k) \
;         acc[ai][bj][m][n] = __builtin_amdgcn_mfma_f32_16x16x32_bf16(Bt[n][k], At[m][k], acc[ai][bj][m][n], 0, 0, 0); __builtin_amdgcn_s_setprio(0); } while (0)
; #define PG8_WAIT_V(n) asm volatile("s_waitcnt vmcnt(" #n ")" ::: "memory")
; #define PG8_WAIT_L(n) asm volatile("s_waitcnt lgkmcnt(" #n ")" ::: "memory")
; #define PG8_BAR __builtin_amdgcn_s_barrier()
; #define PG8_SCHED __builtin_amdgcn_sched_barrier(0)
; template <class Epi, class Sched, bool ALIGN_EPI = false, bool SP2 = false>
; __device__ __forceinline__ void gemm_phase(PG8_LAS unsigned char* lds, const Gemm g, const Sched& S, const Epi& E) {
;     ...
;             PG8_WAIT_V(8); PG8_WAIT_L(0); PG8_BAR; PG8_MMA(1, 0, At, B0); PG8_MMA(1, 1, At, B1); PG8_BAR; PG8_SCHED;
;             PG8_LDB(B0, 1, 0); PG8_LDB(B1, 1, 1); PG8_SCHED; PG8_LDA(At, 1, 0); PG8_STAGE(PG8_SA(0, 1), a2 + hstep, voffA);
;             PG8_WAIT_V(8); PG8_WAIT_L(0); PG8_BAR; PG8_MMA(0, 0, At, B0); PG8_MMA(0, 1, At, B1); PG8_BAR; PG8_SCHED;
	s_setprio 1
	s_waitcnt lgkmcnt(0)
	v_mfma_f32_16x16x32_bf16 v[92:95], v[146:149], v[186:189], v[92:95]
	v_mfma_f32_16x16x32_bf16 v[88:91], v[154:157], v[186:189], v[88:91]
	v_mfma_f32_16x16x32_bf16 v[84:87], v[146:149], v[200:203], v[84:87]
	v_mfma_f32_16x16x32_bf16 v[80:83], v[154:157], v[200:203], v[80:83]
	v_mfma_f32_16x16x32_bf16 v[76:79], v[146:149], v[208:211], v[76:79]
	v_mfma_f32_16x16x32_bf16 v[72:75], v[154:157], v[208:211], v[72:75]
	v_mfma_f32_16x16x32_bf16 v[68:71], v[146:149], v[216:219], v[68:71]
	v_mfma_f32_16x16x32_bf16 v[64:67], v[154:157], v[216:219], v[64:67]
	v_mfma_f32_16x16x32_bf16 v[92:95], v[150:153], v[196:199], v[92:95]
	v_mfma_f32_16x16x32_bf16 v[88:91], v[166:169], v[196:199], v[88:91]
	v_mfma_f32_16x16x32_bf16 v[84:87], v[150:153], v[204:207], v[84:87]
	v_mfma_f32_16x16x32_bf16 v[80:83], v[166:169], v[204:207], v[80:83]
	v_mfma_f32_16x16x32_bf16 v[76:79], v[150:153], v[212:215], v[76:79]
	v_mfma_f32_16x16x32_bf16 v[72:75], v[166:169], v[212:215], v[72:75]
	v_mfma_f32_16x16x32_bf16 v[68:71], v[150:153], v[220:223], v[68:71]
	v_mfma_f32_16x16x32_bf16 v[64:67], v[166:169], v[220:223], v[64:67]
	s_setprio 0
	s_setprio 1
	v_mfma_f32_16x16x32_bf16 v[28:31], v[170:173], v[186:189], v[28:31]
	v_mfma_f32_16x16x32_bf16 v[24:27], v[178:181], v[186:189], v[24:27]
	v_mfma_f32_16x16x32_bf16 v[20:23], v[170:173], v[200:203], v[20:23]
	v_mfma_f32_16x16x32_bf16 v[16:19], v[178:181], v[200:203], v[16:19]
	v_mfma_f32_16x16x32_bf16 v[12:15], v[170:173], v[208:211], v[12:15]
	v_mfma_f32_16x16x32_bf16 v[8:11], v[178:181], v[208:211], v[8:11]
	v_mfma_f32_16x16x32_bf16 v[4:7], v[170:173], v[216:219], v[4:7]
	v_mfma_f32_16x16x32_bf16 v[0:3], v[178:181], v[216:219], v[0:3]
	v_mfma_f32_16x16x32_bf16 v[28:31], v[174:177], v[196:199], v[28:31]
	v_mfma_f32_16x16x32_bf16 v[24:27], v[182:185], v[196:199], v[24:27]
	v_mfma_f32_16x16x32_bf16 v[20:23], v[174:177], v[204:207], v[20:23]
	v_mfma_f32_16x16x32_bf16 v[16:19], v[182:185], v[204:207], v[16:19]
	v_mfma_f32_16x16x32_bf16 v[12:15], v[174:177], v[212:215], v[12:15]
	v_mfma_f32_16x16x32_bf16 v[8:11], v[182:185], v[212:215], v[8:11]
	v_mfma_f32_16x16x32_bf16 v[4:7], v[174:177], v[220:223], v[4:7]
	v_mfma_f32_16x16x32_bf16 v[0:3], v[182:185], v[220:223], v[0:3]
	s_setprio 0
	s_barrier
	s_add_i32 s94, 0, 0x18000
	v_add_u32_e32 v136, s94, v160
	s_add_i32 s95, 0, 0x1c000
	ds_read_b128 v[146:149], v136
	ds_read_b128 v[150:153], v136 offset:1024
	ds_read_b128 v[154:157], v136 offset:2048
	ds_read_b128 v[166:169], v136 offset:3072
	v_add_u32_e32 v136, s95, v160
	ds_read_b128 v[170:173], v136
	ds_read_b128 v[174:177], v136 offset:1024
	ds_read_b128 v[178:181], v136 offset:2048
	ds_read_b128 v[182:185], v136 offset:3072
	s_add_u32 s38, s38, s8
	s_addc_u32 s39, s39, s9
	s_mov_b32 m0, s79
	v_lshl_add_u64 v[232:233], s[38:39], 0, v[128:129]
	ds_read_b128 v[186:189], v164 offset:32768
	ds_read_b128 v[196:199], v164 offset:33792
	ds_read_b128 v[200:203], v164 offset:34816
	ds_read_b128 v[204:207], v164 offset:35840
	ds_read_b128 v[208:211], v164 offset:36864
	ds_read_b128 v[212:215], v164 offset:37888
	ds_read_b128 v[216:219], v164 offset:38912
	ds_read_b128 v[220:223], v164 offset:39936
	global_load_lds_dwordx4 v[232:233], off
	v_lshl_add_u64 v[232:233], s[38:39], 0, v[132:133]
	s_mov_b32 m0, s80
	s_nop 0
	global_load_lds_dwordx4 v[232:233], off
	s_waitcnt vmcnt(8)
	s_waitcnt lgkmcnt(0)
	s_barrier
	s_setprio 1
	s_waitcnt lgkmcnt(0)
	v_mfma_f32_16x16x32_bf16 v[124:127], v[146:149], v[186:189], v[124:127]
	v_mfma_f32_16x16x32_bf16 v[120:123], v[154:157], v[186:189], v[120:123]
	v_mfma_f32_16x16x32_bf16 v[116:119], v[146:149], v[200:203], v[116:119]
	v_mfma_f32_16x16x32_bf16 v[112:115], v[154:157], v[200:203], v[112:115]
	v_mfma_f32_16x16x32_bf16 v[108:111], v[146:149], v[208:211], v[108:111]
	v_mfma_f32_16x16x32_bf16 v[104:107], v[154:157], v[208:211], v[104:107]
	v_mfma_f32_16x16x32_bf16 v[100:103], v[146:149], v[216:219], v[100:103]
	v_mfma_f32_16x16x32_bf16 v[96:99], v[154:157], v[216:219], v[96:99]
	v_mfma_f32_16x16x32_bf16 v[124:127], v[150:153], v[196:199], v[124:127]
	v_mfma_f32_16x16x32_bf16 v[120:123], v[166:169], v[196:199], v[120:123]
	v_mfma_f32_16x16x32_bf16 v[116:119], v[150:153], v[204:207], v[116:119]
	v_mfma_f32_16x16x32_bf16 v[112:115], v[166:169], v[204:207], v[112:115]
	v_mfma_f32_16x16x32_bf16 v[108:111], v[150:153], v[212:215], v[108:111]
	v_mfma_f32_16x16x32_bf16 v[104:107], v[166:169], v[212:215], v[104:107]
	v_mfma_f32_16x16x32_bf16 v[100:103], v[150:153], v[220:223], v[100:103]
	v_mfma_f32_16x16x32_bf16 v[96:99], v[166:169], v[220:223], v[96:99]
	s_setprio 0
	s_setprio 1
	v_mfma_f32_16x16x32_bf16 v[60:63], v[170:173], v[186:189], v[60:63]
	v_mfma_f32_16x16x32_bf16 v[56:59], v[178:181], v[186:189], v[56:59]
	v_mfma_f32_16x16x32_bf16 v[52:55], v[170:173], v[200:203], v[52:55]
	v_mfma_f32_16x16x32_bf16 v[48:51], v[178:181], v[200:203], v[48:51]
	v_mfma_f32_16x16x32_bf16 v[44:47], v[170:173], v[208:211], v[44:47]
	v_mfma_f32_16x16x32_bf16 v[40:43], v[178:181], v[208:211], v[40:43]
	v_mfma_f32_16x16x32_bf16 v[36:39], v[170:173], v[216:219], v[36:39]
	v_mfma_f32_16x16x32_bf16 v[32:35], v[178:181], v[216:219], v[32:35]
	v_mfma_f32_16x16x32_bf16 v[60:63], v[174:177], v[196:199], v[60:63]
	v_mfma_f32_16x16x32_bf16 v[56:59], v[182:185], v[196:199], v[56:59]
	v_mfma_f32_16x16x32_bf16 v[52:55], v[174:177], v[204:207], v[52:55]
	v_mfma_f32_16x16x32_bf16 v[48:51], v[182:185], v[204:207], v[48:51]
	v_mfma_f32_16x16x32_bf16 v[44:47], v[174:177], v[212:215], v[44:47]
	v_mfma_f32_16x16x32_bf16 v[40:43], v[182:185], v[212:215], v[40:43]
	v_mfma_f32_16x16x32_bf16 v[36:39], v[174:177], v[220:223], v[36:39]
	v_mfma_f32_16x16x32_bf16 v[32:35], v[182:185], v[220:223], v[32:35]
	s_setprio 0
	s_barrier
; #define PG8_STAGE(bufoff, gbase, voff) do { _Pragma("unroll") for (int _i = 0; _i < 2; ++_i) \
;         __builtin_amdgcn_global_load_lds((const unsigned*)((const char*)(gbase) + (voff)[_i]), (PG8_LAS unsigned*)(lds + (bufoff) + ldsw + _i * 8192), 16, 0, 0); } while (0)
; #define PG8_LDA(dst, b, h) do { _Pragma("unroll") for (int m = 0; m < 4; ++m) _Pragma("unroll") for (int k = 0; k < 2; ++k) dst[m][k] = *(const PG8_LAS bf16x8*)(lds + PG8_SA(b, h) + aoff + m * 2048 + k * 1024); } while (0)
; #define PG8_MMA(ai, bj, At, Bt) do { __builtin_amdgcn_s_setprio(1); _Pragma("unroll") for (int m = 0; m < 4; ++m) _Pragma("unroll") for (int n = 0; n < 2; ++n) _Pragma("unroll") for (int k = 0; k < 2; ++k) \
;         acc[ai][bj][m][n] = __builtin_amdgcn_mfma_f32_16x16x32_bf16(Bt[n][k], At[m][k], acc[ai][bj][m][n], 0, 0, 0); __builtin_amdgcn_s_setprio(0); } while (0)
; #define PG8_WAIT_V(n) asm volatile("s_waitcnt vmcnt(" #n ")" ::: "memory")
; #define PG8_WAIT_L(n) asm volatile("s_waitcnt lgkmcnt(" #n ")" ::: "memory")
; #define PG8_BAR __builtin_amdgcn_s_barrier()
; #define PG8_SCHED __builtin_amdgcn_sched_barrier(0)
; template <class Epi, class Sched, bool ALIGN_EPI = false, bool SP2 = false>
; __device__ __forceinline__ void gemm_phase(PG8_LAS unsigned char* lds, const Gemm g, const Sched& S, const Epi& E) {
;     ...
;         for (int t = 0; t < nt; t += 2) {
;     ...
;             PG8_LDA(At, 1, 1); PG8_STAGE(PG8_SB(1, 0), b3, voffB); PG8_STAGE(PG8_SB(1, 1), b3 + hstep, voffB); PG8_STAGE(PG8_SA(1, 0), a3, voffA);
;             PG8_WAIT_V(8); PG8_WAIT_L(0); PG8_BAR; PG8_MMA(1, 0, At, B0); PG8_MMA(1, 1, At, B1); PG8_BAR; PG8_SCHED;
	s_add_i32 s38, s94, s46
	v_lshl_add_u64 v[158:159], v[158:159], 0, s[22:23]
	s_mov_b32 m0, s38
	ds_read_b128 v[186:189], v164 offset:49152
	ds_read_b128 v[196:199], v164 offset:50176
	ds_read_b128 v[200:203], v164 offset:51200
	ds_read_b128 v[204:207], v164 offset:52224
	ds_read_b128 v[208:211], v164 offset:53248
	ds_read_b128 v[212:215], v164 offset:54272
	ds_read_b128 v[216:219], v164 offset:55296
	ds_read_b128 v[220:223], v164 offset:56320
	global_load_lds_dwordx4 v[158:159], off
	v_lshl_add_u64 v[158:159], v[190:191], 0, s[22:23]
	s_add_i32 m0, s38, 0x2000
	s_add_i32 s38, s95, s46
	global_load_lds_dwordx4 v[158:159], off
	v_lshl_add_u64 v[158:159], v[224:225], 0, s[22:23]
	s_mov_b32 m0, s38
	s_nop 0
	global_load_lds_dwordx4 v[158:159], off
	v_lshl_add_u64 v[158:159], v[226:227], 0, s[22:23]
	s_add_i32 m0, s38, 0x2000
	s_nop 0
	global_load_lds_dwordx4 v[158:159], off
	v_lshl_add_u64 v[158:159], v[228:229], 0, s[22:23]
	s_mov_b32 m0, s83
	s_nop 0
	global_load_lds_dwordx4 v[158:159], off
	v_lshl_add_u64 v[158:159], v[230:231], 0, s[22:23]
	s_mov_b32 m0, s84
	s_nop 0
	global_load_lds_dwordx4 v[158:159], off
	s_waitcnt vmcnt(8)
	s_waitcnt lgkmcnt(0)
	s_barrier
	s_setprio 1
	s_waitcnt lgkmcnt(0)
	v_mfma_f32_16x16x32_bf16 v[92:95], v[146:149], v[186:189], v[92:95]
	v_mfma_f32_16x16x32_bf16 v[88:91], v[154:157], v[186:189], v[88:91]
	v_mfma_f32_16x16x32_bf16 v[84:87], v[146:149], v[200:203], v[84:87]
	v_mfma_f32_16x16x32_bf16 v[80:83], v[154:157], v[200:203], v[80:83]
	v_mfma_f32_16x16x32_bf16 v[76:79], v[146:149], v[208:211], v[76:79]
	v_mfma_f32_16x16x32_bf16 v[72:75], v[154:157], v[208:211], v[72:75]
	v_mfma_f32_16x16x32_bf16 v[68:71], v[146:149], v[216:219], v[68:71]
	v_mfma_f32_16x16x32_bf16 v[64:67], v[154:157], v[216:219], v[64:67]
	v_mfma_f32_16x16x32_bf16 v[92:95], v[150:153], v[196:199], v[92:95]
	v_mfma_f32_16x16x32_bf16 v[88:91], v[166:169], v[196:199], v[88:91]
	v_mfma_f32_16x16x32_bf16 v[84:87], v[150:153], v[204:207], v[84:87]
	v_mfma_f32_16x16x32_bf16 v[80:83], v[166:169], v[204:207], v[80:83]
	v_mfma_f32_16x16x32_bf16 v[76:79], v[150:153], v[212:215], v[76:79]
	v_mfma_f32_16x16x32_bf16 v[72:75], v[166:169], v[212:215], v[72:75]
	v_mfma_f32_16x16x32_bf16 v[68:71], v[150:153], v[220:223], v[68:71]
	v_mfma_f32_16x16x32_bf16 v[64:67], v[166:169], v[220:223], v[64:67]
	s_setprio 0
	s_setprio 1
	v_mfma_f32_16x16x32_bf16 v[28:31], v[170:173], v[186:189], v[28:31]
	v_mfma_f32_16x16x32_bf16 v[24:27], v[178:181], v[186:189], v[24:27]
	v_mfma_f32_16x16x32_bf16 v[20:23], v[170:173], v[200:203], v[20:23]
	v_mfma_f32_16x16x32_bf16 v[16:19], v[178:181], v[200:203], v[16:19]
	v_mfma_f32_16x16x32_bf16 v[12:15], v[170:173], v[208:211], v[12:15]
	v_mfma_f32_16x16x32_bf16 v[8:11], v[178:181], v[208:211], v[8:11]
	v_mfma_f32_16x16x32_bf16 v[4:7], v[170:173], v[216:219], v[4:7]
	v_mfma_f32_16x16x32_bf16 v[0:3], v[178:181], v[216:219], v[0:3]
	v_mfma_f32_16x16x32_bf16 v[28:31], v[174:177], v[196:199], v[28:31]
	v_mfma_f32_16x16x32_bf16 v[24:27], v[182:185], v[196:199], v[24:27]
	v_mfma_f32_16x16x32_bf16 v[20:23], v[174:177], v[204:207], v[20:23]
	v_mfma_f32_16x16x32_bf16 v[16:19], v[182:185], v[204:207], v[16:19]
	v_mfma_f32_16x16x32_bf16 v[12:15], v[174:177], v[212:215], v[12:15]
	v_mfma_f32_16x16x32_bf16 v[8:11], v[182:185], v[212:215], v[8:11]
	v_mfma_f32_16x16x32_bf16 v[4:7], v[174:177], v[220:223], v[4:7]
	v_mfma_f32_16x16x32_bf16 v[0:3], v[182:185], v[220:223], v[0:3]
	s_setprio 0
	s_barrier
	s_add_u32 s6, s6, 0x100
	s_addc_u32 s7, s7, 0
	s_add_u32 s37, s37, 0x100
	s_addc_u32 s74, s74, 0
	s_cmp_ge_i32 s75, s85
	s_mov_b32 s38, s75
	s_cbranch_scc0 .LBB0_1381

; #define PG8_STAGE(bufoff, gbase, voff) do { _Pragma("unroll") for (int _i = 0; _i < 2; ++_i) \
;         __builtin_amdgcn_global_load_lds((const unsigned*)((const char*)(gbase) + (voff)[_i]), (PG8_LAS unsigned*)(lds + (bufoff) + ldsw + _i * 8192), 16, 0, 0); } while (0)
; #define PG8_LDA(dst, b, h) do { _Pragma("unroll") for (int m = 0; m < 4; ++m) _Pragma("unroll") for (int k = 0; k < 2; ++k) dst[m][k] = *(const PG8_LAS bf16x8*)(lds + PG8_SA(b, h) + aoff + m * 2048 + k * 1024); } while (0)
; #define PG8_LDB(dst, b, h) do { _Pragma("unroll") for (int n = 0; n < 2; ++n) _Pragma("unroll") for (int k = 0; k < 2; ++k) dst[n][k] = *(const PG8_LAS bf16x8*)(lds + PG8_SB(b, h) + boff + n * 2048 + k * 1024); } while (0)
; #define PG8_MMA(ai, bj, At, Bt) do { __builtin_amdgcn_s_setprio(1); _Pragma("unroll") for (int m = 0; m < 4; ++m) _Pragma("unroll") for (int n = 0; n < 2; ++n) _Pragma("unroll") for (int k = 0; k < 2; ++k) \
;         acc[ai][bj][m][n] = __builtin_amdgcn_mfma_f32_16x16x32_bf16(Bt[n][k], At[m][k], acc[ai][bj][m][n], 0, 0, 0); __builtin_amdgcn_s_setprio(0); } while (0)
; #define PG8_WAIT_V(n) asm volatile("s_waitcnt vmcnt(" #n ")" ::: "memory")
; #define PG8_WAIT_L(n) asm volatile("s_waitcnt lgkmcnt(" #n ")" ::: "memory")
; #define PG8_BAR __builtin_amdgcn_s_barrier()
; #define PG8_SCHED __builtin_amdgcn_sched_barrier(0)
; template <class Epi, class Sched, bool ALIGN_EPI = false, bool SP2 = false>
; __device__ __forceinline__ void gemm_phase(PG8_LAS unsigned char* lds, const Gemm g, const Sched& S, const Epi& E) {
;     ...
;             PG8_LDB(B0, 0, 0); PG8_LDB(B1, 0, 1); PG8_SCHED; PG8_LDA(At, 0, 0); PG8_STAGE(PG8_SA(1, 1), a1 + hstep, voffA);
;             PG8_WAIT_V(8); PG8_WAIT_L(0); PG8_BAR; PG8_MMA(0, 0, At, B0); PG8_MMA(0, 1, At, B1); PG8_BAR; PG8_SCHED;
;             PG8_LDA(At, 0, 1); PG8_STAGE(PG8_SB(0, 0), b2, voffB); PG8_STAGE(PG8_SB(0, 1), b2 + hstep, voffB); PG8_STAGE(PG8_SA(0, 0), a2, voffA);
;             PG8_WAIT_V(8); PG8_WAIT_L(0); PG8_BAR; PG8_MMA(1, 0, At, B0); PG8_MMA(1, 1, At, B1); PG8_BAR; PG8_SCHED;
.LBB0_1539:
	s_sleep 2
	ds_read_b128 v[128:131], v204
	ds_read_b128 v[132:135], v204 offset:1024
	ds_read_b128 v[136:139], v204 offset:2048
	ds_read_b128 v[140:143], v204 offset:3072
	ds_read_b128 v[144:147], v205
	ds_read_b128 v[148:151], v205 offset:1024
	ds_read_b128 v[152:155], v205 offset:2048
	ds_read_b128 v[174:177], v205 offset:3072
	s_add_i32 s92, s38, 2
	s_add_u32 s93, s36, 0x80
	s_addc_u32 s39, s37, 0
	s_cmp_eq_u32 s78, s38
	s_cselect_b32 s38, s8, s93
	s_cselect_b32 s39, s9, s39
	s_cselect_b32 s95, s31, s91
	s_cselect_b32 s94, s30, s35
	v_lshl_add_u64 v[190:191], s[36:37], 0, v[168:169]
	s_add_i32 m0, s46, 0xc000
	ds_read_b128 v[178:181], v206
	ds_read_b128 v[182:185], v206 offset:1024
	ds_read_b128 v[186:189], v206 offset:2048
	ds_read_b128 v[196:199], v206 offset:3072
	ds_read_b128 v[200:203], v206 offset:4096
	ds_read_b128 v[208:211], v206 offset:5120
	ds_read_b128 v[212:215], v206 offset:6144
	ds_read_b128 v[216:219], v206 offset:7168
	global_load_lds_dwordx4 v[190:191], off
	v_lshl_add_u64 v[190:191], s[36:37], 0, v[170:171]
	s_add_i32 m0, s46, 0xe000
	s_nop 0
	global_load_lds_dwordx4 v[190:191], off
	s_waitcnt vmcnt(8)
	s_waitcnt lgkmcnt(0)
	s_barrier
	s_setprio 1
	s_waitcnt lgkmcnt(0)
	v_mfma_f32_16x16x32_bf16 v[124:127], v[128:131], v[178:181], v[124:127]
	v_mfma_f32_16x16x32_bf16 v[120:123], v[136:139], v[178:181], v[120:123]
	v_mfma_f32_16x16x32_bf16 v[108:111], v[128:131], v[186:189], v[108:111]
	v_mfma_f32_16x16x32_bf16 v[104:107], v[136:139], v[186:189], v[104:107]
	v_mfma_f32_16x16x32_bf16 v[92:95], v[128:131], v[200:203], v[92:95]
	v_mfma_f32_16x16x32_bf16 v[88:91], v[136:139], v[200:203], v[88:91]
	v_mfma_f32_16x16x32_bf16 v[76:79], v[128:131], v[212:215], v[76:79]
	v_mfma_f32_16x16x32_bf16 v[72:75], v[136:139], v[212:215], v[72:75]
	v_mfma_f32_16x16x32_bf16 v[124:127], v[132:135], v[182:185], v[124:127]
	v_mfma_f32_16x16x32_bf16 v[120:123], v[140:143], v[182:185], v[120:123]
	v_mfma_f32_16x16x32_bf16 v[108:111], v[132:135], v[196:199], v[108:111]
	v_mfma_f32_16x16x32_bf16 v[104:107], v[140:143], v[196:199], v[104:107]
	v_mfma_f32_16x16x32_bf16 v[92:95], v[132:135], v[208:211], v[92:95]
	v_mfma_f32_16x16x32_bf16 v[88:91], v[140:143], v[208:211], v[88:91]
	v_mfma_f32_16x16x32_bf16 v[76:79], v[132:135], v[216:219], v[76:79]
	v_mfma_f32_16x16x32_bf16 v[72:75], v[140:143], v[216:219], v[72:75]
	s_setprio 0
	s_setprio 1
	v_mfma_f32_16x16x32_bf16 v[116:119], v[144:147], v[178:181], v[116:119]
	v_mfma_f32_16x16x32_bf16 v[112:115], v[152:155], v[178:181], v[112:115]
	v_mfma_f32_16x16x32_bf16 v[100:103], v[144:147], v[186:189], v[100:103]
	v_mfma_f32_16x16x32_bf16 v[96:99], v[152:155], v[186:189], v[96:99]
	v_mfma_f32_16x16x32_bf16 v[84:87], v[144:147], v[200:203], v[84:87]
	v_mfma_f32_16x16x32_bf16 v[80:83], v[152:155], v[200:203], v[80:83]
	v_mfma_f32_16x16x32_bf16 v[68:71], v[144:147], v[212:215], v[68:71]
	v_mfma_f32_16x16x32_bf16 v[64:67], v[152:155], v[212:215], v[64:67]
	v_mfma_f32_16x16x32_bf16 v[116:119], v[148:151], v[182:185], v[116:119]
	v_mfma_f32_16x16x32_bf16 v[112:115], v[174:177], v[182:185], v[112:115]
	v_mfma_f32_16x16x32_bf16 v[100:103], v[148:151], v[196:199], v[100:103]
	v_mfma_f32_16x16x32_bf16 v[96:99], v[174:177], v[196:199], v[96:99]
	v_mfma_f32_16x16x32_bf16 v[84:87], v[148:151], v[208:211], v[84:87]
	v_mfma_f32_16x16x32_bf16 v[80:83], v[174:177], v[208:211], v[80:83]
	v_mfma_f32_16x16x32_bf16 v[68:71], v[148:151], v[216:219], v[68:71]
	v_mfma_f32_16x16x32_bf16 v[64:67], v[174:177], v[216:219], v[64:67]
	s_setprio 0
	s_barrier
	s_add_i32 s93, s86, s33
	v_lshl_add_u64 v[190:191], s[94:95], 0, v[158:159]
	s_mov_b32 m0, s93
	ds_read_b128 v[178:181], v206 offset:16384
	ds_read_b128 v[182:185], v206 offset:17408
	ds_read_b128 v[186:189], v206 offset:18432
	ds_read_b128 v[196:199], v206 offset:19456
	ds_read_b128 v[200:203], v206 offset:20480
	ds_read_b128 v[208:211], v206 offset:21504
	ds_read_b128 v[212:215], v206 offset:22528
	ds_read_b128 v[216:219], v206 offset:23552
	global_load_lds_dwordx4 v[190:191], off
	s_add_i32 m0, s93, 0x2000
	v_lshl_add_u64 v[220:221], s[94:95], 0, v[162:163]
	s_add_u32 s94, s94, s12
	s_addc_u32 s95, s95, s13
	s_add_i32 s93, s87, s33
	global_load_lds_dwordx4 v[220:221], off
	v_lshl_add_u64 v[222:223], s[94:95], 0, v[158:159]
	s_mov_b32 m0, s93
	v_lshl_add_u64 v[224:225], s[94:95], 0, v[162:163]
	global_load_lds_dwordx4 v[222:223], off
	s_add_i32 m0, s93, 0x2000
	v_lshl_add_u64 v[226:227], s[38:39], 0, v[156:157]
	global_load_lds_dwordx4 v[224:225], off
	s_mov_b32 m0, s46
	v_lshl_add_u64 v[228:229], s[38:39], 0, v[160:161]
	global_load_lds_dwordx4 v[226:227], off
	s_mov_b32 m0, s47
	s_nop 0
	global_load_lds_dwordx4 v[228:229], off
	s_waitcnt vmcnt(8)
	s_waitcnt lgkmcnt(0)
	s_barrier
; #define PG8_STAGE(bufoff, gbase, voff) do { _Pragma("unroll") for (int _i = 0; _i < 2; ++_i) \
;         __builtin_amdgcn_global_load_lds((const unsigned*)((const char*)(gbase) + (voff)[_i]), (PG8_LAS unsigned*)(lds + (bufoff) + ldsw + _i * 8192), 16, 0, 0); } while (0)
; #define PG8_LDA(dst, b, h) do { _Pragma("unroll") for (int m = 0; m < 4; ++m) _Pragma("unroll") for (int k = 0; k < 2; ++k) dst[m][k] = *(const PG8_LAS bf16x8*)(lds + PG8_SA(b, h) + aoff + m * 2048 + k * 1024); } while (0)
; #define PG8_LDB(dst, b, h) do { _Pragma("unroll") for (int n = 0; n < 2; ++n) _Pragma("unroll") for (int k = 0; k < 2; ++k) dst[n][k] = *(const PG8_LAS bf16x8*)(lds + PG8_SB(b, h) + boff + n * 2048 + k * 1024); } while (0)
; #define PG8_MMA(ai, bj, At, Bt) do { __builtin_amdgcn_s_setprio(1); _Pragma("unroll") for (int m = 0; m < 4; ++m) _Pragma("unroll") for (int n = 0; n < 2; ++n) _Pragma("unroll") for (int k = 0; k < 2; ++k) \
;         acc[ai][bj][m][n] = __builtin_amdgcn_mfma_f32_16x16x32_bf16(Bt[n][k], At[m][k], acc[ai][bj][m][n], 0, 0, 0); __builtin_amdgcn_s_setprio(0); } while (0)
; #define PG8_WAIT_V(n) asm volatile("s_waitcnt vmcnt(" #n ")" ::: "memory")
; #define PG8_WAIT_L(n) asm volatile("s_waitcnt lgkmcnt(" #n ")" ::: "memory")
; #define PG8_BAR __builtin_amdgcn_s_barrier()
; #define PG8_SCHED __builtin_amdgcn_sched_barrier(0)
; template <class Epi, class Sched, bool ALIGN_EPI = false, bool SP2 = false>
; __device__ __forceinline__ void gemm_phase(PG8_LAS unsigned char* lds, const Gemm g, const Sched& S, const Epi& E) {
;     ...
;             PG8_WAIT_V(8); PG8_WAIT_L(0); PG8_BAR; PG8_MMA(1, 0, At, B0); PG8_MMA(1, 1, At, B1); PG8_BAR; PG8_SCHED;
;             PG8_LDB(B0, 1, 0); PG8_LDB(B1, 1, 1); PG8_SCHED; PG8_LDA(At, 1, 0); PG8_STAGE(PG8_SA(0, 1), a2 + hstep, voffA);
;             PG8_WAIT_V(8); PG8_WAIT_L(0); PG8_BAR; PG8_MMA(0, 0, At, B0); PG8_MMA(0, 1, At, B1); PG8_BAR; PG8_SCHED;
	s_setprio 1
	s_waitcnt lgkmcnt(0)
	v_mfma_f32_16x16x32_bf16 v[60:63], v[128:131], v[178:181], v[60:63]
	v_mfma_f32_16x16x32_bf16 v[56:59], v[136:139], v[178:181], v[56:59]
	v_mfma_f32_16x16x32_bf16 v[44:47], v[128:131], v[186:189], v[44:47]
	v_mfma_f32_16x16x32_bf16 v[40:43], v[136:139], v[186:189], v[40:43]
	v_mfma_f32_16x16x32_bf16 v[28:31], v[128:131], v[200:203], v[28:31]
	v_mfma_f32_16x16x32_bf16 v[24:27], v[136:139], v[200:203], v[24:27]
	v_mfma_f32_16x16x32_bf16 v[12:15], v[128:131], v[212:215], v[12:15]
	v_mfma_f32_16x16x32_bf16 v[8:11], v[136:139], v[212:215], v[8:11]
	v_mfma_f32_16x16x32_bf16 v[60:63], v[132:135], v[182:185], v[60:63]
	v_mfma_f32_16x16x32_bf16 v[56:59], v[140:143], v[182:185], v[56:59]
	v_mfma_f32_16x16x32_bf16 v[44:47], v[132:135], v[196:199], v[44:47]
	v_mfma_f32_16x16x32_bf16 v[40:43], v[140:143], v[196:199], v[40:43]
	v_mfma_f32_16x16x32_bf16 v[28:31], v[132:135], v[208:211], v[28:31]
	v_mfma_f32_16x16x32_bf16 v[24:27], v[140:143], v[208:211], v[24:27]
	v_mfma_f32_16x16x32_bf16 v[12:15], v[132:135], v[216:219], v[12:15]
	v_mfma_f32_16x16x32_bf16 v[8:11], v[140:143], v[216:219], v[8:11]
	s_setprio 0
	s_setprio 1
	v_mfma_f32_16x16x32_bf16 v[52:55], v[144:147], v[178:181], v[52:55]
	v_mfma_f32_16x16x32_bf16 v[48:51], v[152:155], v[178:181], v[48:51]
	v_mfma_f32_16x16x32_bf16 v[36:39], v[144:147], v[186:189], v[36:39]
	v_mfma_f32_16x16x32_bf16 v[32:35], v[152:155], v[186:189], v[32:35]
	v_mfma_f32_16x16x32_bf16 v[20:23], v[144:147], v[200:203], v[20:23]
	v_mfma_f32_16x16x32_bf16 v[16:19], v[152:155], v[200:203], v[16:19]
	v_mfma_f32_16x16x32_bf16 v[4:7], v[144:147], v[212:215], v[4:7]
	v_mfma_f32_16x16x32_bf16 v[0:3], v[152:155], v[212:215], v[0:3]
	v_mfma_f32_16x16x32_bf16 v[52:55], v[148:151], v[182:185], v[52:55]
	v_mfma_f32_16x16x32_bf16 v[48:51], v[174:177], v[182:185], v[48:51]
	v_mfma_f32_16x16x32_bf16 v[36:39], v[148:151], v[196:199], v[36:39]
	v_mfma_f32_16x16x32_bf16 v[32:35], v[174:177], v[196:199], v[32:35]
	v_mfma_f32_16x16x32_bf16 v[20:23], v[148:151], v[208:211], v[20:23]
	v_mfma_f32_16x16x32_bf16 v[16:19], v[174:177], v[208:211], v[16:19]
	v_mfma_f32_16x16x32_bf16 v[4:7], v[148:151], v[216:219], v[4:7]
	v_mfma_f32_16x16x32_bf16 v[0:3], v[174:177], v[216:219], v[0:3]
	s_setprio 0
	s_barrier
	s_add_i32 s93, 0, 0x18000
	s_add_i32 s94, 0, 0x1c000
	v_add_u32_e32 v140, s93, v193
	v_add_u32_e32 v165, s94, v193
	ds_read_b128 v[128:131], v140
	ds_read_b128 v[132:135], v140 offset:1024
	ds_read_b128 v[136:139], v140 offset:2048
	ds_read_b128 v[140:143], v140 offset:3072
	ds_read_b128 v[144:147], v165
	ds_read_b128 v[148:151], v165 offset:1024
	ds_read_b128 v[152:155], v165 offset:2048
	ds_read_b128 v[174:177], v165 offset:3072
	s_add_u32 s38, s38, s12
	s_addc_u32 s39, s39, s13
	s_mov_b32 m0, s66
	v_lshl_add_u64 v[230:231], s[38:39], 0, v[156:157]
	ds_read_b128 v[178:181], v206 offset:32768
	ds_read_b128 v[182:185], v206 offset:33792
	ds_read_b128 v[186:189], v206 offset:34816
	ds_read_b128 v[196:199], v206 offset:35840
	ds_read_b128 v[200:203], v206 offset:36864
	ds_read_b128 v[208:211], v206 offset:37888
	ds_read_b128 v[212:215], v206 offset:38912
	ds_read_b128 v[216:219], v206 offset:39936
	global_load_lds_dwordx4 v[230:231], off
	v_lshl_add_u64 v[230:231], s[38:39], 0, v[160:161]
	s_mov_b32 m0, s67
	s_nop 0
	global_load_lds_dwordx4 v[230:231], off
	s_waitcnt vmcnt(8)
	s_waitcnt lgkmcnt(0)
	s_barrier
	s_setprio 1
	s_waitcnt lgkmcnt(0)
	v_mfma_f32_16x16x32_bf16 v[124:127], v[128:131], v[178:181], v[124:127]
	v_mfma_f32_16x16x32_bf16 v[120:123], v[136:139], v[178:181], v[120:123]
	v_mfma_f32_16x16x32_bf16 v[108:111], v[128:131], v[186:189], v[108:111]
	v_mfma_f32_16x16x32_bf16 v[104:107], v[136:139], v[186:189], v[104:107]
	v_mfma_f32_16x16x32_bf16 v[92:95], v[128:131], v[200:203], v[92:95]
	v_mfma_f32_16x16x32_bf16 v[88:91], v[136:139], v[200:203], v[88:91]
	v_mfma_f32_16x16x32_bf16 v[76:79], v[128:131], v[212:215], v[76:79]
	v_mfma_f32_16x16x32_bf16 v[72:75], v[136:139], v[212:215], v[72:75]
	v_mfma_f32_16x16x32_bf16 v[124:127], v[132:135], v[182:185], v[124:127]
	v_mfma_f32_16x16x32_bf16 v[120:123], v[140:143], v[182:185], v[120:123]
	v_mfma_f32_16x16x32_bf16 v[108:111], v[132:135], v[196:199], v[108:111]
	v_mfma_f32_16x16x32_bf16 v[104:107], v[140:143], v[196:199], v[104:107]
	v_mfma_f32_16x16x32_bf16 v[92:95], v[132:135], v[208:211], v[92:95]
	v_mfma_f32_16x16x32_bf16 v[88:91], v[140:143], v[208:211], v[88:91]
	v_mfma_f32_16x16x32_bf16 v[76:79], v[132:135], v[216:219], v[76:79]
	v_mfma_f32_16x16x32_bf16 v[72:75], v[140:143], v[216:219], v[72:75]
	s_setprio 0
	s_setprio 1
	v_mfma_f32_16x16x32_bf16 v[116:119], v[144:147], v[178:181], v[116:119]
	v_mfma_f32_16x16x32_bf16 v[112:115], v[152:155], v[178:181], v[112:115]
	v_mfma_f32_16x16x32_bf16 v[100:103], v[144:147], v[186:189], v[100:103]
	v_mfma_f32_16x16x32_bf16 v[96:99], v[152:155], v[186:189], v[96:99]
	v_mfma_f32_16x16x32_bf16 v[84:87], v[144:147], v[200:203], v[84:87]
	v_mfma_f32_16x16x32_bf16 v[80:83], v[152:155], v[200:203], v[80:83]
	v_mfma_f32_16x16x32_bf16 v[68:71], v[144:147], v[212:215], v[68:71]
	v_mfma_f32_16x16x32_bf16 v[64:67], v[152:155], v[212:215], v[64:67]
	v_mfma_f32_16x16x32_bf16 v[116:119], v[148:151], v[182:185], v[116:119]
	v_mfma_f32_16x16x32_bf16 v[112:115], v[174:177], v[182:185], v[112:115]
	v_mfma_f32_16x16x32_bf16 v[100:103], v[148:151], v[196:199], v[100:103]
	v_mfma_f32_16x16x32_bf16 v[96:99], v[174:177], v[196:199], v[96:99]
	v_mfma_f32_16x16x32_bf16 v[84:87], v[148:151], v[208:211], v[84:87]
	v_mfma_f32_16x16x32_bf16 v[80:83], v[174:177], v[208:211], v[80:83]
	v_mfma_f32_16x16x32_bf16 v[68:71], v[148:151], v[216:219], v[68:71]
	v_mfma_f32_16x16x32_bf16 v[64:67], v[174:177], v[216:219], v[64:67]
	s_setprio 0
	s_barrier
; #define PG8_STAGE(bufoff, gbase, voff) do { _Pragma("unroll") for (int _i = 0; _i < 2; ++_i) \
;         __builtin_amdgcn_global_load_lds((const unsigned*)((const char*)(gbase) + (voff)[_i]), (PG8_LAS unsigned*)(lds + (bufoff) + ldsw + _i * 8192), 16, 0, 0); } while (0)
; #define PG8_LDA(dst, b, h) do { _Pragma("unroll") for (int m = 0; m < 4; ++m) _Pragma("unroll") for (int k = 0; k < 2; ++k) dst[m][k] = *(const PG8_LAS bf16x8*)(lds + PG8_SA(b, h) + aoff + m * 2048 + k * 1024); } while (0)
; #define PG8_MMA(ai, bj, At, Bt) do { __builtin_amdgcn_s_setprio(1); _Pragma("unroll") for (int m = 0; m < 4; ++m) _Pragma("unroll") for (int n = 0; n < 2; ++n) _Pragma("unroll") for (int k = 0; k < 2; ++k) \
;         acc[ai][bj][m][n] = __builtin_amdgcn_mfma_f32_16x16x32_bf16(Bt[n][k], At[m][k], acc[ai][bj][m][n], 0, 0, 0); __builtin_amdgcn_s_setprio(0); } while (0)
; #define PG8_WAIT_V(n) asm volatile("s_waitcnt vmcnt(" #n ")" ::: "memory")
; #define PG8_WAIT_L(n) asm volatile("s_waitcnt lgkmcnt(" #n ")" ::: "memory")
; #define PG8_BAR __builtin_amdgcn_s_barrier()
; #define PG8_SCHED __builtin_amdgcn_sched_barrier(0)
; template <class Epi, class Sched, bool ALIGN_EPI = false, bool SP2 = false>
; __device__ __forceinline__ void gemm_phase(PG8_LAS unsigned char* lds, const Gemm g, const Sched& S, const Epi& E) {
;     ...
;         for (int t = 0; t < nt; t += 2) {
;     ...
;             PG8_LDA(At, 1, 1); PG8_STAGE(PG8_SB(1, 0), b3, voffB); PG8_STAGE(PG8_SB(1, 1), b3 + hstep, voffB); PG8_STAGE(PG8_SA(1, 0), a3, voffA);
;             PG8_WAIT_V(8); PG8_WAIT_L(0); PG8_BAR; PG8_MMA(1, 0, At, B0); PG8_MMA(1, 1, At, B1); PG8_BAR; PG8_SCHED;
	s_add_i32 s38, s93, s33
	v_lshl_add_u64 v[190:191], v[190:191], 0, s[22:23]
	s_mov_b32 m0, s38
	ds_read_b128 v[178:181], v206 offset:49152
	ds_read_b128 v[182:185], v206 offset:50176
	ds_read_b128 v[186:189], v206 offset:51200
	ds_read_b128 v[196:199], v206 offset:52224
	ds_read_b128 v[200:203], v206 offset:53248
	ds_read_b128 v[208:211], v206 offset:54272
	ds_read_b128 v[212:215], v206 offset:55296
	ds_read_b128 v[216:219], v206 offset:56320
	global_load_lds_dwordx4 v[190:191], off
	v_lshl_add_u64 v[190:191], v[220:221], 0, s[22:23]
	s_add_i32 m0, s38, 0x2000
	s_add_i32 s38, s94, s33
	global_load_lds_dwordx4 v[190:191], off
	v_lshl_add_u64 v[190:191], v[222:223], 0, s[22:23]
	s_mov_b32 m0, s38
	s_nop 0
	global_load_lds_dwordx4 v[190:191], off
	v_lshl_add_u64 v[190:191], v[224:225], 0, s[22:23]
	s_add_i32 m0, s38, 0x2000
	s_nop 0
	global_load_lds_dwordx4 v[190:191], off
	v_lshl_add_u64 v[190:191], v[226:227], 0, s[22:23]
	s_mov_b32 m0, s70
	s_nop 0
	global_load_lds_dwordx4 v[190:191], off
	v_lshl_add_u64 v[190:191], v[228:229], 0, s[22:23]
	s_mov_b32 m0, s71
	s_nop 0
	global_load_lds_dwordx4 v[190:191], off
	s_waitcnt vmcnt(8)
	s_waitcnt lgkmcnt(0)
	s_barrier
	s_setprio 1
	s_waitcnt lgkmcnt(0)
	v_mfma_f32_16x16x32_bf16 v[60:63], v[128:131], v[178:181], v[60:63]
	v_mfma_f32_16x16x32_bf16 v[56:59], v[136:139], v[178:181], v[56:59]
	v_mfma_f32_16x16x32_bf16 v[44:47], v[128:131], v[186:189], v[44:47]
	v_mfma_f32_16x16x32_bf16 v[40:43], v[136:139], v[186:189], v[40:43]
	v_mfma_f32_16x16x32_bf16 v[28:31], v[128:131], v[200:203], v[28:31]
	v_mfma_f32_16x16x32_bf16 v[24:27], v[136:139], v[200:203], v[24:27]
	v_mfma_f32_16x16x32_bf16 v[12:15], v[128:131], v[212:215], v[12:15]
	v_mfma_f32_16x16x32_bf16 v[8:11], v[136:139], v[212:215], v[8:11]
	v_mfma_f32_16x16x32_bf16 v[60:63], v[132:135], v[182:185], v[60:63]
	v_mfma_f32_16x16x32_bf16 v[56:59], v[140:143], v[182:185], v[56:59]
	v_mfma_f32_16x16x32_bf16 v[44:47], v[132:135], v[196:199], v[44:47]
	v_mfma_f32_16x16x32_bf16 v[40:43], v[140:143], v[196:199], v[40:43]
	v_mfma_f32_16x16x32_bf16 v[28:31], v[132:135], v[208:211], v[28:31]
	v_mfma_f32_16x16x32_bf16 v[24:27], v[140:143], v[208:211], v[24:27]
	v_mfma_f32_16x16x32_bf16 v[12:15], v[132:135], v[216:219], v[12:15]
	v_mfma_f32_16x16x32_bf16 v[8:11], v[140:143], v[216:219], v[8:11]
	s_setprio 0
	s_setprio 1
	v_mfma_f32_16x16x32_bf16 v[52:55], v[144:147], v[178:181], v[52:55]
	v_mfma_f32_16x16x32_bf16 v[48:51], v[152:155], v[178:181], v[48:51]
	v_mfma_f32_16x16x32_bf16 v[36:39], v[144:147], v[186:189], v[36:39]
	v_mfma_f32_16x16x32_bf16 v[32:35], v[152:155], v[186:189], v[32:35]
	v_mfma_f32_16x16x32_bf16 v[20:23], v[144:147], v[200:203], v[20:23]
	v_mfma_f32_16x16x32_bf16 v[16:19], v[152:155], v[200:203], v[16:19]
	v_mfma_f32_16x16x32_bf16 v[4:7], v[144:147], v[212:215], v[4:7]
	v_mfma_f32_16x16x32_bf16 v[0:3], v[152:155], v[212:215], v[0:3]
	v_mfma_f32_16x16x32_bf16 v[52:55], v[148:151], v[182:185], v[52:55]
	v_mfma_f32_16x16x32_bf16 v[48:51], v[174:177], v[182:185], v[48:51]
	v_mfma_f32_16x16x32_bf16 v[36:39], v[148:151], v[196:199], v[36:39]
	v_mfma_f32_16x16x32_bf16 v[32:35], v[174:177], v[196:199], v[32:35]
	v_mfma_f32_16x16x32_bf16 v[20:23], v[148:151], v[208:211], v[20:23]
	v_mfma_f32_16x16x32_bf16 v[16:19], v[174:177], v[208:211], v[16:19]
	v_mfma_f32_16x16x32_bf16 v[4:7], v[148:151], v[216:219], v[4:7]
	v_mfma_f32_16x16x32_bf16 v[0:3], v[174:177], v[216:219], v[0:3]
	s_setprio 0
	s_barrier
	s_add_u32 s36, s36, 0x100
	s_addc_u32 s37, s37, 0
	s_add_u32 s35, s35, 0x100
	s_addc_u32 s91, s91, 0
	s_cmp_ge_i32 s92, s77
	s_mov_b32 s38, s92
	s_cbranch_scc0 .LBB0_1539

; #define PG8_STAGE(bufoff, gbase, voff) do { _Pragma("unroll") for (int _i = 0; _i < 2; ++_i) \
;         __builtin_amdgcn_global_load_lds((const unsigned*)((const char*)(gbase) + (voff)[_i]), (PG8_LAS unsigned*)(lds + (bufoff) + ldsw + _i * 8192), 16, 0, 0); } while (0)
; #define PG8_LDA(dst, b, h) do { _Pragma("unroll") for (int m = 0; m < 4; ++m) _Pragma("unroll") for (int k = 0; k < 2; ++k) dst[m][k] = *(const PG8_LAS bf16x8*)(lds + PG8_SA(b, h) + aoff + m * 2048 + k * 1024); } while (0)
; #define PG8_LDB(dst, b, h) do { _Pragma("unroll") for (int n = 0; n < 2; ++n) _Pragma("unroll") for (int k = 0; k < 2; ++k) dst[n][k] = *(const PG8_LAS bf16x8*)(lds + PG8_SB(b, h) + boff + n * 2048 + k * 1024); } while (0)
; #define PG8_MMA(ai, bj, At, Bt) do { __builtin_amdgcn_s_setprio(1); _Pragma("unroll") for (int m = 0; m < 4; ++m) _Pragma("unroll") for (int n = 0; n < 2; ++n) _Pragma("unroll") for (int k = 0; k < 2; ++k) \
;         acc[ai][bj][m][n] = __builtin_amdgcn_mfma_f32_16x16x32_bf16(Bt[n][k], At[m][k], acc[ai][bj][m][n], 0, 0, 0); __builtin_amdgcn_s_setprio(0); } while (0)
; #define PG8_WAIT_V(n) asm volatile("s_waitcnt vmcnt(" #n ")" ::: "memory")
; #define PG8_WAIT_L(n) asm volatile("s_waitcnt lgkmcnt(" #n ")" ::: "memory")
; #define PG8_BAR __builtin_amdgcn_s_barrier()
; #define PG8_SCHED __builtin_amdgcn_sched_barrier(0)
; template <class Epi, class Sched, bool ALIGN_EPI = false, bool SP2 = false>
; __device__ __forceinline__ void gemm_phase(PG8_LAS unsigned char* lds, const Gemm g, const Sched& S, const Epi& E) {
;     ...
;             PG8_LDB(B0, 0, 0); PG8_LDB(B1, 0, 1); PG8_SCHED; PG8_LDA(At, 0, 0); PG8_STAGE(PG8_SA(1, 1), a1 + hstep, voffA);
;             PG8_WAIT_V(8); PG8_WAIT_L(0); PG8_BAR; PG8_MMA(0, 0, At, B0); PG8_MMA(0, 1, At, B1); PG8_BAR; PG8_SCHED;
;             PG8_LDA(At, 0, 1); PG8_STAGE(PG8_SB(0, 0), b2, voffB); PG8_STAGE(PG8_SB(0, 1), b2 + hstep, voffB); PG8_STAGE(PG8_SA(0, 0), a2, voffA);
;             PG8_WAIT_V(8); PG8_WAIT_L(0); PG8_BAR; PG8_MMA(1, 0, At, B0); PG8_MMA(1, 1, At, B1); PG8_BAR; PG8_SCHED;
.LBB0_1639:
	s_sleep 2
	ds_read_b128 v[76:79], v195
	ds_read_b128 v[80:83], v195 offset:1024
	ds_read_b128 v[88:91], v195 offset:2048
	ds_read_b128 v[92:95], v195 offset:3072
	ds_read_b128 v[100:103], v197
	ds_read_b128 v[104:107], v197 offset:1024
	ds_read_b128 v[112:115], v197 offset:2048
	ds_read_b128 v[116:119], v197 offset:3072
	s_add_i32 vcc_lo, s36, 2
	s_add_u32 s0, s34, 0x80
	s_addc_u32 s1, s35, 0
	s_cmp_eq_u32 s88, s36
	s_cselect_b32 s36, s6, s0
	s_cselect_b32 s37, s7, s1
	s_cselect_b32 s1, s29, s96
	s_cselect_b32 s0, s28, s31
	v_lshl_add_u64 v[186:187], s[34:35], 0, v[180:181]
	s_add_i32 m0, s80, 0xc000
	ds_read_b128 v[160:163], v201
	ds_read_b128 v[164:167], v201 offset:1024
	ds_read_b128 v[206:209], v201 offset:2048
	ds_read_b128 v[210:213], v201 offset:3072
	ds_read_b128 v[214:217], v201 offset:4096
	ds_read_b128 v[218:221], v201 offset:5120
	ds_read_b128 v[222:225], v201 offset:6144
	ds_read_b128 v[226:229], v201 offset:7168
	global_load_lds_dwordx4 v[186:187], off
	v_lshl_add_u64 v[186:187], s[34:35], 0, v[182:183]
	s_add_i32 m0, s80, 0xe000
	s_nop 0
	global_load_lds_dwordx4 v[186:187], off
	s_waitcnt vmcnt(8)
	s_waitcnt lgkmcnt(0)
	s_barrier
	s_setprio 1
	s_waitcnt lgkmcnt(0)
	v_mfma_f32_16x16x32_bf16 v[156:159], v[76:79], v[160:163], v[156:159]
	v_mfma_f32_16x16x32_bf16 v[148:151], v[88:91], v[160:163], v[148:151]
	v_mfma_f32_16x16x32_bf16 v[140:143], v[76:79], v[206:209], v[140:143]
	v_mfma_f32_16x16x32_bf16 v[132:135], v[88:91], v[206:209], v[132:135]
	v_mfma_f32_16x16x32_bf16 v[124:127], v[76:79], v[214:217], v[124:127]
	v_mfma_f32_16x16x32_bf16 v[108:111], v[88:91], v[214:217], v[108:111]
	v_mfma_f32_16x16x32_bf16 v[84:87], v[76:79], v[222:225], v[84:87]
	v_mfma_f32_16x16x32_bf16 v[68:71], v[88:91], v[222:225], v[68:71]
	v_mfma_f32_16x16x32_bf16 v[156:159], v[80:83], v[164:167], v[156:159]
	v_mfma_f32_16x16x32_bf16 v[148:151], v[92:95], v[164:167], v[148:151]
	v_mfma_f32_16x16x32_bf16 v[140:143], v[80:83], v[210:213], v[140:143]
	v_mfma_f32_16x16x32_bf16 v[132:135], v[92:95], v[210:213], v[132:135]
	v_mfma_f32_16x16x32_bf16 v[124:127], v[80:83], v[218:221], v[124:127]
	v_mfma_f32_16x16x32_bf16 v[108:111], v[92:95], v[218:221], v[108:111]
	v_mfma_f32_16x16x32_bf16 v[84:87], v[80:83], v[226:229], v[84:87]
	v_mfma_f32_16x16x32_bf16 v[68:71], v[92:95], v[226:229], v[68:71]
	s_setprio 0
	s_setprio 1
	v_mfma_f32_16x16x32_bf16 v[152:155], v[100:103], v[160:163], v[152:155]
	v_mfma_f32_16x16x32_bf16 v[144:147], v[112:115], v[160:163], v[144:147]
	v_mfma_f32_16x16x32_bf16 v[136:139], v[100:103], v[206:209], v[136:139]
	v_mfma_f32_16x16x32_bf16 v[128:131], v[112:115], v[206:209], v[128:131]
	v_mfma_f32_16x16x32_bf16 v[120:123], v[100:103], v[214:217], v[120:123]
	v_mfma_f32_16x16x32_bf16 v[96:99], v[112:115], v[214:217], v[96:99]
	v_mfma_f32_16x16x32_bf16 v[72:75], v[100:103], v[222:225], v[72:75]
	v_mfma_f32_16x16x32_bf16 v[64:67], v[112:115], v[222:225], v[64:67]
	v_mfma_f32_16x16x32_bf16 v[152:155], v[104:107], v[164:167], v[152:155]
	v_mfma_f32_16x16x32_bf16 v[144:147], v[116:119], v[164:167], v[144:147]
	v_mfma_f32_16x16x32_bf16 v[136:139], v[104:107], v[210:213], v[136:139]
	v_mfma_f32_16x16x32_bf16 v[128:131], v[116:119], v[210:213], v[128:131]
	v_mfma_f32_16x16x32_bf16 v[120:123], v[104:107], v[218:221], v[120:123]
	v_mfma_f32_16x16x32_bf16 v[96:99], v[116:119], v[218:221], v[96:99]
	v_mfma_f32_16x16x32_bf16 v[72:75], v[104:107], v[226:229], v[72:75]
	v_mfma_f32_16x16x32_bf16 v[64:67], v[116:119], v[226:229], v[64:67]
	s_setprio 0
	s_barrier
	s_add_i32 vcc_hi, s89, s77
	v_lshl_add_u64 v[186:187], s[0:1], 0, v[170:171]
	s_mov_b32 m0, vcc_hi
	ds_read_b128 v[160:163], v201 offset:16384
	ds_read_b128 v[164:167], v201 offset:17408
	ds_read_b128 v[206:209], v201 offset:18432
	ds_read_b128 v[210:213], v201 offset:19456
	ds_read_b128 v[214:217], v201 offset:20480
	ds_read_b128 v[218:221], v201 offset:21504
	ds_read_b128 v[222:225], v201 offset:22528
	ds_read_b128 v[226:229], v201 offset:23552
	global_load_lds_dwordx4 v[186:187], off
	s_add_i32 m0, vcc_hi, 0x2000
	v_lshl_add_u64 v[190:191], s[0:1], 0, v[174:175]
	s_add_u32 s0, s0, s10
	s_addc_u32 s1, s1, s11
	s_add_i32 vcc_hi, s90, s77
	global_load_lds_dwordx4 v[190:191], off
	v_lshl_add_u64 v[198:199], s[0:1], 0, v[170:171]
	s_mov_b32 m0, vcc_hi
	v_lshl_add_u64 v[202:203], s[0:1], 0, v[174:175]
	global_load_lds_dwordx4 v[198:199], off
	s_add_i32 m0, vcc_hi, 0x2000
	v_lshl_add_u64 v[230:231], s[36:37], 0, v[168:169]
	global_load_lds_dwordx4 v[202:203], off
	s_mov_b32 m0, s80
	v_lshl_add_u64 v[232:233], s[36:37], 0, v[172:173]
	global_load_lds_dwordx4 v[230:231], off
	s_mov_b32 m0, s81
	s_nop 0
	global_load_lds_dwordx4 v[232:233], off
	s_waitcnt vmcnt(8)
	s_waitcnt lgkmcnt(0)
	s_barrier
; #define PG8_STAGE(bufoff, gbase, voff) do { _Pragma("unroll") for (int _i = 0; _i < 2; ++_i) \
;         __builtin_amdgcn_global_load_lds((const unsigned*)((const char*)(gbase) + (voff)[_i]), (PG8_LAS unsigned*)(lds + (bufoff) + ldsw + _i * 8192), 16, 0, 0); } while (0)
; #define PG8_LDA(dst, b, h) do { _Pragma("unroll") for (int m = 0; m < 4; ++m) _Pragma("unroll") for (int k = 0; k < 2; ++k) dst[m][k] = *(const PG8_LAS bf16x8*)(lds + PG8_SA(b, h) + aoff + m * 2048 + k * 1024); } while (0)
; #define PG8_LDB(dst, b, h) do { _Pragma("unroll") for (int n = 0; n < 2; ++n) _Pragma("unroll") for (int k = 0; k < 2; ++k) dst[n][k] = *(const PG8_LAS bf16x8*)(lds + PG8_SB(b, h) + boff + n * 2048 + k * 1024); } while (0)
; #define PG8_MMA(ai, bj, At, Bt) do { __builtin_amdgcn_s_setprio(1); _Pragma("unroll") for (int m = 0; m < 4; ++m) _Pragma("unroll") for (int n = 0; n < 2; ++n) _Pragma("unroll") for (int k = 0; k < 2; ++k) \
;         acc[ai][bj][m][n] = __builtin_amdgcn_mfma_f32_16x16x32_bf16(Bt[n][k], At[m][k], acc[ai][bj][m][n], 0, 0, 0); __builtin_amdgcn_s_setprio(0); } while (0)
; #define PG8_WAIT_V(n) asm volatile("s_waitcnt vmcnt(" #n ")" ::: "memory")
; #define PG8_WAIT_L(n) asm volatile("s_waitcnt lgkmcnt(" #n ")" ::: "memory")
; #define PG8_BAR __builtin_amdgcn_s_barrier()
; #define PG8_SCHED __builtin_amdgcn_sched_barrier(0)
; template <class Epi, class Sched, bool ALIGN_EPI = false, bool SP2 = false>
; __device__ __forceinline__ void gemm_phase(PG8_LAS unsigned char* lds, const Gemm g, const Sched& S, const Epi& E) {
;     ...
;             PG8_WAIT_V(8); PG8_WAIT_L(0); PG8_BAR; PG8_MMA(1, 0, At, B0); PG8_MMA(1, 1, At, B1); PG8_BAR; PG8_SCHED;
;             PG8_LDB(B0, 1, 0); PG8_LDB(B1, 1, 1); PG8_SCHED; PG8_LDA(At, 1, 0); PG8_STAGE(PG8_SA(0, 1), a2 + hstep, voffA);
;             PG8_WAIT_V(8); PG8_WAIT_L(0); PG8_BAR; PG8_MMA(0, 0, At, B0); PG8_MMA(0, 1, At, B1); PG8_BAR; PG8_SCHED;
	s_setprio 1
	s_waitcnt lgkmcnt(0)
	v_mfma_f32_16x16x32_bf16 v[60:63], v[76:79], v[160:163], v[60:63]
	v_mfma_f32_16x16x32_bf16 v[52:55], v[88:91], v[160:163], v[52:55]
	v_mfma_f32_16x16x32_bf16 v[44:47], v[76:79], v[206:209], v[44:47]
	v_mfma_f32_16x16x32_bf16 v[36:39], v[88:91], v[206:209], v[36:39]
	v_mfma_f32_16x16x32_bf16 v[28:31], v[76:79], v[214:217], v[28:31]
	v_mfma_f32_16x16x32_bf16 v[20:23], v[88:91], v[214:217], v[20:23]
	v_mfma_f32_16x16x32_bf16 v[12:15], v[76:79], v[222:225], v[12:15]
	v_mfma_f32_16x16x32_bf16 v[4:7], v[88:91], v[222:225], v[4:7]
	v_mfma_f32_16x16x32_bf16 v[60:63], v[80:83], v[164:167], v[60:63]
	v_mfma_f32_16x16x32_bf16 v[52:55], v[92:95], v[164:167], v[52:55]
	v_mfma_f32_16x16x32_bf16 v[44:47], v[80:83], v[210:213], v[44:47]
	v_mfma_f32_16x16x32_bf16 v[36:39], v[92:95], v[210:213], v[36:39]
	v_mfma_f32_16x16x32_bf16 v[28:31], v[80:83], v[218:221], v[28:31]
	v_mfma_f32_16x16x32_bf16 v[20:23], v[92:95], v[218:221], v[20:23]
	v_mfma_f32_16x16x32_bf16 v[12:15], v[80:83], v[226:229], v[12:15]
	v_mfma_f32_16x16x32_bf16 v[4:7], v[92:95], v[226:229], v[4:7]
	s_setprio 0
	s_setprio 1
	v_mfma_f32_16x16x32_bf16 v[56:59], v[100:103], v[160:163], v[56:59]
	v_mfma_f32_16x16x32_bf16 v[48:51], v[112:115], v[160:163], v[48:51]
	v_mfma_f32_16x16x32_bf16 v[40:43], v[100:103], v[206:209], v[40:43]
	v_mfma_f32_16x16x32_bf16 v[32:35], v[112:115], v[206:209], v[32:35]
	v_mfma_f32_16x16x32_bf16 v[24:27], v[100:103], v[214:217], v[24:27]
	v_mfma_f32_16x16x32_bf16 v[16:19], v[112:115], v[214:217], v[16:19]
	v_mfma_f32_16x16x32_bf16 v[8:11], v[100:103], v[222:225], v[8:11]
	v_mfma_f32_16x16x32_bf16 v[0:3], v[112:115], v[222:225], v[0:3]
	v_mfma_f32_16x16x32_bf16 v[56:59], v[104:107], v[164:167], v[56:59]
	v_mfma_f32_16x16x32_bf16 v[48:51], v[116:119], v[164:167], v[48:51]
	v_mfma_f32_16x16x32_bf16 v[40:43], v[104:107], v[210:213], v[40:43]
	v_mfma_f32_16x16x32_bf16 v[32:35], v[116:119], v[210:213], v[32:35]
	v_mfma_f32_16x16x32_bf16 v[24:27], v[104:107], v[218:221], v[24:27]
	v_mfma_f32_16x16x32_bf16 v[16:19], v[116:119], v[218:221], v[16:19]
	v_mfma_f32_16x16x32_bf16 v[8:11], v[104:107], v[226:229], v[8:11]
	v_mfma_f32_16x16x32_bf16 v[0:3], v[116:119], v[226:229], v[0:3]
	s_setprio 0
	s_barrier
	s_add_i32 vcc_hi, 0, 0x18000
	s_add_i32 s66, 0, 0x1c000
	v_add_u32_e32 v92, vcc_hi, v189
	v_add_u32_e32 v116, s66, v189
	ds_read_b128 v[76:79], v92
	ds_read_b128 v[80:83], v92 offset:1024
	ds_read_b128 v[88:91], v92 offset:2048
	ds_read_b128 v[92:95], v92 offset:3072
	ds_read_b128 v[100:103], v116
	ds_read_b128 v[104:107], v116 offset:1024
	ds_read_b128 v[112:115], v116 offset:2048
	ds_read_b128 v[116:119], v116 offset:3072
	s_add_u32 s0, s36, s10
	s_addc_u32 s1, s37, s11
	s_mov_b32 m0, s82
	v_lshl_add_u64 v[234:235], s[0:1], 0, v[168:169]
	ds_read_b128 v[160:163], v201 offset:32768
	ds_read_b128 v[164:167], v201 offset:33792
	ds_read_b128 v[206:209], v201 offset:34816
	ds_read_b128 v[210:213], v201 offset:35840
	ds_read_b128 v[214:217], v201 offset:36864
	ds_read_b128 v[218:221], v201 offset:37888
	ds_read_b128 v[222:225], v201 offset:38912
	ds_read_b128 v[226:229], v201 offset:39936
	global_load_lds_dwordx4 v[234:235], off
	v_lshl_add_u64 v[234:235], s[0:1], 0, v[172:173]
	s_mov_b32 m0, s83
	s_nop 0
	global_load_lds_dwordx4 v[234:235], off
	s_waitcnt vmcnt(8)
	s_waitcnt lgkmcnt(0)
	s_barrier
	s_setprio 1
	s_waitcnt lgkmcnt(0)
	v_mfma_f32_16x16x32_bf16 v[156:159], v[76:79], v[160:163], v[156:159]
	v_mfma_f32_16x16x32_bf16 v[148:151], v[88:91], v[160:163], v[148:151]
	v_mfma_f32_16x16x32_bf16 v[140:143], v[76:79], v[206:209], v[140:143]
	v_mfma_f32_16x16x32_bf16 v[132:135], v[88:91], v[206:209], v[132:135]
	v_mfma_f32_16x16x32_bf16 v[124:127], v[76:79], v[214:217], v[124:127]
	v_mfma_f32_16x16x32_bf16 v[108:111], v[88:91], v[214:217], v[108:111]
	v_mfma_f32_16x16x32_bf16 v[84:87], v[76:79], v[222:225], v[84:87]
	v_mfma_f32_16x16x32_bf16 v[68:71], v[88:91], v[222:225], v[68:71]
	v_mfma_f32_16x16x32_bf16 v[156:159], v[80:83], v[164:167], v[156:159]
	v_mfma_f32_16x16x32_bf16 v[148:151], v[92:95], v[164:167], v[148:151]
	v_mfma_f32_16x16x32_bf16 v[140:143], v[80:83], v[210:213], v[140:143]
	v_mfma_f32_16x16x32_bf16 v[132:135], v[92:95], v[210:213], v[132:135]
	v_mfma_f32_16x16x32_bf16 v[124:127], v[80:83], v[218:221], v[124:127]
	v_mfma_f32_16x16x32_bf16 v[108:111], v[92:95], v[218:221], v[108:111]
	v_mfma_f32_16x16x32_bf16 v[84:87], v[80:83], v[226:229], v[84:87]
	v_mfma_f32_16x16x32_bf16 v[68:71], v[92:95], v[226:229], v[68:71]
	s_setprio 0
	s_setprio 1
	v_mfma_f32_16x16x32_bf16 v[152:155], v[100:103], v[160:163], v[152:155]
	v_mfma_f32_16x16x32_bf16 v[144:147], v[112:115], v[160:163], v[144:147]
	v_mfma_f32_16x16x32_bf16 v[136:139], v[100:103], v[206:209], v[136:139]
	v_mfma_f32_16x16x32_bf16 v[128:131], v[112:115], v[206:209], v[128:131]
	v_mfma_f32_16x16x32_bf16 v[120:123], v[100:103], v[214:217], v[120:123]
	v_mfma_f32_16x16x32_bf16 v[96:99], v[112:115], v[214:217], v[96:99]
	v_mfma_f32_16x16x32_bf16 v[72:75], v[100:103], v[222:225], v[72:75]
	v_mfma_f32_16x16x32_bf16 v[64:67], v[112:115], v[222:225], v[64:67]
	v_mfma_f32_16x16x32_bf16 v[152:155], v[104:107], v[164:167], v[152:155]
	v_mfma_f32_16x16x32_bf16 v[144:147], v[116:119], v[164:167], v[144:147]
	v_mfma_f32_16x16x32_bf16 v[136:139], v[104:107], v[210:213], v[136:139]
	v_mfma_f32_16x16x32_bf16 v[128:131], v[116:119], v[210:213], v[128:131]
	v_mfma_f32_16x16x32_bf16 v[120:123], v[104:107], v[218:221], v[120:123]
	v_mfma_f32_16x16x32_bf16 v[96:99], v[116:119], v[218:221], v[96:99]
	v_mfma_f32_16x16x32_bf16 v[72:75], v[104:107], v[226:229], v[72:75]
	v_mfma_f32_16x16x32_bf16 v[64:67], v[116:119], v[226:229], v[64:67]
	s_setprio 0
	s_barrier
; #define PG8_STAGE(bufoff, gbase, voff) do { _Pragma("unroll") for (int _i = 0; _i < 2; ++_i) \
;         __builtin_amdgcn_global_load_lds((const unsigned*)((const char*)(gbase) + (voff)[_i]), (PG8_LAS unsigned*)(lds + (bufoff) + ldsw + _i * 8192), 16, 0, 0); } while (0)
; #define PG8_LDA(dst, b, h) do { _Pragma("unroll") for (int m = 0; m < 4; ++m) _Pragma("unroll") for (int k = 0; k < 2; ++k) dst[m][k] = *(const PG8_LAS bf16x8*)(lds + PG8_SA(b, h) + aoff + m * 2048 + k * 1024); } while (0)
; #define PG8_MMA(ai, bj, At, Bt) do { __builtin_amdgcn_s_setprio(1); _Pragma("unroll") for (int m = 0; m < 4; ++m) _Pragma("unroll") for (int n = 0; n < 2; ++n) _Pragma("unroll") for (int k = 0; k < 2; ++k) \
;         acc[ai][bj][m][n] = __builtin_amdgcn_mfma_f32_16x16x32_bf16(Bt[n][k], At[m][k], acc[ai][bj][m][n], 0, 0, 0); __builtin_amdgcn_s_setprio(0); } while (0)
; #define PG8_WAIT_V(n) asm volatile("s_waitcnt vmcnt(" #n ")" ::: "memory")
; #define PG8_WAIT_L(n) asm volatile("s_waitcnt lgkmcnt(" #n ")" ::: "memory")
; #define PG8_BAR __builtin_amdgcn_s_barrier()
; #define PG8_SCHED __builtin_amdgcn_sched_barrier(0)
; template <class Epi, class Sched, bool ALIGN_EPI = false, bool SP2 = false>
; __device__ __forceinline__ void gemm_phase(PG8_LAS unsigned char* lds, const Gemm g, const Sched& S, const Epi& E) {
;     ...
;         for (int t = 0; t < nt; t += 2) {
;     ...
;             PG8_LDA(At, 1, 1); PG8_STAGE(PG8_SB(1, 0), b3, voffB); PG8_STAGE(PG8_SB(1, 1), b3 + hstep, voffB); PG8_STAGE(PG8_SA(1, 0), a3, voffA);
;             PG8_WAIT_V(8); PG8_WAIT_L(0); PG8_BAR; PG8_MMA(1, 0, At, B0); PG8_MMA(1, 1, At, B1); PG8_BAR; PG8_SCHED;
	s_add_i32 s0, vcc_hi, s77
	v_lshl_add_u64 v[186:187], v[186:187], 0, s[20:21]
	s_mov_b32 m0, s0
	ds_read_b128 v[160:163], v201 offset:49152
	ds_read_b128 v[164:167], v201 offset:50176
	ds_read_b128 v[206:209], v201 offset:51200
	ds_read_b128 v[210:213], v201 offset:52224
	ds_read_b128 v[214:217], v201 offset:53248
	ds_read_b128 v[218:221], v201 offset:54272
	ds_read_b128 v[222:225], v201 offset:55296
	ds_read_b128 v[226:229], v201 offset:56320
	global_load_lds_dwordx4 v[186:187], off
	v_lshl_add_u64 v[186:187], v[190:191], 0, s[20:21]
	s_add_i32 m0, s0, 0x2000
	s_add_i32 s0, s66, s77
	global_load_lds_dwordx4 v[186:187], off
	v_lshl_add_u64 v[186:187], v[198:199], 0, s[20:21]
	s_mov_b32 m0, s0
	s_nop 0
	global_load_lds_dwordx4 v[186:187], off
	v_lshl_add_u64 v[186:187], v[202:203], 0, s[20:21]
	s_add_i32 m0, s0, 0x2000
	s_nop 0
	global_load_lds_dwordx4 v[186:187], off
	v_lshl_add_u64 v[186:187], v[230:231], 0, s[20:21]
	s_mov_b32 m0, s85
	s_nop 0
	global_load_lds_dwordx4 v[186:187], off
	v_lshl_add_u64 v[186:187], v[232:233], 0, s[20:21]
	s_mov_b32 m0, s86
	s_nop 0
	global_load_lds_dwordx4 v[186:187], off
	s_waitcnt vmcnt(8)
	s_waitcnt lgkmcnt(0)
	s_barrier
	s_setprio 1
	s_waitcnt lgkmcnt(0)
	v_mfma_f32_16x16x32_bf16 v[60:63], v[76:79], v[160:163], v[60:63]
	v_mfma_f32_16x16x32_bf16 v[52:55], v[88:91], v[160:163], v[52:55]
	v_mfma_f32_16x16x32_bf16 v[44:47], v[76:79], v[206:209], v[44:47]
	v_mfma_f32_16x16x32_bf16 v[36:39], v[88:91], v[206:209], v[36:39]
	v_mfma_f32_16x16x32_bf16 v[28:31], v[76:79], v[214:217], v[28:31]
	v_mfma_f32_16x16x32_bf16 v[20:23], v[88:91], v[214:217], v[20:23]
	v_mfma_f32_16x16x32_bf16 v[12:15], v[76:79], v[222:225], v[12:15]
	v_mfma_f32_16x16x32_bf16 v[4:7], v[88:91], v[222:225], v[4:7]
	v_mfma_f32_16x16x32_bf16 v[60:63], v[80:83], v[164:167], v[60:63]
	v_mfma_f32_16x16x32_bf16 v[52:55], v[92:95], v[164:167], v[52:55]
	v_mfma_f32_16x16x32_bf16 v[44:47], v[80:83], v[210:213], v[44:47]
	v_mfma_f32_16x16x32_bf16 v[36:39], v[92:95], v[210:213], v[36:39]
	v_mfma_f32_16x16x32_bf16 v[28:31], v[80:83], v[218:221], v[28:31]
	v_mfma_f32_16x16x32_bf16 v[20:23], v[92:95], v[218:221], v[20:23]
	v_mfma_f32_16x16x32_bf16 v[12:15], v[80:83], v[226:229], v[12:15]
	v_mfma_f32_16x16x32_bf16 v[4:7], v[92:95], v[226:229], v[4:7]
	s_setprio 0
	s_setprio 1
	v_mfma_f32_16x16x32_bf16 v[56:59], v[100:103], v[160:163], v[56:59]
	v_mfma_f32_16x16x32_bf16 v[48:51], v[112:115], v[160:163], v[48:51]
	v_mfma_f32_16x16x32_bf16 v[40:43], v[100:103], v[206:209], v[40:43]
	v_mfma_f32_16x16x32_bf16 v[32:35], v[112:115], v[206:209], v[32:35]
	v_mfma_f32_16x16x32_bf16 v[24:27], v[100:103], v[214:217], v[24:27]
	v_mfma_f32_16x16x32_bf16 v[16:19], v[112:115], v[214:217], v[16:19]
	v_mfma_f32_16x16x32_bf16 v[8:11], v[100:103], v[222:225], v[8:11]
	v_mfma_f32_16x16x32_bf16 v[0:3], v[112:115], v[222:225], v[0:3]
	v_mfma_f32_16x16x32_bf16 v[56:59], v[104:107], v[164:167], v[56:59]
	v_mfma_f32_16x16x32_bf16 v[48:51], v[116:119], v[164:167], v[48:51]
	v_mfma_f32_16x16x32_bf16 v[40:43], v[104:107], v[210:213], v[40:43]
	v_mfma_f32_16x16x32_bf16 v[32:35], v[116:119], v[210:213], v[32:35]
	v_mfma_f32_16x16x32_bf16 v[24:27], v[104:107], v[218:221], v[24:27]
	v_mfma_f32_16x16x32_bf16 v[16:19], v[116:119], v[218:221], v[16:19]
	v_mfma_f32_16x16x32_bf16 v[8:11], v[104:107], v[226:229], v[8:11]
	v_mfma_f32_16x16x32_bf16 v[0:3], v[116:119], v[226:229], v[0:3]
	s_setprio 0
	s_barrier
	s_add_u32 s34, s34, 0x100
	s_addc_u32 s35, s35, 0
	s_add_u32 s31, s31, 0x100
	s_addc_u32 s96, s96, 0
	s_cmp_ge_i32 vcc_lo, s87
	s_mov_b32 s36, vcc_lo
	s_cbranch_scc0 .LBB0_1639

; #define PG8_STAGE(bufoff, gbase, voff) do { _Pragma("unroll") for (int _i = 0; _i < 2; ++_i) \
;         __builtin_amdgcn_global_load_lds((const unsigned*)((const char*)(gbase) + (voff)[_i]), (PG8_LAS unsigned*)(lds + (bufoff) + ldsw + _i * 8192), 16, 0, 0); } while (0)
; #define PG8_LDA(dst, b, h) do { _Pragma("unroll") for (int m = 0; m < 4; ++m) _Pragma("unroll") for (int k = 0; k < 2; ++k) dst[m][k] = *(const PG8_LAS bf16x8*)(lds + PG8_SA(b, h) + aoff + m * 2048 + k * 1024); } while (0)
; #define PG8_LDB(dst, b, h) do { _Pragma("unroll") for (int n = 0; n < 2; ++n) _Pragma("unroll") for (int k = 0; k < 2; ++k) dst[n][k] = *(const PG8_LAS bf16x8*)(lds + PG8_SB(b, h) + boff + n * 2048 + k * 1024); } while (0)
; #define PG8_MMA(ai, bj, At, Bt) do { __builtin_amdgcn_s_setprio(1); _Pragma("unroll") for (int m = 0; m < 4; ++m) _Pragma("unroll") for (int n = 0; n < 2; ++n) _Pragma("unroll") for (int k = 0; k < 2; ++k) \
;         acc[ai][bj][m][n] = __builtin_amdgcn_mfma_f32_16x16x32_bf16(Bt[n][k], At[m][k], acc[ai][bj][m][n], 0, 0, 0); __builtin_amdgcn_s_setprio(0); } while (0)
; #define PG8_WAIT_V(n) asm volatile("s_waitcnt vmcnt(" #n ")" ::: "memory")
; #define PG8_WAIT_L(n) asm volatile("s_waitcnt lgkmcnt(" #n ")" ::: "memory")
; #define PG8_BAR __builtin_amdgcn_s_barrier()
; #define PG8_SCHED __builtin_amdgcn_sched_barrier(0)
; template <class Epi, class Sched, bool ALIGN_EPI = false, bool SP2 = false>
; __device__ __forceinline__ void gemm_phase(PG8_LAS unsigned char* lds, const Gemm g, const Sched& S, const Epi& E) {
;     ...
;             PG8_LDB(B0, 0, 0); PG8_LDB(B1, 0, 1); PG8_SCHED; PG8_LDA(At, 0, 0); PG8_STAGE(PG8_SA(1, 1), a1 + hstep, voffA);
;             PG8_WAIT_V(8); PG8_WAIT_L(0); PG8_BAR; PG8_MMA(0, 0, At, B0); PG8_MMA(0, 1, At, B1); PG8_BAR; PG8_SCHED;
;             PG8_LDA(At, 0, 1); PG8_STAGE(PG8_SB(0, 0), b2, voffB); PG8_STAGE(PG8_SB(0, 1), b2 + hstep, voffB); PG8_STAGE(PG8_SA(0, 0), a2, voffA);
;             PG8_WAIT_V(8); PG8_WAIT_L(0); PG8_BAR; PG8_MMA(1, 0, At, B0); PG8_MMA(1, 1, At, B1); PG8_BAR; PG8_SCHED;
.LBB0_1668:
	s_sleep 2
	ds_read_b128 v[150:153], v146
	ds_read_b128 v[154:157], v146 offset:1024
	ds_read_b128 v[158:161], v146 offset:2048
	ds_read_b128 v[162:165], v146 offset:3072
	ds_read_b128 v[166:169], v147
	ds_read_b128 v[170:173], v147 offset:1024
	ds_read_b128 v[174:177], v147 offset:2048
	ds_read_b128 v[178:181], v147 offset:3072
	s_add_i32 s90, s30, 2
	s_add_u32 s91, s28, 0x80
	s_addc_u32 s31, s29, 0
	s_cmp_eq_u32 s84, s30
	s_cselect_b32 s30, s6, s91
	s_cselect_b32 s31, s7, s31
	s_cselect_b32 s93, s27, s89
	s_cselect_b32 s92, s26, s21
	v_lshl_add_u64 v[190:191], s[28:29], 0, v[138:139]
	s_add_i32 m0, s71, 0xc000
	ds_read_b128 v[182:185], v148
	ds_read_b128 v[186:189], v148 offset:1024
	ds_read_b128 v[196:199], v148 offset:2048
	ds_read_b128 v[200:203], v148 offset:3072
	ds_read_b128 v[204:207], v148 offset:4096
	ds_read_b128 v[208:211], v148 offset:5120
	ds_read_b128 v[212:215], v148 offset:6144
	ds_read_b128 v[216:219], v148 offset:7168
	global_load_lds_dwordx4 v[190:191], off
	v_lshl_add_u64 v[190:191], s[28:29], 0, v[140:141]
	s_add_i32 m0, s71, 0xe000
	s_nop 0
	global_load_lds_dwordx4 v[190:191], off
	s_waitcnt vmcnt(8)
	s_waitcnt lgkmcnt(0)
	s_barrier
	s_setprio 1
	s_waitcnt lgkmcnt(0)
	v_mfma_f32_16x16x32_bf16 v[120:123], v[150:153], v[182:185], v[120:123]
	v_mfma_f32_16x16x32_bf16 v[124:127], v[158:161], v[182:185], v[124:127]
	v_mfma_f32_16x16x32_bf16 v[108:111], v[150:153], v[196:199], v[108:111]
	v_mfma_f32_16x16x32_bf16 v[104:107], v[158:161], v[196:199], v[104:107]
	v_mfma_f32_16x16x32_bf16 v[92:95], v[150:153], v[204:207], v[92:95]
	v_mfma_f32_16x16x32_bf16 v[88:91], v[158:161], v[204:207], v[88:91]
	v_mfma_f32_16x16x32_bf16 v[76:79], v[150:153], v[212:215], v[76:79]
	v_mfma_f32_16x16x32_bf16 v[72:75], v[158:161], v[212:215], v[72:75]
	v_mfma_f32_16x16x32_bf16 v[120:123], v[154:157], v[186:189], v[120:123]
	v_mfma_f32_16x16x32_bf16 v[124:127], v[162:165], v[186:189], v[124:127]
	v_mfma_f32_16x16x32_bf16 v[108:111], v[154:157], v[200:203], v[108:111]
	v_mfma_f32_16x16x32_bf16 v[104:107], v[162:165], v[200:203], v[104:107]
	v_mfma_f32_16x16x32_bf16 v[92:95], v[154:157], v[208:211], v[92:95]
	v_mfma_f32_16x16x32_bf16 v[88:91], v[162:165], v[208:211], v[88:91]
	v_mfma_f32_16x16x32_bf16 v[76:79], v[154:157], v[216:219], v[76:79]
	v_mfma_f32_16x16x32_bf16 v[72:75], v[162:165], v[216:219], v[72:75]
	s_setprio 0
	s_setprio 1
	v_mfma_f32_16x16x32_bf16 v[116:119], v[166:169], v[182:185], v[116:119]
	v_mfma_f32_16x16x32_bf16 v[112:115], v[174:177], v[182:185], v[112:115]
	v_mfma_f32_16x16x32_bf16 v[100:103], v[166:169], v[196:199], v[100:103]
	v_mfma_f32_16x16x32_bf16 v[96:99], v[174:177], v[196:199], v[96:99]
	v_mfma_f32_16x16x32_bf16 v[84:87], v[166:169], v[204:207], v[84:87]
	v_mfma_f32_16x16x32_bf16 v[80:83], v[174:177], v[204:207], v[80:83]
	v_mfma_f32_16x16x32_bf16 v[68:71], v[166:169], v[212:215], v[68:71]
	v_mfma_f32_16x16x32_bf16 v[64:67], v[174:177], v[212:215], v[64:67]
	v_mfma_f32_16x16x32_bf16 v[116:119], v[170:173], v[186:189], v[116:119]
	v_mfma_f32_16x16x32_bf16 v[112:115], v[178:181], v[186:189], v[112:115]
	v_mfma_f32_16x16x32_bf16 v[100:103], v[170:173], v[200:203], v[100:103]
	v_mfma_f32_16x16x32_bf16 v[96:99], v[178:181], v[200:203], v[96:99]
	v_mfma_f32_16x16x32_bf16 v[84:87], v[170:173], v[208:211], v[84:87]
	v_mfma_f32_16x16x32_bf16 v[80:83], v[178:181], v[208:211], v[80:83]
	v_mfma_f32_16x16x32_bf16 v[68:71], v[170:173], v[216:219], v[68:71]
	v_mfma_f32_16x16x32_bf16 v[64:67], v[178:181], v[216:219], v[64:67]
	s_setprio 0
	s_barrier
	s_add_i32 s91, s85, s1
	v_lshl_add_u64 v[190:191], s[92:93], 0, v[130:131]
	s_mov_b32 m0, s91
	ds_read_b128 v[182:185], v148 offset:16384
	ds_read_b128 v[186:189], v148 offset:17408
	ds_read_b128 v[196:199], v148 offset:18432
	ds_read_b128 v[200:203], v148 offset:19456
	ds_read_b128 v[204:207], v148 offset:20480
	ds_read_b128 v[208:211], v148 offset:21504
	ds_read_b128 v[212:215], v148 offset:22528
	ds_read_b128 v[216:219], v148 offset:23552
	global_load_lds_dwordx4 v[190:191], off
	s_add_i32 m0, s91, 0x2000
	v_lshl_add_u64 v[220:221], s[92:93], 0, v[134:135]
	s_add_u32 s92, s92, s10
	s_addc_u32 s93, s93, s11
	s_add_i32 s91, s86, s1
	global_load_lds_dwordx4 v[220:221], off
	v_lshl_add_u64 v[222:223], s[92:93], 0, v[130:131]
	s_mov_b32 m0, s91
	v_lshl_add_u64 v[224:225], s[92:93], 0, v[134:135]
	global_load_lds_dwordx4 v[222:223], off
	s_add_i32 m0, s91, 0x2000
	v_lshl_add_u64 v[226:227], s[30:31], 0, v[128:129]
	global_load_lds_dwordx4 v[224:225], off
	s_mov_b32 m0, s71
	v_lshl_add_u64 v[228:229], s[30:31], 0, v[132:133]
	global_load_lds_dwordx4 v[226:227], off
	s_mov_b32 m0, s76
	s_nop 0
	global_load_lds_dwordx4 v[228:229], off
	s_waitcnt vmcnt(8)
	s_waitcnt lgkmcnt(0)
	s_barrier
; #define PG8_STAGE(bufoff, gbase, voff) do { _Pragma("unroll") for (int _i = 0; _i < 2; ++_i) \
;         __builtin_amdgcn_global_load_lds((const unsigned*)((const char*)(gbase) + (voff)[_i]), (PG8_LAS unsigned*)(lds + (bufoff) + ldsw + _i * 8192), 16, 0, 0); } while (0)
; #define PG8_LDA(dst, b, h) do { _Pragma("unroll") for (int m = 0; m < 4; ++m) _Pragma("unroll") for (int k = 0; k < 2; ++k) dst[m][k] = *(const PG8_LAS bf16x8*)(lds + PG8_SA(b, h) + aoff + m * 2048 + k * 1024); } while (0)
; #define PG8_LDB(dst, b, h) do { _Pragma("unroll") for (int n = 0; n < 2; ++n) _Pragma("unroll") for (int k = 0; k < 2; ++k) dst[n][k] = *(const PG8_LAS bf16x8*)(lds + PG8_SB(b, h) + boff + n * 2048 + k * 1024); } while (0)
; #define PG8_MMA(ai, bj, At, Bt) do { __builtin_amdgcn_s_setprio(1); _Pragma("unroll") for (int m = 0; m < 4; ++m) _Pragma("unroll") for (int n = 0; n < 2; ++n) _Pragma("unroll") for (int k = 0; k < 2; ++k) \
;         acc[ai][bj][m][n] = __builtin_amdgcn_mfma_f32_16x16x32_bf16(Bt[n][k], At[m][k], acc[ai][bj][m][n], 0, 0, 0); __builtin_amdgcn_s_setprio(0); } while (0)
; #define PG8_WAIT_V(n) asm volatile("s_waitcnt vmcnt(" #n ")" ::: "memory")
; #define PG8_WAIT_L(n) asm volatile("s_waitcnt lgkmcnt(" #n ")" ::: "memory")
; #define PG8_BAR __builtin_amdgcn_s_barrier()
; #define PG8_SCHED __builtin_amdgcn_sched_barrier(0)
; template <class Epi, class Sched, bool ALIGN_EPI = false, bool SP2 = false>
; __device__ __forceinline__ void gemm_phase(PG8_LAS unsigned char* lds, const Gemm g, const Sched& S, const Epi& E) {
;     ...
;             PG8_WAIT_V(8); PG8_WAIT_L(0); PG8_BAR; PG8_MMA(1, 0, At, B0); PG8_MMA(1, 1, At, B1); PG8_BAR; PG8_SCHED;
;             PG8_LDB(B0, 1, 0); PG8_LDB(B1, 1, 1); PG8_SCHED; PG8_LDA(At, 1, 0); PG8_STAGE(PG8_SA(0, 1), a2 + hstep, voffA);
;             PG8_WAIT_V(8); PG8_WAIT_L(0); PG8_BAR; PG8_MMA(0, 0, At, B0); PG8_MMA(0, 1, At, B1); PG8_BAR; PG8_SCHED;
	s_setprio 1
	s_waitcnt lgkmcnt(0)
	v_mfma_f32_16x16x32_bf16 v[60:63], v[150:153], v[182:185], v[60:63]
	v_mfma_f32_16x16x32_bf16 v[56:59], v[158:161], v[182:185], v[56:59]
	v_mfma_f32_16x16x32_bf16 v[44:47], v[150:153], v[196:199], v[44:47]
	v_mfma_f32_16x16x32_bf16 v[40:43], v[158:161], v[196:199], v[40:43]
	v_mfma_f32_16x16x32_bf16 v[28:31], v[150:153], v[204:207], v[28:31]
	v_mfma_f32_16x16x32_bf16 v[24:27], v[158:161], v[204:207], v[24:27]
	v_mfma_f32_16x16x32_bf16 v[12:15], v[150:153], v[212:215], v[12:15]
	v_mfma_f32_16x16x32_bf16 v[8:11], v[158:161], v[212:215], v[8:11]
	v_mfma_f32_16x16x32_bf16 v[60:63], v[154:157], v[186:189], v[60:63]
	v_mfma_f32_16x16x32_bf16 v[56:59], v[162:165], v[186:189], v[56:59]
	v_mfma_f32_16x16x32_bf16 v[44:47], v[154:157], v[200:203], v[44:47]
	v_mfma_f32_16x16x32_bf16 v[40:43], v[162:165], v[200:203], v[40:43]
	v_mfma_f32_16x16x32_bf16 v[28:31], v[154:157], v[208:211], v[28:31]
	v_mfma_f32_16x16x32_bf16 v[24:27], v[162:165], v[208:211], v[24:27]
	v_mfma_f32_16x16x32_bf16 v[12:15], v[154:157], v[216:219], v[12:15]
	v_mfma_f32_16x16x32_bf16 v[8:11], v[162:165], v[216:219], v[8:11]
	s_setprio 0
	s_setprio 1
	v_mfma_f32_16x16x32_bf16 v[52:55], v[166:169], v[182:185], v[52:55]
	v_mfma_f32_16x16x32_bf16 v[48:51], v[174:177], v[182:185], v[48:51]
	v_mfma_f32_16x16x32_bf16 v[36:39], v[166:169], v[196:199], v[36:39]
	v_mfma_f32_16x16x32_bf16 v[32:35], v[174:177], v[196:199], v[32:35]
	v_mfma_f32_16x16x32_bf16 v[20:23], v[166:169], v[204:207], v[20:23]
	v_mfma_f32_16x16x32_bf16 v[16:19], v[174:177], v[204:207], v[16:19]
	v_mfma_f32_16x16x32_bf16 v[4:7], v[166:169], v[212:215], v[4:7]
	v_mfma_f32_16x16x32_bf16 v[0:3], v[174:177], v[212:215], v[0:3]
	v_mfma_f32_16x16x32_bf16 v[52:55], v[170:173], v[186:189], v[52:55]
	v_mfma_f32_16x16x32_bf16 v[48:51], v[178:181], v[186:189], v[48:51]
	v_mfma_f32_16x16x32_bf16 v[36:39], v[170:173], v[200:203], v[36:39]
	v_mfma_f32_16x16x32_bf16 v[32:35], v[178:181], v[200:203], v[32:35]
	v_mfma_f32_16x16x32_bf16 v[20:23], v[170:173], v[208:211], v[20:23]
	v_mfma_f32_16x16x32_bf16 v[16:19], v[178:181], v[208:211], v[16:19]
	v_mfma_f32_16x16x32_bf16 v[4:7], v[170:173], v[216:219], v[4:7]
	v_mfma_f32_16x16x32_bf16 v[0:3], v[178:181], v[216:219], v[0:3]
	s_setprio 0
	s_barrier
	s_add_i32 s91, 0, 0x18000
	v_add_u32_e32 v149, s91, v144
	s_add_i32 s92, 0, 0x1c000
	ds_read_b128 v[150:153], v149
	ds_read_b128 v[154:157], v149 offset:1024
	ds_read_b128 v[158:161], v149 offset:2048
	ds_read_b128 v[162:165], v149 offset:3072
	v_add_u32_e32 v149, s92, v144
	ds_read_b128 v[166:169], v149
	ds_read_b128 v[170:173], v149 offset:1024
	ds_read_b128 v[174:177], v149 offset:2048
	ds_read_b128 v[178:181], v149 offset:3072
	s_add_u32 s30, s30, s10
	s_addc_u32 s31, s31, s11
	s_mov_b32 m0, s77
	v_lshl_add_u64 v[230:231], s[30:31], 0, v[128:129]
	ds_read_b128 v[182:185], v148 offset:32768
	ds_read_b128 v[186:189], v148 offset:33792
	ds_read_b128 v[196:199], v148 offset:34816
	ds_read_b128 v[200:203], v148 offset:35840
	ds_read_b128 v[204:207], v148 offset:36864
	ds_read_b128 v[208:211], v148 offset:37888
	ds_read_b128 v[212:215], v148 offset:38912
	ds_read_b128 v[216:219], v148 offset:39936
	global_load_lds_dwordx4 v[230:231], off
	v_lshl_add_u64 v[230:231], s[30:31], 0, v[132:133]
	s_mov_b32 m0, s78
	s_nop 0
	global_load_lds_dwordx4 v[230:231], off
	s_waitcnt vmcnt(8)
	s_waitcnt lgkmcnt(0)
	s_barrier
	s_setprio 1
	s_waitcnt lgkmcnt(0)
	v_mfma_f32_16x16x32_bf16 v[120:123], v[150:153], v[182:185], v[120:123]
	v_mfma_f32_16x16x32_bf16 v[124:127], v[158:161], v[182:185], v[124:127]
	v_mfma_f32_16x16x32_bf16 v[108:111], v[150:153], v[196:199], v[108:111]
	v_mfma_f32_16x16x32_bf16 v[104:107], v[158:161], v[196:199], v[104:107]
	v_mfma_f32_16x16x32_bf16 v[92:95], v[150:153], v[204:207], v[92:95]
	v_mfma_f32_16x16x32_bf16 v[88:91], v[158:161], v[204:207], v[88:91]
	v_mfma_f32_16x16x32_bf16 v[76:79], v[150:153], v[212:215], v[76:79]
	v_mfma_f32_16x16x32_bf16 v[72:75], v[158:161], v[212:215], v[72:75]
	v_mfma_f32_16x16x32_bf16 v[120:123], v[154:157], v[186:189], v[120:123]
	v_mfma_f32_16x16x32_bf16 v[124:127], v[162:165], v[186:189], v[124:127]
	v_mfma_f32_16x16x32_bf16 v[108:111], v[154:157], v[200:203], v[108:111]
	v_mfma_f32_16x16x32_bf16 v[104:107], v[162:165], v[200:203], v[104:107]
	v_mfma_f32_16x16x32_bf16 v[92:95], v[154:157], v[208:211], v[92:95]
	v_mfma_f32_16x16x32_bf16 v[88:91], v[162:165], v[208:211], v[88:91]
	v_mfma_f32_16x16x32_bf16 v[76:79], v[154:157], v[216:219], v[76:79]
	v_mfma_f32_16x16x32_bf16 v[72:75], v[162:165], v[216:219], v[72:75]
	s_setprio 0
	s_setprio 1
	v_mfma_f32_16x16x32_bf16 v[116:119], v[166:169], v[182:185], v[116:119]
	v_mfma_f32_16x16x32_bf16 v[112:115], v[174:177], v[182:185], v[112:115]
	v_mfma_f32_16x16x32_bf16 v[100:103], v[166:169], v[196:199], v[100:103]
	v_mfma_f32_16x16x32_bf16 v[96:99], v[174:177], v[196:199], v[96:99]
	v_mfma_f32_16x16x32_bf16 v[84:87], v[166:169], v[204:207], v[84:87]
	v_mfma_f32_16x16x32_bf16 v[80:83], v[174:177], v[204:207], v[80:83]
	v_mfma_f32_16x16x32_bf16 v[68:71], v[166:169], v[212:215], v[68:71]
	v_mfma_f32_16x16x32_bf16 v[64:67], v[174:177], v[212:215], v[64:67]
	v_mfma_f32_16x16x32_bf16 v[116:119], v[170:173], v[186:189], v[116:119]
	v_mfma_f32_16x16x32_bf16 v[112:115], v[178:181], v[186:189], v[112:115]
	v_mfma_f32_16x16x32_bf16 v[100:103], v[170:173], v[200:203], v[100:103]
	v_mfma_f32_16x16x32_bf16 v[96:99], v[178:181], v[200:203], v[96:99]
	v_mfma_f32_16x16x32_bf16 v[84:87], v[170:173], v[208:211], v[84:87]
	v_mfma_f32_16x16x32_bf16 v[80:83], v[178:181], v[208:211], v[80:83]
	v_mfma_f32_16x16x32_bf16 v[68:71], v[170:173], v[216:219], v[68:71]
	v_mfma_f32_16x16x32_bf16 v[64:67], v[178:181], v[216:219], v[64:67]
	s_setprio 0
	s_barrier
; #define PG8_STAGE(bufoff, gbase, voff) do { _Pragma("unroll") for (int _i = 0; _i < 2; ++_i) \
;         __builtin_amdgcn_global_load_lds((const unsigned*)((const char*)(gbase) + (voff)[_i]), (PG8_LAS unsigned*)(lds + (bufoff) + ldsw + _i * 8192), 16, 0, 0); } while (0)
; #define PG8_LDA(dst, b, h) do { _Pragma("unroll") for (int m = 0; m < 4; ++m) _Pragma("unroll") for (int k = 0; k < 2; ++k) dst[m][k] = *(const PG8_LAS bf16x8*)(lds + PG8_SA(b, h) + aoff + m * 2048 + k * 1024); } while (0)
; #define PG8_MMA(ai, bj, At, Bt) do { __builtin_amdgcn_s_setprio(1); _Pragma("unroll") for (int m = 0; m < 4; ++m) _Pragma("unroll") for (int n = 0; n < 2; ++n) _Pragma("unroll") for (int k = 0; k < 2; ++k) \
;         acc[ai][bj][m][n] = __builtin_amdgcn_mfma_f32_16x16x32_bf16(Bt[n][k], At[m][k], acc[ai][bj][m][n], 0, 0, 0); __builtin_amdgcn_s_setprio(0); } while (0)
; #define PG8_WAIT_V(n) asm volatile("s_waitcnt vmcnt(" #n ")" ::: "memory")
; #define PG8_WAIT_L(n) asm volatile("s_waitcnt lgkmcnt(" #n ")" ::: "memory")
; #define PG8_BAR __builtin_amdgcn_s_barrier()
; #define PG8_SCHED __builtin_amdgcn_sched_barrier(0)
; template <class Epi, class Sched, bool ALIGN_EPI = false, bool SP2 = false>
; __device__ __forceinline__ void gemm_phase(PG8_LAS unsigned char* lds, const Gemm g, const Sched& S, const Epi& E) {
;     ...
;             PG8_LDA(At, 1, 1); PG8_STAGE(PG8_SB(1, 0), b3, voffB); PG8_STAGE(PG8_SB(1, 1), b3 + hstep, voffB); PG8_STAGE(PG8_SA(1, 0), a3, voffA);
;             PG8_WAIT_V(8); PG8_WAIT_L(0); PG8_BAR; PG8_MMA(1, 0, At, B0); PG8_MMA(1, 1, At, B1); PG8_BAR; PG8_SCHED;
	s_add_i32 s30, s91, s1
	v_lshl_add_u64 v[190:191], v[190:191], 0, s[16:17]
	s_mov_b32 m0, s30
	ds_read_b128 v[182:185], v148 offset:49152
	ds_read_b128 v[186:189], v148 offset:50176
	ds_read_b128 v[196:199], v148 offset:51200
	ds_read_b128 v[200:203], v148 offset:52224
	ds_read_b128 v[204:207], v148 offset:53248
	ds_read_b128 v[208:211], v148 offset:54272
	ds_read_b128 v[212:215], v148 offset:55296
	ds_read_b128 v[216:219], v148 offset:56320
	global_load_lds_dwordx4 v[190:191], off
	v_lshl_add_u64 v[190:191], v[220:221], 0, s[16:17]
	s_add_i32 m0, s30, 0x2000
	s_add_i32 s30, s92, s1
	global_load_lds_dwordx4 v[190:191], off
	v_lshl_add_u64 v[190:191], v[222:223], 0, s[16:17]
	s_mov_b32 m0, s30
	s_nop 0
	global_load_lds_dwordx4 v[190:191], off
	v_lshl_add_u64 v[190:191], v[224:225], 0, s[16:17]
	s_add_i32 m0, s30, 0x2000
	s_nop 0
	global_load_lds_dwordx4 v[190:191], off
	v_lshl_add_u64 v[190:191], v[226:227], 0, s[16:17]
	s_mov_b32 m0, s80
	s_nop 0
	global_load_lds_dwordx4 v[190:191], off
	v_lshl_add_u64 v[190:191], v[228:229], 0, s[16:17]
	s_mov_b32 m0, s81
	s_nop 0
	global_load_lds_dwordx4 v[190:191], off
	s_waitcnt vmcnt(8)
	s_waitcnt lgkmcnt(0)
	s_barrier
	s_setprio 1
	s_waitcnt lgkmcnt(0)
	v_mfma_f32_16x16x32_bf16 v[60:63], v[150:153], v[182:185], v[60:63]
	v_mfma_f32_16x16x32_bf16 v[56:59], v[158:161], v[182:185], v[56:59]
	v_mfma_f32_16x16x32_bf16 v[44:47], v[150:153], v[196:199], v[44:47]
	v_mfma_f32_16x16x32_bf16 v[40:43], v[158:161], v[196:199], v[40:43]
	v_mfma_f32_16x16x32_bf16 v[28:31], v[150:153], v[204:207], v[28:31]
	v_mfma_f32_16x16x32_bf16 v[24:27], v[158:161], v[204:207], v[24:27]
	v_mfma_f32_16x16x32_bf16 v[12:15], v[150:153], v[212:215], v[12:15]
	v_mfma_f32_16x16x32_bf16 v[8:11], v[158:161], v[212:215], v[8:11]
	v_mfma_f32_16x16x32_bf16 v[60:63], v[154:157], v[186:189], v[60:63]
	v_mfma_f32_16x16x32_bf16 v[56:59], v[162:165], v[186:189], v[56:59]
	v_mfma_f32_16x16x32_bf16 v[44:47], v[154:157], v[200:203], v[44:47]
	v_mfma_f32_16x16x32_bf16 v[40:43], v[162:165], v[200:203], v[40:43]
	v_mfma_f32_16x16x32_bf16 v[28:31], v[154:157], v[208:211], v[28:31]
	v_mfma_f32_16x16x32_bf16 v[24:27], v[162:165], v[208:211], v[24:27]
	v_mfma_f32_16x16x32_bf16 v[12:15], v[154:157], v[216:219], v[12:15]
	v_mfma_f32_16x16x32_bf16 v[8:11], v[162:165], v[216:219], v[8:11]
	s_setprio 0
	s_setprio 1
	v_mfma_f32_16x16x32_bf16 v[52:55], v[166:169], v[182:185], v[52:55]
	v_mfma_f32_16x16x32_bf16 v[48:51], v[174:177], v[182:185], v[48:51]
	v_mfma_f32_16x16x32_bf16 v[36:39], v[166:169], v[196:199], v[36:39]
	v_mfma_f32_16x16x32_bf16 v[32:35], v[174:177], v[196:199], v[32:35]
	v_mfma_f32_16x16x32_bf16 v[20:23], v[166:169], v[204:207], v[20:23]
	v_mfma_f32_16x16x32_bf16 v[16:19], v[174:177], v[204:207], v[16:19]
	v_mfma_f32_16x16x32_bf16 v[4:7], v[166:169], v[212:215], v[4:7]
	v_mfma_f32_16x16x32_bf16 v[0:3], v[174:177], v[212:215], v[0:3]
	v_mfma_f32_16x16x32_bf16 v[52:55], v[170:173], v[186:189], v[52:55]
	v_mfma_f32_16x16x32_bf16 v[48:51], v[178:181], v[186:189], v[48:51]
	v_mfma_f32_16x16x32_bf16 v[36:39], v[170:173], v[200:203], v[36:39]
	v_mfma_f32_16x16x32_bf16 v[32:35], v[178:181], v[200:203], v[32:35]
	v_mfma_f32_16x16x32_bf16 v[20:23], v[170:173], v[208:211], v[20:23]
	v_mfma_f32_16x16x32_bf16 v[16:19], v[178:181], v[208:211], v[16:19]
	v_mfma_f32_16x16x32_bf16 v[4:7], v[170:173], v[216:219], v[4:7]
	v_mfma_f32_16x16x32_bf16 v[0:3], v[178:181], v[216:219], v[0:3]
	s_setprio 0
	s_barrier
	s_add_u32 s28, s28, 0x100
	s_addc_u32 s29, s29, 0
	s_add_u32 s21, s21, 0x100
	s_addc_u32 s89, s89, 0
	s_cmp_ge_i32 s90, s82
	s_mov_b32 s30, s90
	s_cbranch_scc0 .LBB0_1668

; #define PG8_STAGE(bufoff, gbase, voff) do { _Pragma("unroll") for (int _i = 0; _i < 2; ++_i) \
;         __builtin_amdgcn_global_load_lds((const unsigned*)((const char*)(gbase) + (voff)[_i]), (PG8_LAS unsigned*)(lds + (bufoff) + ldsw + _i * 8192), 16, 0, 0); } while (0)
; #define PG8_LDA(dst, b, h) do { _Pragma("unroll") for (int m = 0; m < 4; ++m) _Pragma("unroll") for (int k = 0; k < 2; ++k) dst[m][k] = *(const PG8_LAS bf16x8*)(lds + PG8_SA(b, h) + aoff + m * 2048 + k * 1024); } while (0)
; #define PG8_LDB(dst, b, h) do { _Pragma("unroll") for (int n = 0; n < 2; ++n) _Pragma("unroll") for (int k = 0; k < 2; ++k) dst[n][k] = *(const PG8_LAS bf16x8*)(lds + PG8_SB(b, h) + boff + n * 2048 + k * 1024); } while (0)
; #define PG8_MMA(ai, bj, At, Bt) do { __builtin_amdgcn_s_setprio(1); _Pragma("unroll") for (int m = 0; m < 4; ++m) _Pragma("unroll") for (int n = 0; n < 2; ++n) _Pragma("unroll") for (int k = 0; k < 2; ++k) \
;         acc[ai][bj][m][n] = __builtin_amdgcn_mfma_f32_16x16x32_bf16(Bt[n][k], At[m][k], acc[ai][bj][m][n], 0, 0, 0); __builtin_amdgcn_s_setprio(0); } while (0)
; #define PG8_WAIT_V(n) asm volatile("s_waitcnt vmcnt(" #n ")" ::: "memory")
; #define PG8_BAR __builtin_amdgcn_s_barrier()
; template <class Epi, class Sched, bool ALIGN_EPI = false, bool SP2 = false>
; __device__ __forceinline__ void gemm_phase(PG8_LAS unsigned char* lds, const Gemm g, const Sched& S, const Epi& E) {
;     ...
;         for (int t = 0; t < nt; t += 2) {
;             const bool last = (t == nt - 2);
;             const char* a1 = cA + (size_t)(t + 1) * kstep;
;             const char* a2 = last ? nA : cA + (size_t)(t + 2) * kstep; const char* b2 = last ? nB : cB + (size_t)(t + 2) * kstep;
;             const char* a3 = a2 + kstep; const char* b3 = b2 + kstep;
;             if (last && has_next) S.a_ready(nxt);
;             if constexpr (SP2) {
;             PG8_LDB(B0, 0, 0); PG8_LDB(B1, 0, 1); PG8_SCHED; PG8_LDA(At, 0, 0); PG8_STAGE(PG8_SA(1, 1), a1 + hstep, voffA);
;             PG8_WAIT_V(8); PG8_WAIT_L(0); PG8_BAR; PG8_MMA(0, 0, At, B0); PG8_MMA(0, 1, At, B1); PG8_BAR; PG8_SCHED;
;             PG8_LDA(At, 0, 1); PG8_STAGE(PG8_SB(0, 0), b2, voffB); PG8_STAGE(PG8_SB(0, 1), b2 + hstep, voffB); PG8_STAGE(PG8_SA(0, 0), a2, voffA);
;             PG8_WAIT_V(8); PG8_WAIT_L(0); PG8_BAR; PG8_MMA(1, 0, At, B0); PG8_MMA(1, 1, At, B1); PG8_BAR; PG8_SCHED;
.LBB0_1754:
	s_sleep 2
	ds_read_b128 v[116:119], v240
	ds_read_b128 v[124:127], v240 offset:1024
	ds_read_b128 v[128:131], v240 offset:2048
	ds_read_b128 v[132:135], v240 offset:3072
	ds_read_b128 v[136:139], v241
	ds_read_b128 v[148:151], v241 offset:1024
	ds_read_b128 v[152:155], v241 offset:2048
	ds_read_b128 v[176:179], v241 offset:3072
	s_add_i32 s96, s78, 2
	s_add_u32 vcc_lo, s38, 0x80
	s_addc_u32 s79, s39, 0
	s_cmp_eq_u32 s81, s78
	s_cselect_b32 s78, s8, vcc_lo
	s_cselect_b32 s79, s9, s79
	s_cselect_b32 vcc_hi, s35, s95
	s_cselect_b32 vcc_lo, s34, s37
	v_lshl_add_u64 v[216:217], s[38:39], 0, v[170:171]
	s_add_i32 m0, s33, 0xc000
	ds_read_b128 v[180:183], v242
	ds_read_b128 v[184:187], v242 offset:1024
	ds_read_b128 v[188:191], v242 offset:2048
	ds_read_b128 v[196:199], v242 offset:3072
	ds_read_b128 v[200:203], v242 offset:4096
	ds_read_b128 v[204:207], v242 offset:5120
	ds_read_b128 v[208:211], v242 offset:6144
	ds_read_b128 v[212:215], v242 offset:7168
	global_load_lds_dwordx4 v[216:217], off
	v_lshl_add_u64 v[216:217], s[38:39], 0, v[172:173]
	s_add_i32 m0, s33, 0xe000
	s_nop 0
	global_load_lds_dwordx4 v[216:217], off
	s_waitcnt vmcnt(8)
	s_waitcnt lgkmcnt(0)
	s_barrier
	s_setprio 1
	s_waitcnt lgkmcnt(0)
	v_mfma_f32_16x16x32_bf16 v[144:147], v[116:119], v[180:183], v[144:147]
	v_mfma_f32_16x16x32_bf16 v[140:143], v[128:131], v[180:183], v[140:143]
	v_mfma_f32_16x16x32_bf16 v[108:111], v[116:119], v[188:191], v[108:111]
	v_mfma_f32_16x16x32_bf16 v[104:107], v[128:131], v[188:191], v[104:107]
	v_mfma_f32_16x16x32_bf16 v[92:95], v[116:119], v[200:203], v[92:95]
	v_mfma_f32_16x16x32_bf16 v[88:91], v[128:131], v[200:203], v[88:91]
	v_mfma_f32_16x16x32_bf16 v[76:79], v[116:119], v[208:211], v[76:79]
	v_mfma_f32_16x16x32_bf16 v[72:75], v[128:131], v[208:211], v[72:75]
	v_mfma_f32_16x16x32_bf16 v[144:147], v[124:127], v[184:187], v[144:147]
	v_mfma_f32_16x16x32_bf16 v[140:143], v[132:135], v[184:187], v[140:143]
	v_mfma_f32_16x16x32_bf16 v[108:111], v[124:127], v[196:199], v[108:111]
	v_mfma_f32_16x16x32_bf16 v[104:107], v[132:135], v[196:199], v[104:107]
	v_mfma_f32_16x16x32_bf16 v[92:95], v[124:127], v[204:207], v[92:95]
	v_mfma_f32_16x16x32_bf16 v[88:91], v[132:135], v[204:207], v[88:91]
	v_mfma_f32_16x16x32_bf16 v[76:79], v[124:127], v[212:215], v[76:79]
	v_mfma_f32_16x16x32_bf16 v[72:75], v[132:135], v[212:215], v[72:75]
	s_setprio 0
	s_setprio 1
	v_mfma_f32_16x16x32_bf16 v[120:123], v[136:139], v[180:183], v[120:123]
	v_mfma_f32_16x16x32_bf16 v[112:115], v[152:155], v[180:183], v[112:115]
	v_mfma_f32_16x16x32_bf16 v[100:103], v[136:139], v[188:191], v[100:103]
	v_mfma_f32_16x16x32_bf16 v[96:99], v[152:155], v[188:191], v[96:99]
	v_mfma_f32_16x16x32_bf16 v[84:87], v[136:139], v[200:203], v[84:87]
	v_mfma_f32_16x16x32_bf16 v[80:83], v[152:155], v[200:203], v[80:83]
	v_mfma_f32_16x16x32_bf16 v[68:71], v[136:139], v[208:211], v[68:71]
	v_mfma_f32_16x16x32_bf16 v[64:67], v[152:155], v[208:211], v[64:67]
	v_mfma_f32_16x16x32_bf16 v[120:123], v[148:151], v[184:187], v[120:123]
	v_mfma_f32_16x16x32_bf16 v[112:115], v[176:179], v[184:187], v[112:115]
	v_mfma_f32_16x16x32_bf16 v[100:103], v[148:151], v[196:199], v[100:103]
	v_mfma_f32_16x16x32_bf16 v[96:99], v[176:179], v[196:199], v[96:99]
	v_mfma_f32_16x16x32_bf16 v[84:87], v[148:151], v[204:207], v[84:87]
	v_mfma_f32_16x16x32_bf16 v[80:83], v[176:179], v[204:207], v[80:83]
	v_mfma_f32_16x16x32_bf16 v[68:71], v[148:151], v[212:215], v[68:71]
	v_mfma_f32_16x16x32_bf16 v[64:67], v[176:179], v[212:215], v[64:67]
	s_setprio 0
	s_barrier
	s_add_i32 s84, s89, s31
	v_lshl_add_u64 v[216:217], vcc, 0, v[158:159]
	s_mov_b32 m0, s84
	ds_read_b128 v[180:183], v242 offset:16384
	ds_read_b128 v[184:187], v242 offset:17408
	ds_read_b128 v[188:191], v242 offset:18432
	ds_read_b128 v[196:199], v242 offset:19456
	ds_read_b128 v[200:203], v242 offset:20480
	ds_read_b128 v[204:207], v242 offset:21504
	ds_read_b128 v[208:211], v242 offset:22528
	ds_read_b128 v[212:215], v242 offset:23552
	global_load_lds_dwordx4 v[216:217], off
	s_add_i32 m0, s84, 0x2000
	v_lshl_add_u64 v[218:219], vcc, 0, v[162:163]
	s_add_u32 vcc_lo, vcc_lo, s12
	s_addc_u32 vcc_hi, vcc_hi, s13
	s_add_i32 s84, s90, s31
	global_load_lds_dwordx4 v[218:219], off
	v_lshl_add_u64 v[220:221], vcc, 0, v[158:159]
	s_mov_b32 m0, s84
	v_lshl_add_u64 v[222:223], vcc, 0, v[162:163]
	global_load_lds_dwordx4 v[220:221], off
	s_add_i32 m0, s84, 0x2000
	v_lshl_add_u64 v[224:225], s[78:79], 0, v[156:157]
	global_load_lds_dwordx4 v[222:223], off
	s_mov_b32 m0, s33
	v_lshl_add_u64 v[226:227], s[78:79], 0, v[160:161]
	global_load_lds_dwordx4 v[224:225], off
	s_mov_b32 m0, s46
	s_nop 0
	global_load_lds_dwordx4 v[226:227], off
	s_waitcnt vmcnt(8)
	s_waitcnt lgkmcnt(0)
	s_barrier
; #define PG8_STAGE(bufoff, gbase, voff) do { _Pragma("unroll") for (int _i = 0; _i < 2; ++_i) \
;         __builtin_amdgcn_global_load_lds((const unsigned*)((const char*)(gbase) + (voff)[_i]), (PG8_LAS unsigned*)(lds + (bufoff) + ldsw + _i * 8192), 16, 0, 0); } while (0)
; #define PG8_LDA(dst, b, h) do { _Pragma("unroll") for (int m = 0; m < 4; ++m) _Pragma("unroll") for (int k = 0; k < 2; ++k) dst[m][k] = *(const PG8_LAS bf16x8*)(lds + PG8_SA(b, h) + aoff + m * 2048 + k * 1024); } while (0)
; #define PG8_LDB(dst, b, h) do { _Pragma("unroll") for (int n = 0; n < 2; ++n) _Pragma("unroll") for (int k = 0; k < 2; ++k) dst[n][k] = *(const PG8_LAS bf16x8*)(lds + PG8_SB(b, h) + boff + n * 2048 + k * 1024); } while (0)
; #define PG8_MMA(ai, bj, At, Bt) do { __builtin_amdgcn_s_setprio(1); _Pragma("unroll") for (int m = 0; m < 4; ++m) _Pragma("unroll") for (int n = 0; n < 2; ++n) _Pragma("unroll") for (int k = 0; k < 2; ++k) \
;         acc[ai][bj][m][n] = __builtin_amdgcn_mfma_f32_16x16x32_bf16(Bt[n][k], At[m][k], acc[ai][bj][m][n], 0, 0, 0); __builtin_amdgcn_s_setprio(0); } while (0)
; #define PG8_WAIT_V(n) asm volatile("s_waitcnt vmcnt(" #n ")" ::: "memory")
; #define PG8_WAIT_L(n) asm volatile("s_waitcnt lgkmcnt(" #n ")" ::: "memory")
; #define PG8_BAR __builtin_amdgcn_s_barrier()
; #define PG8_SCHED __builtin_amdgcn_sched_barrier(0)
; template <class Epi, class Sched, bool ALIGN_EPI = false, bool SP2 = false>
; __device__ __forceinline__ void gemm_phase(PG8_LAS unsigned char* lds, const Gemm g, const Sched& S, const Epi& E) {
;     ...
;             PG8_WAIT_V(8); PG8_WAIT_L(0); PG8_BAR; PG8_MMA(1, 0, At, B0); PG8_MMA(1, 1, At, B1); PG8_BAR; PG8_SCHED;
;             PG8_LDB(B0, 1, 0); PG8_LDB(B1, 1, 1); PG8_SCHED; PG8_LDA(At, 1, 0); PG8_STAGE(PG8_SA(0, 1), a2 + hstep, voffA);
;             PG8_WAIT_V(8); PG8_WAIT_L(0); PG8_BAR; PG8_MMA(0, 0, At, B0); PG8_MMA(0, 1, At, B1); PG8_BAR; PG8_SCHED;
	s_setprio 1
	s_waitcnt lgkmcnt(0)
	v_mfma_f32_16x16x32_bf16 v[60:63], v[116:119], v[180:183], v[60:63]
	v_mfma_f32_16x16x32_bf16 v[56:59], v[128:131], v[180:183], v[56:59]
	v_mfma_f32_16x16x32_bf16 v[44:47], v[116:119], v[188:191], v[44:47]
	v_mfma_f32_16x16x32_bf16 v[40:43], v[128:131], v[188:191], v[40:43]
	v_mfma_f32_16x16x32_bf16 v[28:31], v[116:119], v[200:203], v[28:31]
	v_mfma_f32_16x16x32_bf16 v[24:27], v[128:131], v[200:203], v[24:27]
	v_mfma_f32_16x16x32_bf16 v[12:15], v[116:119], v[208:211], v[12:15]
	v_mfma_f32_16x16x32_bf16 v[8:11], v[128:131], v[208:211], v[8:11]
	v_mfma_f32_16x16x32_bf16 v[60:63], v[124:127], v[184:187], v[60:63]
	v_mfma_f32_16x16x32_bf16 v[56:59], v[132:135], v[184:187], v[56:59]
	v_mfma_f32_16x16x32_bf16 v[44:47], v[124:127], v[196:199], v[44:47]
	v_mfma_f32_16x16x32_bf16 v[40:43], v[132:135], v[196:199], v[40:43]
	v_mfma_f32_16x16x32_bf16 v[28:31], v[124:127], v[204:207], v[28:31]
	v_mfma_f32_16x16x32_bf16 v[24:27], v[132:135], v[204:207], v[24:27]
	v_mfma_f32_16x16x32_bf16 v[12:15], v[124:127], v[212:215], v[12:15]
	v_mfma_f32_16x16x32_bf16 v[8:11], v[132:135], v[212:215], v[8:11]
	s_setprio 0
	s_setprio 1
	v_mfma_f32_16x16x32_bf16 v[52:55], v[136:139], v[180:183], v[52:55]
	v_mfma_f32_16x16x32_bf16 v[48:51], v[152:155], v[180:183], v[48:51]
	v_mfma_f32_16x16x32_bf16 v[36:39], v[136:139], v[188:191], v[36:39]
	v_mfma_f32_16x16x32_bf16 v[32:35], v[152:155], v[188:191], v[32:35]
	v_mfma_f32_16x16x32_bf16 v[20:23], v[136:139], v[200:203], v[20:23]
	v_mfma_f32_16x16x32_bf16 v[16:19], v[152:155], v[200:203], v[16:19]
	v_mfma_f32_16x16x32_bf16 v[4:7], v[136:139], v[208:211], v[4:7]
	v_mfma_f32_16x16x32_bf16 v[0:3], v[152:155], v[208:211], v[0:3]
	v_mfma_f32_16x16x32_bf16 v[52:55], v[148:151], v[184:187], v[52:55]
	v_mfma_f32_16x16x32_bf16 v[48:51], v[176:179], v[184:187], v[48:51]
	v_mfma_f32_16x16x32_bf16 v[36:39], v[148:151], v[196:199], v[36:39]
	v_mfma_f32_16x16x32_bf16 v[32:35], v[176:179], v[196:199], v[32:35]
	v_mfma_f32_16x16x32_bf16 v[20:23], v[148:151], v[204:207], v[20:23]
	v_mfma_f32_16x16x32_bf16 v[16:19], v[176:179], v[204:207], v[16:19]
	v_mfma_f32_16x16x32_bf16 v[4:7], v[148:151], v[212:215], v[4:7]
	v_mfma_f32_16x16x32_bf16 v[0:3], v[176:179], v[212:215], v[0:3]
	s_setprio 0
	s_barrier
	s_add_i32 s84, 0, 0x18000
	s_add_i32 vcc_lo, 0, 0x1c000
	v_add_u32_e32 v132, s84, v193
	v_add_u32_e32 v165, vcc_lo, v193
	ds_read_b128 v[116:119], v132
	ds_read_b128 v[124:127], v132 offset:1024
	ds_read_b128 v[128:131], v132 offset:2048
	ds_read_b128 v[132:135], v132 offset:3072
	ds_read_b128 v[136:139], v165
	ds_read_b128 v[148:151], v165 offset:1024
	ds_read_b128 v[152:155], v165 offset:2048
	ds_read_b128 v[176:179], v165 offset:3072
	s_add_u32 s78, s78, s12
	s_addc_u32 s79, s79, s13
	s_mov_b32 m0, s47
	v_lshl_add_u64 v[228:229], s[78:79], 0, v[156:157]
	ds_read_b128 v[180:183], v242 offset:32768
	ds_read_b128 v[184:187], v242 offset:33792
	ds_read_b128 v[188:191], v242 offset:34816
	ds_read_b128 v[196:199], v242 offset:35840
	ds_read_b128 v[200:203], v242 offset:36864
	ds_read_b128 v[204:207], v242 offset:37888
	ds_read_b128 v[208:211], v242 offset:38912
	ds_read_b128 v[212:215], v242 offset:39936
	global_load_lds_dwordx4 v[228:229], off
	v_lshl_add_u64 v[228:229], s[78:79], 0, v[160:161]
	s_mov_b32 m0, s66
	s_nop 0
	global_load_lds_dwordx4 v[228:229], off
	s_waitcnt vmcnt(8)
	s_waitcnt lgkmcnt(0)
	s_barrier
	s_setprio 1
	s_waitcnt lgkmcnt(0)
	v_mfma_f32_16x16x32_bf16 v[144:147], v[116:119], v[180:183], v[144:147]
	v_mfma_f32_16x16x32_bf16 v[140:143], v[128:131], v[180:183], v[140:143]
	v_mfma_f32_16x16x32_bf16 v[108:111], v[116:119], v[188:191], v[108:111]
	v_mfma_f32_16x16x32_bf16 v[104:107], v[128:131], v[188:191], v[104:107]
	v_mfma_f32_16x16x32_bf16 v[92:95], v[116:119], v[200:203], v[92:95]
	v_mfma_f32_16x16x32_bf16 v[88:91], v[128:131], v[200:203], v[88:91]
	v_mfma_f32_16x16x32_bf16 v[76:79], v[116:119], v[208:211], v[76:79]
	v_mfma_f32_16x16x32_bf16 v[72:75], v[128:131], v[208:211], v[72:75]
	v_mfma_f32_16x16x32_bf16 v[144:147], v[124:127], v[184:187], v[144:147]
	v_mfma_f32_16x16x32_bf16 v[140:143], v[132:135], v[184:187], v[140:143]
	v_mfma_f32_16x16x32_bf16 v[108:111], v[124:127], v[196:199], v[108:111]
	v_mfma_f32_16x16x32_bf16 v[104:107], v[132:135], v[196:199], v[104:107]
	v_mfma_f32_16x16x32_bf16 v[92:95], v[124:127], v[204:207], v[92:95]
	v_mfma_f32_16x16x32_bf16 v[88:91], v[132:135], v[204:207], v[88:91]
	v_mfma_f32_16x16x32_bf16 v[76:79], v[124:127], v[212:215], v[76:79]
	v_mfma_f32_16x16x32_bf16 v[72:75], v[132:135], v[212:215], v[72:75]
	s_setprio 0
	s_setprio 1
	v_mfma_f32_16x16x32_bf16 v[120:123], v[136:139], v[180:183], v[120:123]
	v_mfma_f32_16x16x32_bf16 v[112:115], v[152:155], v[180:183], v[112:115]
	v_mfma_f32_16x16x32_bf16 v[100:103], v[136:139], v[188:191], v[100:103]
	v_mfma_f32_16x16x32_bf16 v[96:99], v[152:155], v[188:191], v[96:99]
	v_mfma_f32_16x16x32_bf16 v[84:87], v[136:139], v[200:203], v[84:87]
	v_mfma_f32_16x16x32_bf16 v[80:83], v[152:155], v[200:203], v[80:83]
	v_mfma_f32_16x16x32_bf16 v[68:71], v[136:139], v[208:211], v[68:71]
	v_mfma_f32_16x16x32_bf16 v[64:67], v[152:155], v[208:211], v[64:67]
	v_mfma_f32_16x16x32_bf16 v[120:123], v[148:151], v[184:187], v[120:123]
	v_mfma_f32_16x16x32_bf16 v[112:115], v[176:179], v[184:187], v[112:115]
	v_mfma_f32_16x16x32_bf16 v[100:103], v[148:151], v[196:199], v[100:103]
	v_mfma_f32_16x16x32_bf16 v[96:99], v[176:179], v[196:199], v[96:99]
	v_mfma_f32_16x16x32_bf16 v[84:87], v[148:151], v[204:207], v[84:87]
	v_mfma_f32_16x16x32_bf16 v[80:83], v[176:179], v[204:207], v[80:83]
	v_mfma_f32_16x16x32_bf16 v[68:71], v[148:151], v[212:215], v[68:71]
	v_mfma_f32_16x16x32_bf16 v[64:67], v[176:179], v[212:215], v[64:67]
	s_setprio 0
	s_barrier
; #define PG8_STAGE(bufoff, gbase, voff) do { _Pragma("unroll") for (int _i = 0; _i < 2; ++_i) \
;         __builtin_amdgcn_global_load_lds((const unsigned*)((const char*)(gbase) + (voff)[_i]), (PG8_LAS unsigned*)(lds + (bufoff) + ldsw + _i * 8192), 16, 0, 0); } while (0)
; #define PG8_LDA(dst, b, h) do { _Pragma("unroll") for (int m = 0; m < 4; ++m) _Pragma("unroll") for (int k = 0; k < 2; ++k) dst[m][k] = *(const PG8_LAS bf16x8*)(lds + PG8_SA(b, h) + aoff + m * 2048 + k * 1024); } while (0)
; #define PG8_MMA(ai, bj, At, Bt) do { __builtin_amdgcn_s_setprio(1); _Pragma("unroll") for (int m = 0; m < 4; ++m) _Pragma("unroll") for (int n = 0; n < 2; ++n) _Pragma("unroll") for (int k = 0; k < 2; ++k) \
;         acc[ai][bj][m][n] = __builtin_amdgcn_mfma_f32_16x16x32_bf16(Bt[n][k], At[m][k], acc[ai][bj][m][n], 0, 0, 0); __builtin_amdgcn_s_setprio(0); } while (0)
; #define PG8_WAIT_V(n) asm volatile("s_waitcnt vmcnt(" #n ")" ::: "memory")
; #define PG8_WAIT_L(n) asm volatile("s_waitcnt lgkmcnt(" #n ")" ::: "memory")
; #define PG8_BAR __builtin_amdgcn_s_barrier()
; #define PG8_SCHED __builtin_amdgcn_sched_barrier(0)
; template <class Epi, class Sched, bool ALIGN_EPI = false, bool SP2 = false>
; __device__ __forceinline__ void gemm_phase(PG8_LAS unsigned char* lds, const Gemm g, const Sched& S, const Epi& E) {
;     ...
;             PG8_LDA(At, 1, 1); PG8_STAGE(PG8_SB(1, 0), b3, voffB); PG8_STAGE(PG8_SB(1, 1), b3 + hstep, voffB); PG8_STAGE(PG8_SA(1, 0), a3, voffA);
;             PG8_WAIT_V(8); PG8_WAIT_L(0); PG8_BAR; PG8_MMA(1, 0, At, B0); PG8_MMA(1, 1, At, B1); PG8_BAR; PG8_SCHED;
	s_add_i32 s78, s84, s31
	v_lshl_add_u64 v[216:217], v[216:217], 0, s[22:23]
	s_mov_b32 m0, s78
	ds_read_b128 v[180:183], v242 offset:49152
	ds_read_b128 v[184:187], v242 offset:50176
	ds_read_b128 v[188:191], v242 offset:51200
	ds_read_b128 v[196:199], v242 offset:52224
	ds_read_b128 v[200:203], v242 offset:53248
	ds_read_b128 v[204:207], v242 offset:54272
	ds_read_b128 v[208:211], v242 offset:55296
	ds_read_b128 v[212:215], v242 offset:56320
	global_load_lds_dwordx4 v[216:217], off
	v_lshl_add_u64 v[216:217], v[218:219], 0, s[22:23]
	s_add_i32 m0, s78, 0x2000
	s_add_i32 s78, vcc_lo, s31
	global_load_lds_dwordx4 v[216:217], off
	v_lshl_add_u64 v[216:217], v[220:221], 0, s[22:23]
	s_mov_b32 m0, s78
	s_nop 0
	global_load_lds_dwordx4 v[216:217], off
	v_lshl_add_u64 v[216:217], v[222:223], 0, s[22:23]
	s_add_i32 m0, s78, 0x2000
	s_nop 0
	global_load_lds_dwordx4 v[216:217], off
	v_lshl_add_u64 v[216:217], v[224:225], 0, s[22:23]
	s_mov_b32 m0, s67
	s_nop 0
	global_load_lds_dwordx4 v[216:217], off
	v_lshl_add_u64 v[216:217], v[226:227], 0, s[22:23]
	s_mov_b32 m0, s70
	s_nop 0
	global_load_lds_dwordx4 v[216:217], off
	s_waitcnt vmcnt(8)
	s_waitcnt lgkmcnt(0)
	s_barrier
	s_setprio 1
	s_waitcnt lgkmcnt(0)
	v_mfma_f32_16x16x32_bf16 v[60:63], v[116:119], v[180:183], v[60:63]
	v_mfma_f32_16x16x32_bf16 v[56:59], v[128:131], v[180:183], v[56:59]
	v_mfma_f32_16x16x32_bf16 v[44:47], v[116:119], v[188:191], v[44:47]
	v_mfma_f32_16x16x32_bf16 v[40:43], v[128:131], v[188:191], v[40:43]
	v_mfma_f32_16x16x32_bf16 v[28:31], v[116:119], v[200:203], v[28:31]
	v_mfma_f32_16x16x32_bf16 v[24:27], v[128:131], v[200:203], v[24:27]
	v_mfma_f32_16x16x32_bf16 v[12:15], v[116:119], v[208:211], v[12:15]
	v_mfma_f32_16x16x32_bf16 v[8:11], v[128:131], v[208:211], v[8:11]
	v_mfma_f32_16x16x32_bf16 v[60:63], v[124:127], v[184:187], v[60:63]
	v_mfma_f32_16x16x32_bf16 v[56:59], v[132:135], v[184:187], v[56:59]
	v_mfma_f32_16x16x32_bf16 v[44:47], v[124:127], v[196:199], v[44:47]
	v_mfma_f32_16x16x32_bf16 v[40:43], v[132:135], v[196:199], v[40:43]
	v_mfma_f32_16x16x32_bf16 v[28:31], v[124:127], v[204:207], v[28:31]
	v_mfma_f32_16x16x32_bf16 v[24:27], v[132:135], v[204:207], v[24:27]
	v_mfma_f32_16x16x32_bf16 v[12:15], v[124:127], v[212:215], v[12:15]
	v_mfma_f32_16x16x32_bf16 v[8:11], v[132:135], v[212:215], v[8:11]
	s_setprio 0
	s_setprio 1
	v_mfma_f32_16x16x32_bf16 v[52:55], v[136:139], v[180:183], v[52:55]
	v_mfma_f32_16x16x32_bf16 v[48:51], v[152:155], v[180:183], v[48:51]
	v_mfma_f32_16x16x32_bf16 v[36:39], v[136:139], v[188:191], v[36:39]
	v_mfma_f32_16x16x32_bf16 v[32:35], v[152:155], v[188:191], v[32:35]
	v_mfma_f32_16x16x32_bf16 v[20:23], v[136:139], v[200:203], v[20:23]
	v_mfma_f32_16x16x32_bf16 v[16:19], v[152:155], v[200:203], v[16:19]
	v_mfma_f32_16x16x32_bf16 v[4:7], v[136:139], v[208:211], v[4:7]
	v_mfma_f32_16x16x32_bf16 v[0:3], v[152:155], v[208:211], v[0:3]
	v_mfma_f32_16x16x32_bf16 v[52:55], v[148:151], v[184:187], v[52:55]
	v_mfma_f32_16x16x32_bf16 v[48:51], v[176:179], v[184:187], v[48:51]
	v_mfma_f32_16x16x32_bf16 v[36:39], v[148:151], v[196:199], v[36:39]
	v_mfma_f32_16x16x32_bf16 v[32:35], v[176:179], v[196:199], v[32:35]
	v_mfma_f32_16x16x32_bf16 v[20:23], v[148:151], v[204:207], v[20:23]
	v_mfma_f32_16x16x32_bf16 v[16:19], v[176:179], v[204:207], v[16:19]
	v_mfma_f32_16x16x32_bf16 v[4:7], v[148:151], v[212:215], v[4:7]
	v_mfma_f32_16x16x32_bf16 v[0:3], v[176:179], v[212:215], v[0:3]
	s_setprio 0
	s_barrier
	s_add_u32 s38, s38, 0x100
	s_addc_u32 s39, s39, 0
	s_add_u32 s37, s37, 0x100
	s_addc_u32 s95, s95, 0
	s_cmp_ge_i32 s96, s80
	s_mov_b32 s78, s96
	s_cbranch_scc0 .LBB0_1754

; #define PG8_STAGE(bufoff, gbase, voff) do { _Pragma("unroll") for (int _i = 0; _i < 2; ++_i) \
;         __builtin_amdgcn_global_load_lds((const unsigned*)((const char*)(gbase) + (voff)[_i]), (PG8_LAS unsigned*)(lds + (bufoff) + ldsw + _i * 8192), 16, 0, 0); } while (0)
; #define PG8_LDA(dst, b, h) do { _Pragma("unroll") for (int m = 0; m < 4; ++m) _Pragma("unroll") for (int k = 0; k < 2; ++k) dst[m][k] = *(const PG8_LAS bf16x8*)(lds + PG8_SA(b, h) + aoff + m * 2048 + k * 1024); } while (0)
; #define PG8_LDB(dst, b, h) do { _Pragma("unroll") for (int n = 0; n < 2; ++n) _Pragma("unroll") for (int k = 0; k < 2; ++k) dst[n][k] = *(const PG8_LAS bf16x8*)(lds + PG8_SB(b, h) + boff + n * 2048 + k * 1024); } while (0)
; #define PG8_MMA(ai, bj, At, Bt) do { __builtin_amdgcn_s_setprio(1); _Pragma("unroll") for (int m = 0; m < 4; ++m) _Pragma("unroll") for (int n = 0; n < 2; ++n) _Pragma("unroll") for (int k = 0; k < 2; ++k) \
;         acc[ai][bj][m][n] = __builtin_amdgcn_mfma_f32_16x16x32_bf16(Bt[n][k], At[m][k], acc[ai][bj][m][n], 0, 0, 0); __builtin_amdgcn_s_setprio(0); } while (0)
; #define PG8_WAIT_V(n) asm volatile("s_waitcnt vmcnt(" #n ")" ::: "memory")
; #define PG8_BAR __builtin_amdgcn_s_barrier()
; template <class Epi, class Sched, bool ALIGN_EPI = false, bool SP2 = false>
; __device__ __forceinline__ void gemm_phase(PG8_LAS unsigned char* lds, const Gemm g, const Sched& S, const Epi& E) {
;     ...
;         for (int t = 0; t < nt; t += 2) {
;             const bool last = (t == nt - 2);
;             const char* a1 = cA + (size_t)(t + 1) * kstep;
;             const char* a2 = last ? nA : cA + (size_t)(t + 2) * kstep; const char* b2 = last ? nB : cB + (size_t)(t + 2) * kstep;
;             const char* a3 = a2 + kstep; const char* b3 = b2 + kstep;
;             if (last && has_next) S.a_ready(nxt);
;             if constexpr (SP2) {
;             PG8_LDB(B0, 0, 0); PG8_LDB(B1, 0, 1); PG8_SCHED; PG8_LDA(At, 0, 0); PG8_STAGE(PG8_SA(1, 1), a1 + hstep, voffA);
;             PG8_WAIT_V(8); PG8_WAIT_L(0); PG8_BAR; PG8_MMA(0, 0, At, B0); PG8_MMA(0, 1, At, B1); PG8_BAR; PG8_SCHED;
;             PG8_LDA(At, 0, 1); PG8_STAGE(PG8_SB(0, 0), b2, voffB); PG8_STAGE(PG8_SB(0, 1), b2 + hstep, voffB); PG8_STAGE(PG8_SA(0, 0), a2, voffA);
;             PG8_WAIT_V(8); PG8_WAIT_L(0); PG8_BAR; PG8_MMA(1, 0, At, B0); PG8_MMA(1, 1, At, B1); PG8_BAR; PG8_SCHED;
.LBB0_1854:
	s_sleep 2
	ds_read_b128 v[120:123], v231
	ds_read_b128 v[124:127], v231 offset:1024
	ds_read_b128 v[136:139], v231 offset:2048
	ds_read_b128 v[140:143], v231 offset:3072
	ds_read_b128 v[144:147], v237
	ds_read_b128 v[148:151], v237 offset:1024
	ds_read_b128 v[152:155], v237 offset:2048
	ds_read_b128 v[156:159], v237 offset:3072
	s_add_i32 s96, s38, 2
	s_add_u32 vcc_lo, s36, 0x80
	s_addc_u32 s39, s37, 0
	s_cmp_eq_u32 s88, s38
	s_cselect_b32 s38, s6, vcc_lo
	s_cselect_b32 s39, s7, s39
	s_cselect_b32 vcc_hi, s31, s95
	s_cselect_b32 vcc_lo, s30, s35
	v_lshl_add_u64 v[214:215], s[36:37], 0, v[208:209]
	s_add_i32 m0, s80, 0xc000
	ds_read_b128 v[160:163], v240
	ds_read_b128 v[164:167], v240 offset:1024
	ds_read_b128 v[168:171], v240 offset:2048
	ds_read_b128 v[172:175], v240 offset:3072
	ds_read_b128 v[176:179], v240 offset:4096
	ds_read_b128 v[180:183], v240 offset:5120
	ds_read_b128 v[184:187], v240 offset:6144
	ds_read_b128 v[188:191], v240 offset:7168
	global_load_lds_dwordx4 v[214:215], off
	v_lshl_add_u64 v[214:215], s[36:37], 0, v[210:211]
	s_add_i32 m0, s80, 0xe000
	s_nop 0
	global_load_lds_dwordx4 v[214:215], off
	s_waitcnt vmcnt(8)
	s_waitcnt lgkmcnt(0)
	s_barrier
	s_setprio 1
	s_waitcnt lgkmcnt(0)
	v_mfma_f32_16x16x32_bf16 v[132:135], v[120:123], v[160:163], v[132:135]
	v_mfma_f32_16x16x32_bf16 v[128:131], v[136:139], v[160:163], v[128:131]
	v_mfma_f32_16x16x32_bf16 v[108:111], v[120:123], v[168:171], v[108:111]
	v_mfma_f32_16x16x32_bf16 v[104:107], v[136:139], v[168:171], v[104:107]
	v_mfma_f32_16x16x32_bf16 v[92:95], v[120:123], v[176:179], v[92:95]
	v_mfma_f32_16x16x32_bf16 v[88:91], v[136:139], v[176:179], v[88:91]
	v_mfma_f32_16x16x32_bf16 v[76:79], v[120:123], v[184:187], v[76:79]
	v_mfma_f32_16x16x32_bf16 v[72:75], v[136:139], v[184:187], v[72:75]
	v_mfma_f32_16x16x32_bf16 v[132:135], v[124:127], v[164:167], v[132:135]
	v_mfma_f32_16x16x32_bf16 v[128:131], v[140:143], v[164:167], v[128:131]
	v_mfma_f32_16x16x32_bf16 v[108:111], v[124:127], v[172:175], v[108:111]
	v_mfma_f32_16x16x32_bf16 v[104:107], v[140:143], v[172:175], v[104:107]
	v_mfma_f32_16x16x32_bf16 v[92:95], v[124:127], v[180:183], v[92:95]
	v_mfma_f32_16x16x32_bf16 v[88:91], v[140:143], v[180:183], v[88:91]
	v_mfma_f32_16x16x32_bf16 v[76:79], v[124:127], v[188:191], v[76:79]
	v_mfma_f32_16x16x32_bf16 v[72:75], v[140:143], v[188:191], v[72:75]
	s_setprio 0
	s_setprio 1
	v_mfma_f32_16x16x32_bf16 v[116:119], v[144:147], v[160:163], v[116:119]
	v_mfma_f32_16x16x32_bf16 v[112:115], v[152:155], v[160:163], v[112:115]
	v_mfma_f32_16x16x32_bf16 v[100:103], v[144:147], v[168:171], v[100:103]
	v_mfma_f32_16x16x32_bf16 v[96:99], v[152:155], v[168:171], v[96:99]
	v_mfma_f32_16x16x32_bf16 v[84:87], v[144:147], v[176:179], v[84:87]
	v_mfma_f32_16x16x32_bf16 v[80:83], v[152:155], v[176:179], v[80:83]
	v_mfma_f32_16x16x32_bf16 v[68:71], v[144:147], v[184:187], v[68:71]
	v_mfma_f32_16x16x32_bf16 v[64:67], v[152:155], v[184:187], v[64:67]
	v_mfma_f32_16x16x32_bf16 v[116:119], v[148:151], v[164:167], v[116:119]
	v_mfma_f32_16x16x32_bf16 v[112:115], v[156:159], v[164:167], v[112:115]
	v_mfma_f32_16x16x32_bf16 v[100:103], v[148:151], v[172:175], v[100:103]
	v_mfma_f32_16x16x32_bf16 v[96:99], v[156:159], v[172:175], v[96:99]
	v_mfma_f32_16x16x32_bf16 v[84:87], v[148:151], v[180:183], v[84:87]
	v_mfma_f32_16x16x32_bf16 v[80:83], v[156:159], v[180:183], v[80:83]
	v_mfma_f32_16x16x32_bf16 v[68:71], v[148:151], v[188:191], v[68:71]
	v_mfma_f32_16x16x32_bf16 v[64:67], v[156:159], v[188:191], v[64:67]
	s_setprio 0
	s_barrier
	s_add_i32 s46, s89, s71
	v_lshl_add_u64 v[214:215], vcc, 0, v[198:199]
	s_mov_b32 m0, s46
	ds_read_b128 v[160:163], v240 offset:16384
	ds_read_b128 v[164:167], v240 offset:17408
	ds_read_b128 v[168:171], v240 offset:18432
	ds_read_b128 v[172:175], v240 offset:19456
	ds_read_b128 v[176:179], v240 offset:20480
	ds_read_b128 v[180:183], v240 offset:21504
	ds_read_b128 v[184:187], v240 offset:22528
	ds_read_b128 v[188:191], v240 offset:23552
	global_load_lds_dwordx4 v[214:215], off
	s_add_i32 m0, s46, 0x2000
	v_lshl_add_u64 v[216:217], vcc, 0, v[202:203]
	s_add_u32 vcc_lo, vcc_lo, s10
	s_addc_u32 vcc_hi, vcc_hi, s11
	s_add_i32 s46, s90, s71
	global_load_lds_dwordx4 v[216:217], off
	v_lshl_add_u64 v[218:219], vcc, 0, v[198:199]
	s_mov_b32 m0, s46
	v_lshl_add_u64 v[220:221], vcc, 0, v[202:203]
	global_load_lds_dwordx4 v[218:219], off
	s_add_i32 m0, s46, 0x2000
	v_lshl_add_u64 v[222:223], s[38:39], 0, v[196:197]
	global_load_lds_dwordx4 v[220:221], off
	s_mov_b32 m0, s80
	v_lshl_add_u64 v[224:225], s[38:39], 0, v[200:201]
	global_load_lds_dwordx4 v[222:223], off
	s_mov_b32 m0, s81
	s_nop 0
	global_load_lds_dwordx4 v[224:225], off
	s_waitcnt vmcnt(8)
	s_waitcnt lgkmcnt(0)
	s_barrier
; #define PG8_STAGE(bufoff, gbase, voff) do { _Pragma("unroll") for (int _i = 0; _i < 2; ++_i) \
;         __builtin_amdgcn_global_load_lds((const unsigned*)((const char*)(gbase) + (voff)[_i]), (PG8_LAS unsigned*)(lds + (bufoff) + ldsw + _i * 8192), 16, 0, 0); } while (0)
; #define PG8_LDA(dst, b, h) do { _Pragma("unroll") for (int m = 0; m < 4; ++m) _Pragma("unroll") for (int k = 0; k < 2; ++k) dst[m][k] = *(const PG8_LAS bf16x8*)(lds + PG8_SA(b, h) + aoff + m * 2048 + k * 1024); } while (0)
; #define PG8_LDB(dst, b, h) do { _Pragma("unroll") for (int n = 0; n < 2; ++n) _Pragma("unroll") for (int k = 0; k < 2; ++k) dst[n][k] = *(const PG8_LAS bf16x8*)(lds + PG8_SB(b, h) + boff + n * 2048 + k * 1024); } while (0)
; #define PG8_MMA(ai, bj, At, Bt) do { __builtin_amdgcn_s_setprio(1); _Pragma("unroll") for (int m = 0; m < 4; ++m) _Pragma("unroll") for (int n = 0; n < 2; ++n) _Pragma("unroll") for (int k = 0; k < 2; ++k) \
;         acc[ai][bj][m][n] = __builtin_amdgcn_mfma_f32_16x16x32_bf16(Bt[n][k], At[m][k], acc[ai][bj][m][n], 0, 0, 0); __builtin_amdgcn_s_setprio(0); } while (0)
; #define PG8_WAIT_V(n) asm volatile("s_waitcnt vmcnt(" #n ")" ::: "memory")
; #define PG8_WAIT_L(n) asm volatile("s_waitcnt lgkmcnt(" #n ")" ::: "memory")
; #define PG8_BAR __builtin_amdgcn_s_barrier()
; #define PG8_SCHED __builtin_amdgcn_sched_barrier(0)
; template <class Epi, class Sched, bool ALIGN_EPI = false, bool SP2 = false>
; __device__ __forceinline__ void gemm_phase(PG8_LAS unsigned char* lds, const Gemm g, const Sched& S, const Epi& E) {
;     ...
;             PG8_WAIT_V(8); PG8_WAIT_L(0); PG8_BAR; PG8_MMA(1, 0, At, B0); PG8_MMA(1, 1, At, B1); PG8_BAR; PG8_SCHED;
;             PG8_LDB(B0, 1, 0); PG8_LDB(B1, 1, 1); PG8_SCHED; PG8_LDA(At, 1, 0); PG8_STAGE(PG8_SA(0, 1), a2 + hstep, voffA);
;             PG8_WAIT_V(8); PG8_WAIT_L(0); PG8_BAR; PG8_MMA(0, 0, At, B0); PG8_MMA(0, 1, At, B1); PG8_BAR; PG8_SCHED;
	s_setprio 1
	s_waitcnt lgkmcnt(0)
	v_mfma_f32_16x16x32_bf16 v[60:63], v[120:123], v[160:163], v[60:63]
	v_mfma_f32_16x16x32_bf16 v[56:59], v[136:139], v[160:163], v[56:59]
	v_mfma_f32_16x16x32_bf16 v[44:47], v[120:123], v[168:171], v[44:47]
	v_mfma_f32_16x16x32_bf16 v[40:43], v[136:139], v[168:171], v[40:43]
	v_mfma_f32_16x16x32_bf16 v[28:31], v[120:123], v[176:179], v[28:31]
	v_mfma_f32_16x16x32_bf16 v[24:27], v[136:139], v[176:179], v[24:27]
	v_mfma_f32_16x16x32_bf16 v[12:15], v[120:123], v[184:187], v[12:15]
	v_mfma_f32_16x16x32_bf16 v[8:11], v[136:139], v[184:187], v[8:11]
	v_mfma_f32_16x16x32_bf16 v[60:63], v[124:127], v[164:167], v[60:63]
	v_mfma_f32_16x16x32_bf16 v[56:59], v[140:143], v[164:167], v[56:59]
	v_mfma_f32_16x16x32_bf16 v[44:47], v[124:127], v[172:175], v[44:47]
	v_mfma_f32_16x16x32_bf16 v[40:43], v[140:143], v[172:175], v[40:43]
	v_mfma_f32_16x16x32_bf16 v[28:31], v[124:127], v[180:183], v[28:31]
	v_mfma_f32_16x16x32_bf16 v[24:27], v[140:143], v[180:183], v[24:27]
	v_mfma_f32_16x16x32_bf16 v[12:15], v[124:127], v[188:191], v[12:15]
	v_mfma_f32_16x16x32_bf16 v[8:11], v[140:143], v[188:191], v[8:11]
	s_setprio 0
	s_setprio 1
	v_mfma_f32_16x16x32_bf16 v[52:55], v[144:147], v[160:163], v[52:55]
	v_mfma_f32_16x16x32_bf16 v[48:51], v[152:155], v[160:163], v[48:51]
	v_mfma_f32_16x16x32_bf16 v[36:39], v[144:147], v[168:171], v[36:39]
	v_mfma_f32_16x16x32_bf16 v[32:35], v[152:155], v[168:171], v[32:35]
	v_mfma_f32_16x16x32_bf16 v[20:23], v[144:147], v[176:179], v[20:23]
	v_mfma_f32_16x16x32_bf16 v[16:19], v[152:155], v[176:179], v[16:19]
	v_mfma_f32_16x16x32_bf16 v[4:7], v[144:147], v[184:187], v[4:7]
	v_mfma_f32_16x16x32_bf16 v[0:3], v[152:155], v[184:187], v[0:3]
	v_mfma_f32_16x16x32_bf16 v[52:55], v[148:151], v[164:167], v[52:55]
	v_mfma_f32_16x16x32_bf16 v[48:51], v[156:159], v[164:167], v[48:51]
	v_mfma_f32_16x16x32_bf16 v[36:39], v[148:151], v[172:175], v[36:39]
	v_mfma_f32_16x16x32_bf16 v[32:35], v[156:159], v[172:175], v[32:35]
	v_mfma_f32_16x16x32_bf16 v[20:23], v[148:151], v[180:183], v[20:23]
	v_mfma_f32_16x16x32_bf16 v[16:19], v[156:159], v[180:183], v[16:19]
	v_mfma_f32_16x16x32_bf16 v[4:7], v[148:151], v[188:191], v[4:7]
	v_mfma_f32_16x16x32_bf16 v[0:3], v[156:159], v[188:191], v[0:3]
	s_setprio 0
	s_barrier
	s_add_i32 s46, 0, 0x18000
	s_add_i32 vcc_lo, 0, 0x1c000
	v_add_u32_e32 v140, s46, v193
	v_add_u32_e32 v156, vcc_lo, v193
	ds_read_b128 v[120:123], v140
	ds_read_b128 v[124:127], v140 offset:1024
	ds_read_b128 v[136:139], v140 offset:2048
	ds_read_b128 v[140:143], v140 offset:3072
	ds_read_b128 v[144:147], v156
	ds_read_b128 v[148:151], v156 offset:1024
	ds_read_b128 v[152:155], v156 offset:2048
	ds_read_b128 v[156:159], v156 offset:3072
	s_add_u32 s38, s38, s10
	s_addc_u32 s39, s39, s11
	s_mov_b32 m0, s82
	v_lshl_add_u64 v[226:227], s[38:39], 0, v[196:197]
	ds_read_b128 v[160:163], v240 offset:32768
	ds_read_b128 v[164:167], v240 offset:33792
	ds_read_b128 v[168:171], v240 offset:34816
	ds_read_b128 v[172:175], v240 offset:35840
	ds_read_b128 v[176:179], v240 offset:36864
	ds_read_b128 v[180:183], v240 offset:37888
	ds_read_b128 v[184:187], v240 offset:38912
	ds_read_b128 v[188:191], v240 offset:39936
	global_load_lds_dwordx4 v[226:227], off
	v_lshl_add_u64 v[226:227], s[38:39], 0, v[200:201]
	s_mov_b32 m0, s83
	s_nop 0
	global_load_lds_dwordx4 v[226:227], off
	s_waitcnt vmcnt(8)
	s_waitcnt lgkmcnt(0)
	s_barrier
	s_setprio 1
	s_waitcnt lgkmcnt(0)
	v_mfma_f32_16x16x32_bf16 v[132:135], v[120:123], v[160:163], v[132:135]
	v_mfma_f32_16x16x32_bf16 v[128:131], v[136:139], v[160:163], v[128:131]
	v_mfma_f32_16x16x32_bf16 v[108:111], v[120:123], v[168:171], v[108:111]
	v_mfma_f32_16x16x32_bf16 v[104:107], v[136:139], v[168:171], v[104:107]
	v_mfma_f32_16x16x32_bf16 v[92:95], v[120:123], v[176:179], v[92:95]
	v_mfma_f32_16x16x32_bf16 v[88:91], v[136:139], v[176:179], v[88:91]
	v_mfma_f32_16x16x32_bf16 v[76:79], v[120:123], v[184:187], v[76:79]
	v_mfma_f32_16x16x32_bf16 v[72:75], v[136:139], v[184:187], v[72:75]
	v_mfma_f32_16x16x32_bf16 v[132:135], v[124:127], v[164:167], v[132:135]
	v_mfma_f32_16x16x32_bf16 v[128:131], v[140:143], v[164:167], v[128:131]
	v_mfma_f32_16x16x32_bf16 v[108:111], v[124:127], v[172:175], v[108:111]
	v_mfma_f32_16x16x32_bf16 v[104:107], v[140:143], v[172:175], v[104:107]
	v_mfma_f32_16x16x32_bf16 v[92:95], v[124:127], v[180:183], v[92:95]
	v_mfma_f32_16x16x32_bf16 v[88:91], v[140:143], v[180:183], v[88:91]
	v_mfma_f32_16x16x32_bf16 v[76:79], v[124:127], v[188:191], v[76:79]
	v_mfma_f32_16x16x32_bf16 v[72:75], v[140:143], v[188:191], v[72:75]
	s_setprio 0
	s_setprio 1
	v_mfma_f32_16x16x32_bf16 v[116:119], v[144:147], v[160:163], v[116:119]
	v_mfma_f32_16x16x32_bf16 v[112:115], v[152:155], v[160:163], v[112:115]
	v_mfma_f32_16x16x32_bf16 v[100:103], v[144:147], v[168:171], v[100:103]
	v_mfma_f32_16x16x32_bf16 v[96:99], v[152:155], v[168:171], v[96:99]
	v_mfma_f32_16x16x32_bf16 v[84:87], v[144:147], v[176:179], v[84:87]
	v_mfma_f32_16x16x32_bf16 v[80:83], v[152:155], v[176:179], v[80:83]
	v_mfma_f32_16x16x32_bf16 v[68:71], v[144:147], v[184:187], v[68:71]
	v_mfma_f32_16x16x32_bf16 v[64:67], v[152:155], v[184:187], v[64:67]
	v_mfma_f32_16x16x32_bf16 v[116:119], v[148:151], v[164:167], v[116:119]
	v_mfma_f32_16x16x32_bf16 v[112:115], v[156:159], v[164:167], v[112:115]
	v_mfma_f32_16x16x32_bf16 v[100:103], v[148:151], v[172:175], v[100:103]
	v_mfma_f32_16x16x32_bf16 v[96:99], v[156:159], v[172:175], v[96:99]
	v_mfma_f32_16x16x32_bf16 v[84:87], v[148:151], v[180:183], v[84:87]
	v_mfma_f32_16x16x32_bf16 v[80:83], v[156:159], v[180:183], v[80:83]
	v_mfma_f32_16x16x32_bf16 v[68:71], v[148:151], v[188:191], v[68:71]
	v_mfma_f32_16x16x32_bf16 v[64:67], v[156:159], v[188:191], v[64:67]
	s_setprio 0
	s_barrier
; #define PG8_STAGE(bufoff, gbase, voff) do { _Pragma("unroll") for (int _i = 0; _i < 2; ++_i) \
;         __builtin_amdgcn_global_load_lds((const unsigned*)((const char*)(gbase) + (voff)[_i]), (PG8_LAS unsigned*)(lds + (bufoff) + ldsw + _i * 8192), 16, 0, 0); } while (0)
; #define PG8_LDA(dst, b, h) do { _Pragma("unroll") for (int m = 0; m < 4; ++m) _Pragma("unroll") for (int k = 0; k < 2; ++k) dst[m][k] = *(const PG8_LAS bf16x8*)(lds + PG8_SA(b, h) + aoff + m * 2048 + k * 1024); } while (0)
; #define PG8_MMA(ai, bj, At, Bt) do { __builtin_amdgcn_s_setprio(1); _Pragma("unroll") for (int m = 0; m < 4; ++m) _Pragma("unroll") for (int n = 0; n < 2; ++n) _Pragma("unroll") for (int k = 0; k < 2; ++k) \
;         acc[ai][bj][m][n] = __builtin_amdgcn_mfma_f32_16x16x32_bf16(Bt[n][k], At[m][k], acc[ai][bj][m][n], 0, 0, 0); __builtin_amdgcn_s_setprio(0); } while (0)
; #define PG8_WAIT_V(n) asm volatile("s_waitcnt vmcnt(" #n ")" ::: "memory")
; #define PG8_WAIT_L(n) asm volatile("s_waitcnt lgkmcnt(" #n ")" ::: "memory")
; #define PG8_BAR __builtin_amdgcn_s_barrier()
; #define PG8_SCHED __builtin_amdgcn_sched_barrier(0)
; template <class Epi, class Sched, bool ALIGN_EPI = false, bool SP2 = false>
; __device__ __forceinline__ void gemm_phase(PG8_LAS unsigned char* lds, const Gemm g, const Sched& S, const Epi& E) {
;     ...
;             PG8_LDA(At, 1, 1); PG8_STAGE(PG8_SB(1, 0), b3, voffB); PG8_STAGE(PG8_SB(1, 1), b3 + hstep, voffB); PG8_STAGE(PG8_SA(1, 0), a3, voffA);
;             PG8_WAIT_V(8); PG8_WAIT_L(0); PG8_BAR; PG8_MMA(1, 0, At, B0); PG8_MMA(1, 1, At, B1); PG8_BAR; PG8_SCHED;
	s_add_i32 s38, s46, s71
	v_lshl_add_u64 v[214:215], v[214:215], 0, s[22:23]
	s_mov_b32 m0, s38
	ds_read_b128 v[160:163], v240 offset:49152
	ds_read_b128 v[164:167], v240 offset:50176
	ds_read_b128 v[168:171], v240 offset:51200
	ds_read_b128 v[172:175], v240 offset:52224
	ds_read_b128 v[176:179], v240 offset:53248
	ds_read_b128 v[180:183], v240 offset:54272
	ds_read_b128 v[184:187], v240 offset:55296
	ds_read_b128 v[188:191], v240 offset:56320
	global_load_lds_dwordx4 v[214:215], off
	v_lshl_add_u64 v[214:215], v[216:217], 0, s[22:23]
	s_add_i32 m0, s38, 0x2000
	s_add_i32 s38, vcc_lo, s71
	global_load_lds_dwordx4 v[214:215], off
	v_lshl_add_u64 v[214:215], v[218:219], 0, s[22:23]
	s_mov_b32 m0, s38
	s_nop 0
	global_load_lds_dwordx4 v[214:215], off
	v_lshl_add_u64 v[214:215], v[220:221], 0, s[22:23]
	s_add_i32 m0, s38, 0x2000
	s_nop 0
	global_load_lds_dwordx4 v[214:215], off
	v_lshl_add_u64 v[214:215], v[222:223], 0, s[22:23]
	s_mov_b32 m0, s85
	s_nop 0
	global_load_lds_dwordx4 v[214:215], off
	v_lshl_add_u64 v[214:215], v[224:225], 0, s[22:23]
	s_mov_b32 m0, s86
	s_nop 0
	global_load_lds_dwordx4 v[214:215], off
	s_waitcnt vmcnt(8)
	s_waitcnt lgkmcnt(0)
	s_barrier
	s_setprio 1
	s_waitcnt lgkmcnt(0)
	v_mfma_f32_16x16x32_bf16 v[60:63], v[120:123], v[160:163], v[60:63]
	v_mfma_f32_16x16x32_bf16 v[56:59], v[136:139], v[160:163], v[56:59]
	v_mfma_f32_16x16x32_bf16 v[44:47], v[120:123], v[168:171], v[44:47]
	v_mfma_f32_16x16x32_bf16 v[40:43], v[136:139], v[168:171], v[40:43]
	v_mfma_f32_16x16x32_bf16 v[28:31], v[120:123], v[176:179], v[28:31]
	v_mfma_f32_16x16x32_bf16 v[24:27], v[136:139], v[176:179], v[24:27]
	v_mfma_f32_16x16x32_bf16 v[12:15], v[120:123], v[184:187], v[12:15]
	v_mfma_f32_16x16x32_bf16 v[8:11], v[136:139], v[184:187], v[8:11]
	v_mfma_f32_16x16x32_bf16 v[60:63], v[124:127], v[164:167], v[60:63]
	v_mfma_f32_16x16x32_bf16 v[56:59], v[140:143], v[164:167], v[56:59]
	v_mfma_f32_16x16x32_bf16 v[44:47], v[124:127], v[172:175], v[44:47]
	v_mfma_f32_16x16x32_bf16 v[40:43], v[140:143], v[172:175], v[40:43]
	v_mfma_f32_16x16x32_bf16 v[28:31], v[124:127], v[180:183], v[28:31]
	v_mfma_f32_16x16x32_bf16 v[24:27], v[140:143], v[180:183], v[24:27]
	v_mfma_f32_16x16x32_bf16 v[12:15], v[124:127], v[188:191], v[12:15]
	v_mfma_f32_16x16x32_bf16 v[8:11], v[140:143], v[188:191], v[8:11]
	s_setprio 0
	s_setprio 1
	v_mfma_f32_16x16x32_bf16 v[52:55], v[144:147], v[160:163], v[52:55]
	v_mfma_f32_16x16x32_bf16 v[48:51], v[152:155], v[160:163], v[48:51]
	v_mfma_f32_16x16x32_bf16 v[36:39], v[144:147], v[168:171], v[36:39]
	v_mfma_f32_16x16x32_bf16 v[32:35], v[152:155], v[168:171], v[32:35]
	v_mfma_f32_16x16x32_bf16 v[20:23], v[144:147], v[176:179], v[20:23]
	v_mfma_f32_16x16x32_bf16 v[16:19], v[152:155], v[176:179], v[16:19]
	v_mfma_f32_16x16x32_bf16 v[4:7], v[144:147], v[184:187], v[4:7]
	v_mfma_f32_16x16x32_bf16 v[0:3], v[152:155], v[184:187], v[0:3]
	v_mfma_f32_16x16x32_bf16 v[52:55], v[148:151], v[164:167], v[52:55]
	v_mfma_f32_16x16x32_bf16 v[48:51], v[156:159], v[164:167], v[48:51]
	v_mfma_f32_16x16x32_bf16 v[36:39], v[148:151], v[172:175], v[36:39]
	v_mfma_f32_16x16x32_bf16 v[32:35], v[156:159], v[172:175], v[32:35]
	v_mfma_f32_16x16x32_bf16 v[20:23], v[148:151], v[180:183], v[20:23]
	v_mfma_f32_16x16x32_bf16 v[16:19], v[156:159], v[180:183], v[16:19]
	v_mfma_f32_16x16x32_bf16 v[4:7], v[148:151], v[188:191], v[4:7]
	v_mfma_f32_16x16x32_bf16 v[0:3], v[156:159], v[188:191], v[0:3]
	s_setprio 0
	s_barrier
	s_add_u32 s36, s36, 0x100
	s_addc_u32 s37, s37, 0
	s_add_u32 s35, s35, 0x100
	s_addc_u32 s95, s95, 0
	s_cmp_ge_i32 s96, s87
	s_mov_b32 s38, s96
	s_cbranch_scc0 .LBB0_1854

; #define PG8_STAGE(bufoff, gbase, voff) do { _Pragma("unroll") for (int _i = 0; _i < 2; ++_i) \
;         __builtin_amdgcn_global_load_lds((const unsigned*)((const char*)(gbase) + (voff)[_i]), (PG8_LAS unsigned*)(lds + (bufoff) + ldsw + _i * 8192), 16, 0, 0); } while (0)
; #define PG8_LDA(dst, b, h) do { _Pragma("unroll") for (int m = 0; m < 4; ++m) _Pragma("unroll") for (int k = 0; k < 2; ++k) dst[m][k] = *(const PG8_LAS bf16x8*)(lds + PG8_SA(b, h) + aoff + m * 2048 + k * 1024); } while (0)
; #define PG8_LDB(dst, b, h) do { _Pragma("unroll") for (int n = 0; n < 2; ++n) _Pragma("unroll") for (int k = 0; k < 2; ++k) dst[n][k] = *(const PG8_LAS bf16x8*)(lds + PG8_SB(b, h) + boff + n * 2048 + k * 1024); } while (0)
; #define PG8_MMA(ai, bj, At, Bt) do { __builtin_amdgcn_s_setprio(1); _Pragma("unroll") for (int m = 0; m < 4; ++m) _Pragma("unroll") for (int n = 0; n < 2; ++n) _Pragma("unroll") for (int k = 0; k < 2; ++k) \
;         acc[ai][bj][m][n] = __builtin_amdgcn_mfma_f32_16x16x32_bf16(Bt[n][k], At[m][k], acc[ai][bj][m][n], 0, 0, 0); __builtin_amdgcn_s_setprio(0); } while (0)
; #define PG8_WAIT_V(n) asm volatile("s_waitcnt vmcnt(" #n ")" ::: "memory")
; #define PG8_BAR __builtin_amdgcn_s_barrier()
; template <class Epi, class Sched, bool ALIGN_EPI = false, bool SP2 = false>
; __device__ __forceinline__ void gemm_phase(PG8_LAS unsigned char* lds, const Gemm g, const Sched& S, const Epi& E) {
;     ...
;         for (int t = 0; t < nt; t += 2) {
;             const bool last = (t == nt - 2);
;             const char* a1 = cA + (size_t)(t + 1) * kstep;
;             const char* a2 = last ? nA : cA + (size_t)(t + 2) * kstep; const char* b2 = last ? nB : cB + (size_t)(t + 2) * kstep;
;             const char* a3 = a2 + kstep; const char* b3 = b2 + kstep;
;             if (last && has_next) S.a_ready(nxt);
;             if constexpr (SP2) {
;             PG8_LDB(B0, 0, 0); PG8_LDB(B1, 0, 1); PG8_SCHED; PG8_LDA(At, 0, 0); PG8_STAGE(PG8_SA(1, 1), a1 + hstep, voffA);
;             PG8_WAIT_V(8); PG8_WAIT_L(0); PG8_BAR; PG8_MMA(0, 0, At, B0); PG8_MMA(0, 1, At, B1); PG8_BAR; PG8_SCHED;
;             PG8_LDA(At, 0, 1); PG8_STAGE(PG8_SB(0, 0), b2, voffB); PG8_STAGE(PG8_SB(0, 1), b2 + hstep, voffB); PG8_STAGE(PG8_SA(0, 0), a2, voffA);
;             PG8_WAIT_V(8); PG8_WAIT_L(0); PG8_BAR; PG8_MMA(1, 0, At, B0); PG8_MMA(1, 1, At, B1); PG8_BAR; PG8_SCHED;
.LBB0_1940:
	s_sleep 2
	ds_read_b128 v[128:131], v163
	ds_read_b128 v[132:135], v163 offset:1024
	ds_read_b128 v[136:139], v163 offset:2048
	ds_read_b128 v[140:143], v163 offset:3072
	ds_read_b128 v[172:175], v193
	ds_read_b128 v[176:179], v193 offset:1024
	ds_read_b128 v[180:183], v193 offset:2048
	ds_read_b128 v[184:187], v193 offset:3072
	s_add_i32 s89, s86, 2
	s_add_u32 s90, s14, 0x80
	s_addc_u32 s87, s15, 0
	s_cmp_eq_u32 s37, s86
	s_cselect_b32 s86, s80, s90
	s_cselect_b32 s87, s81, s87
	s_cselect_b32 s91, s83, s85
	s_cselect_b32 s90, s82, s67
	v_lshl_add_u64 v[220:221], s[14:15], 0, v[166:167]
	s_add_i32 m0, s70, 0xc000
	ds_read_b128 v[188:191], v195
	ds_read_b128 v[196:199], v195 offset:1024
	ds_read_b128 v[200:203], v195 offset:2048
	ds_read_b128 v[204:207], v195 offset:3072
	ds_read_b128 v[208:211], v195 offset:4096
	ds_read_b128 v[212:215], v195 offset:5120
	ds_read_b128 v[216:219], v195 offset:6144
	ds_read_b128 v[224:227], v195 offset:7168
	global_load_lds_dwordx4 v[220:221], off
	v_lshl_add_u64 v[220:221], s[14:15], 0, v[168:169]
	s_add_i32 m0, s70, 0xe000
	s_nop 0
	global_load_lds_dwordx4 v[220:221], off
	s_waitcnt vmcnt(8)
	s_waitcnt lgkmcnt(0)
	s_barrier
	s_setprio 1
	s_waitcnt lgkmcnt(0)
	v_mfma_f32_16x16x32_bf16 v[124:127], v[128:131], v[188:191], v[124:127]
	v_mfma_f32_16x16x32_bf16 v[120:123], v[136:139], v[188:191], v[120:123]
	v_mfma_f32_16x16x32_bf16 v[108:111], v[128:131], v[200:203], v[108:111]
	v_mfma_f32_16x16x32_bf16 v[104:107], v[136:139], v[200:203], v[104:107]
	v_mfma_f32_16x16x32_bf16 v[92:95], v[128:131], v[208:211], v[92:95]
	v_mfma_f32_16x16x32_bf16 v[88:91], v[136:139], v[208:211], v[88:91]
	v_mfma_f32_16x16x32_bf16 v[76:79], v[128:131], v[216:219], v[76:79]
	v_mfma_f32_16x16x32_bf16 v[72:75], v[136:139], v[216:219], v[72:75]
	v_mfma_f32_16x16x32_bf16 v[124:127], v[132:135], v[196:199], v[124:127]
	v_mfma_f32_16x16x32_bf16 v[120:123], v[140:143], v[196:199], v[120:123]
	v_mfma_f32_16x16x32_bf16 v[108:111], v[132:135], v[204:207], v[108:111]
	v_mfma_f32_16x16x32_bf16 v[104:107], v[140:143], v[204:207], v[104:107]
	v_mfma_f32_16x16x32_bf16 v[92:95], v[132:135], v[212:215], v[92:95]
	v_mfma_f32_16x16x32_bf16 v[88:91], v[140:143], v[212:215], v[88:91]
	v_mfma_f32_16x16x32_bf16 v[76:79], v[132:135], v[224:227], v[76:79]
	v_mfma_f32_16x16x32_bf16 v[72:75], v[140:143], v[224:227], v[72:75]
	s_setprio 0
	s_setprio 1
	v_mfma_f32_16x16x32_bf16 v[116:119], v[172:175], v[188:191], v[116:119]
	v_mfma_f32_16x16x32_bf16 v[112:115], v[180:183], v[188:191], v[112:115]
	v_mfma_f32_16x16x32_bf16 v[100:103], v[172:175], v[200:203], v[100:103]
	v_mfma_f32_16x16x32_bf16 v[96:99], v[180:183], v[200:203], v[96:99]
	v_mfma_f32_16x16x32_bf16 v[84:87], v[172:175], v[208:211], v[84:87]
	v_mfma_f32_16x16x32_bf16 v[80:83], v[180:183], v[208:211], v[80:83]
	v_mfma_f32_16x16x32_bf16 v[68:71], v[172:175], v[216:219], v[68:71]
	v_mfma_f32_16x16x32_bf16 v[64:67], v[180:183], v[216:219], v[64:67]
	v_mfma_f32_16x16x32_bf16 v[116:119], v[176:179], v[196:199], v[116:119]
	v_mfma_f32_16x16x32_bf16 v[112:115], v[184:187], v[196:199], v[112:115]
	v_mfma_f32_16x16x32_bf16 v[100:103], v[176:179], v[204:207], v[100:103]
	v_mfma_f32_16x16x32_bf16 v[96:99], v[184:187], v[204:207], v[96:99]
	v_mfma_f32_16x16x32_bf16 v[84:87], v[176:179], v[212:215], v[84:87]
	v_mfma_f32_16x16x32_bf16 v[80:83], v[184:187], v[212:215], v[80:83]
	v_mfma_f32_16x16x32_bf16 v[68:71], v[176:179], v[224:227], v[68:71]
	v_mfma_f32_16x16x32_bf16 v[64:67], v[184:187], v[224:227], v[64:67]
	s_setprio 0
	s_barrier
	s_add_i32 s92, s79, s17
	v_lshl_add_u64 v[220:221], s[90:91], 0, v[146:147]
	s_mov_b32 m0, s92
	ds_read_b128 v[188:191], v195 offset:16384
	ds_read_b128 v[196:199], v195 offset:17408
	ds_read_b128 v[200:203], v195 offset:18432
	ds_read_b128 v[204:207], v195 offset:19456
	ds_read_b128 v[208:211], v195 offset:20480
	ds_read_b128 v[212:215], v195 offset:21504
	ds_read_b128 v[216:219], v195 offset:22528
	ds_read_b128 v[224:227], v195 offset:23552
	global_load_lds_dwordx4 v[220:221], off
	s_add_i32 m0, s92, 0x2000
	v_lshl_add_u64 v[228:229], s[90:91], 0, v[150:151]
	s_add_u32 s90, s90, s20
	s_addc_u32 s91, s91, s21
	s_add_i32 s92, s46, s17
	global_load_lds_dwordx4 v[228:229], off
	v_lshl_add_u64 v[230:231], s[90:91], 0, v[146:147]
	s_mov_b32 m0, s92
	v_lshl_add_u64 v[232:233], s[90:91], 0, v[150:151]
	global_load_lds_dwordx4 v[230:231], off
	s_add_i32 m0, s92, 0x2000
	v_lshl_add_u64 v[234:235], s[86:87], 0, v[144:145]
	global_load_lds_dwordx4 v[232:233], off
	s_mov_b32 m0, s70
	v_lshl_add_u64 v[236:237], s[86:87], 0, v[148:149]
	global_load_lds_dwordx4 v[234:235], off
	s_mov_b32 m0, s71
	s_nop 0
	global_load_lds_dwordx4 v[236:237], off
	s_waitcnt vmcnt(8)
	s_waitcnt lgkmcnt(0)
	s_barrier
; #define PG8_STAGE(bufoff, gbase, voff) do { _Pragma("unroll") for (int _i = 0; _i < 2; ++_i) \
;         __builtin_amdgcn_global_load_lds((const unsigned*)((const char*)(gbase) + (voff)[_i]), (PG8_LAS unsigned*)(lds + (bufoff) + ldsw + _i * 8192), 16, 0, 0); } while (0)
; #define PG8_LDA(dst, b, h) do { _Pragma("unroll") for (int m = 0; m < 4; ++m) _Pragma("unroll") for (int k = 0; k < 2; ++k) dst[m][k] = *(const PG8_LAS bf16x8*)(lds + PG8_SA(b, h) + aoff + m * 2048 + k * 1024); } while (0)
; #define PG8_LDB(dst, b, h) do { _Pragma("unroll") for (int n = 0; n < 2; ++n) _Pragma("unroll") for (int k = 0; k < 2; ++k) dst[n][k] = *(const PG8_LAS bf16x8*)(lds + PG8_SB(b, h) + boff + n * 2048 + k * 1024); } while (0)
; #define PG8_MMA(ai, bj, At, Bt) do { __builtin_amdgcn_s_setprio(1); _Pragma("unroll") for (int m = 0; m < 4; ++m) _Pragma("unroll") for (int n = 0; n < 2; ++n) _Pragma("unroll") for (int k = 0; k < 2; ++k) \
;         acc[ai][bj][m][n] = __builtin_amdgcn_mfma_f32_16x16x32_bf16(Bt[n][k], At[m][k], acc[ai][bj][m][n], 0, 0, 0); __builtin_amdgcn_s_setprio(0); } while (0)
; #define PG8_WAIT_V(n) asm volatile("s_waitcnt vmcnt(" #n ")" ::: "memory")
; #define PG8_WAIT_L(n) asm volatile("s_waitcnt lgkmcnt(" #n ")" ::: "memory")
; #define PG8_BAR __builtin_amdgcn_s_barrier()
; #define PG8_SCHED __builtin_amdgcn_sched_barrier(0)
; template <class Epi, class Sched, bool ALIGN_EPI = false, bool SP2 = false>
; __device__ __forceinline__ void gemm_phase(PG8_LAS unsigned char* lds, const Gemm g, const Sched& S, const Epi& E) {
;     ...
;             PG8_WAIT_V(8); PG8_WAIT_L(0); PG8_BAR; PG8_MMA(1, 0, At, B0); PG8_MMA(1, 1, At, B1); PG8_BAR; PG8_SCHED;
;             PG8_LDB(B0, 1, 0); PG8_LDB(B1, 1, 1); PG8_SCHED; PG8_LDA(At, 1, 0); PG8_STAGE(PG8_SA(0, 1), a2 + hstep, voffA);
;             PG8_WAIT_V(8); PG8_WAIT_L(0); PG8_BAR; PG8_MMA(0, 0, At, B0); PG8_MMA(0, 1, At, B1); PG8_BAR; PG8_SCHED;
	s_setprio 1
	s_waitcnt lgkmcnt(0)
	v_mfma_f32_16x16x32_bf16 v[60:63], v[128:131], v[188:191], v[60:63]
	v_mfma_f32_16x16x32_bf16 v[56:59], v[136:139], v[188:191], v[56:59]
	v_mfma_f32_16x16x32_bf16 v[44:47], v[128:131], v[200:203], v[44:47]
	v_mfma_f32_16x16x32_bf16 v[40:43], v[136:139], v[200:203], v[40:43]
	v_mfma_f32_16x16x32_bf16 v[28:31], v[128:131], v[208:211], v[28:31]
	v_mfma_f32_16x16x32_bf16 v[24:27], v[136:139], v[208:211], v[24:27]
	v_mfma_f32_16x16x32_bf16 v[12:15], v[128:131], v[216:219], v[12:15]
	v_mfma_f32_16x16x32_bf16 v[8:11], v[136:139], v[216:219], v[8:11]
	v_mfma_f32_16x16x32_bf16 v[60:63], v[132:135], v[196:199], v[60:63]
	v_mfma_f32_16x16x32_bf16 v[56:59], v[140:143], v[196:199], v[56:59]
	v_mfma_f32_16x16x32_bf16 v[44:47], v[132:135], v[204:207], v[44:47]
	v_mfma_f32_16x16x32_bf16 v[40:43], v[140:143], v[204:207], v[40:43]
	v_mfma_f32_16x16x32_bf16 v[28:31], v[132:135], v[212:215], v[28:31]
	v_mfma_f32_16x16x32_bf16 v[24:27], v[140:143], v[212:215], v[24:27]
	v_mfma_f32_16x16x32_bf16 v[12:15], v[132:135], v[224:227], v[12:15]
	v_mfma_f32_16x16x32_bf16 v[8:11], v[140:143], v[224:227], v[8:11]
	s_setprio 0
	s_setprio 1
	v_mfma_f32_16x16x32_bf16 v[52:55], v[172:175], v[188:191], v[52:55]
	v_mfma_f32_16x16x32_bf16 v[48:51], v[180:183], v[188:191], v[48:51]
	v_mfma_f32_16x16x32_bf16 v[36:39], v[172:175], v[200:203], v[36:39]
	v_mfma_f32_16x16x32_bf16 v[32:35], v[180:183], v[200:203], v[32:35]
	v_mfma_f32_16x16x32_bf16 v[20:23], v[172:175], v[208:211], v[20:23]
	v_mfma_f32_16x16x32_bf16 v[16:19], v[180:183], v[208:211], v[16:19]
	v_mfma_f32_16x16x32_bf16 v[4:7], v[172:175], v[216:219], v[4:7]
	v_mfma_f32_16x16x32_bf16 v[0:3], v[180:183], v[216:219], v[0:3]
	v_mfma_f32_16x16x32_bf16 v[52:55], v[176:179], v[196:199], v[52:55]
	v_mfma_f32_16x16x32_bf16 v[48:51], v[184:187], v[196:199], v[48:51]
	v_mfma_f32_16x16x32_bf16 v[36:39], v[176:179], v[204:207], v[36:39]
	v_mfma_f32_16x16x32_bf16 v[32:35], v[184:187], v[204:207], v[32:35]
	v_mfma_f32_16x16x32_bf16 v[20:23], v[176:179], v[212:215], v[20:23]
	v_mfma_f32_16x16x32_bf16 v[16:19], v[184:187], v[212:215], v[16:19]
	v_mfma_f32_16x16x32_bf16 v[4:7], v[176:179], v[224:227], v[4:7]
	v_mfma_f32_16x16x32_bf16 v[0:3], v[184:187], v[224:227], v[0:3]
	s_setprio 0
	s_barrier
	s_add_i32 s90, 0, 0x18000
	s_add_i32 s91, 0, 0x1c000
	v_add_u32_e32 v140, s90, v159
	v_add_u32_e32 v152, s91, v159
	ds_read_b128 v[128:131], v140
	ds_read_b128 v[132:135], v140 offset:1024
	ds_read_b128 v[136:139], v140 offset:2048
	ds_read_b128 v[140:143], v140 offset:3072
	ds_read_b128 v[172:175], v152
	ds_read_b128 v[176:179], v152 offset:1024
	ds_read_b128 v[180:183], v152 offset:2048
	ds_read_b128 v[184:187], v152 offset:3072
	s_add_u32 s86, s86, s20
	s_addc_u32 s87, s87, s21
	s_mov_b32 m0, s34
	v_lshl_add_u64 v[238:239], s[86:87], 0, v[144:145]
	ds_read_b128 v[188:191], v195 offset:32768
	ds_read_b128 v[196:199], v195 offset:33792
	ds_read_b128 v[200:203], v195 offset:34816
	ds_read_b128 v[204:207], v195 offset:35840
	ds_read_b128 v[208:211], v195 offset:36864
	ds_read_b128 v[212:215], v195 offset:37888
	ds_read_b128 v[216:219], v195 offset:38912
	ds_read_b128 v[224:227], v195 offset:39936
	global_load_lds_dwordx4 v[238:239], off
	v_lshl_add_u64 v[238:239], s[86:87], 0, v[148:149]
	s_mov_b32 m0, s35
	s_nop 0
	global_load_lds_dwordx4 v[238:239], off
	s_waitcnt vmcnt(8)
	s_waitcnt lgkmcnt(0)
	s_barrier
	s_setprio 1
	s_waitcnt lgkmcnt(0)
	v_mfma_f32_16x16x32_bf16 v[124:127], v[128:131], v[188:191], v[124:127]
	v_mfma_f32_16x16x32_bf16 v[120:123], v[136:139], v[188:191], v[120:123]
	v_mfma_f32_16x16x32_bf16 v[108:111], v[128:131], v[200:203], v[108:111]
	v_mfma_f32_16x16x32_bf16 v[104:107], v[136:139], v[200:203], v[104:107]
	v_mfma_f32_16x16x32_bf16 v[92:95], v[128:131], v[208:211], v[92:95]
	v_mfma_f32_16x16x32_bf16 v[88:91], v[136:139], v[208:211], v[88:91]
	v_mfma_f32_16x16x32_bf16 v[76:79], v[128:131], v[216:219], v[76:79]
	v_mfma_f32_16x16x32_bf16 v[72:75], v[136:139], v[216:219], v[72:75]
	v_mfma_f32_16x16x32_bf16 v[124:127], v[132:135], v[196:199], v[124:127]
	v_mfma_f32_16x16x32_bf16 v[120:123], v[140:143], v[196:199], v[120:123]
	v_mfma_f32_16x16x32_bf16 v[108:111], v[132:135], v[204:207], v[108:111]
	v_mfma_f32_16x16x32_bf16 v[104:107], v[140:143], v[204:207], v[104:107]
	v_mfma_f32_16x16x32_bf16 v[92:95], v[132:135], v[212:215], v[92:95]
	v_mfma_f32_16x16x32_bf16 v[88:91], v[140:143], v[212:215], v[88:91]
	v_mfma_f32_16x16x32_bf16 v[76:79], v[132:135], v[224:227], v[76:79]
	v_mfma_f32_16x16x32_bf16 v[72:75], v[140:143], v[224:227], v[72:75]
	s_setprio 0
	s_setprio 1
	v_mfma_f32_16x16x32_bf16 v[116:119], v[172:175], v[188:191], v[116:119]
	v_mfma_f32_16x16x32_bf16 v[112:115], v[180:183], v[188:191], v[112:115]
	v_mfma_f32_16x16x32_bf16 v[100:103], v[172:175], v[200:203], v[100:103]
	v_mfma_f32_16x16x32_bf16 v[96:99], v[180:183], v[200:203], v[96:99]
	v_mfma_f32_16x16x32_bf16 v[84:87], v[172:175], v[208:211], v[84:87]
	v_mfma_f32_16x16x32_bf16 v[80:83], v[180:183], v[208:211], v[80:83]
	v_mfma_f32_16x16x32_bf16 v[68:71], v[172:175], v[216:219], v[68:71]
	v_mfma_f32_16x16x32_bf16 v[64:67], v[180:183], v[216:219], v[64:67]
	v_mfma_f32_16x16x32_bf16 v[116:119], v[176:179], v[196:199], v[116:119]
	v_mfma_f32_16x16x32_bf16 v[112:115], v[184:187], v[196:199], v[112:115]
	v_mfma_f32_16x16x32_bf16 v[100:103], v[176:179], v[204:207], v[100:103]
	v_mfma_f32_16x16x32_bf16 v[96:99], v[184:187], v[204:207], v[96:99]
	v_mfma_f32_16x16x32_bf16 v[84:87], v[176:179], v[212:215], v[84:87]
	v_mfma_f32_16x16x32_bf16 v[80:83], v[184:187], v[212:215], v[80:83]
	v_mfma_f32_16x16x32_bf16 v[68:71], v[176:179], v[224:227], v[68:71]
	v_mfma_f32_16x16x32_bf16 v[64:67], v[184:187], v[224:227], v[64:67]
	s_setprio 0
	s_barrier
; #define PG8_STAGE(bufoff, gbase, voff) do { _Pragma("unroll") for (int _i = 0; _i < 2; ++_i) \
;         __builtin_amdgcn_global_load_lds((const unsigned*)((const char*)(gbase) + (voff)[_i]), (PG8_LAS unsigned*)(lds + (bufoff) + ldsw + _i * 8192), 16, 0, 0); } while (0)
; #define PG8_LDA(dst, b, h) do { _Pragma("unroll") for (int m = 0; m < 4; ++m) _Pragma("unroll") for (int k = 0; k < 2; ++k) dst[m][k] = *(const PG8_LAS bf16x8*)(lds + PG8_SA(b, h) + aoff + m * 2048 + k * 1024); } while (0)
; #define PG8_MMA(ai, bj, At, Bt) do { __builtin_amdgcn_s_setprio(1); _Pragma("unroll") for (int m = 0; m < 4; ++m) _Pragma("unroll") for (int n = 0; n < 2; ++n) _Pragma("unroll") for (int k = 0; k < 2; ++k) \
;         acc[ai][bj][m][n] = __builtin_amdgcn_mfma_f32_16x16x32_bf16(Bt[n][k], At[m][k], acc[ai][bj][m][n], 0, 0, 0); __builtin_amdgcn_s_setprio(0); } while (0)
; #define PG8_WAIT_V(n) asm volatile("s_waitcnt vmcnt(" #n ")" ::: "memory")
; #define PG8_WAIT_L(n) asm volatile("s_waitcnt lgkmcnt(" #n ")" ::: "memory")
; #define PG8_BAR __builtin_amdgcn_s_barrier()
; #define PG8_SCHED __builtin_amdgcn_sched_barrier(0)
; template <class Epi, class Sched, bool ALIGN_EPI = false, bool SP2 = false>
; __device__ __forceinline__ void gemm_phase(PG8_LAS unsigned char* lds, const Gemm g, const Sched& S, const Epi& E) {
;     ...
;             PG8_LDA(At, 1, 1); PG8_STAGE(PG8_SB(1, 0), b3, voffB); PG8_STAGE(PG8_SB(1, 1), b3 + hstep, voffB); PG8_STAGE(PG8_SA(1, 0), a3, voffA);
;             PG8_WAIT_V(8); PG8_WAIT_L(0); PG8_BAR; PG8_MMA(1, 0, At, B0); PG8_MMA(1, 1, At, B1); PG8_BAR; PG8_SCHED;
	s_add_i32 s86, s90, s17
	v_lshl_add_u64 v[220:221], v[220:221], 0, s[26:27]
	s_mov_b32 m0, s86
	ds_read_b128 v[188:191], v195 offset:49152
	ds_read_b128 v[196:199], v195 offset:50176
	ds_read_b128 v[200:203], v195 offset:51200
	ds_read_b128 v[204:207], v195 offset:52224
	ds_read_b128 v[208:211], v195 offset:53248
	ds_read_b128 v[212:215], v195 offset:54272
	ds_read_b128 v[216:219], v195 offset:55296
	ds_read_b128 v[224:227], v195 offset:56320
	global_load_lds_dwordx4 v[220:221], off
	v_lshl_add_u64 v[220:221], v[228:229], 0, s[26:27]
	s_add_i32 m0, s86, 0x2000
	s_add_i32 s86, s91, s17
	global_load_lds_dwordx4 v[220:221], off
	v_lshl_add_u64 v[220:221], v[230:231], 0, s[26:27]
	s_mov_b32 m0, s86
	s_nop 0
	global_load_lds_dwordx4 v[220:221], off
	v_lshl_add_u64 v[220:221], v[232:233], 0, s[26:27]
	s_add_i32 m0, s86, 0x2000
	s_nop 0
	global_load_lds_dwordx4 v[220:221], off
	v_lshl_add_u64 v[220:221], v[234:235], 0, s[26:27]
	s_mov_b32 m0, s38
	s_nop 0
	global_load_lds_dwordx4 v[220:221], off
	v_lshl_add_u64 v[220:221], v[236:237], 0, s[26:27]
	s_mov_b32 m0, s39
	s_nop 0
	global_load_lds_dwordx4 v[220:221], off
	s_waitcnt vmcnt(8)
	s_waitcnt lgkmcnt(0)
	s_barrier
	s_setprio 1
	s_waitcnt lgkmcnt(0)
	v_mfma_f32_16x16x32_bf16 v[60:63], v[128:131], v[188:191], v[60:63]
	v_mfma_f32_16x16x32_bf16 v[56:59], v[136:139], v[188:191], v[56:59]
	v_mfma_f32_16x16x32_bf16 v[44:47], v[128:131], v[200:203], v[44:47]
	v_mfma_f32_16x16x32_bf16 v[40:43], v[136:139], v[200:203], v[40:43]
	v_mfma_f32_16x16x32_bf16 v[28:31], v[128:131], v[208:211], v[28:31]
	v_mfma_f32_16x16x32_bf16 v[24:27], v[136:139], v[208:211], v[24:27]
	v_mfma_f32_16x16x32_bf16 v[12:15], v[128:131], v[216:219], v[12:15]
	v_mfma_f32_16x16x32_bf16 v[8:11], v[136:139], v[216:219], v[8:11]
	v_mfma_f32_16x16x32_bf16 v[60:63], v[132:135], v[196:199], v[60:63]
	v_mfma_f32_16x16x32_bf16 v[56:59], v[140:143], v[196:199], v[56:59]
	v_mfma_f32_16x16x32_bf16 v[44:47], v[132:135], v[204:207], v[44:47]
	v_mfma_f32_16x16x32_bf16 v[40:43], v[140:143], v[204:207], v[40:43]
	v_mfma_f32_16x16x32_bf16 v[28:31], v[132:135], v[212:215], v[28:31]
	v_mfma_f32_16x16x32_bf16 v[24:27], v[140:143], v[212:215], v[24:27]
	v_mfma_f32_16x16x32_bf16 v[12:15], v[132:135], v[224:227], v[12:15]
	v_mfma_f32_16x16x32_bf16 v[8:11], v[140:143], v[224:227], v[8:11]
	s_setprio 0
	s_setprio 1
	v_mfma_f32_16x16x32_bf16 v[52:55], v[172:175], v[188:191], v[52:55]
	v_mfma_f32_16x16x32_bf16 v[48:51], v[180:183], v[188:191], v[48:51]
	v_mfma_f32_16x16x32_bf16 v[36:39], v[172:175], v[200:203], v[36:39]
	v_mfma_f32_16x16x32_bf16 v[32:35], v[180:183], v[200:203], v[32:35]
	v_mfma_f32_16x16x32_bf16 v[20:23], v[172:175], v[208:211], v[20:23]
	v_mfma_f32_16x16x32_bf16 v[16:19], v[180:183], v[208:211], v[16:19]
	v_mfma_f32_16x16x32_bf16 v[4:7], v[172:175], v[216:219], v[4:7]
	v_mfma_f32_16x16x32_bf16 v[0:3], v[180:183], v[216:219], v[0:3]
	v_mfma_f32_16x16x32_bf16 v[52:55], v[176:179], v[196:199], v[52:55]
	v_mfma_f32_16x16x32_bf16 v[48:51], v[184:187], v[196:199], v[48:51]
	v_mfma_f32_16x16x32_bf16 v[36:39], v[176:179], v[204:207], v[36:39]
	v_mfma_f32_16x16x32_bf16 v[32:35], v[184:187], v[204:207], v[32:35]
	v_mfma_f32_16x16x32_bf16 v[20:23], v[176:179], v[212:215], v[20:23]
	v_mfma_f32_16x16x32_bf16 v[16:19], v[184:187], v[212:215], v[16:19]
	v_mfma_f32_16x16x32_bf16 v[4:7], v[176:179], v[224:227], v[4:7]
	v_mfma_f32_16x16x32_bf16 v[0:3], v[184:187], v[224:227], v[0:3]
	s_setprio 0
	s_barrier
	s_add_u32 s14, s14, 0x100
	s_addc_u32 s15, s15, 0
	s_add_u32 s67, s67, 0x100
	s_addc_u32 s85, s85, 0
	s_cmp_ge_i32 s89, s78
	s_mov_b32 s86, s89
	s_cbranch_scc0 .LBB0_1940

; #define PG8_STAGE(bufoff, gbase, voff) do { _Pragma("unroll") for (int _i = 0; _i < 2; ++_i) \
;         __builtin_amdgcn_global_load_lds((const unsigned*)((const char*)(gbase) + (voff)[_i]), (PG8_LAS unsigned*)(lds + (bufoff) + ldsw + _i * 8192), 16, 0, 0); } while (0)
; #define PG8_LDA(dst, b, h) do { _Pragma("unroll") for (int m = 0; m < 4; ++m) _Pragma("unroll") for (int k = 0; k < 2; ++k) dst[m][k] = *(const PG8_LAS bf16x8*)(lds + PG8_SA(b, h) + aoff + m * 2048 + k * 1024); } while (0)
; #define PG8_LDB(dst, b, h) do { _Pragma("unroll") for (int n = 0; n < 2; ++n) _Pragma("unroll") for (int k = 0; k < 2; ++k) dst[n][k] = *(const PG8_LAS bf16x8*)(lds + PG8_SB(b, h) + boff + n * 2048 + k * 1024); } while (0)
; #define PG8_MMA(ai, bj, At, Bt) do { __builtin_amdgcn_s_setprio(1); _Pragma("unroll") for (int m = 0; m < 4; ++m) _Pragma("unroll") for (int n = 0; n < 2; ++n) _Pragma("unroll") for (int k = 0; k < 2; ++k) \
;         acc[ai][bj][m][n] = __builtin_amdgcn_mfma_f32_16x16x32_bf16(Bt[n][k], At[m][k], acc[ai][bj][m][n], 0, 0, 0); __builtin_amdgcn_s_setprio(0); } while (0)
; #define PG8_WAIT_V(n) asm volatile("s_waitcnt vmcnt(" #n ")" ::: "memory")
; #define PG8_BAR __builtin_amdgcn_s_barrier()
; template <class Epi, class Sched, bool ALIGN_EPI = false, bool SP2 = false>
; __device__ __forceinline__ void gemm_phase(PG8_LAS unsigned char* lds, const Gemm g, const Sched& S, const Epi& E) {
;     ...
;         for (int t = 0; t < nt; t += 2) {
;             const bool last = (t == nt - 2);
;             const char* a1 = cA + (size_t)(t + 1) * kstep;
;             const char* a2 = last ? nA : cA + (size_t)(t + 2) * kstep; const char* b2 = last ? nB : cB + (size_t)(t + 2) * kstep;
;             const char* a3 = a2 + kstep; const char* b3 = b2 + kstep;
;             if (last && has_next) S.a_ready(nxt);
;             if constexpr (SP2) {
;             PG8_LDB(B0, 0, 0); PG8_LDB(B1, 0, 1); PG8_SCHED; PG8_LDA(At, 0, 0); PG8_STAGE(PG8_SA(1, 1), a1 + hstep, voffA);
;             PG8_WAIT_V(8); PG8_WAIT_L(0); PG8_BAR; PG8_MMA(0, 0, At, B0); PG8_MMA(0, 1, At, B1); PG8_BAR; PG8_SCHED;
;             PG8_LDA(At, 0, 1); PG8_STAGE(PG8_SB(0, 0), b2, voffB); PG8_STAGE(PG8_SB(0, 1), b2 + hstep, voffB); PG8_STAGE(PG8_SA(0, 0), a2, voffA);
;             PG8_WAIT_V(8); PG8_WAIT_L(0); PG8_BAR; PG8_MMA(1, 0, At, B0); PG8_MMA(1, 1, At, B1); PG8_BAR; PG8_SCHED;
.LBB0_1989:
	s_sleep 2
	ds_read_b128 v[152:155], v148
	ds_read_b128 v[156:159], v148 offset:1024
	ds_read_b128 v[160:163], v148 offset:2048
	ds_read_b128 v[164:167], v148 offset:3072
	ds_read_b128 v[168:171], v149
	ds_read_b128 v[172:175], v149 offset:1024
	ds_read_b128 v[176:179], v149 offset:2048
	ds_read_b128 v[180:183], v149 offset:3072
	s_add_i32 s88, s30, 2
	s_add_u32 s89, s28, 0x80
	s_addc_u32 s31, s29, 0
	s_cmp_eq_u32 s81, s30
	s_cselect_b32 s30, s6, s89
	s_cselect_b32 s31, s7, s31
	s_cselect_b32 s91, s27, s87
	s_cselect_b32 s90, s26, s25
	v_lshl_add_u64 v[220:221], s[28:29], 0, v[140:141]
	s_add_i32 m0, s47, 0xc000
	ds_read_b128 v[184:187], v150
	ds_read_b128 v[188:191], v150 offset:1024
	ds_read_b128 v[196:199], v150 offset:2048
	ds_read_b128 v[200:203], v150 offset:3072
	ds_read_b128 v[204:207], v150 offset:4096
	ds_read_b128 v[208:211], v150 offset:5120
	ds_read_b128 v[212:215], v150 offset:6144
	ds_read_b128 v[216:219], v150 offset:7168
	global_load_lds_dwordx4 v[220:221], off
	v_lshl_add_u64 v[220:221], s[28:29], 0, v[142:143]
	s_add_i32 m0, s47, 0xe000
	s_nop 0
	global_load_lds_dwordx4 v[220:221], off
	s_waitcnt vmcnt(8)
	s_waitcnt lgkmcnt(0)
	s_barrier
	s_setprio 1
	s_waitcnt lgkmcnt(0)
	v_mfma_f32_16x16x32_bf16 v[120:123], v[152:155], v[184:187], v[120:123]
	v_mfma_f32_16x16x32_bf16 v[124:127], v[160:163], v[184:187], v[124:127]
	v_mfma_f32_16x16x32_bf16 v[108:111], v[152:155], v[196:199], v[108:111]
	v_mfma_f32_16x16x32_bf16 v[104:107], v[160:163], v[196:199], v[104:107]
	v_mfma_f32_16x16x32_bf16 v[92:95], v[152:155], v[204:207], v[92:95]
	v_mfma_f32_16x16x32_bf16 v[88:91], v[160:163], v[204:207], v[88:91]
	v_mfma_f32_16x16x32_bf16 v[76:79], v[152:155], v[212:215], v[76:79]
	v_mfma_f32_16x16x32_bf16 v[72:75], v[160:163], v[212:215], v[72:75]
	v_mfma_f32_16x16x32_bf16 v[120:123], v[156:159], v[188:191], v[120:123]
	v_mfma_f32_16x16x32_bf16 v[124:127], v[164:167], v[188:191], v[124:127]
	v_mfma_f32_16x16x32_bf16 v[108:111], v[156:159], v[200:203], v[108:111]
	v_mfma_f32_16x16x32_bf16 v[104:107], v[164:167], v[200:203], v[104:107]
	v_mfma_f32_16x16x32_bf16 v[92:95], v[156:159], v[208:211], v[92:95]
	v_mfma_f32_16x16x32_bf16 v[88:91], v[164:167], v[208:211], v[88:91]
	v_mfma_f32_16x16x32_bf16 v[76:79], v[156:159], v[216:219], v[76:79]
	v_mfma_f32_16x16x32_bf16 v[72:75], v[164:167], v[216:219], v[72:75]
	s_setprio 0
	s_setprio 1
	v_mfma_f32_16x16x32_bf16 v[116:119], v[168:171], v[184:187], v[116:119]
	v_mfma_f32_16x16x32_bf16 v[112:115], v[176:179], v[184:187], v[112:115]
	v_mfma_f32_16x16x32_bf16 v[100:103], v[168:171], v[196:199], v[100:103]
	v_mfma_f32_16x16x32_bf16 v[96:99], v[176:179], v[196:199], v[96:99]
	v_mfma_f32_16x16x32_bf16 v[84:87], v[168:171], v[204:207], v[84:87]
	v_mfma_f32_16x16x32_bf16 v[80:83], v[176:179], v[204:207], v[80:83]
	v_mfma_f32_16x16x32_bf16 v[68:71], v[168:171], v[212:215], v[68:71]
	v_mfma_f32_16x16x32_bf16 v[64:67], v[176:179], v[212:215], v[64:67]
	v_mfma_f32_16x16x32_bf16 v[116:119], v[172:175], v[188:191], v[116:119]
	v_mfma_f32_16x16x32_bf16 v[112:115], v[180:183], v[188:191], v[112:115]
	v_mfma_f32_16x16x32_bf16 v[100:103], v[172:175], v[200:203], v[100:103]
	v_mfma_f32_16x16x32_bf16 v[96:99], v[180:183], v[200:203], v[96:99]
	v_mfma_f32_16x16x32_bf16 v[84:87], v[172:175], v[208:211], v[84:87]
	v_mfma_f32_16x16x32_bf16 v[80:83], v[180:183], v[208:211], v[80:83]
	v_mfma_f32_16x16x32_bf16 v[68:71], v[172:175], v[216:219], v[68:71]
	v_mfma_f32_16x16x32_bf16 v[64:67], v[180:183], v[216:219], v[64:67]
	s_setprio 0
	s_barrier
	s_add_i32 s89, s82, s36
	v_lshl_add_u64 v[220:221], s[90:91], 0, v[130:131]
	s_mov_b32 m0, s89
	ds_read_b128 v[184:187], v150 offset:16384
	ds_read_b128 v[188:191], v150 offset:17408
	ds_read_b128 v[196:199], v150 offset:18432
	ds_read_b128 v[200:203], v150 offset:19456
	ds_read_b128 v[204:207], v150 offset:20480
	ds_read_b128 v[208:211], v150 offset:21504
	ds_read_b128 v[212:215], v150 offset:22528
	ds_read_b128 v[216:219], v150 offset:23552
	global_load_lds_dwordx4 v[220:221], off
	s_add_i32 m0, s89, 0x2000
	v_lshl_add_u64 v[222:223], s[90:91], 0, v[134:135]
	s_add_u32 s90, s90, s8
	s_addc_u32 s91, s91, s9
	s_add_i32 s89, s83, s36
	global_load_lds_dwordx4 v[222:223], off
	v_lshl_add_u64 v[224:225], s[90:91], 0, v[130:131]
	s_mov_b32 m0, s89
	v_lshl_add_u64 v[226:227], s[90:91], 0, v[134:135]
	global_load_lds_dwordx4 v[224:225], off
	s_add_i32 m0, s89, 0x2000
	v_lshl_add_u64 v[228:229], s[30:31], 0, v[128:129]
	global_load_lds_dwordx4 v[226:227], off
	s_mov_b32 m0, s47
	v_lshl_add_u64 v[230:231], s[30:31], 0, v[132:133]
	global_load_lds_dwordx4 v[228:229], off
	s_mov_b32 m0, s66
	s_nop 0
	global_load_lds_dwordx4 v[230:231], off
	s_waitcnt vmcnt(8)
	s_waitcnt lgkmcnt(0)
	s_barrier
; #define PG8_STAGE(bufoff, gbase, voff) do { _Pragma("unroll") for (int _i = 0; _i < 2; ++_i) \
;         __builtin_amdgcn_global_load_lds((const unsigned*)((const char*)(gbase) + (voff)[_i]), (PG8_LAS unsigned*)(lds + (bufoff) + ldsw + _i * 8192), 16, 0, 0); } while (0)
; #define PG8_LDA(dst, b, h) do { _Pragma("unroll") for (int m = 0; m < 4; ++m) _Pragma("unroll") for (int k = 0; k < 2; ++k) dst[m][k] = *(const PG8_LAS bf16x8*)(lds + PG8_SA(b, h) + aoff + m * 2048 + k * 1024); } while (0)
; #define PG8_LDB(dst, b, h) do { _Pragma("unroll") for (int n = 0; n < 2; ++n) _Pragma("unroll") for (int k = 0; k < 2; ++k) dst[n][k] = *(const PG8_LAS bf16x8*)(lds + PG8_SB(b, h) + boff + n * 2048 + k * 1024); } while (0)
; #define PG8_MMA(ai, bj, At, Bt) do { __builtin_amdgcn_s_setprio(1); _Pragma("unroll") for (int m = 0; m < 4; ++m) _Pragma("unroll") for (int n = 0; n < 2; ++n) _Pragma("unroll") for (int k = 0; k < 2; ++k) \
;         acc[ai][bj][m][n] = __builtin_amdgcn_mfma_f32_16x16x32_bf16(Bt[n][k], At[m][k], acc[ai][bj][m][n], 0, 0, 0); __builtin_amdgcn_s_setprio(0); } while (0)
; #define PG8_WAIT_V(n) asm volatile("s_waitcnt vmcnt(" #n ")" ::: "memory")
; #define PG8_WAIT_L(n) asm volatile("s_waitcnt lgkmcnt(" #n ")" ::: "memory")
; #define PG8_BAR __builtin_amdgcn_s_barrier()
; #define PG8_SCHED __builtin_amdgcn_sched_barrier(0)
; template <class Epi, class Sched, bool ALIGN_EPI = false, bool SP2 = false>
; __device__ __forceinline__ void gemm_phase(PG8_LAS unsigned char* lds, const Gemm g, const Sched& S, const Epi& E) {
;     ...
;             PG8_WAIT_V(8); PG8_WAIT_L(0); PG8_BAR; PG8_MMA(1, 0, At, B0); PG8_MMA(1, 1, At, B1); PG8_BAR; PG8_SCHED;
;             PG8_LDB(B0, 1, 0); PG8_LDB(B1, 1, 1); PG8_SCHED; PG8_LDA(At, 1, 0); PG8_STAGE(PG8_SA(0, 1), a2 + hstep, voffA);
;             PG8_WAIT_V(8); PG8_WAIT_L(0); PG8_BAR; PG8_MMA(0, 0, At, B0); PG8_MMA(0, 1, At, B1); PG8_BAR; PG8_SCHED;
	s_setprio 1
	s_waitcnt lgkmcnt(0)
	v_mfma_f32_16x16x32_bf16 v[60:63], v[152:155], v[184:187], v[60:63]
	v_mfma_f32_16x16x32_bf16 v[56:59], v[160:163], v[184:187], v[56:59]
	v_mfma_f32_16x16x32_bf16 v[44:47], v[152:155], v[196:199], v[44:47]
	v_mfma_f32_16x16x32_bf16 v[40:43], v[160:163], v[196:199], v[40:43]
	v_mfma_f32_16x16x32_bf16 v[28:31], v[152:155], v[204:207], v[28:31]
	v_mfma_f32_16x16x32_bf16 v[24:27], v[160:163], v[204:207], v[24:27]
	v_mfma_f32_16x16x32_bf16 v[12:15], v[152:155], v[212:215], v[12:15]
	v_mfma_f32_16x16x32_bf16 v[8:11], v[160:163], v[212:215], v[8:11]
	v_mfma_f32_16x16x32_bf16 v[60:63], v[156:159], v[188:191], v[60:63]
	v_mfma_f32_16x16x32_bf16 v[56:59], v[164:167], v[188:191], v[56:59]
	v_mfma_f32_16x16x32_bf16 v[44:47], v[156:159], v[200:203], v[44:47]
	v_mfma_f32_16x16x32_bf16 v[40:43], v[164:167], v[200:203], v[40:43]
	v_mfma_f32_16x16x32_bf16 v[28:31], v[156:159], v[208:211], v[28:31]
	v_mfma_f32_16x16x32_bf16 v[24:27], v[164:167], v[208:211], v[24:27]
	v_mfma_f32_16x16x32_bf16 v[12:15], v[156:159], v[216:219], v[12:15]
	v_mfma_f32_16x16x32_bf16 v[8:11], v[164:167], v[216:219], v[8:11]
	s_setprio 0
	s_setprio 1
	v_mfma_f32_16x16x32_bf16 v[52:55], v[168:171], v[184:187], v[52:55]
	v_mfma_f32_16x16x32_bf16 v[48:51], v[176:179], v[184:187], v[48:51]
	v_mfma_f32_16x16x32_bf16 v[36:39], v[168:171], v[196:199], v[36:39]
	v_mfma_f32_16x16x32_bf16 v[32:35], v[176:179], v[196:199], v[32:35]
	v_mfma_f32_16x16x32_bf16 v[20:23], v[168:171], v[204:207], v[20:23]
	v_mfma_f32_16x16x32_bf16 v[16:19], v[176:179], v[204:207], v[16:19]
	v_mfma_f32_16x16x32_bf16 v[4:7], v[168:171], v[212:215], v[4:7]
	v_mfma_f32_16x16x32_bf16 v[0:3], v[176:179], v[212:215], v[0:3]
	v_mfma_f32_16x16x32_bf16 v[52:55], v[172:175], v[188:191], v[52:55]
	v_mfma_f32_16x16x32_bf16 v[48:51], v[180:183], v[188:191], v[48:51]
	v_mfma_f32_16x16x32_bf16 v[36:39], v[172:175], v[200:203], v[36:39]
	v_mfma_f32_16x16x32_bf16 v[32:35], v[180:183], v[200:203], v[32:35]
	v_mfma_f32_16x16x32_bf16 v[20:23], v[172:175], v[208:211], v[20:23]
	v_mfma_f32_16x16x32_bf16 v[16:19], v[180:183], v[208:211], v[16:19]
	v_mfma_f32_16x16x32_bf16 v[4:7], v[172:175], v[216:219], v[4:7]
	v_mfma_f32_16x16x32_bf16 v[0:3], v[180:183], v[216:219], v[0:3]
	s_setprio 0
	s_barrier
	s_add_i32 s89, 0, 0x18000
	v_add_u32_e32 v136, s89, v146
	s_add_i32 s90, 0, 0x1c000
	ds_read_b128 v[152:155], v136
	ds_read_b128 v[156:159], v136 offset:1024
	ds_read_b128 v[160:163], v136 offset:2048
	ds_read_b128 v[164:167], v136 offset:3072
	v_add_u32_e32 v136, s90, v146
	ds_read_b128 v[168:171], v136
	ds_read_b128 v[172:175], v136 offset:1024
	ds_read_b128 v[176:179], v136 offset:2048
	ds_read_b128 v[180:183], v136 offset:3072
	s_add_u32 s30, s30, s8
	s_addc_u32 s31, s31, s9
	s_mov_b32 m0, s67
	v_lshl_add_u64 v[232:233], s[30:31], 0, v[128:129]
	ds_read_b128 v[184:187], v150 offset:32768
	ds_read_b128 v[188:191], v150 offset:33792
	ds_read_b128 v[196:199], v150 offset:34816
	ds_read_b128 v[200:203], v150 offset:35840
	ds_read_b128 v[204:207], v150 offset:36864
	ds_read_b128 v[208:211], v150 offset:37888
	ds_read_b128 v[212:215], v150 offset:38912
	ds_read_b128 v[216:219], v150 offset:39936
	global_load_lds_dwordx4 v[232:233], off
	v_lshl_add_u64 v[232:233], s[30:31], 0, v[132:133]
	s_mov_b32 m0, s70
	s_nop 0
	global_load_lds_dwordx4 v[232:233], off
	s_waitcnt vmcnt(8)
	s_waitcnt lgkmcnt(0)
	s_barrier
	s_setprio 1
	s_waitcnt lgkmcnt(0)
	v_mfma_f32_16x16x32_bf16 v[120:123], v[152:155], v[184:187], v[120:123]
	v_mfma_f32_16x16x32_bf16 v[124:127], v[160:163], v[184:187], v[124:127]
	v_mfma_f32_16x16x32_bf16 v[108:111], v[152:155], v[196:199], v[108:111]
	v_mfma_f32_16x16x32_bf16 v[104:107], v[160:163], v[196:199], v[104:107]
	v_mfma_f32_16x16x32_bf16 v[92:95], v[152:155], v[204:207], v[92:95]
	v_mfma_f32_16x16x32_bf16 v[88:91], v[160:163], v[204:207], v[88:91]
	v_mfma_f32_16x16x32_bf16 v[76:79], v[152:155], v[212:215], v[76:79]
	v_mfma_f32_16x16x32_bf16 v[72:75], v[160:163], v[212:215], v[72:75]
	v_mfma_f32_16x16x32_bf16 v[120:123], v[156:159], v[188:191], v[120:123]
	v_mfma_f32_16x16x32_bf16 v[124:127], v[164:167], v[188:191], v[124:127]
	v_mfma_f32_16x16x32_bf16 v[108:111], v[156:159], v[200:203], v[108:111]
	v_mfma_f32_16x16x32_bf16 v[104:107], v[164:167], v[200:203], v[104:107]
	v_mfma_f32_16x16x32_bf16 v[92:95], v[156:159], v[208:211], v[92:95]
	v_mfma_f32_16x16x32_bf16 v[88:91], v[164:167], v[208:211], v[88:91]
	v_mfma_f32_16x16x32_bf16 v[76:79], v[156:159], v[216:219], v[76:79]
	v_mfma_f32_16x16x32_bf16 v[72:75], v[164:167], v[216:219], v[72:75]
	s_setprio 0
	s_setprio 1
	v_mfma_f32_16x16x32_bf16 v[116:119], v[168:171], v[184:187], v[116:119]
	v_mfma_f32_16x16x32_bf16 v[112:115], v[176:179], v[184:187], v[112:115]
	v_mfma_f32_16x16x32_bf16 v[100:103], v[168:171], v[196:199], v[100:103]
	v_mfma_f32_16x16x32_bf16 v[96:99], v[176:179], v[196:199], v[96:99]
	v_mfma_f32_16x16x32_bf16 v[84:87], v[168:171], v[204:207], v[84:87]
	v_mfma_f32_16x16x32_bf16 v[80:83], v[176:179], v[204:207], v[80:83]
	v_mfma_f32_16x16x32_bf16 v[68:71], v[168:171], v[212:215], v[68:71]
	v_mfma_f32_16x16x32_bf16 v[64:67], v[176:179], v[212:215], v[64:67]
	v_mfma_f32_16x16x32_bf16 v[116:119], v[172:175], v[188:191], v[116:119]
	v_mfma_f32_16x16x32_bf16 v[112:115], v[180:183], v[188:191], v[112:115]
	v_mfma_f32_16x16x32_bf16 v[100:103], v[172:175], v[200:203], v[100:103]
	v_mfma_f32_16x16x32_bf16 v[96:99], v[180:183], v[200:203], v[96:99]
	v_mfma_f32_16x16x32_bf16 v[84:87], v[172:175], v[208:211], v[84:87]
	v_mfma_f32_16x16x32_bf16 v[80:83], v[180:183], v[208:211], v[80:83]
	v_mfma_f32_16x16x32_bf16 v[68:71], v[172:175], v[216:219], v[68:71]
	v_mfma_f32_16x16x32_bf16 v[64:67], v[180:183], v[216:219], v[64:67]
	s_setprio 0
	s_barrier
; #define PG8_STAGE(bufoff, gbase, voff) do { _Pragma("unroll") for (int _i = 0; _i < 2; ++_i) \
;         __builtin_amdgcn_global_load_lds((const unsigned*)((const char*)(gbase) + (voff)[_i]), (PG8_LAS unsigned*)(lds + (bufoff) + ldsw + _i * 8192), 16, 0, 0); } while (0)
; #define PG8_LDA(dst, b, h) do { _Pragma("unroll") for (int m = 0; m < 4; ++m) _Pragma("unroll") for (int k = 0; k < 2; ++k) dst[m][k] = *(const PG8_LAS bf16x8*)(lds + PG8_SA(b, h) + aoff + m * 2048 + k * 1024); } while (0)
; #define PG8_MMA(ai, bj, At, Bt) do { __builtin_amdgcn_s_setprio(1); _Pragma("unroll") for (int m = 0; m < 4; ++m) _Pragma("unroll") for (int n = 0; n < 2; ++n) _Pragma("unroll") for (int k = 0; k < 2; ++k) \
;         acc[ai][bj][m][n] = __builtin_amdgcn_mfma_f32_16x16x32_bf16(Bt[n][k], At[m][k], acc[ai][bj][m][n], 0, 0, 0); __builtin_amdgcn_s_setprio(0); } while (0)
; #define PG8_WAIT_V(n) asm volatile("s_waitcnt vmcnt(" #n ")" ::: "memory")
; #define PG8_WAIT_L(n) asm volatile("s_waitcnt lgkmcnt(" #n ")" ::: "memory")
; #define PG8_BAR __builtin_amdgcn_s_barrier()
; #define PG8_SCHED __builtin_amdgcn_sched_barrier(0)
; template <class Epi, class Sched, bool ALIGN_EPI = false, bool SP2 = false>
; __device__ __forceinline__ void gemm_phase(PG8_LAS unsigned char* lds, const Gemm g, const Sched& S, const Epi& E) {
;     ...
;             PG8_LDA(At, 1, 1); PG8_STAGE(PG8_SB(1, 0), b3, voffB); PG8_STAGE(PG8_SB(1, 1), b3 + hstep, voffB); PG8_STAGE(PG8_SA(1, 0), a3, voffA);
;             PG8_WAIT_V(8); PG8_WAIT_L(0); PG8_BAR; PG8_MMA(1, 0, At, B0); PG8_MMA(1, 1, At, B1); PG8_BAR; PG8_SCHED;
	s_add_i32 s30, s89, s36
	v_lshl_add_u64 v[220:221], v[220:221], 0, s[14:15]
	s_mov_b32 m0, s30
	ds_read_b128 v[184:187], v150 offset:49152
	ds_read_b128 v[188:191], v150 offset:50176
	ds_read_b128 v[196:199], v150 offset:51200
	ds_read_b128 v[200:203], v150 offset:52224
	ds_read_b128 v[204:207], v150 offset:53248
	ds_read_b128 v[208:211], v150 offset:54272
	ds_read_b128 v[212:215], v150 offset:55296
	ds_read_b128 v[216:219], v150 offset:56320
	global_load_lds_dwordx4 v[220:221], off
	v_lshl_add_u64 v[220:221], v[222:223], 0, s[14:15]
	s_add_i32 m0, s30, 0x2000
	s_add_i32 s30, s90, s36
	global_load_lds_dwordx4 v[220:221], off
	v_lshl_add_u64 v[220:221], v[224:225], 0, s[14:15]
	s_mov_b32 m0, s30
	s_nop 0
	global_load_lds_dwordx4 v[220:221], off
	v_lshl_add_u64 v[220:221], v[226:227], 0, s[14:15]
	s_add_i32 m0, s30, 0x2000
	s_nop 0
	global_load_lds_dwordx4 v[220:221], off
	v_lshl_add_u64 v[220:221], v[228:229], 0, s[14:15]
	s_mov_b32 m0, s78
	s_nop 0
	global_load_lds_dwordx4 v[220:221], off
	v_lshl_add_u64 v[220:221], v[230:231], 0, s[14:15]
	s_mov_b32 m0, s79
	s_nop 0
	global_load_lds_dwordx4 v[220:221], off
	s_waitcnt vmcnt(8)
	s_waitcnt lgkmcnt(0)
	s_barrier
	s_setprio 1
	s_waitcnt lgkmcnt(0)
	v_mfma_f32_16x16x32_bf16 v[60:63], v[152:155], v[184:187], v[60:63]
	v_mfma_f32_16x16x32_bf16 v[56:59], v[160:163], v[184:187], v[56:59]
	v_mfma_f32_16x16x32_bf16 v[44:47], v[152:155], v[196:199], v[44:47]
	v_mfma_f32_16x16x32_bf16 v[40:43], v[160:163], v[196:199], v[40:43]
	v_mfma_f32_16x16x32_bf16 v[28:31], v[152:155], v[204:207], v[28:31]
	v_mfma_f32_16x16x32_bf16 v[24:27], v[160:163], v[204:207], v[24:27]
	v_mfma_f32_16x16x32_bf16 v[12:15], v[152:155], v[212:215], v[12:15]
	v_mfma_f32_16x16x32_bf16 v[8:11], v[160:163], v[212:215], v[8:11]
	v_mfma_f32_16x16x32_bf16 v[60:63], v[156:159], v[188:191], v[60:63]
	v_mfma_f32_16x16x32_bf16 v[56:59], v[164:167], v[188:191], v[56:59]
	v_mfma_f32_16x16x32_bf16 v[44:47], v[156:159], v[200:203], v[44:47]
	v_mfma_f32_16x16x32_bf16 v[40:43], v[164:167], v[200:203], v[40:43]
	v_mfma_f32_16x16x32_bf16 v[28:31], v[156:159], v[208:211], v[28:31]
	v_mfma_f32_16x16x32_bf16 v[24:27], v[164:167], v[208:211], v[24:27]
	v_mfma_f32_16x16x32_bf16 v[12:15], v[156:159], v[216:219], v[12:15]
	v_mfma_f32_16x16x32_bf16 v[8:11], v[164:167], v[216:219], v[8:11]
	s_setprio 0
	s_setprio 1
	v_mfma_f32_16x16x32_bf16 v[52:55], v[168:171], v[184:187], v[52:55]
	v_mfma_f32_16x16x32_bf16 v[48:51], v[176:179], v[184:187], v[48:51]
	v_mfma_f32_16x16x32_bf16 v[36:39], v[168:171], v[196:199], v[36:39]
	v_mfma_f32_16x16x32_bf16 v[32:35], v[176:179], v[196:199], v[32:35]
	v_mfma_f32_16x16x32_bf16 v[20:23], v[168:171], v[204:207], v[20:23]
	v_mfma_f32_16x16x32_bf16 v[16:19], v[176:179], v[204:207], v[16:19]
	v_mfma_f32_16x16x32_bf16 v[4:7], v[168:171], v[212:215], v[4:7]
	v_mfma_f32_16x16x32_bf16 v[0:3], v[176:179], v[212:215], v[0:3]
	v_mfma_f32_16x16x32_bf16 v[52:55], v[172:175], v[188:191], v[52:55]
	v_mfma_f32_16x16x32_bf16 v[48:51], v[180:183], v[188:191], v[48:51]
	v_mfma_f32_16x16x32_bf16 v[36:39], v[172:175], v[200:203], v[36:39]
	v_mfma_f32_16x16x32_bf16 v[32:35], v[180:183], v[200:203], v[32:35]
	v_mfma_f32_16x16x32_bf16 v[20:23], v[172:175], v[208:211], v[20:23]
	v_mfma_f32_16x16x32_bf16 v[16:19], v[180:183], v[208:211], v[16:19]
	v_mfma_f32_16x16x32_bf16 v[4:7], v[172:175], v[216:219], v[4:7]
	v_mfma_f32_16x16x32_bf16 v[0:3], v[180:183], v[216:219], v[0:3]
	s_setprio 0
	s_barrier
	s_add_u32 s28, s28, 0x100
	s_addc_u32 s29, s29, 0
	s_add_u32 s25, s25, 0x100
	s_addc_u32 s87, s87, 0
	s_cmp_ge_i32 s88, s80
	s_mov_b32 s30, s88
	s_cbranch_scc0 .LBB0_1989

; #define PG8_STAGE(bufoff, gbase, voff) do { _Pragma("unroll") for (int _i = 0; _i < 2; ++_i) \
;         __builtin_amdgcn_global_load_lds((const unsigned*)((const char*)(gbase) + (voff)[_i]), (PG8_LAS unsigned*)(lds + (bufoff) + ldsw + _i * 8192), 16, 0, 0); } while (0)
; #define PG8_LDA(dst, b, h) do { _Pragma("unroll") for (int m = 0; m < 4; ++m) _Pragma("unroll") for (int k = 0; k < 2; ++k) dst[m][k] = *(const PG8_LAS bf16x8*)(lds + PG8_SA(b, h) + aoff + m * 2048 + k * 1024); } while (0)
; #define PG8_LDB(dst, b, h) do { _Pragma("unroll") for (int n = 0; n < 2; ++n) _Pragma("unroll") for (int k = 0; k < 2; ++k) dst[n][k] = *(const PG8_LAS bf16x8*)(lds + PG8_SB(b, h) + boff + n * 2048 + k * 1024); } while (0)
; #define PG8_MMA(ai, bj, At, Bt) do { __builtin_amdgcn_s_setprio(1); _Pragma("unroll") for (int m = 0; m < 4; ++m) _Pragma("unroll") for (int n = 0; n < 2; ++n) _Pragma("unroll") for (int k = 0; k < 2; ++k) \
;         acc[ai][bj][m][n] = __builtin_amdgcn_mfma_f32_16x16x32_bf16(Bt[n][k], At[m][k], acc[ai][bj][m][n], 0, 0, 0); __builtin_amdgcn_s_setprio(0); } while (0)
; #define PG8_WAIT_V(n) asm volatile("s_waitcnt vmcnt(" #n ")" ::: "memory")
; #define PG8_BAR __builtin_amdgcn_s_barrier()
; template <class Epi, class Sched, bool ALIGN_EPI = false, bool SP2 = false>
; __device__ __forceinline__ void gemm_phase(PG8_LAS unsigned char* lds, const Gemm g, const Sched& S, const Epi& E) {
;     ...
;         for (int t = 0; t < nt; t += 2) {
;             const bool last = (t == nt - 2);
;             const char* a1 = cA + (size_t)(t + 1) * kstep;
;             const char* a2 = last ? nA : cA + (size_t)(t + 2) * kstep; const char* b2 = last ? nB : cB + (size_t)(t + 2) * kstep;
;             const char* a3 = a2 + kstep; const char* b3 = b2 + kstep;
;             if (last && has_next) S.a_ready(nxt);
;             if constexpr (SP2) {
;             PG8_LDB(B0, 0, 0); PG8_LDB(B1, 0, 1); PG8_SCHED; PG8_LDA(At, 0, 0); PG8_STAGE(PG8_SA(1, 1), a1 + hstep, voffA);
;             PG8_WAIT_V(8); PG8_WAIT_L(0); PG8_BAR; PG8_MMA(0, 0, At, B0); PG8_MMA(0, 1, At, B1); PG8_BAR; PG8_SCHED;
;             PG8_LDA(At, 0, 1); PG8_STAGE(PG8_SB(0, 0), b2, voffB); PG8_STAGE(PG8_SB(0, 1), b2 + hstep, voffB); PG8_STAGE(PG8_SA(0, 0), a2, voffA);
;             PG8_WAIT_V(8); PG8_WAIT_L(0); PG8_BAR; PG8_MMA(1, 0, At, B0); PG8_MMA(1, 1, At, B1); PG8_BAR; PG8_SCHED;
.LBB0_2253:
	s_sleep 2
	ds_read_b128 v[128:131], v190
	ds_read_b128 v[132:135], v190 offset:1024
	ds_read_b128 v[136:139], v190 offset:2048
	ds_read_b128 v[140:143], v190 offset:3072
	ds_read_b128 v[144:147], v191
	ds_read_b128 v[148:151], v191 offset:1024
	ds_read_b128 v[170:173], v191 offset:2048
	ds_read_b128 v[174:177], v191 offset:3072
	s_add_i32 s93, s42, 2
	s_add_u32 s94, s40, 0x80
	s_addc_u32 s43, s41, 0
	s_cmp_eq_u32 s78, s42
	s_cselect_b32 s42, s8, s94
	s_cselect_b32 s43, s9, s43
	s_cselect_b32 s95, s37, s92
	s_cselect_b32 s94, s36, s39
	v_lshl_add_u64 v[186:187], s[40:41], 0, v[164:165]
	s_add_i32 m0, s46, 0xc000
	ds_read_b128 v[178:181], v193
	ds_read_b128 v[182:185], v193 offset:1024
	ds_read_b128 v[196:199], v193 offset:2048
	ds_read_b128 v[200:203], v193 offset:3072
	ds_read_b128 v[204:207], v193 offset:4096
	ds_read_b128 v[208:211], v193 offset:5120
	ds_read_b128 v[212:215], v193 offset:6144
	ds_read_b128 v[216:219], v193 offset:7168
	global_load_lds_dwordx4 v[186:187], off
	v_lshl_add_u64 v[186:187], s[40:41], 0, v[166:167]
	s_add_i32 m0, s46, 0xe000
	s_nop 0
	global_load_lds_dwordx4 v[186:187], off
	s_waitcnt vmcnt(8)
	s_waitcnt lgkmcnt(0)
	s_barrier
	s_setprio 1
	s_waitcnt lgkmcnt(0)
	v_mfma_f32_16x16x32_bf16 v[120:123], v[128:131], v[178:181], v[120:123]
	v_mfma_f32_16x16x32_bf16 v[124:127], v[136:139], v[178:181], v[124:127]
	v_mfma_f32_16x16x32_bf16 v[108:111], v[128:131], v[196:199], v[108:111]
	v_mfma_f32_16x16x32_bf16 v[104:107], v[136:139], v[196:199], v[104:107]
	v_mfma_f32_16x16x32_bf16 v[92:95], v[128:131], v[204:207], v[92:95]
	v_mfma_f32_16x16x32_bf16 v[88:91], v[136:139], v[204:207], v[88:91]
	v_mfma_f32_16x16x32_bf16 v[76:79], v[128:131], v[212:215], v[76:79]
	v_mfma_f32_16x16x32_bf16 v[72:75], v[136:139], v[212:215], v[72:75]
	v_mfma_f32_16x16x32_bf16 v[120:123], v[132:135], v[182:185], v[120:123]
	v_mfma_f32_16x16x32_bf16 v[124:127], v[140:143], v[182:185], v[124:127]
	v_mfma_f32_16x16x32_bf16 v[108:111], v[132:135], v[200:203], v[108:111]
	v_mfma_f32_16x16x32_bf16 v[104:107], v[140:143], v[200:203], v[104:107]
	v_mfma_f32_16x16x32_bf16 v[92:95], v[132:135], v[208:211], v[92:95]
	v_mfma_f32_16x16x32_bf16 v[88:91], v[140:143], v[208:211], v[88:91]
	v_mfma_f32_16x16x32_bf16 v[76:79], v[132:135], v[216:219], v[76:79]
	v_mfma_f32_16x16x32_bf16 v[72:75], v[140:143], v[216:219], v[72:75]
	s_setprio 0
	s_setprio 1
	v_mfma_f32_16x16x32_bf16 v[116:119], v[144:147], v[178:181], v[116:119]
	v_mfma_f32_16x16x32_bf16 v[112:115], v[170:173], v[178:181], v[112:115]
	v_mfma_f32_16x16x32_bf16 v[100:103], v[144:147], v[196:199], v[100:103]
	v_mfma_f32_16x16x32_bf16 v[96:99], v[170:173], v[196:199], v[96:99]
	v_mfma_f32_16x16x32_bf16 v[84:87], v[144:147], v[204:207], v[84:87]
	v_mfma_f32_16x16x32_bf16 v[80:83], v[170:173], v[204:207], v[80:83]
	v_mfma_f32_16x16x32_bf16 v[68:71], v[144:147], v[212:215], v[68:71]
	v_mfma_f32_16x16x32_bf16 v[64:67], v[170:173], v[212:215], v[64:67]
	v_mfma_f32_16x16x32_bf16 v[116:119], v[148:151], v[182:185], v[116:119]
	v_mfma_f32_16x16x32_bf16 v[112:115], v[174:177], v[182:185], v[112:115]
	v_mfma_f32_16x16x32_bf16 v[100:103], v[148:151], v[200:203], v[100:103]
	v_mfma_f32_16x16x32_bf16 v[96:99], v[174:177], v[200:203], v[96:99]
	v_mfma_f32_16x16x32_bf16 v[84:87], v[148:151], v[208:211], v[84:87]
	v_mfma_f32_16x16x32_bf16 v[80:83], v[174:177], v[208:211], v[80:83]
	v_mfma_f32_16x16x32_bf16 v[68:71], v[148:151], v[216:219], v[68:71]
	v_mfma_f32_16x16x32_bf16 v[64:67], v[174:177], v[216:219], v[64:67]
	s_setprio 0
	s_barrier
	s_add_i32 s96, s87, s33
	v_lshl_add_u64 v[186:187], s[94:95], 0, v[154:155]
	s_mov_b32 m0, s96
	ds_read_b128 v[178:181], v193 offset:16384
	ds_read_b128 v[182:185], v193 offset:17408
	ds_read_b128 v[196:199], v193 offset:18432
	ds_read_b128 v[200:203], v193 offset:19456
	ds_read_b128 v[204:207], v193 offset:20480
	ds_read_b128 v[208:211], v193 offset:21504
	ds_read_b128 v[212:215], v193 offset:22528
	ds_read_b128 v[216:219], v193 offset:23552
	global_load_lds_dwordx4 v[186:187], off
	s_add_i32 m0, s96, 0x2000
	v_lshl_add_u64 v[220:221], s[94:95], 0, v[158:159]
	s_add_u32 s94, s94, s12
	s_addc_u32 s95, s95, s13
	s_add_i32 s96, s88, s33
	global_load_lds_dwordx4 v[220:221], off
	v_lshl_add_u64 v[222:223], s[94:95], 0, v[154:155]
	s_mov_b32 m0, s96
	v_lshl_add_u64 v[224:225], s[94:95], 0, v[158:159]
	global_load_lds_dwordx4 v[222:223], off
	s_add_i32 m0, s96, 0x2000
	v_lshl_add_u64 v[226:227], s[42:43], 0, v[152:153]
	global_load_lds_dwordx4 v[224:225], off
	s_mov_b32 m0, s46
	v_lshl_add_u64 v[228:229], s[42:43], 0, v[156:157]
	global_load_lds_dwordx4 v[226:227], off
	s_mov_b32 m0, s47
	s_nop 0
	global_load_lds_dwordx4 v[228:229], off
	s_waitcnt vmcnt(8)
	s_waitcnt lgkmcnt(0)
	s_barrier
; #define PG8_STAGE(bufoff, gbase, voff) do { _Pragma("unroll") for (int _i = 0; _i < 2; ++_i) \
;         __builtin_amdgcn_global_load_lds((const unsigned*)((const char*)(gbase) + (voff)[_i]), (PG8_LAS unsigned*)(lds + (bufoff) + ldsw + _i * 8192), 16, 0, 0); } while (0)
; #define PG8_LDA(dst, b, h) do { _Pragma("unroll") for (int m = 0; m < 4; ++m) _Pragma("unroll") for (int k = 0; k < 2; ++k) dst[m][k] = *(const PG8_LAS bf16x8*)(lds + PG8_SA(b, h) + aoff + m * 2048 + k * 1024); } while (0)
; #define PG8_LDB(dst, b, h) do { _Pragma("unroll") for (int n = 0; n < 2; ++n) _Pragma("unroll") for (int k = 0; k < 2; ++k) dst[n][k] = *(const PG8_LAS bf16x8*)(lds + PG8_SB(b, h) + boff + n * 2048 + k * 1024); } while (0)
; #define PG8_MMA(ai, bj, At, Bt) do { __builtin_amdgcn_s_setprio(1); _Pragma("unroll") for (int m = 0; m < 4; ++m) _Pragma("unroll") for (int n = 0; n < 2; ++n) _Pragma("unroll") for (int k = 0; k < 2; ++k) \
;         acc[ai][bj][m][n] = __builtin_amdgcn_mfma_f32_16x16x32_bf16(Bt[n][k], At[m][k], acc[ai][bj][m][n], 0, 0, 0); __builtin_amdgcn_s_setprio(0); } while (0)
; #define PG8_WAIT_V(n) asm volatile("s_waitcnt vmcnt(" #n ")" ::: "memory")
; #define PG8_WAIT_L(n) asm volatile("s_waitcnt lgkmcnt(" #n ")" ::: "memory")
; #define PG8_BAR __builtin_amdgcn_s_barrier()
; #define PG8_SCHED __builtin_amdgcn_sched_barrier(0)
; template <class Epi, class Sched, bool ALIGN_EPI = false, bool SP2 = false>
; __device__ __forceinline__ void gemm_phase(PG8_LAS unsigned char* lds, const Gemm g, const Sched& S, const Epi& E) {
;     ...
;             PG8_WAIT_V(8); PG8_WAIT_L(0); PG8_BAR; PG8_MMA(1, 0, At, B0); PG8_MMA(1, 1, At, B1); PG8_BAR; PG8_SCHED;
;             PG8_LDB(B0, 1, 0); PG8_LDB(B1, 1, 1); PG8_SCHED; PG8_LDA(At, 1, 0); PG8_STAGE(PG8_SA(0, 1), a2 + hstep, voffA);
;             PG8_WAIT_V(8); PG8_WAIT_L(0); PG8_BAR; PG8_MMA(0, 0, At, B0); PG8_MMA(0, 1, At, B1); PG8_BAR; PG8_SCHED;
	s_setprio 1
	s_waitcnt lgkmcnt(0)
	v_mfma_f32_16x16x32_bf16 v[60:63], v[128:131], v[178:181], v[60:63]
	v_mfma_f32_16x16x32_bf16 v[56:59], v[136:139], v[178:181], v[56:59]
	v_mfma_f32_16x16x32_bf16 v[44:47], v[128:131], v[196:199], v[44:47]
	v_mfma_f32_16x16x32_bf16 v[40:43], v[136:139], v[196:199], v[40:43]
	v_mfma_f32_16x16x32_bf16 v[28:31], v[128:131], v[204:207], v[28:31]
	v_mfma_f32_16x16x32_bf16 v[24:27], v[136:139], v[204:207], v[24:27]
	v_mfma_f32_16x16x32_bf16 v[12:15], v[128:131], v[212:215], v[12:15]
	v_mfma_f32_16x16x32_bf16 v[8:11], v[136:139], v[212:215], v[8:11]
	v_mfma_f32_16x16x32_bf16 v[60:63], v[132:135], v[182:185], v[60:63]
	v_mfma_f32_16x16x32_bf16 v[56:59], v[140:143], v[182:185], v[56:59]
	v_mfma_f32_16x16x32_bf16 v[44:47], v[132:135], v[200:203], v[44:47]
	v_mfma_f32_16x16x32_bf16 v[40:43], v[140:143], v[200:203], v[40:43]
	v_mfma_f32_16x16x32_bf16 v[28:31], v[132:135], v[208:211], v[28:31]
	v_mfma_f32_16x16x32_bf16 v[24:27], v[140:143], v[208:211], v[24:27]
	v_mfma_f32_16x16x32_bf16 v[12:15], v[132:135], v[216:219], v[12:15]
	v_mfma_f32_16x16x32_bf16 v[8:11], v[140:143], v[216:219], v[8:11]
	s_setprio 0
	s_setprio 1
	v_mfma_f32_16x16x32_bf16 v[52:55], v[144:147], v[178:181], v[52:55]
	v_mfma_f32_16x16x32_bf16 v[48:51], v[170:173], v[178:181], v[48:51]
	v_mfma_f32_16x16x32_bf16 v[36:39], v[144:147], v[196:199], v[36:39]
	v_mfma_f32_16x16x32_bf16 v[32:35], v[170:173], v[196:199], v[32:35]
	v_mfma_f32_16x16x32_bf16 v[20:23], v[144:147], v[204:207], v[20:23]
	v_mfma_f32_16x16x32_bf16 v[16:19], v[170:173], v[204:207], v[16:19]
	v_mfma_f32_16x16x32_bf16 v[4:7], v[144:147], v[212:215], v[4:7]
	v_mfma_f32_16x16x32_bf16 v[0:3], v[170:173], v[212:215], v[0:3]
	v_mfma_f32_16x16x32_bf16 v[52:55], v[148:151], v[182:185], v[52:55]
	v_mfma_f32_16x16x32_bf16 v[48:51], v[174:177], v[182:185], v[48:51]
	v_mfma_f32_16x16x32_bf16 v[36:39], v[148:151], v[200:203], v[36:39]
	v_mfma_f32_16x16x32_bf16 v[32:35], v[174:177], v[200:203], v[32:35]
	v_mfma_f32_16x16x32_bf16 v[20:23], v[148:151], v[208:211], v[20:23]
	v_mfma_f32_16x16x32_bf16 v[16:19], v[174:177], v[208:211], v[16:19]
	v_mfma_f32_16x16x32_bf16 v[4:7], v[148:151], v[216:219], v[4:7]
	v_mfma_f32_16x16x32_bf16 v[0:3], v[174:177], v[216:219], v[0:3]
	s_setprio 0
	s_barrier
	s_add_i32 s94, 0, 0x18000
	s_add_i32 s95, 0, 0x1c000
	v_add_u32_e32 v140, s94, v188
	v_add_u32_e32 v161, s95, v188
	ds_read_b128 v[128:131], v140
	ds_read_b128 v[132:135], v140 offset:1024
	ds_read_b128 v[136:139], v140 offset:2048
	ds_read_b128 v[140:143], v140 offset:3072
	ds_read_b128 v[144:147], v161
	ds_read_b128 v[148:151], v161 offset:1024
	ds_read_b128 v[170:173], v161 offset:2048
	ds_read_b128 v[174:177], v161 offset:3072
	s_add_u32 s42, s42, s12
	s_addc_u32 s43, s43, s13
	s_mov_b32 m0, s66
	v_lshl_add_u64 v[230:231], s[42:43], 0, v[152:153]
	ds_read_b128 v[178:181], v193 offset:32768
	ds_read_b128 v[182:185], v193 offset:33792
	ds_read_b128 v[196:199], v193 offset:34816
	ds_read_b128 v[200:203], v193 offset:35840
	ds_read_b128 v[204:207], v193 offset:36864
	ds_read_b128 v[208:211], v193 offset:37888
	ds_read_b128 v[212:215], v193 offset:38912
	ds_read_b128 v[216:219], v193 offset:39936
	global_load_lds_dwordx4 v[230:231], off
	v_lshl_add_u64 v[230:231], s[42:43], 0, v[156:157]
	s_mov_b32 m0, s67
	s_nop 0
	global_load_lds_dwordx4 v[230:231], off
	s_waitcnt vmcnt(8)
	s_waitcnt lgkmcnt(0)
	s_barrier
	s_setprio 1
	s_waitcnt lgkmcnt(0)
	v_mfma_f32_16x16x32_bf16 v[120:123], v[128:131], v[178:181], v[120:123]
	v_mfma_f32_16x16x32_bf16 v[124:127], v[136:139], v[178:181], v[124:127]
	v_mfma_f32_16x16x32_bf16 v[108:111], v[128:131], v[196:199], v[108:111]
	v_mfma_f32_16x16x32_bf16 v[104:107], v[136:139], v[196:199], v[104:107]
	v_mfma_f32_16x16x32_bf16 v[92:95], v[128:131], v[204:207], v[92:95]
	v_mfma_f32_16x16x32_bf16 v[88:91], v[136:139], v[204:207], v[88:91]
	v_mfma_f32_16x16x32_bf16 v[76:79], v[128:131], v[212:215], v[76:79]
	v_mfma_f32_16x16x32_bf16 v[72:75], v[136:139], v[212:215], v[72:75]
	v_mfma_f32_16x16x32_bf16 v[120:123], v[132:135], v[182:185], v[120:123]
	v_mfma_f32_16x16x32_bf16 v[124:127], v[140:143], v[182:185], v[124:127]
	v_mfma_f32_16x16x32_bf16 v[108:111], v[132:135], v[200:203], v[108:111]
	v_mfma_f32_16x16x32_bf16 v[104:107], v[140:143], v[200:203], v[104:107]
	v_mfma_f32_16x16x32_bf16 v[92:95], v[132:135], v[208:211], v[92:95]
	v_mfma_f32_16x16x32_bf16 v[88:91], v[140:143], v[208:211], v[88:91]
	v_mfma_f32_16x16x32_bf16 v[76:79], v[132:135], v[216:219], v[76:79]
	v_mfma_f32_16x16x32_bf16 v[72:75], v[140:143], v[216:219], v[72:75]
	s_setprio 0
	s_setprio 1
	v_mfma_f32_16x16x32_bf16 v[116:119], v[144:147], v[178:181], v[116:119]
	v_mfma_f32_16x16x32_bf16 v[112:115], v[170:173], v[178:181], v[112:115]
	v_mfma_f32_16x16x32_bf16 v[100:103], v[144:147], v[196:199], v[100:103]
	v_mfma_f32_16x16x32_bf16 v[96:99], v[170:173], v[196:199], v[96:99]
	v_mfma_f32_16x16x32_bf16 v[84:87], v[144:147], v[204:207], v[84:87]
	v_mfma_f32_16x16x32_bf16 v[80:83], v[170:173], v[204:207], v[80:83]
	v_mfma_f32_16x16x32_bf16 v[68:71], v[144:147], v[212:215], v[68:71]
	v_mfma_f32_16x16x32_bf16 v[64:67], v[170:173], v[212:215], v[64:67]
	v_mfma_f32_16x16x32_bf16 v[116:119], v[148:151], v[182:185], v[116:119]
	v_mfma_f32_16x16x32_bf16 v[112:115], v[174:177], v[182:185], v[112:115]
	v_mfma_f32_16x16x32_bf16 v[100:103], v[148:151], v[200:203], v[100:103]
	v_mfma_f32_16x16x32_bf16 v[96:99], v[174:177], v[200:203], v[96:99]
	v_mfma_f32_16x16x32_bf16 v[84:87], v[148:151], v[208:211], v[84:87]
	v_mfma_f32_16x16x32_bf16 v[80:83], v[174:177], v[208:211], v[80:83]
	v_mfma_f32_16x16x32_bf16 v[68:71], v[148:151], v[216:219], v[68:71]
	v_mfma_f32_16x16x32_bf16 v[64:67], v[174:177], v[216:219], v[64:67]
	s_setprio 0
	s_barrier
; #define PG8_STAGE(bufoff, gbase, voff) do { _Pragma("unroll") for (int _i = 0; _i < 2; ++_i) \
;         __builtin_amdgcn_global_load_lds((const unsigned*)((const char*)(gbase) + (voff)[_i]), (PG8_LAS unsigned*)(lds + (bufoff) + ldsw + _i * 8192), 16, 0, 0); } while (0)
; #define PG8_LDA(dst, b, h) do { _Pragma("unroll") for (int m = 0; m < 4; ++m) _Pragma("unroll") for (int k = 0; k < 2; ++k) dst[m][k] = *(const PG8_LAS bf16x8*)(lds + PG8_SA(b, h) + aoff + m * 2048 + k * 1024); } while (0)
; #define PG8_MMA(ai, bj, At, Bt) do { __builtin_amdgcn_s_setprio(1); _Pragma("unroll") for (int m = 0; m < 4; ++m) _Pragma("unroll") for (int n = 0; n < 2; ++n) _Pragma("unroll") for (int k = 0; k < 2; ++k) \
;         acc[ai][bj][m][n] = __builtin_amdgcn_mfma_f32_16x16x32_bf16(Bt[n][k], At[m][k], acc[ai][bj][m][n], 0, 0, 0); __builtin_amdgcn_s_setprio(0); } while (0)
; #define PG8_WAIT_V(n) asm volatile("s_waitcnt vmcnt(" #n ")" ::: "memory")
; #define PG8_WAIT_L(n) asm volatile("s_waitcnt lgkmcnt(" #n ")" ::: "memory")
; #define PG8_BAR __builtin_amdgcn_s_barrier()
; #define PG8_SCHED __builtin_amdgcn_sched_barrier(0)
; template <class Epi, class Sched, bool ALIGN_EPI = false, bool SP2 = false>
; __device__ __forceinline__ void gemm_phase(PG8_LAS unsigned char* lds, const Gemm g, const Sched& S, const Epi& E) {
;     ...
;             PG8_LDA(At, 1, 1); PG8_STAGE(PG8_SB(1, 0), b3, voffB); PG8_STAGE(PG8_SB(1, 1), b3 + hstep, voffB); PG8_STAGE(PG8_SA(1, 0), a3, voffA);
;             PG8_WAIT_V(8); PG8_WAIT_L(0); PG8_BAR; PG8_MMA(1, 0, At, B0); PG8_MMA(1, 1, At, B1); PG8_BAR; PG8_SCHED;
	s_add_i32 s42, s94, s33
	v_lshl_add_u64 v[186:187], v[186:187], 0, s[20:21]
	s_mov_b32 m0, s42
	ds_read_b128 v[178:181], v193 offset:49152
	ds_read_b128 v[182:185], v193 offset:50176
	ds_read_b128 v[196:199], v193 offset:51200
	ds_read_b128 v[200:203], v193 offset:52224
	ds_read_b128 v[204:207], v193 offset:53248
	ds_read_b128 v[208:211], v193 offset:54272
	ds_read_b128 v[212:215], v193 offset:55296
	ds_read_b128 v[216:219], v193 offset:56320
	global_load_lds_dwordx4 v[186:187], off
	v_lshl_add_u64 v[186:187], v[220:221], 0, s[20:21]
	s_add_i32 m0, s42, 0x2000
	s_add_i32 s42, s95, s33
	global_load_lds_dwordx4 v[186:187], off
	v_lshl_add_u64 v[186:187], v[222:223], 0, s[20:21]
	s_mov_b32 m0, s42
	s_nop 0
	global_load_lds_dwordx4 v[186:187], off
	v_lshl_add_u64 v[186:187], v[224:225], 0, s[20:21]
	s_add_i32 m0, s42, 0x2000
	s_nop 0
	global_load_lds_dwordx4 v[186:187], off
	v_lshl_add_u64 v[186:187], v[226:227], 0, s[20:21]
	s_mov_b32 m0, s70
	s_nop 0
	global_load_lds_dwordx4 v[186:187], off
	v_lshl_add_u64 v[186:187], v[228:229], 0, s[20:21]
	s_mov_b32 m0, s71
	s_nop 0
	global_load_lds_dwordx4 v[186:187], off
	s_waitcnt vmcnt(8)
	s_waitcnt lgkmcnt(0)
	s_barrier
	s_setprio 1
	s_waitcnt lgkmcnt(0)
	v_mfma_f32_16x16x32_bf16 v[60:63], v[128:131], v[178:181], v[60:63]
	v_mfma_f32_16x16x32_bf16 v[56:59], v[136:139], v[178:181], v[56:59]
	v_mfma_f32_16x16x32_bf16 v[44:47], v[128:131], v[196:199], v[44:47]
	v_mfma_f32_16x16x32_bf16 v[40:43], v[136:139], v[196:199], v[40:43]
	v_mfma_f32_16x16x32_bf16 v[28:31], v[128:131], v[204:207], v[28:31]
	v_mfma_f32_16x16x32_bf16 v[24:27], v[136:139], v[204:207], v[24:27]
	v_mfma_f32_16x16x32_bf16 v[12:15], v[128:131], v[212:215], v[12:15]
	v_mfma_f32_16x16x32_bf16 v[8:11], v[136:139], v[212:215], v[8:11]
	v_mfma_f32_16x16x32_bf16 v[60:63], v[132:135], v[182:185], v[60:63]
	v_mfma_f32_16x16x32_bf16 v[56:59], v[140:143], v[182:185], v[56:59]
	v_mfma_f32_16x16x32_bf16 v[44:47], v[132:135], v[200:203], v[44:47]
	v_mfma_f32_16x16x32_bf16 v[40:43], v[140:143], v[200:203], v[40:43]
	v_mfma_f32_16x16x32_bf16 v[28:31], v[132:135], v[208:211], v[28:31]
	v_mfma_f32_16x16x32_bf16 v[24:27], v[140:143], v[208:211], v[24:27]
	v_mfma_f32_16x16x32_bf16 v[12:15], v[132:135], v[216:219], v[12:15]
	v_mfma_f32_16x16x32_bf16 v[8:11], v[140:143], v[216:219], v[8:11]
	s_setprio 0
	s_setprio 1
	v_mfma_f32_16x16x32_bf16 v[52:55], v[144:147], v[178:181], v[52:55]
	v_mfma_f32_16x16x32_bf16 v[48:51], v[170:173], v[178:181], v[48:51]
	v_mfma_f32_16x16x32_bf16 v[36:39], v[144:147], v[196:199], v[36:39]
	v_mfma_f32_16x16x32_bf16 v[32:35], v[170:173], v[196:199], v[32:35]
	v_mfma_f32_16x16x32_bf16 v[20:23], v[144:147], v[204:207], v[20:23]
	v_mfma_f32_16x16x32_bf16 v[16:19], v[170:173], v[204:207], v[16:19]
	v_mfma_f32_16x16x32_bf16 v[4:7], v[144:147], v[212:215], v[4:7]
	v_mfma_f32_16x16x32_bf16 v[0:3], v[170:173], v[212:215], v[0:3]
	v_mfma_f32_16x16x32_bf16 v[52:55], v[148:151], v[182:185], v[52:55]
	v_mfma_f32_16x16x32_bf16 v[48:51], v[174:177], v[182:185], v[48:51]
	v_mfma_f32_16x16x32_bf16 v[36:39], v[148:151], v[200:203], v[36:39]
	v_mfma_f32_16x16x32_bf16 v[32:35], v[174:177], v[200:203], v[32:35]
	v_mfma_f32_16x16x32_bf16 v[20:23], v[148:151], v[208:211], v[20:23]
	v_mfma_f32_16x16x32_bf16 v[16:19], v[174:177], v[208:211], v[16:19]
	v_mfma_f32_16x16x32_bf16 v[4:7], v[148:151], v[216:219], v[4:7]
	v_mfma_f32_16x16x32_bf16 v[0:3], v[174:177], v[216:219], v[0:3]
	s_setprio 0
	s_barrier
	s_add_u32 s40, s40, 0x100
	s_addc_u32 s41, s41, 0
	s_add_u32 s39, s39, 0x100
	s_addc_u32 s92, s92, 0
	s_cmp_ge_i32 s93, s73
	s_mov_b32 s42, s93
	s_cbranch_scc0 .LBB0_2253

; #define PG8_STAGE(bufoff, gbase, voff) do { _Pragma("unroll") for (int _i = 0; _i < 2; ++_i) \
;         __builtin_amdgcn_global_load_lds((const unsigned*)((const char*)(gbase) + (voff)[_i]), (PG8_LAS unsigned*)(lds + (bufoff) + ldsw + _i * 8192), 16, 0, 0); } while (0)
; #define PG8_LDA(dst, b, h) do { _Pragma("unroll") for (int m = 0; m < 4; ++m) _Pragma("unroll") for (int k = 0; k < 2; ++k) dst[m][k] = *(const PG8_LAS bf16x8*)(lds + PG8_SA(b, h) + aoff + m * 2048 + k * 1024); } while (0)
; #define PG8_LDB(dst, b, h) do { _Pragma("unroll") for (int n = 0; n < 2; ++n) _Pragma("unroll") for (int k = 0; k < 2; ++k) dst[n][k] = *(const PG8_LAS bf16x8*)(lds + PG8_SB(b, h) + boff + n * 2048 + k * 1024); } while (0)
; #define PG8_MMA(ai, bj, At, Bt) do { __builtin_amdgcn_s_setprio(1); _Pragma("unroll") for (int m = 0; m < 4; ++m) _Pragma("unroll") for (int n = 0; n < 2; ++n) _Pragma("unroll") for (int k = 0; k < 2; ++k) \
;         acc[ai][bj][m][n] = __builtin_amdgcn_mfma_f32_16x16x32_bf16(Bt[n][k], At[m][k], acc[ai][bj][m][n], 0, 0, 0); __builtin_amdgcn_s_setprio(0); } while (0)
; #define PG8_WAIT_V(n) asm volatile("s_waitcnt vmcnt(" #n ")" ::: "memory")
; #define PG8_BAR __builtin_amdgcn_s_barrier()
; template <class Epi, class Sched, bool ALIGN_EPI = false, bool SP2 = false>
; __device__ __forceinline__ void gemm_phase(PG8_LAS unsigned char* lds, const Gemm g, const Sched& S, const Epi& E) {
;     ...
;         for (int t = 0; t < nt; t += 2) {
;             const bool last = (t == nt - 2);
;             const char* a1 = cA + (size_t)(t + 1) * kstep;
;             const char* a2 = last ? nA : cA + (size_t)(t + 2) * kstep; const char* b2 = last ? nB : cB + (size_t)(t + 2) * kstep;
;             const char* a3 = a2 + kstep; const char* b3 = b2 + kstep;
;             if (last && has_next) S.a_ready(nxt);
;             if constexpr (SP2) {
;             PG8_LDB(B0, 0, 0); PG8_LDB(B1, 0, 1); PG8_SCHED; PG8_LDA(At, 0, 0); PG8_STAGE(PG8_SA(1, 1), a1 + hstep, voffA);
;             PG8_WAIT_V(8); PG8_WAIT_L(0); PG8_BAR; PG8_MMA(0, 0, At, B0); PG8_MMA(0, 1, At, B1); PG8_BAR; PG8_SCHED;
;             PG8_LDA(At, 0, 1); PG8_STAGE(PG8_SB(0, 0), b2, voffB); PG8_STAGE(PG8_SB(0, 1), b2 + hstep, voffB); PG8_STAGE(PG8_SA(0, 0), a2, voffA);
;             PG8_WAIT_V(8); PG8_WAIT_L(0); PG8_BAR; PG8_MMA(1, 0, At, B0); PG8_MMA(1, 1, At, B1); PG8_BAR; PG8_SCHED;
.LBB0_2353:
	s_sleep 2
	ds_read_b128 v[76:79], v195
	ds_read_b128 v[80:83], v195 offset:1024
	ds_read_b128 v[88:91], v195 offset:2048
	ds_read_b128 v[92:95], v195 offset:3072
	ds_read_b128 v[100:103], v199
	ds_read_b128 v[104:107], v199 offset:1024
	ds_read_b128 v[112:115], v199 offset:2048
	ds_read_b128 v[116:119], v199 offset:3072
	s_add_i32 s93, s36, 2
	s_add_u32 s94, s34, 0x80
	s_addc_u32 s37, s35, 0
	s_cmp_eq_u32 s84, s36
	s_cselect_b32 s36, s6, s94
	s_cselect_b32 s37, s7, s37
	s_cselect_b32 s95, s29, s92
	s_cselect_b32 s94, s28, s31
	v_lshl_add_u64 v[186:187], s[34:35], 0, v[180:181]
	s_add_i32 m0, s72, 0xc000
	ds_read_b128 v[160:163], v203
	ds_read_b128 v[164:167], v203 offset:1024
	ds_read_b128 v[204:207], v203 offset:2048
	ds_read_b128 v[210:213], v203 offset:3072
	ds_read_b128 v[214:217], v203 offset:4096
	ds_read_b128 v[218:221], v203 offset:5120
	ds_read_b128 v[222:225], v203 offset:6144
	ds_read_b128 v[226:229], v203 offset:7168
	global_load_lds_dwordx4 v[186:187], off
	v_lshl_add_u64 v[186:187], s[34:35], 0, v[182:183]
	s_add_i32 m0, s72, 0xe000
	s_nop 0
	global_load_lds_dwordx4 v[186:187], off
	s_waitcnt vmcnt(8)
	s_waitcnt lgkmcnt(0)
	s_barrier
	s_setprio 1
	s_waitcnt lgkmcnt(0)
	v_mfma_f32_16x16x32_bf16 v[156:159], v[76:79], v[160:163], v[156:159]
	v_mfma_f32_16x16x32_bf16 v[148:151], v[88:91], v[160:163], v[148:151]
	v_mfma_f32_16x16x32_bf16 v[140:143], v[76:79], v[204:207], v[140:143]
	v_mfma_f32_16x16x32_bf16 v[132:135], v[88:91], v[204:207], v[132:135]
	v_mfma_f32_16x16x32_bf16 v[124:127], v[76:79], v[214:217], v[124:127]
	v_mfma_f32_16x16x32_bf16 v[108:111], v[88:91], v[214:217], v[108:111]
	v_mfma_f32_16x16x32_bf16 v[84:87], v[76:79], v[222:225], v[84:87]
	v_mfma_f32_16x16x32_bf16 v[68:71], v[88:91], v[222:225], v[68:71]
	v_mfma_f32_16x16x32_bf16 v[156:159], v[80:83], v[164:167], v[156:159]
	v_mfma_f32_16x16x32_bf16 v[148:151], v[92:95], v[164:167], v[148:151]
	v_mfma_f32_16x16x32_bf16 v[140:143], v[80:83], v[210:213], v[140:143]
	v_mfma_f32_16x16x32_bf16 v[132:135], v[92:95], v[210:213], v[132:135]
	v_mfma_f32_16x16x32_bf16 v[124:127], v[80:83], v[218:221], v[124:127]
	v_mfma_f32_16x16x32_bf16 v[108:111], v[92:95], v[218:221], v[108:111]
	v_mfma_f32_16x16x32_bf16 v[84:87], v[80:83], v[226:229], v[84:87]
	v_mfma_f32_16x16x32_bf16 v[68:71], v[92:95], v[226:229], v[68:71]
	s_setprio 0
	s_setprio 1
	v_mfma_f32_16x16x32_bf16 v[152:155], v[100:103], v[160:163], v[152:155]
	v_mfma_f32_16x16x32_bf16 v[144:147], v[112:115], v[160:163], v[144:147]
	v_mfma_f32_16x16x32_bf16 v[136:139], v[100:103], v[204:207], v[136:139]
	v_mfma_f32_16x16x32_bf16 v[128:131], v[112:115], v[204:207], v[128:131]
	v_mfma_f32_16x16x32_bf16 v[120:123], v[100:103], v[214:217], v[120:123]
	v_mfma_f32_16x16x32_bf16 v[96:99], v[112:115], v[214:217], v[96:99]
	v_mfma_f32_16x16x32_bf16 v[72:75], v[100:103], v[222:225], v[72:75]
	v_mfma_f32_16x16x32_bf16 v[64:67], v[112:115], v[222:225], v[64:67]
	v_mfma_f32_16x16x32_bf16 v[152:155], v[104:107], v[164:167], v[152:155]
	v_mfma_f32_16x16x32_bf16 v[144:147], v[116:119], v[164:167], v[144:147]
	v_mfma_f32_16x16x32_bf16 v[136:139], v[104:107], v[210:213], v[136:139]
	v_mfma_f32_16x16x32_bf16 v[128:131], v[116:119], v[210:213], v[128:131]
	v_mfma_f32_16x16x32_bf16 v[120:123], v[104:107], v[218:221], v[120:123]
	v_mfma_f32_16x16x32_bf16 v[96:99], v[116:119], v[218:221], v[96:99]
	v_mfma_f32_16x16x32_bf16 v[72:75], v[104:107], v[226:229], v[72:75]
	v_mfma_f32_16x16x32_bf16 v[64:67], v[116:119], v[226:229], v[64:67]
	s_setprio 0
	s_barrier
	s_add_i32 s96, s85, s67
	v_lshl_add_u64 v[186:187], s[94:95], 0, v[170:171]
	s_mov_b32 m0, s96
	ds_read_b128 v[160:163], v203 offset:16384
	ds_read_b128 v[164:167], v203 offset:17408
	ds_read_b128 v[204:207], v203 offset:18432
	ds_read_b128 v[210:213], v203 offset:19456
	ds_read_b128 v[214:217], v203 offset:20480
	ds_read_b128 v[218:221], v203 offset:21504
	ds_read_b128 v[222:225], v203 offset:22528
	ds_read_b128 v[226:229], v203 offset:23552
	global_load_lds_dwordx4 v[186:187], off
	s_add_i32 m0, s96, 0x2000
	v_lshl_add_u64 v[190:191], s[94:95], 0, v[174:175]
	s_add_u32 s94, s94, s10
	s_addc_u32 s95, s95, s11
	s_add_i32 s96, s86, s67
	global_load_lds_dwordx4 v[190:191], off
	v_lshl_add_u64 v[196:197], s[94:95], 0, v[170:171]
	s_mov_b32 m0, s96
	v_lshl_add_u64 v[200:201], s[94:95], 0, v[174:175]
	global_load_lds_dwordx4 v[196:197], off
	s_add_i32 m0, s96, 0x2000
	v_lshl_add_u64 v[230:231], s[36:37], 0, v[168:169]
	global_load_lds_dwordx4 v[200:201], off
	s_mov_b32 m0, s72
	v_lshl_add_u64 v[232:233], s[36:37], 0, v[172:173]
	global_load_lds_dwordx4 v[230:231], off
	s_mov_b32 m0, s73
	s_nop 0
	global_load_lds_dwordx4 v[232:233], off
	s_waitcnt vmcnt(8)
	s_waitcnt lgkmcnt(0)
	s_barrier
; #define PG8_STAGE(bufoff, gbase, voff) do { _Pragma("unroll") for (int _i = 0; _i < 2; ++_i) \
;         __builtin_amdgcn_global_load_lds((const unsigned*)((const char*)(gbase) + (voff)[_i]), (PG8_LAS unsigned*)(lds + (bufoff) + ldsw + _i * 8192), 16, 0, 0); } while (0)
; #define PG8_LDA(dst, b, h) do { _Pragma("unroll") for (int m = 0; m < 4; ++m) _Pragma("unroll") for (int k = 0; k < 2; ++k) dst[m][k] = *(const PG8_LAS bf16x8*)(lds + PG8_SA(b, h) + aoff + m * 2048 + k * 1024); } while (0)
; #define PG8_LDB(dst, b, h) do { _Pragma("unroll") for (int n = 0; n < 2; ++n) _Pragma("unroll") for (int k = 0; k < 2; ++k) dst[n][k] = *(const PG8_LAS bf16x8*)(lds + PG8_SB(b, h) + boff + n * 2048 + k * 1024); } while (0)
; #define PG8_MMA(ai, bj, At, Bt) do { __builtin_amdgcn_s_setprio(1); _Pragma("unroll") for (int m = 0; m < 4; ++m) _Pragma("unroll") for (int n = 0; n < 2; ++n) _Pragma("unroll") for (int k = 0; k < 2; ++k) \
;         acc[ai][bj][m][n] = __builtin_amdgcn_mfma_f32_16x16x32_bf16(Bt[n][k], At[m][k], acc[ai][bj][m][n], 0, 0, 0); __builtin_amdgcn_s_setprio(0); } while (0)
; #define PG8_WAIT_V(n) asm volatile("s_waitcnt vmcnt(" #n ")" ::: "memory")
; #define PG8_WAIT_L(n) asm volatile("s_waitcnt lgkmcnt(" #n ")" ::: "memory")
; #define PG8_BAR __builtin_amdgcn_s_barrier()
; #define PG8_SCHED __builtin_amdgcn_sched_barrier(0)
; template <class Epi, class Sched, bool ALIGN_EPI = false, bool SP2 = false>
; __device__ __forceinline__ void gemm_phase(PG8_LAS unsigned char* lds, const Gemm g, const Sched& S, const Epi& E) {
;     ...
;             PG8_WAIT_V(8); PG8_WAIT_L(0); PG8_BAR; PG8_MMA(1, 0, At, B0); PG8_MMA(1, 1, At, B1); PG8_BAR; PG8_SCHED;
;             PG8_LDB(B0, 1, 0); PG8_LDB(B1, 1, 1); PG8_SCHED; PG8_LDA(At, 1, 0); PG8_STAGE(PG8_SA(0, 1), a2 + hstep, voffA);
;             PG8_WAIT_V(8); PG8_WAIT_L(0); PG8_BAR; PG8_MMA(0, 0, At, B0); PG8_MMA(0, 1, At, B1); PG8_BAR; PG8_SCHED;
	s_setprio 1
	s_waitcnt lgkmcnt(0)
	v_mfma_f32_16x16x32_bf16 v[60:63], v[76:79], v[160:163], v[60:63]
	v_mfma_f32_16x16x32_bf16 v[52:55], v[88:91], v[160:163], v[52:55]
	v_mfma_f32_16x16x32_bf16 v[44:47], v[76:79], v[204:207], v[44:47]
	v_mfma_f32_16x16x32_bf16 v[36:39], v[88:91], v[204:207], v[36:39]
	v_mfma_f32_16x16x32_bf16 v[28:31], v[76:79], v[214:217], v[28:31]
	v_mfma_f32_16x16x32_bf16 v[20:23], v[88:91], v[214:217], v[20:23]
	v_mfma_f32_16x16x32_bf16 v[12:15], v[76:79], v[222:225], v[12:15]
	v_mfma_f32_16x16x32_bf16 v[4:7], v[88:91], v[222:225], v[4:7]
	v_mfma_f32_16x16x32_bf16 v[60:63], v[80:83], v[164:167], v[60:63]
	v_mfma_f32_16x16x32_bf16 v[52:55], v[92:95], v[164:167], v[52:55]
	v_mfma_f32_16x16x32_bf16 v[44:47], v[80:83], v[210:213], v[44:47]
	v_mfma_f32_16x16x32_bf16 v[36:39], v[92:95], v[210:213], v[36:39]
	v_mfma_f32_16x16x32_bf16 v[28:31], v[80:83], v[218:221], v[28:31]
	v_mfma_f32_16x16x32_bf16 v[20:23], v[92:95], v[218:221], v[20:23]
	v_mfma_f32_16x16x32_bf16 v[12:15], v[80:83], v[226:229], v[12:15]
	v_mfma_f32_16x16x32_bf16 v[4:7], v[92:95], v[226:229], v[4:7]
	s_setprio 0
	s_setprio 1
	v_mfma_f32_16x16x32_bf16 v[56:59], v[100:103], v[160:163], v[56:59]
	v_mfma_f32_16x16x32_bf16 v[48:51], v[112:115], v[160:163], v[48:51]
	v_mfma_f32_16x16x32_bf16 v[40:43], v[100:103], v[204:207], v[40:43]
	v_mfma_f32_16x16x32_bf16 v[32:35], v[112:115], v[204:207], v[32:35]
	v_mfma_f32_16x16x32_bf16 v[24:27], v[100:103], v[214:217], v[24:27]
	v_mfma_f32_16x16x32_bf16 v[16:19], v[112:115], v[214:217], v[16:19]
	v_mfma_f32_16x16x32_bf16 v[8:11], v[100:103], v[222:225], v[8:11]
	v_mfma_f32_16x16x32_bf16 v[0:3], v[112:115], v[222:225], v[0:3]
	v_mfma_f32_16x16x32_bf16 v[56:59], v[104:107], v[164:167], v[56:59]
	v_mfma_f32_16x16x32_bf16 v[48:51], v[116:119], v[164:167], v[48:51]
	v_mfma_f32_16x16x32_bf16 v[40:43], v[104:107], v[210:213], v[40:43]
	v_mfma_f32_16x16x32_bf16 v[32:35], v[116:119], v[210:213], v[32:35]
	v_mfma_f32_16x16x32_bf16 v[24:27], v[104:107], v[218:221], v[24:27]
	v_mfma_f32_16x16x32_bf16 v[16:19], v[116:119], v[218:221], v[16:19]
	v_mfma_f32_16x16x32_bf16 v[8:11], v[104:107], v[226:229], v[8:11]
	v_mfma_f32_16x16x32_bf16 v[0:3], v[116:119], v[226:229], v[0:3]
	s_setprio 0
	s_barrier
	s_add_i32 s94, 0, 0x18000
	s_add_i32 s95, 0, 0x1c000
	v_add_u32_e32 v92, s94, v189
	v_add_u32_e32 v116, s95, v189
	ds_read_b128 v[76:79], v92
	ds_read_b128 v[80:83], v92 offset:1024
	ds_read_b128 v[88:91], v92 offset:2048
	ds_read_b128 v[92:95], v92 offset:3072
	ds_read_b128 v[100:103], v116
	ds_read_b128 v[104:107], v116 offset:1024
	ds_read_b128 v[112:115], v116 offset:2048
	ds_read_b128 v[116:119], v116 offset:3072
	s_add_u32 s36, s36, s10
	s_addc_u32 s37, s37, s11
	s_mov_b32 m0, s78
	v_lshl_add_u64 v[234:235], s[36:37], 0, v[168:169]
	ds_read_b128 v[160:163], v203 offset:32768
	ds_read_b128 v[164:167], v203 offset:33792
	ds_read_b128 v[204:207], v203 offset:34816
	ds_read_b128 v[210:213], v203 offset:35840
	ds_read_b128 v[214:217], v203 offset:36864
	ds_read_b128 v[218:221], v203 offset:37888
	ds_read_b128 v[222:225], v203 offset:38912
	ds_read_b128 v[226:229], v203 offset:39936
	global_load_lds_dwordx4 v[234:235], off
	v_lshl_add_u64 v[234:235], s[36:37], 0, v[172:173]
	s_mov_b32 m0, s79
	s_nop 0
	global_load_lds_dwordx4 v[234:235], off
	s_waitcnt vmcnt(8)
	s_waitcnt lgkmcnt(0)
	s_barrier
	s_setprio 1
	s_waitcnt lgkmcnt(0)
	v_mfma_f32_16x16x32_bf16 v[156:159], v[76:79], v[160:163], v[156:159]
	v_mfma_f32_16x16x32_bf16 v[148:151], v[88:91], v[160:163], v[148:151]
	v_mfma_f32_16x16x32_bf16 v[140:143], v[76:79], v[204:207], v[140:143]
	v_mfma_f32_16x16x32_bf16 v[132:135], v[88:91], v[204:207], v[132:135]
	v_mfma_f32_16x16x32_bf16 v[124:127], v[76:79], v[214:217], v[124:127]
	v_mfma_f32_16x16x32_bf16 v[108:111], v[88:91], v[214:217], v[108:111]
	v_mfma_f32_16x16x32_bf16 v[84:87], v[76:79], v[222:225], v[84:87]
	v_mfma_f32_16x16x32_bf16 v[68:71], v[88:91], v[222:225], v[68:71]
	v_mfma_f32_16x16x32_bf16 v[156:159], v[80:83], v[164:167], v[156:159]
	v_mfma_f32_16x16x32_bf16 v[148:151], v[92:95], v[164:167], v[148:151]
	v_mfma_f32_16x16x32_bf16 v[140:143], v[80:83], v[210:213], v[140:143]
	v_mfma_f32_16x16x32_bf16 v[132:135], v[92:95], v[210:213], v[132:135]
	v_mfma_f32_16x16x32_bf16 v[124:127], v[80:83], v[218:221], v[124:127]
	v_mfma_f32_16x16x32_bf16 v[108:111], v[92:95], v[218:221], v[108:111]
	v_mfma_f32_16x16x32_bf16 v[84:87], v[80:83], v[226:229], v[84:87]
	v_mfma_f32_16x16x32_bf16 v[68:71], v[92:95], v[226:229], v[68:71]
	s_setprio 0
	s_setprio 1
	v_mfma_f32_16x16x32_bf16 v[152:155], v[100:103], v[160:163], v[152:155]
	v_mfma_f32_16x16x32_bf16 v[144:147], v[112:115], v[160:163], v[144:147]
	v_mfma_f32_16x16x32_bf16 v[136:139], v[100:103], v[204:207], v[136:139]
	v_mfma_f32_16x16x32_bf16 v[128:131], v[112:115], v[204:207], v[128:131]
	v_mfma_f32_16x16x32_bf16 v[120:123], v[100:103], v[214:217], v[120:123]
	v_mfma_f32_16x16x32_bf16 v[96:99], v[112:115], v[214:217], v[96:99]
	v_mfma_f32_16x16x32_bf16 v[72:75], v[100:103], v[222:225], v[72:75]
	v_mfma_f32_16x16x32_bf16 v[64:67], v[112:115], v[222:225], v[64:67]
	v_mfma_f32_16x16x32_bf16 v[152:155], v[104:107], v[164:167], v[152:155]
	v_mfma_f32_16x16x32_bf16 v[144:147], v[116:119], v[164:167], v[144:147]
	v_mfma_f32_16x16x32_bf16 v[136:139], v[104:107], v[210:213], v[136:139]
	v_mfma_f32_16x16x32_bf16 v[128:131], v[116:119], v[210:213], v[128:131]
	v_mfma_f32_16x16x32_bf16 v[120:123], v[104:107], v[218:221], v[120:123]
	v_mfma_f32_16x16x32_bf16 v[96:99], v[116:119], v[218:221], v[96:99]
	v_mfma_f32_16x16x32_bf16 v[72:75], v[104:107], v[226:229], v[72:75]
	v_mfma_f32_16x16x32_bf16 v[64:67], v[116:119], v[226:229], v[64:67]
	s_setprio 0
	s_barrier
; #define PG8_STAGE(bufoff, gbase, voff) do { _Pragma("unroll") for (int _i = 0; _i < 2; ++_i) \
;         __builtin_amdgcn_global_load_lds((const unsigned*)((const char*)(gbase) + (voff)[_i]), (PG8_LAS unsigned*)(lds + (bufoff) + ldsw + _i * 8192), 16, 0, 0); } while (0)
; #define PG8_LDA(dst, b, h) do { _Pragma("unroll") for (int m = 0; m < 4; ++m) _Pragma("unroll") for (int k = 0; k < 2; ++k) dst[m][k] = *(const PG8_LAS bf16x8*)(lds + PG8_SA(b, h) + aoff + m * 2048 + k * 1024); } while (0)
; #define PG8_MMA(ai, bj, At, Bt) do { __builtin_amdgcn_s_setprio(1); _Pragma("unroll") for (int m = 0; m < 4; ++m) _Pragma("unroll") for (int n = 0; n < 2; ++n) _Pragma("unroll") for (int k = 0; k < 2; ++k) \
;         acc[ai][bj][m][n] = __builtin_amdgcn_mfma_f32_16x16x32_bf16(Bt[n][k], At[m][k], acc[ai][bj][m][n], 0, 0, 0); __builtin_amdgcn_s_setprio(0); } while (0)
; #define PG8_WAIT_V(n) asm volatile("s_waitcnt vmcnt(" #n ")" ::: "memory")
; #define PG8_WAIT_L(n) asm volatile("s_waitcnt lgkmcnt(" #n ")" ::: "memory")
; #define PG8_BAR __builtin_amdgcn_s_barrier()
; #define PG8_SCHED __builtin_amdgcn_sched_barrier(0)
; template <class Epi, class Sched, bool ALIGN_EPI = false, bool SP2 = false>
; __device__ __forceinline__ void gemm_phase(PG8_LAS unsigned char* lds, const Gemm g, const Sched& S, const Epi& E) {
;     ...
;             PG8_LDA(At, 1, 1); PG8_STAGE(PG8_SB(1, 0), b3, voffB); PG8_STAGE(PG8_SB(1, 1), b3 + hstep, voffB); PG8_STAGE(PG8_SA(1, 0), a3, voffA);
;             PG8_WAIT_V(8); PG8_WAIT_L(0); PG8_BAR; PG8_MMA(1, 0, At, B0); PG8_MMA(1, 1, At, B1); PG8_BAR; PG8_SCHED;
	s_add_i32 s36, s94, s67
	v_lshl_add_u64 v[186:187], v[186:187], 0, s[20:21]
	s_mov_b32 m0, s36
	ds_read_b128 v[160:163], v203 offset:49152
	ds_read_b128 v[164:167], v203 offset:50176
	ds_read_b128 v[204:207], v203 offset:51200
	ds_read_b128 v[210:213], v203 offset:52224
	ds_read_b128 v[214:217], v203 offset:53248
	ds_read_b128 v[218:221], v203 offset:54272
	ds_read_b128 v[222:225], v203 offset:55296
	ds_read_b128 v[226:229], v203 offset:56320
	global_load_lds_dwordx4 v[186:187], off
	v_lshl_add_u64 v[186:187], v[190:191], 0, s[20:21]
	s_add_i32 m0, s36, 0x2000
	s_add_i32 s36, s95, s67
	global_load_lds_dwordx4 v[186:187], off
	v_lshl_add_u64 v[186:187], v[196:197], 0, s[20:21]
	s_mov_b32 m0, s36
	s_nop 0
	global_load_lds_dwordx4 v[186:187], off
	v_lshl_add_u64 v[186:187], v[200:201], 0, s[20:21]
	s_add_i32 m0, s36, 0x2000
	s_nop 0
	global_load_lds_dwordx4 v[186:187], off
	v_lshl_add_u64 v[186:187], v[230:231], 0, s[20:21]
	s_mov_b32 m0, s81
	s_nop 0
	global_load_lds_dwordx4 v[186:187], off
	v_lshl_add_u64 v[186:187], v[232:233], 0, s[20:21]
	s_mov_b32 m0, s82
	s_nop 0
	global_load_lds_dwordx4 v[186:187], off
	s_waitcnt vmcnt(8)
	s_waitcnt lgkmcnt(0)
	s_barrier
	s_setprio 1
	s_waitcnt lgkmcnt(0)
	v_mfma_f32_16x16x32_bf16 v[60:63], v[76:79], v[160:163], v[60:63]
	v_mfma_f32_16x16x32_bf16 v[52:55], v[88:91], v[160:163], v[52:55]
	v_mfma_f32_16x16x32_bf16 v[44:47], v[76:79], v[204:207], v[44:47]
	v_mfma_f32_16x16x32_bf16 v[36:39], v[88:91], v[204:207], v[36:39]
	v_mfma_f32_16x16x32_bf16 v[28:31], v[76:79], v[214:217], v[28:31]
	v_mfma_f32_16x16x32_bf16 v[20:23], v[88:91], v[214:217], v[20:23]
	v_mfma_f32_16x16x32_bf16 v[12:15], v[76:79], v[222:225], v[12:15]
	v_mfma_f32_16x16x32_bf16 v[4:7], v[88:91], v[222:225], v[4:7]
	v_mfma_f32_16x16x32_bf16 v[60:63], v[80:83], v[164:167], v[60:63]
	v_mfma_f32_16x16x32_bf16 v[52:55], v[92:95], v[164:167], v[52:55]
	v_mfma_f32_16x16x32_bf16 v[44:47], v[80:83], v[210:213], v[44:47]
	v_mfma_f32_16x16x32_bf16 v[36:39], v[92:95], v[210:213], v[36:39]
	v_mfma_f32_16x16x32_bf16 v[28:31], v[80:83], v[218:221], v[28:31]
	v_mfma_f32_16x16x32_bf16 v[20:23], v[92:95], v[218:221], v[20:23]
	v_mfma_f32_16x16x32_bf16 v[12:15], v[80:83], v[226:229], v[12:15]
	v_mfma_f32_16x16x32_bf16 v[4:7], v[92:95], v[226:229], v[4:7]
	s_setprio 0
	s_setprio 1
	v_mfma_f32_16x16x32_bf16 v[56:59], v[100:103], v[160:163], v[56:59]
	v_mfma_f32_16x16x32_bf16 v[48:51], v[112:115], v[160:163], v[48:51]
	v_mfma_f32_16x16x32_bf16 v[40:43], v[100:103], v[204:207], v[40:43]
	v_mfma_f32_16x16x32_bf16 v[32:35], v[112:115], v[204:207], v[32:35]
	v_mfma_f32_16x16x32_bf16 v[24:27], v[100:103], v[214:217], v[24:27]
	v_mfma_f32_16x16x32_bf16 v[16:19], v[112:115], v[214:217], v[16:19]
	v_mfma_f32_16x16x32_bf16 v[8:11], v[100:103], v[222:225], v[8:11]
	v_mfma_f32_16x16x32_bf16 v[0:3], v[112:115], v[222:225], v[0:3]
	v_mfma_f32_16x16x32_bf16 v[56:59], v[104:107], v[164:167], v[56:59]
	v_mfma_f32_16x16x32_bf16 v[48:51], v[116:119], v[164:167], v[48:51]
	v_mfma_f32_16x16x32_bf16 v[40:43], v[104:107], v[210:213], v[40:43]
	v_mfma_f32_16x16x32_bf16 v[32:35], v[116:119], v[210:213], v[32:35]
	v_mfma_f32_16x16x32_bf16 v[24:27], v[104:107], v[218:221], v[24:27]
	v_mfma_f32_16x16x32_bf16 v[16:19], v[116:119], v[218:221], v[16:19]
	v_mfma_f32_16x16x32_bf16 v[8:11], v[104:107], v[226:229], v[8:11]
	v_mfma_f32_16x16x32_bf16 v[0:3], v[116:119], v[226:229], v[0:3]
	s_setprio 0
	s_barrier
	s_add_u32 s34, s34, 0x100
	s_addc_u32 s35, s35, 0
	s_add_u32 s31, s31, 0x100
	s_addc_u32 s92, s92, 0
	s_cmp_ge_i32 s93, s83
	s_mov_b32 s36, s93
	s_cbranch_scc0 .LBB0_2353

; #define PG8_STAGE(bufoff, gbase, voff) do { _Pragma("unroll") for (int _i = 0; _i < 2; ++_i) \
;         __builtin_amdgcn_global_load_lds((const unsigned*)((const char*)(gbase) + (voff)[_i]), (PG8_LAS unsigned*)(lds + (bufoff) + ldsw + _i * 8192), 16, 0, 0); } while (0)
; #define PG8_LDA(dst, b, h) do { _Pragma("unroll") for (int m = 0; m < 4; ++m) _Pragma("unroll") for (int k = 0; k < 2; ++k) dst[m][k] = *(const PG8_LAS bf16x8*)(lds + PG8_SA(b, h) + aoff + m * 2048 + k * 1024); } while (0)
; #define PG8_LDB(dst, b, h) do { _Pragma("unroll") for (int n = 0; n < 2; ++n) _Pragma("unroll") for (int k = 0; k < 2; ++k) dst[n][k] = *(const PG8_LAS bf16x8*)(lds + PG8_SB(b, h) + boff + n * 2048 + k * 1024); } while (0)
; #define PG8_MMA(ai, bj, At, Bt) do { __builtin_amdgcn_s_setprio(1); _Pragma("unroll") for (int m = 0; m < 4; ++m) _Pragma("unroll") for (int n = 0; n < 2; ++n) _Pragma("unroll") for (int k = 0; k < 2; ++k) \
;         acc[ai][bj][m][n] = __builtin_amdgcn_mfma_f32_16x16x32_bf16(Bt[n][k], At[m][k], acc[ai][bj][m][n], 0, 0, 0); __builtin_amdgcn_s_setprio(0); } while (0)
; #define PG8_WAIT_V(n) asm volatile("s_waitcnt vmcnt(" #n ")" ::: "memory")
; #define PG8_BAR __builtin_amdgcn_s_barrier()
; template <class Epi, class Sched, bool ALIGN_EPI = false, bool SP2 = false>
; __device__ __forceinline__ void gemm_phase(PG8_LAS unsigned char* lds, const Gemm g, const Sched& S, const Epi& E) {
;     ...
;         for (int t = 0; t < nt; t += 2) {
;             const bool last = (t == nt - 2);
;             const char* a1 = cA + (size_t)(t + 1) * kstep;
;             const char* a2 = last ? nA : cA + (size_t)(t + 2) * kstep; const char* b2 = last ? nB : cB + (size_t)(t + 2) * kstep;
;             const char* a3 = a2 + kstep; const char* b3 = b2 + kstep;
;             if (last && has_next) S.a_ready(nxt);
;             if constexpr (SP2) {
;             PG8_LDB(B0, 0, 0); PG8_LDB(B1, 0, 1); PG8_SCHED; PG8_LDA(At, 0, 0); PG8_STAGE(PG8_SA(1, 1), a1 + hstep, voffA);
;             PG8_WAIT_V(8); PG8_WAIT_L(0); PG8_BAR; PG8_MMA(0, 0, At, B0); PG8_MMA(0, 1, At, B1); PG8_BAR; PG8_SCHED;
;             PG8_LDA(At, 0, 1); PG8_STAGE(PG8_SB(0, 0), b2, voffB); PG8_STAGE(PG8_SB(0, 1), b2 + hstep, voffB); PG8_STAGE(PG8_SA(0, 0), a2, voffA);
;             PG8_WAIT_V(8); PG8_WAIT_L(0); PG8_BAR; PG8_MMA(1, 0, At, B0); PG8_MMA(1, 1, At, B1); PG8_BAR; PG8_SCHED;
.LBB0_2382:
	s_sleep 2
	ds_read_b128 v[150:153], v146
	ds_read_b128 v[154:157], v146 offset:1024
	ds_read_b128 v[158:161], v146 offset:2048
	ds_read_b128 v[162:165], v146 offset:3072
	ds_read_b128 v[166:169], v147
	ds_read_b128 v[170:173], v147 offset:1024
	ds_read_b128 v[174:177], v147 offset:2048
	ds_read_b128 v[178:181], v147 offset:3072
	s_add_i32 s93, s36, 2
	s_add_u32 s94, s34, 0x80
	s_addc_u32 s37, s35, 0
	s_cmp_eq_u32 s83, s36
	s_cselect_b32 s36, s6, s94
	s_cselect_b32 s37, s7, s37
	s_cselect_b32 s95, s31, s92
	s_cselect_b32 s94, s30, s29
	v_lshl_add_u64 v[190:191], s[34:35], 0, v[138:139]
	s_add_i32 m0, s71, 0xc000
	ds_read_b128 v[182:185], v148
	ds_read_b128 v[186:189], v148 offset:1024
	ds_read_b128 v[194:197], v148 offset:2048
	ds_read_b128 v[198:201], v148 offset:3072
	ds_read_b128 v[202:205], v148 offset:4096
	ds_read_b128 v[206:209], v148 offset:5120
	ds_read_b128 v[210:213], v148 offset:6144
	ds_read_b128 v[214:217], v148 offset:7168
	global_load_lds_dwordx4 v[190:191], off
	v_lshl_add_u64 v[190:191], s[34:35], 0, v[140:141]
	s_add_i32 m0, s71, 0xe000
	s_nop 0
	global_load_lds_dwordx4 v[190:191], off
	s_waitcnt vmcnt(8)
	s_waitcnt lgkmcnt(0)
	s_barrier
	s_setprio 1
	s_waitcnt lgkmcnt(0)
	v_mfma_f32_16x16x32_bf16 v[120:123], v[150:153], v[182:185], v[120:123]
	v_mfma_f32_16x16x32_bf16 v[124:127], v[158:161], v[182:185], v[124:127]
	v_mfma_f32_16x16x32_bf16 v[108:111], v[150:153], v[194:197], v[108:111]
	v_mfma_f32_16x16x32_bf16 v[104:107], v[158:161], v[194:197], v[104:107]
	v_mfma_f32_16x16x32_bf16 v[92:95], v[150:153], v[202:205], v[92:95]
	v_mfma_f32_16x16x32_bf16 v[88:91], v[158:161], v[202:205], v[88:91]
	v_mfma_f32_16x16x32_bf16 v[76:79], v[150:153], v[210:213], v[76:79]
	v_mfma_f32_16x16x32_bf16 v[72:75], v[158:161], v[210:213], v[72:75]
	v_mfma_f32_16x16x32_bf16 v[120:123], v[154:157], v[186:189], v[120:123]
	v_mfma_f32_16x16x32_bf16 v[124:127], v[162:165], v[186:189], v[124:127]
	v_mfma_f32_16x16x32_bf16 v[108:111], v[154:157], v[198:201], v[108:111]
	v_mfma_f32_16x16x32_bf16 v[104:107], v[162:165], v[198:201], v[104:107]
	v_mfma_f32_16x16x32_bf16 v[92:95], v[154:157], v[206:209], v[92:95]
	v_mfma_f32_16x16x32_bf16 v[88:91], v[162:165], v[206:209], v[88:91]
	v_mfma_f32_16x16x32_bf16 v[76:79], v[154:157], v[214:217], v[76:79]
	v_mfma_f32_16x16x32_bf16 v[72:75], v[162:165], v[214:217], v[72:75]
	s_setprio 0
	s_setprio 1
	v_mfma_f32_16x16x32_bf16 v[116:119], v[166:169], v[182:185], v[116:119]
	v_mfma_f32_16x16x32_bf16 v[112:115], v[174:177], v[182:185], v[112:115]
	v_mfma_f32_16x16x32_bf16 v[100:103], v[166:169], v[194:197], v[100:103]
	v_mfma_f32_16x16x32_bf16 v[96:99], v[174:177], v[194:197], v[96:99]
	v_mfma_f32_16x16x32_bf16 v[84:87], v[166:169], v[202:205], v[84:87]
	v_mfma_f32_16x16x32_bf16 v[80:83], v[174:177], v[202:205], v[80:83]
	v_mfma_f32_16x16x32_bf16 v[68:71], v[166:169], v[210:213], v[68:71]
	v_mfma_f32_16x16x32_bf16 v[64:67], v[174:177], v[210:213], v[64:67]
	v_mfma_f32_16x16x32_bf16 v[116:119], v[170:173], v[186:189], v[116:119]
	v_mfma_f32_16x16x32_bf16 v[112:115], v[178:181], v[186:189], v[112:115]
	v_mfma_f32_16x16x32_bf16 v[100:103], v[170:173], v[198:201], v[100:103]
	v_mfma_f32_16x16x32_bf16 v[96:99], v[178:181], v[198:201], v[96:99]
	v_mfma_f32_16x16x32_bf16 v[84:87], v[170:173], v[206:209], v[84:87]
	v_mfma_f32_16x16x32_bf16 v[80:83], v[178:181], v[206:209], v[80:83]
	v_mfma_f32_16x16x32_bf16 v[68:71], v[170:173], v[214:217], v[68:71]
	v_mfma_f32_16x16x32_bf16 v[64:67], v[178:181], v[214:217], v[64:67]
	s_setprio 0
	s_barrier
	s_add_i32 s96, s84, s1
	v_lshl_add_u64 v[190:191], s[94:95], 0, v[130:131]
	s_mov_b32 m0, s96
	ds_read_b128 v[182:185], v148 offset:16384
	ds_read_b128 v[186:189], v148 offset:17408
	ds_read_b128 v[194:197], v148 offset:18432
	ds_read_b128 v[198:201], v148 offset:19456
	ds_read_b128 v[202:205], v148 offset:20480
	ds_read_b128 v[206:209], v148 offset:21504
	ds_read_b128 v[210:213], v148 offset:22528
	ds_read_b128 v[214:217], v148 offset:23552
	global_load_lds_dwordx4 v[190:191], off
	s_add_i32 m0, s96, 0x2000
	v_lshl_add_u64 v[218:219], s[94:95], 0, v[134:135]
	s_add_u32 s94, s94, s10
	s_addc_u32 s95, s95, s11
	s_add_i32 s96, s85, s1
	global_load_lds_dwordx4 v[218:219], off
	v_lshl_add_u64 v[220:221], s[94:95], 0, v[130:131]
	s_mov_b32 m0, s96
	v_lshl_add_u64 v[222:223], s[94:95], 0, v[134:135]
	global_load_lds_dwordx4 v[220:221], off
	s_add_i32 m0, s96, 0x2000
	v_lshl_add_u64 v[224:225], s[36:37], 0, v[128:129]
	global_load_lds_dwordx4 v[222:223], off
	s_mov_b32 m0, s71
	v_lshl_add_u64 v[226:227], s[36:37], 0, v[132:133]
	global_load_lds_dwordx4 v[224:225], off
	s_mov_b32 m0, s72
	s_nop 0
	global_load_lds_dwordx4 v[226:227], off
	s_waitcnt vmcnt(8)
	s_waitcnt lgkmcnt(0)
	s_barrier
; #define PG8_STAGE(bufoff, gbase, voff) do { _Pragma("unroll") for (int _i = 0; _i < 2; ++_i) \
;         __builtin_amdgcn_global_load_lds((const unsigned*)((const char*)(gbase) + (voff)[_i]), (PG8_LAS unsigned*)(lds + (bufoff) + ldsw + _i * 8192), 16, 0, 0); } while (0)
; #define PG8_LDA(dst, b, h) do { _Pragma("unroll") for (int m = 0; m < 4; ++m) _Pragma("unroll") for (int k = 0; k < 2; ++k) dst[m][k] = *(const PG8_LAS bf16x8*)(lds + PG8_SA(b, h) + aoff + m * 2048 + k * 1024); } while (0)
; #define PG8_LDB(dst, b, h) do { _Pragma("unroll") for (int n = 0; n < 2; ++n) _Pragma("unroll") for (int k = 0; k < 2; ++k) dst[n][k] = *(const PG8_LAS bf16x8*)(lds + PG8_SB(b, h) + boff + n * 2048 + k * 1024); } while (0)
; #define PG8_MMA(ai, bj, At, Bt) do { __builtin_amdgcn_s_setprio(1); _Pragma("unroll") for (int m = 0; m < 4; ++m) _Pragma("unroll") for (int n = 0; n < 2; ++n) _Pragma("unroll") for (int k = 0; k < 2; ++k) \
;         acc[ai][bj][m][n] = __builtin_amdgcn_mfma_f32_16x16x32_bf16(Bt[n][k], At[m][k], acc[ai][bj][m][n], 0, 0, 0); __builtin_amdgcn_s_setprio(0); } while (0)
; #define PG8_WAIT_V(n) asm volatile("s_waitcnt vmcnt(" #n ")" ::: "memory")
; #define PG8_WAIT_L(n) asm volatile("s_waitcnt lgkmcnt(" #n ")" ::: "memory")
; #define PG8_BAR __builtin_amdgcn_s_barrier()
; #define PG8_SCHED __builtin_amdgcn_sched_barrier(0)
; template <class Epi, class Sched, bool ALIGN_EPI = false, bool SP2 = false>
; __device__ __forceinline__ void gemm_phase(PG8_LAS unsigned char* lds, const Gemm g, const Sched& S, const Epi& E) {
;     ...
;             PG8_WAIT_V(8); PG8_WAIT_L(0); PG8_BAR; PG8_MMA(1, 0, At, B0); PG8_MMA(1, 1, At, B1); PG8_BAR; PG8_SCHED;
;             PG8_LDB(B0, 1, 0); PG8_LDB(B1, 1, 1); PG8_SCHED; PG8_LDA(At, 1, 0); PG8_STAGE(PG8_SA(0, 1), a2 + hstep, voffA);
;             PG8_WAIT_V(8); PG8_WAIT_L(0); PG8_BAR; PG8_MMA(0, 0, At, B0); PG8_MMA(0, 1, At, B1); PG8_BAR; PG8_SCHED;
	s_setprio 1
	s_waitcnt lgkmcnt(0)
	v_mfma_f32_16x16x32_bf16 v[60:63], v[150:153], v[182:185], v[60:63]
	v_mfma_f32_16x16x32_bf16 v[56:59], v[158:161], v[182:185], v[56:59]
	v_mfma_f32_16x16x32_bf16 v[44:47], v[150:153], v[194:197], v[44:47]
	v_mfma_f32_16x16x32_bf16 v[40:43], v[158:161], v[194:197], v[40:43]
	v_mfma_f32_16x16x32_bf16 v[28:31], v[150:153], v[202:205], v[28:31]
	v_mfma_f32_16x16x32_bf16 v[24:27], v[158:161], v[202:205], v[24:27]
	v_mfma_f32_16x16x32_bf16 v[12:15], v[150:153], v[210:213], v[12:15]
	v_mfma_f32_16x16x32_bf16 v[8:11], v[158:161], v[210:213], v[8:11]
	v_mfma_f32_16x16x32_bf16 v[60:63], v[154:157], v[186:189], v[60:63]
	v_mfma_f32_16x16x32_bf16 v[56:59], v[162:165], v[186:189], v[56:59]
	v_mfma_f32_16x16x32_bf16 v[44:47], v[154:157], v[198:201], v[44:47]
	v_mfma_f32_16x16x32_bf16 v[40:43], v[162:165], v[198:201], v[40:43]
	v_mfma_f32_16x16x32_bf16 v[28:31], v[154:157], v[206:209], v[28:31]
	v_mfma_f32_16x16x32_bf16 v[24:27], v[162:165], v[206:209], v[24:27]
	v_mfma_f32_16x16x32_bf16 v[12:15], v[154:157], v[214:217], v[12:15]
	v_mfma_f32_16x16x32_bf16 v[8:11], v[162:165], v[214:217], v[8:11]
	s_setprio 0
	s_setprio 1
	v_mfma_f32_16x16x32_bf16 v[52:55], v[166:169], v[182:185], v[52:55]
	v_mfma_f32_16x16x32_bf16 v[48:51], v[174:177], v[182:185], v[48:51]
	v_mfma_f32_16x16x32_bf16 v[36:39], v[166:169], v[194:197], v[36:39]
	v_mfma_f32_16x16x32_bf16 v[32:35], v[174:177], v[194:197], v[32:35]
	v_mfma_f32_16x16x32_bf16 v[20:23], v[166:169], v[202:205], v[20:23]
	v_mfma_f32_16x16x32_bf16 v[16:19], v[174:177], v[202:205], v[16:19]
	v_mfma_f32_16x16x32_bf16 v[4:7], v[166:169], v[210:213], v[4:7]
	v_mfma_f32_16x16x32_bf16 v[0:3], v[174:177], v[210:213], v[0:3]
	v_mfma_f32_16x16x32_bf16 v[52:55], v[170:173], v[186:189], v[52:55]
	v_mfma_f32_16x16x32_bf16 v[48:51], v[178:181], v[186:189], v[48:51]
	v_mfma_f32_16x16x32_bf16 v[36:39], v[170:173], v[198:201], v[36:39]
	v_mfma_f32_16x16x32_bf16 v[32:35], v[178:181], v[198:201], v[32:35]
	v_mfma_f32_16x16x32_bf16 v[20:23], v[170:173], v[206:209], v[20:23]
	v_mfma_f32_16x16x32_bf16 v[16:19], v[178:181], v[206:209], v[16:19]
	v_mfma_f32_16x16x32_bf16 v[4:7], v[170:173], v[214:217], v[4:7]
	v_mfma_f32_16x16x32_bf16 v[0:3], v[178:181], v[214:217], v[0:3]
	s_setprio 0
	s_barrier
	s_add_i32 s94, 0, 0x18000
	v_add_u32_e32 v149, s94, v144
	s_add_i32 s95, 0, 0x1c000
	ds_read_b128 v[150:153], v149
	ds_read_b128 v[154:157], v149 offset:1024
	ds_read_b128 v[158:161], v149 offset:2048
	ds_read_b128 v[162:165], v149 offset:3072
	v_add_u32_e32 v149, s95, v144
	ds_read_b128 v[166:169], v149
	ds_read_b128 v[170:173], v149 offset:1024
	ds_read_b128 v[174:177], v149 offset:2048
	ds_read_b128 v[178:181], v149 offset:3072
	s_add_u32 s36, s36, s10
	s_addc_u32 s37, s37, s11
	s_mov_b32 m0, s73
	v_lshl_add_u64 v[228:229], s[36:37], 0, v[128:129]
	ds_read_b128 v[182:185], v148 offset:32768
	ds_read_b128 v[186:189], v148 offset:33792
	ds_read_b128 v[194:197], v148 offset:34816
	ds_read_b128 v[198:201], v148 offset:35840
	ds_read_b128 v[202:205], v148 offset:36864
	ds_read_b128 v[206:209], v148 offset:37888
	ds_read_b128 v[210:213], v148 offset:38912
	ds_read_b128 v[214:217], v148 offset:39936
	global_load_lds_dwordx4 v[228:229], off
	v_lshl_add_u64 v[228:229], s[36:37], 0, v[132:133]
	s_mov_b32 m0, s78
	s_nop 0
	global_load_lds_dwordx4 v[228:229], off
	s_waitcnt vmcnt(8)
	s_waitcnt lgkmcnt(0)
	s_barrier
	s_setprio 1
	s_waitcnt lgkmcnt(0)
	v_mfma_f32_16x16x32_bf16 v[120:123], v[150:153], v[182:185], v[120:123]
	v_mfma_f32_16x16x32_bf16 v[124:127], v[158:161], v[182:185], v[124:127]
	v_mfma_f32_16x16x32_bf16 v[108:111], v[150:153], v[194:197], v[108:111]
	v_mfma_f32_16x16x32_bf16 v[104:107], v[158:161], v[194:197], v[104:107]
	v_mfma_f32_16x16x32_bf16 v[92:95], v[150:153], v[202:205], v[92:95]
	v_mfma_f32_16x16x32_bf16 v[88:91], v[158:161], v[202:205], v[88:91]
	v_mfma_f32_16x16x32_bf16 v[76:79], v[150:153], v[210:213], v[76:79]
	v_mfma_f32_16x16x32_bf16 v[72:75], v[158:161], v[210:213], v[72:75]
	v_mfma_f32_16x16x32_bf16 v[120:123], v[154:157], v[186:189], v[120:123]
	v_mfma_f32_16x16x32_bf16 v[124:127], v[162:165], v[186:189], v[124:127]
	v_mfma_f32_16x16x32_bf16 v[108:111], v[154:157], v[198:201], v[108:111]
	v_mfma_f32_16x16x32_bf16 v[104:107], v[162:165], v[198:201], v[104:107]
	v_mfma_f32_16x16x32_bf16 v[92:95], v[154:157], v[206:209], v[92:95]
	v_mfma_f32_16x16x32_bf16 v[88:91], v[162:165], v[206:209], v[88:91]
	v_mfma_f32_16x16x32_bf16 v[76:79], v[154:157], v[214:217], v[76:79]
	v_mfma_f32_16x16x32_bf16 v[72:75], v[162:165], v[214:217], v[72:75]
	s_setprio 0
	s_setprio 1
	v_mfma_f32_16x16x32_bf16 v[116:119], v[166:169], v[182:185], v[116:119]
	v_mfma_f32_16x16x32_bf16 v[112:115], v[174:177], v[182:185], v[112:115]
	v_mfma_f32_16x16x32_bf16 v[100:103], v[166:169], v[194:197], v[100:103]
	v_mfma_f32_16x16x32_bf16 v[96:99], v[174:177], v[194:197], v[96:99]
	v_mfma_f32_16x16x32_bf16 v[84:87], v[166:169], v[202:205], v[84:87]
	v_mfma_f32_16x16x32_bf16 v[80:83], v[174:177], v[202:205], v[80:83]
	v_mfma_f32_16x16x32_bf16 v[68:71], v[166:169], v[210:213], v[68:71]
	v_mfma_f32_16x16x32_bf16 v[64:67], v[174:177], v[210:213], v[64:67]
	v_mfma_f32_16x16x32_bf16 v[116:119], v[170:173], v[186:189], v[116:119]
	v_mfma_f32_16x16x32_bf16 v[112:115], v[178:181], v[186:189], v[112:115]
	v_mfma_f32_16x16x32_bf16 v[100:103], v[170:173], v[198:201], v[100:103]
	v_mfma_f32_16x16x32_bf16 v[96:99], v[178:181], v[198:201], v[96:99]
	v_mfma_f32_16x16x32_bf16 v[84:87], v[170:173], v[206:209], v[84:87]
	v_mfma_f32_16x16x32_bf16 v[80:83], v[178:181], v[206:209], v[80:83]
	v_mfma_f32_16x16x32_bf16 v[68:71], v[170:173], v[214:217], v[68:71]
	v_mfma_f32_16x16x32_bf16 v[64:67], v[178:181], v[214:217], v[64:67]
	s_setprio 0
	s_barrier
; #define PG8_STAGE(bufoff, gbase, voff) do { _Pragma("unroll") for (int _i = 0; _i < 2; ++_i) \
;         __builtin_amdgcn_global_load_lds((const unsigned*)((const char*)(gbase) + (voff)[_i]), (PG8_LAS unsigned*)(lds + (bufoff) + ldsw + _i * 8192), 16, 0, 0); } while (0)
; #define PG8_LDA(dst, b, h) do { _Pragma("unroll") for (int m = 0; m < 4; ++m) _Pragma("unroll") for (int k = 0; k < 2; ++k) dst[m][k] = *(const PG8_LAS bf16x8*)(lds + PG8_SA(b, h) + aoff + m * 2048 + k * 1024); } while (0)
; #define PG8_MMA(ai, bj, At, Bt) do { __builtin_amdgcn_s_setprio(1); _Pragma("unroll") for (int m = 0; m < 4; ++m) _Pragma("unroll") for (int n = 0; n < 2; ++n) _Pragma("unroll") for (int k = 0; k < 2; ++k) \
;         acc[ai][bj][m][n] = __builtin_amdgcn_mfma_f32_16x16x32_bf16(Bt[n][k], At[m][k], acc[ai][bj][m][n], 0, 0, 0); __builtin_amdgcn_s_setprio(0); } while (0)
; #define PG8_WAIT_V(n) asm volatile("s_waitcnt vmcnt(" #n ")" ::: "memory")
; #define PG8_WAIT_L(n) asm volatile("s_waitcnt lgkmcnt(" #n ")" ::: "memory")
; #define PG8_BAR __builtin_amdgcn_s_barrier()
; #define PG8_SCHED __builtin_amdgcn_sched_barrier(0)
; template <class Epi, class Sched, bool ALIGN_EPI = false, bool SP2 = false>
; __device__ __forceinline__ void gemm_phase(PG8_LAS unsigned char* lds, const Gemm g, const Sched& S, const Epi& E) {
;     ...
;             PG8_LDA(At, 1, 1); PG8_STAGE(PG8_SB(1, 0), b3, voffB); PG8_STAGE(PG8_SB(1, 1), b3 + hstep, voffB); PG8_STAGE(PG8_SA(1, 0), a3, voffA);
;             PG8_WAIT_V(8); PG8_WAIT_L(0); PG8_BAR; PG8_MMA(1, 0, At, B0); PG8_MMA(1, 1, At, B1); PG8_BAR; PG8_SCHED;
	s_add_i32 s36, s94, s1
	v_lshl_add_u64 v[190:191], v[190:191], 0, s[16:17]
	s_mov_b32 m0, s36
	ds_read_b128 v[182:185], v148 offset:49152
	ds_read_b128 v[186:189], v148 offset:50176
	ds_read_b128 v[194:197], v148 offset:51200
	ds_read_b128 v[198:201], v148 offset:52224
	ds_read_b128 v[202:205], v148 offset:53248
	ds_read_b128 v[206:209], v148 offset:54272
	ds_read_b128 v[210:213], v148 offset:55296
	ds_read_b128 v[214:217], v148 offset:56320
	global_load_lds_dwordx4 v[190:191], off
	v_lshl_add_u64 v[190:191], v[218:219], 0, s[16:17]
	s_add_i32 m0, s36, 0x2000
	s_add_i32 s36, s95, s1
	global_load_lds_dwordx4 v[190:191], off
	v_lshl_add_u64 v[190:191], v[220:221], 0, s[16:17]
	s_mov_b32 m0, s36
	s_nop 0
	global_load_lds_dwordx4 v[190:191], off
	v_lshl_add_u64 v[190:191], v[222:223], 0, s[16:17]
	s_add_i32 m0, s36, 0x2000
	s_nop 0
	global_load_lds_dwordx4 v[190:191], off
	v_lshl_add_u64 v[190:191], v[224:225], 0, s[16:17]
	s_mov_b32 m0, s80
	s_nop 0
	global_load_lds_dwordx4 v[190:191], off
	v_lshl_add_u64 v[190:191], v[226:227], 0, s[16:17]
	s_mov_b32 m0, s81
	s_nop 0
	global_load_lds_dwordx4 v[190:191], off
	s_waitcnt vmcnt(8)
	s_waitcnt lgkmcnt(0)
	s_barrier
	s_setprio 1
	s_waitcnt lgkmcnt(0)
	v_mfma_f32_16x16x32_bf16 v[60:63], v[150:153], v[182:185], v[60:63]
	v_mfma_f32_16x16x32_bf16 v[56:59], v[158:161], v[182:185], v[56:59]
	v_mfma_f32_16x16x32_bf16 v[44:47], v[150:153], v[194:197], v[44:47]
	v_mfma_f32_16x16x32_bf16 v[40:43], v[158:161], v[194:197], v[40:43]
	v_mfma_f32_16x16x32_bf16 v[28:31], v[150:153], v[202:205], v[28:31]
	v_mfma_f32_16x16x32_bf16 v[24:27], v[158:161], v[202:205], v[24:27]
	v_mfma_f32_16x16x32_bf16 v[12:15], v[150:153], v[210:213], v[12:15]
	v_mfma_f32_16x16x32_bf16 v[8:11], v[158:161], v[210:213], v[8:11]
	v_mfma_f32_16x16x32_bf16 v[60:63], v[154:157], v[186:189], v[60:63]
	v_mfma_f32_16x16x32_bf16 v[56:59], v[162:165], v[186:189], v[56:59]
	v_mfma_f32_16x16x32_bf16 v[44:47], v[154:157], v[198:201], v[44:47]
	v_mfma_f32_16x16x32_bf16 v[40:43], v[162:165], v[198:201], v[40:43]
	v_mfma_f32_16x16x32_bf16 v[28:31], v[154:157], v[206:209], v[28:31]
	v_mfma_f32_16x16x32_bf16 v[24:27], v[162:165], v[206:209], v[24:27]
	v_mfma_f32_16x16x32_bf16 v[12:15], v[154:157], v[214:217], v[12:15]
	v_mfma_f32_16x16x32_bf16 v[8:11], v[162:165], v[214:217], v[8:11]
	s_setprio 0
	s_setprio 1
	v_mfma_f32_16x16x32_bf16 v[52:55], v[166:169], v[182:185], v[52:55]
	v_mfma_f32_16x16x32_bf16 v[48:51], v[174:177], v[182:185], v[48:51]
	v_mfma_f32_16x16x32_bf16 v[36:39], v[166:169], v[194:197], v[36:39]
	v_mfma_f32_16x16x32_bf16 v[32:35], v[174:177], v[194:197], v[32:35]
	v_mfma_f32_16x16x32_bf16 v[20:23], v[166:169], v[202:205], v[20:23]
	v_mfma_f32_16x16x32_bf16 v[16:19], v[174:177], v[202:205], v[16:19]
	v_mfma_f32_16x16x32_bf16 v[4:7], v[166:169], v[210:213], v[4:7]
	v_mfma_f32_16x16x32_bf16 v[0:3], v[174:177], v[210:213], v[0:3]
	v_mfma_f32_16x16x32_bf16 v[52:55], v[170:173], v[186:189], v[52:55]
	v_mfma_f32_16x16x32_bf16 v[48:51], v[178:181], v[186:189], v[48:51]
	v_mfma_f32_16x16x32_bf16 v[36:39], v[170:173], v[198:201], v[36:39]
	v_mfma_f32_16x16x32_bf16 v[32:35], v[178:181], v[198:201], v[32:35]
	v_mfma_f32_16x16x32_bf16 v[20:23], v[170:173], v[206:209], v[20:23]
	v_mfma_f32_16x16x32_bf16 v[16:19], v[178:181], v[206:209], v[16:19]
	v_mfma_f32_16x16x32_bf16 v[4:7], v[170:173], v[214:217], v[4:7]
	v_mfma_f32_16x16x32_bf16 v[0:3], v[178:181], v[214:217], v[0:3]
	s_setprio 0
	s_barrier
	s_add_u32 s34, s34, 0x100
	s_addc_u32 s35, s35, 0
	s_add_u32 s29, s29, 0x100
	s_addc_u32 s92, s92, 0
	s_cmp_ge_i32 s93, s82
	s_mov_b32 s36, s93
	s_cbranch_scc0 .LBB0_2382

; #define PG8_STAGE(bufoff, gbase, voff) do { _Pragma("unroll") for (int _i = 0; _i < 2; ++_i) \
;         __builtin_amdgcn_global_load_lds((const unsigned*)((const char*)(gbase) + (voff)[_i]), (PG8_LAS unsigned*)(lds + (bufoff) + ldsw + _i * 8192), 16, 0, 0); } while (0)
; #define PG8_LDA(dst, b, h) do { _Pragma("unroll") for (int m = 0; m < 4; ++m) _Pragma("unroll") for (int k = 0; k < 2; ++k) dst[m][k] = *(const PG8_LAS bf16x8*)(lds + PG8_SA(b, h) + aoff + m * 2048 + k * 1024); } while (0)
; #define PG8_LDB(dst, b, h) do { _Pragma("unroll") for (int n = 0; n < 2; ++n) _Pragma("unroll") for (int k = 0; k < 2; ++k) dst[n][k] = *(const PG8_LAS bf16x8*)(lds + PG8_SB(b, h) + boff + n * 2048 + k * 1024); } while (0)
; #define PG8_MMA(ai, bj, At, Bt) do { __builtin_amdgcn_s_setprio(1); _Pragma("unroll") for (int m = 0; m < 4; ++m) _Pragma("unroll") for (int n = 0; n < 2; ++n) _Pragma("unroll") for (int k = 0; k < 2; ++k) \
;         acc[ai][bj][m][n] = __builtin_amdgcn_mfma_f32_16x16x32_bf16(Bt[n][k], At[m][k], acc[ai][bj][m][n], 0, 0, 0); __builtin_amdgcn_s_setprio(0); } while (0)
; #define PG8_WAIT_V(n) asm volatile("s_waitcnt vmcnt(" #n ")" ::: "memory")
; #define PG8_BAR __builtin_amdgcn_s_barrier()
; template <class Epi, class Sched, bool ALIGN_EPI = false, bool SP2 = false>
; __device__ __forceinline__ void gemm_phase(PG8_LAS unsigned char* lds, const Gemm g, const Sched& S, const Epi& E) {
;     ...
;         for (int t = 0; t < nt; t += 2) {
;             const bool last = (t == nt - 2);
;             const char* a1 = cA + (size_t)(t + 1) * kstep;
;             const char* a2 = last ? nA : cA + (size_t)(t + 2) * kstep; const char* b2 = last ? nB : cB + (size_t)(t + 2) * kstep;
;             const char* a3 = a2 + kstep; const char* b3 = b2 + kstep;
;             if (last && has_next) S.a_ready(nxt);
;             if constexpr (SP2) {
;             PG8_LDB(B0, 0, 0); PG8_LDB(B1, 0, 1); PG8_SCHED; PG8_LDA(At, 0, 0); PG8_STAGE(PG8_SA(1, 1), a1 + hstep, voffA);
;             PG8_WAIT_V(8); PG8_WAIT_L(0); PG8_BAR; PG8_MMA(0, 0, At, B0); PG8_MMA(0, 1, At, B1); PG8_BAR; PG8_SCHED;
;             PG8_LDA(At, 0, 1); PG8_STAGE(PG8_SB(0, 0), b2, voffB); PG8_STAGE(PG8_SB(0, 1), b2 + hstep, voffB); PG8_STAGE(PG8_SA(0, 0), a2, voffA);
;             PG8_WAIT_V(8); PG8_WAIT_L(0); PG8_BAR; PG8_MMA(1, 0, At, B0); PG8_MMA(1, 1, At, B1); PG8_BAR; PG8_SCHED;
.LBB0_2468:
	s_sleep 2
	ds_read_b128 v[116:119], v243
	ds_read_b128 v[124:127], v243 offset:1024
	ds_read_b128 v[128:131], v243 offset:2048
	ds_read_b128 v[132:135], v243 offset:3072
	ds_read_b128 v[144:147], v244
	ds_read_b128 v[148:151], v244 offset:1024
	ds_read_b128 v[152:155], v244 offset:2048
	ds_read_b128 v[176:179], v244 offset:3072
	s_add_i32 s73, s60, 2
	s_add_u32 s78, s50, 0x80
	s_addc_u32 s61, s51, 0
	s_cmp_eq_u32 s83, s60
	s_cselect_b32 s60, s8, s78
	s_cselect_b32 s61, s9, s61
	s_cselect_b32 s79, s43, s72
	s_cselect_b32 s78, s42, s67
	v_lshl_add_u64 v[214:215], s[50:51], 0, v[170:171]
	s_add_i32 m0, s35, 0xc000
	ds_read_b128 v[180:183], v245
	ds_read_b128 v[184:187], v245 offset:1024
	ds_read_b128 v[188:191], v245 offset:2048
	ds_read_b128 v[194:197], v245 offset:3072
	ds_read_b128 v[198:201], v245 offset:4096
	ds_read_b128 v[202:205], v245 offset:5120
	ds_read_b128 v[206:209], v245 offset:6144
	ds_read_b128 v[210:213], v245 offset:7168
	global_load_lds_dwordx4 v[214:215], off
	v_lshl_add_u64 v[214:215], s[50:51], 0, v[172:173]
	s_add_i32 m0, s35, 0xe000
	s_nop 0
	global_load_lds_dwordx4 v[214:215], off
	s_waitcnt vmcnt(8)
	s_waitcnt lgkmcnt(0)
	s_barrier
	s_setprio 1
	s_waitcnt lgkmcnt(0)
	v_mfma_f32_16x16x32_bf16 v[140:143], v[116:119], v[180:183], v[140:143]
	v_mfma_f32_16x16x32_bf16 v[136:139], v[128:131], v[180:183], v[136:139]
	v_mfma_f32_16x16x32_bf16 v[108:111], v[116:119], v[188:191], v[108:111]
	v_mfma_f32_16x16x32_bf16 v[104:107], v[128:131], v[188:191], v[104:107]
	v_mfma_f32_16x16x32_bf16 v[92:95], v[116:119], v[198:201], v[92:95]
	v_mfma_f32_16x16x32_bf16 v[88:91], v[128:131], v[198:201], v[88:91]
	v_mfma_f32_16x16x32_bf16 v[76:79], v[116:119], v[206:209], v[76:79]
	v_mfma_f32_16x16x32_bf16 v[72:75], v[128:131], v[206:209], v[72:75]
	v_mfma_f32_16x16x32_bf16 v[140:143], v[124:127], v[184:187], v[140:143]
	v_mfma_f32_16x16x32_bf16 v[136:139], v[132:135], v[184:187], v[136:139]
	v_mfma_f32_16x16x32_bf16 v[108:111], v[124:127], v[194:197], v[108:111]
	v_mfma_f32_16x16x32_bf16 v[104:107], v[132:135], v[194:197], v[104:107]
	v_mfma_f32_16x16x32_bf16 v[92:95], v[124:127], v[202:205], v[92:95]
	v_mfma_f32_16x16x32_bf16 v[88:91], v[132:135], v[202:205], v[88:91]
	v_mfma_f32_16x16x32_bf16 v[76:79], v[124:127], v[210:213], v[76:79]
	v_mfma_f32_16x16x32_bf16 v[72:75], v[132:135], v[210:213], v[72:75]
	s_setprio 0
	s_setprio 1
	v_mfma_f32_16x16x32_bf16 v[120:123], v[144:147], v[180:183], v[120:123]
	v_mfma_f32_16x16x32_bf16 v[112:115], v[152:155], v[180:183], v[112:115]
	v_mfma_f32_16x16x32_bf16 v[100:103], v[144:147], v[188:191], v[100:103]
	v_mfma_f32_16x16x32_bf16 v[96:99], v[152:155], v[188:191], v[96:99]
	v_mfma_f32_16x16x32_bf16 v[84:87], v[144:147], v[198:201], v[84:87]
	v_mfma_f32_16x16x32_bf16 v[80:83], v[152:155], v[198:201], v[80:83]
	v_mfma_f32_16x16x32_bf16 v[68:71], v[144:147], v[206:209], v[68:71]
	v_mfma_f32_16x16x32_bf16 v[64:67], v[152:155], v[206:209], v[64:67]
	v_mfma_f32_16x16x32_bf16 v[120:123], v[148:151], v[184:187], v[120:123]
	v_mfma_f32_16x16x32_bf16 v[112:115], v[176:179], v[184:187], v[112:115]
	v_mfma_f32_16x16x32_bf16 v[100:103], v[148:151], v[194:197], v[100:103]
	v_mfma_f32_16x16x32_bf16 v[96:99], v[176:179], v[194:197], v[96:99]
	v_mfma_f32_16x16x32_bf16 v[84:87], v[148:151], v[202:205], v[84:87]
	v_mfma_f32_16x16x32_bf16 v[80:83], v[176:179], v[202:205], v[80:83]
	v_mfma_f32_16x16x32_bf16 v[68:71], v[148:151], v[210:213], v[68:71]
	v_mfma_f32_16x16x32_bf16 v[64:67], v[176:179], v[210:213], v[64:67]
	s_setprio 0
	s_barrier
	s_add_i32 s96, s90, s33
	v_lshl_add_u64 v[214:215], s[78:79], 0, v[158:159]
	s_mov_b32 m0, s96
	ds_read_b128 v[180:183], v245 offset:16384
	ds_read_b128 v[184:187], v245 offset:17408
	ds_read_b128 v[188:191], v245 offset:18432
	ds_read_b128 v[194:197], v245 offset:19456
	ds_read_b128 v[198:201], v245 offset:20480
	ds_read_b128 v[202:205], v245 offset:21504
	ds_read_b128 v[206:209], v245 offset:22528
	ds_read_b128 v[210:213], v245 offset:23552
	global_load_lds_dwordx4 v[214:215], off
	s_add_i32 m0, s96, 0x2000
	v_lshl_add_u64 v[216:217], s[78:79], 0, v[162:163]
	s_add_u32 s78, s78, s12
	s_addc_u32 s79, s79, s13
	s_add_i32 s96, s91, s33
	global_load_lds_dwordx4 v[216:217], off
	v_lshl_add_u64 v[218:219], s[78:79], 0, v[158:159]
	s_mov_b32 m0, s96
	v_lshl_add_u64 v[220:221], s[78:79], 0, v[162:163]
	global_load_lds_dwordx4 v[218:219], off
	s_add_i32 m0, s96, 0x2000
	v_lshl_add_u64 v[222:223], s[60:61], 0, v[156:157]
	global_load_lds_dwordx4 v[220:221], off
	s_mov_b32 m0, s35
	v_lshl_add_u64 v[224:225], s[60:61], 0, v[160:161]
	global_load_lds_dwordx4 v[222:223], off
	s_mov_b32 m0, s46
	s_nop 0
	global_load_lds_dwordx4 v[224:225], off
	s_waitcnt vmcnt(8)
	s_waitcnt lgkmcnt(0)
	s_barrier
; #define PG8_STAGE(bufoff, gbase, voff) do { _Pragma("unroll") for (int _i = 0; _i < 2; ++_i) \
;         __builtin_amdgcn_global_load_lds((const unsigned*)((const char*)(gbase) + (voff)[_i]), (PG8_LAS unsigned*)(lds + (bufoff) + ldsw + _i * 8192), 16, 0, 0); } while (0)
; #define PG8_LDA(dst, b, h) do { _Pragma("unroll") for (int m = 0; m < 4; ++m) _Pragma("unroll") for (int k = 0; k < 2; ++k) dst[m][k] = *(const PG8_LAS bf16x8*)(lds + PG8_SA(b, h) + aoff + m * 2048 + k * 1024); } while (0)
; #define PG8_LDB(dst, b, h) do { _Pragma("unroll") for (int n = 0; n < 2; ++n) _Pragma("unroll") for (int k = 0; k < 2; ++k) dst[n][k] = *(const PG8_LAS bf16x8*)(lds + PG8_SB(b, h) + boff + n * 2048 + k * 1024); } while (0)
; #define PG8_MMA(ai, bj, At, Bt) do { __builtin_amdgcn_s_setprio(1); _Pragma("unroll") for (int m = 0; m < 4; ++m) _Pragma("unroll") for (int n = 0; n < 2; ++n) _Pragma("unroll") for (int k = 0; k < 2; ++k) \
;         acc[ai][bj][m][n] = __builtin_amdgcn_mfma_f32_16x16x32_bf16(Bt[n][k], At[m][k], acc[ai][bj][m][n], 0, 0, 0); __builtin_amdgcn_s_setprio(0); } while (0)
; #define PG8_WAIT_V(n) asm volatile("s_waitcnt vmcnt(" #n ")" ::: "memory")
; #define PG8_WAIT_L(n) asm volatile("s_waitcnt lgkmcnt(" #n ")" ::: "memory")
; #define PG8_BAR __builtin_amdgcn_s_barrier()
; #define PG8_SCHED __builtin_amdgcn_sched_barrier(0)
; template <class Epi, class Sched, bool ALIGN_EPI = false, bool SP2 = false>
; __device__ __forceinline__ void gemm_phase(PG8_LAS unsigned char* lds, const Gemm g, const Sched& S, const Epi& E) {
;     ...
;             PG8_WAIT_V(8); PG8_WAIT_L(0); PG8_BAR; PG8_MMA(1, 0, At, B0); PG8_MMA(1, 1, At, B1); PG8_BAR; PG8_SCHED;
;             PG8_LDB(B0, 1, 0); PG8_LDB(B1, 1, 1); PG8_SCHED; PG8_LDA(At, 1, 0); PG8_STAGE(PG8_SA(0, 1), a2 + hstep, voffA);
;             PG8_WAIT_V(8); PG8_WAIT_L(0); PG8_BAR; PG8_MMA(0, 0, At, B0); PG8_MMA(0, 1, At, B1); PG8_BAR; PG8_SCHED;
	s_setprio 1
	s_waitcnt lgkmcnt(0)
	v_mfma_f32_16x16x32_bf16 v[60:63], v[116:119], v[180:183], v[60:63]
	v_mfma_f32_16x16x32_bf16 v[56:59], v[128:131], v[180:183], v[56:59]
	v_mfma_f32_16x16x32_bf16 v[44:47], v[116:119], v[188:191], v[44:47]
	v_mfma_f32_16x16x32_bf16 v[40:43], v[128:131], v[188:191], v[40:43]
	v_mfma_f32_16x16x32_bf16 v[28:31], v[116:119], v[198:201], v[28:31]
	v_mfma_f32_16x16x32_bf16 v[24:27], v[128:131], v[198:201], v[24:27]
	v_mfma_f32_16x16x32_bf16 v[12:15], v[116:119], v[206:209], v[12:15]
	v_mfma_f32_16x16x32_bf16 v[8:11], v[128:131], v[206:209], v[8:11]
	v_mfma_f32_16x16x32_bf16 v[60:63], v[124:127], v[184:187], v[60:63]
	v_mfma_f32_16x16x32_bf16 v[56:59], v[132:135], v[184:187], v[56:59]
	v_mfma_f32_16x16x32_bf16 v[44:47], v[124:127], v[194:197], v[44:47]
	v_mfma_f32_16x16x32_bf16 v[40:43], v[132:135], v[194:197], v[40:43]
	v_mfma_f32_16x16x32_bf16 v[28:31], v[124:127], v[202:205], v[28:31]
	v_mfma_f32_16x16x32_bf16 v[24:27], v[132:135], v[202:205], v[24:27]
	v_mfma_f32_16x16x32_bf16 v[12:15], v[124:127], v[210:213], v[12:15]
	v_mfma_f32_16x16x32_bf16 v[8:11], v[132:135], v[210:213], v[8:11]
	s_setprio 0
	s_setprio 1
	v_mfma_f32_16x16x32_bf16 v[52:55], v[144:147], v[180:183], v[52:55]
	v_mfma_f32_16x16x32_bf16 v[48:51], v[152:155], v[180:183], v[48:51]
	v_mfma_f32_16x16x32_bf16 v[36:39], v[144:147], v[188:191], v[36:39]
	v_mfma_f32_16x16x32_bf16 v[32:35], v[152:155], v[188:191], v[32:35]
	v_mfma_f32_16x16x32_bf16 v[20:23], v[144:147], v[198:201], v[20:23]
	v_mfma_f32_16x16x32_bf16 v[16:19], v[152:155], v[198:201], v[16:19]
	v_mfma_f32_16x16x32_bf16 v[4:7], v[144:147], v[206:209], v[4:7]
	v_mfma_f32_16x16x32_bf16 v[0:3], v[152:155], v[206:209], v[0:3]
	v_mfma_f32_16x16x32_bf16 v[52:55], v[148:151], v[184:187], v[52:55]
	v_mfma_f32_16x16x32_bf16 v[48:51], v[176:179], v[184:187], v[48:51]
	v_mfma_f32_16x16x32_bf16 v[36:39], v[148:151], v[194:197], v[36:39]
	v_mfma_f32_16x16x32_bf16 v[32:35], v[176:179], v[194:197], v[32:35]
	v_mfma_f32_16x16x32_bf16 v[20:23], v[148:151], v[202:205], v[20:23]
	v_mfma_f32_16x16x32_bf16 v[16:19], v[176:179], v[202:205], v[16:19]
	v_mfma_f32_16x16x32_bf16 v[4:7], v[148:151], v[210:213], v[4:7]
	v_mfma_f32_16x16x32_bf16 v[0:3], v[176:179], v[210:213], v[0:3]
	s_setprio 0
	s_barrier
	s_add_i32 s78, 0, 0x18000
	s_add_i32 s79, 0, 0x1c000
	v_add_u32_e32 v132, s78, v193
	v_add_u32_e32 v165, s79, v193
	ds_read_b128 v[116:119], v132
	ds_read_b128 v[124:127], v132 offset:1024
	ds_read_b128 v[128:131], v132 offset:2048
	ds_read_b128 v[132:135], v132 offset:3072
	ds_read_b128 v[144:147], v165
	ds_read_b128 v[148:151], v165 offset:1024
	ds_read_b128 v[152:155], v165 offset:2048
	ds_read_b128 v[176:179], v165 offset:3072
	s_add_u32 s60, s60, s12
	s_addc_u32 s61, s61, s13
	s_mov_b32 m0, s47
	v_lshl_add_u64 v[226:227], s[60:61], 0, v[156:157]
	ds_read_b128 v[180:183], v245 offset:32768
	ds_read_b128 v[184:187], v245 offset:33792
	ds_read_b128 v[188:191], v245 offset:34816
	ds_read_b128 v[194:197], v245 offset:35840
	ds_read_b128 v[198:201], v245 offset:36864
	ds_read_b128 v[202:205], v245 offset:37888
	ds_read_b128 v[206:209], v245 offset:38912
	ds_read_b128 v[210:213], v245 offset:39936
	global_load_lds_dwordx4 v[226:227], off
	v_lshl_add_u64 v[226:227], s[60:61], 0, v[160:161]
	s_mov_b32 m0, s70
	s_nop 0
	global_load_lds_dwordx4 v[226:227], off
	s_waitcnt vmcnt(8)
	s_waitcnt lgkmcnt(0)
	s_barrier
	s_setprio 1
	s_waitcnt lgkmcnt(0)
	v_mfma_f32_16x16x32_bf16 v[140:143], v[116:119], v[180:183], v[140:143]
	v_mfma_f32_16x16x32_bf16 v[136:139], v[128:131], v[180:183], v[136:139]
	v_mfma_f32_16x16x32_bf16 v[108:111], v[116:119], v[188:191], v[108:111]
	v_mfma_f32_16x16x32_bf16 v[104:107], v[128:131], v[188:191], v[104:107]
	v_mfma_f32_16x16x32_bf16 v[92:95], v[116:119], v[198:201], v[92:95]
	v_mfma_f32_16x16x32_bf16 v[88:91], v[128:131], v[198:201], v[88:91]
	v_mfma_f32_16x16x32_bf16 v[76:79], v[116:119], v[206:209], v[76:79]
	v_mfma_f32_16x16x32_bf16 v[72:75], v[128:131], v[206:209], v[72:75]
	v_mfma_f32_16x16x32_bf16 v[140:143], v[124:127], v[184:187], v[140:143]
	v_mfma_f32_16x16x32_bf16 v[136:139], v[132:135], v[184:187], v[136:139]
	v_mfma_f32_16x16x32_bf16 v[108:111], v[124:127], v[194:197], v[108:111]
	v_mfma_f32_16x16x32_bf16 v[104:107], v[132:135], v[194:197], v[104:107]
	v_mfma_f32_16x16x32_bf16 v[92:95], v[124:127], v[202:205], v[92:95]
	v_mfma_f32_16x16x32_bf16 v[88:91], v[132:135], v[202:205], v[88:91]
	v_mfma_f32_16x16x32_bf16 v[76:79], v[124:127], v[210:213], v[76:79]
	v_mfma_f32_16x16x32_bf16 v[72:75], v[132:135], v[210:213], v[72:75]
	s_setprio 0
	s_setprio 1
	v_mfma_f32_16x16x32_bf16 v[120:123], v[144:147], v[180:183], v[120:123]
	v_mfma_f32_16x16x32_bf16 v[112:115], v[152:155], v[180:183], v[112:115]
	v_mfma_f32_16x16x32_bf16 v[100:103], v[144:147], v[188:191], v[100:103]
	v_mfma_f32_16x16x32_bf16 v[96:99], v[152:155], v[188:191], v[96:99]
	v_mfma_f32_16x16x32_bf16 v[84:87], v[144:147], v[198:201], v[84:87]
	v_mfma_f32_16x16x32_bf16 v[80:83], v[152:155], v[198:201], v[80:83]
	v_mfma_f32_16x16x32_bf16 v[68:71], v[144:147], v[206:209], v[68:71]
	v_mfma_f32_16x16x32_bf16 v[64:67], v[152:155], v[206:209], v[64:67]
	v_mfma_f32_16x16x32_bf16 v[120:123], v[148:151], v[184:187], v[120:123]
	v_mfma_f32_16x16x32_bf16 v[112:115], v[176:179], v[184:187], v[112:115]
	v_mfma_f32_16x16x32_bf16 v[100:103], v[148:151], v[194:197], v[100:103]
	v_mfma_f32_16x16x32_bf16 v[96:99], v[176:179], v[194:197], v[96:99]
	v_mfma_f32_16x16x32_bf16 v[84:87], v[148:151], v[202:205], v[84:87]
	v_mfma_f32_16x16x32_bf16 v[80:83], v[176:179], v[202:205], v[80:83]
	v_mfma_f32_16x16x32_bf16 v[68:71], v[148:151], v[210:213], v[68:71]
	v_mfma_f32_16x16x32_bf16 v[64:67], v[176:179], v[210:213], v[64:67]
	s_setprio 0
	s_barrier
; #define PG8_STAGE(bufoff, gbase, voff) do { _Pragma("unroll") for (int _i = 0; _i < 2; ++_i) \
;         __builtin_amdgcn_global_load_lds((const unsigned*)((const char*)(gbase) + (voff)[_i]), (PG8_LAS unsigned*)(lds + (bufoff) + ldsw + _i * 8192), 16, 0, 0); } while (0)
; #define PG8_LDA(dst, b, h) do { _Pragma("unroll") for (int m = 0; m < 4; ++m) _Pragma("unroll") for (int k = 0; k < 2; ++k) dst[m][k] = *(const PG8_LAS bf16x8*)(lds + PG8_SA(b, h) + aoff + m * 2048 + k * 1024); } while (0)
; #define PG8_MMA(ai, bj, At, Bt) do { __builtin_amdgcn_s_setprio(1); _Pragma("unroll") for (int m = 0; m < 4; ++m) _Pragma("unroll") for (int n = 0; n < 2; ++n) _Pragma("unroll") for (int k = 0; k < 2; ++k) \
;         acc[ai][bj][m][n] = __builtin_amdgcn_mfma_f32_16x16x32_bf16(Bt[n][k], At[m][k], acc[ai][bj][m][n], 0, 0, 0); __builtin_amdgcn_s_setprio(0); } while (0)
; #define PG8_WAIT_V(n) asm volatile("s_waitcnt vmcnt(" #n ")" ::: "memory")
; #define PG8_WAIT_L(n) asm volatile("s_waitcnt lgkmcnt(" #n ")" ::: "memory")
; #define PG8_BAR __builtin_amdgcn_s_barrier()
; #define PG8_SCHED __builtin_amdgcn_sched_barrier(0)
; template <class Epi, class Sched, bool ALIGN_EPI = false, bool SP2 = false>
; __device__ __forceinline__ void gemm_phase(PG8_LAS unsigned char* lds, const Gemm g, const Sched& S, const Epi& E) {
;     ...
;             PG8_LDA(At, 1, 1); PG8_STAGE(PG8_SB(1, 0), b3, voffB); PG8_STAGE(PG8_SB(1, 1), b3 + hstep, voffB); PG8_STAGE(PG8_SA(1, 0), a3, voffA);
;             PG8_WAIT_V(8); PG8_WAIT_L(0); PG8_BAR; PG8_MMA(1, 0, At, B0); PG8_MMA(1, 1, At, B1); PG8_BAR; PG8_SCHED;
	s_add_i32 s60, s78, s33
	v_lshl_add_u64 v[214:215], v[214:215], 0, s[24:25]
	s_mov_b32 m0, s60
	ds_read_b128 v[180:183], v245 offset:49152
	ds_read_b128 v[184:187], v245 offset:50176
	ds_read_b128 v[188:191], v245 offset:51200
	ds_read_b128 v[194:197], v245 offset:52224
	ds_read_b128 v[198:201], v245 offset:53248
	ds_read_b128 v[202:205], v245 offset:54272
	ds_read_b128 v[206:209], v245 offset:55296
	ds_read_b128 v[210:213], v245 offset:56320
	global_load_lds_dwordx4 v[214:215], off
	v_lshl_add_u64 v[214:215], v[216:217], 0, s[24:25]
	s_add_i32 m0, s60, 0x2000
	s_add_i32 s60, s79, s33
	global_load_lds_dwordx4 v[214:215], off
	v_lshl_add_u64 v[214:215], v[218:219], 0, s[24:25]
	s_mov_b32 m0, s60
	s_nop 0
	global_load_lds_dwordx4 v[214:215], off
	v_lshl_add_u64 v[214:215], v[220:221], 0, s[24:25]
	s_add_i32 m0, s60, 0x2000
	s_nop 0
	global_load_lds_dwordx4 v[214:215], off
	v_lshl_add_u64 v[214:215], v[222:223], 0, s[24:25]
	s_mov_b32 m0, s71
	s_nop 0
	global_load_lds_dwordx4 v[214:215], off
	v_lshl_add_u64 v[214:215], v[224:225], 0, s[24:25]
	s_mov_b32 m0, s80
	s_nop 0
	global_load_lds_dwordx4 v[214:215], off
	s_waitcnt vmcnt(8)
	s_waitcnt lgkmcnt(0)
	s_barrier
	s_setprio 1
	s_waitcnt lgkmcnt(0)
	v_mfma_f32_16x16x32_bf16 v[60:63], v[116:119], v[180:183], v[60:63]
	v_mfma_f32_16x16x32_bf16 v[56:59], v[128:131], v[180:183], v[56:59]
	v_mfma_f32_16x16x32_bf16 v[44:47], v[116:119], v[188:191], v[44:47]
	v_mfma_f32_16x16x32_bf16 v[40:43], v[128:131], v[188:191], v[40:43]
	v_mfma_f32_16x16x32_bf16 v[28:31], v[116:119], v[198:201], v[28:31]
	v_mfma_f32_16x16x32_bf16 v[24:27], v[128:131], v[198:201], v[24:27]
	v_mfma_f32_16x16x32_bf16 v[12:15], v[116:119], v[206:209], v[12:15]
	v_mfma_f32_16x16x32_bf16 v[8:11], v[128:131], v[206:209], v[8:11]
	v_mfma_f32_16x16x32_bf16 v[60:63], v[124:127], v[184:187], v[60:63]
	v_mfma_f32_16x16x32_bf16 v[56:59], v[132:135], v[184:187], v[56:59]
	v_mfma_f32_16x16x32_bf16 v[44:47], v[124:127], v[194:197], v[44:47]
	v_mfma_f32_16x16x32_bf16 v[40:43], v[132:135], v[194:197], v[40:43]
	v_mfma_f32_16x16x32_bf16 v[28:31], v[124:127], v[202:205], v[28:31]
	v_mfma_f32_16x16x32_bf16 v[24:27], v[132:135], v[202:205], v[24:27]
	v_mfma_f32_16x16x32_bf16 v[12:15], v[124:127], v[210:213], v[12:15]
	v_mfma_f32_16x16x32_bf16 v[8:11], v[132:135], v[210:213], v[8:11]
	s_setprio 0
	s_setprio 1
	v_mfma_f32_16x16x32_bf16 v[52:55], v[144:147], v[180:183], v[52:55]
	v_mfma_f32_16x16x32_bf16 v[48:51], v[152:155], v[180:183], v[48:51]
	v_mfma_f32_16x16x32_bf16 v[36:39], v[144:147], v[188:191], v[36:39]
	v_mfma_f32_16x16x32_bf16 v[32:35], v[152:155], v[188:191], v[32:35]
	v_mfma_f32_16x16x32_bf16 v[20:23], v[144:147], v[198:201], v[20:23]
	v_mfma_f32_16x16x32_bf16 v[16:19], v[152:155], v[198:201], v[16:19]
	v_mfma_f32_16x16x32_bf16 v[4:7], v[144:147], v[206:209], v[4:7]
	v_mfma_f32_16x16x32_bf16 v[0:3], v[152:155], v[206:209], v[0:3]
	v_mfma_f32_16x16x32_bf16 v[52:55], v[148:151], v[184:187], v[52:55]
	v_mfma_f32_16x16x32_bf16 v[48:51], v[176:179], v[184:187], v[48:51]
	v_mfma_f32_16x16x32_bf16 v[36:39], v[148:151], v[194:197], v[36:39]
	v_mfma_f32_16x16x32_bf16 v[32:35], v[176:179], v[194:197], v[32:35]
	v_mfma_f32_16x16x32_bf16 v[20:23], v[148:151], v[202:205], v[20:23]
	v_mfma_f32_16x16x32_bf16 v[16:19], v[176:179], v[202:205], v[16:19]
	v_mfma_f32_16x16x32_bf16 v[4:7], v[148:151], v[210:213], v[4:7]
	v_mfma_f32_16x16x32_bf16 v[0:3], v[176:179], v[210:213], v[0:3]
	s_setprio 0
	s_barrier
	s_add_u32 s50, s50, 0x100
	s_addc_u32 s51, s51, 0
	s_add_u32 s67, s67, 0x100
	s_addc_u32 s72, s72, 0
	s_cmp_ge_i32 s73, s82
	s_mov_b32 s60, s73
	s_cbranch_scc0 .LBB0_2468

; #define PG8_STAGE(bufoff, gbase, voff) do { _Pragma("unroll") for (int _i = 0; _i < 2; ++_i) \
;         __builtin_amdgcn_global_load_lds((const unsigned*)((const char*)(gbase) + (voff)[_i]), (PG8_LAS unsigned*)(lds + (bufoff) + ldsw + _i * 8192), 16, 0, 0); } while (0)
; #define PG8_LDA(dst, b, h) do { _Pragma("unroll") for (int m = 0; m < 4; ++m) _Pragma("unroll") for (int k = 0; k < 2; ++k) dst[m][k] = *(const PG8_LAS bf16x8*)(lds + PG8_SA(b, h) + aoff + m * 2048 + k * 1024); } while (0)
; #define PG8_LDB(dst, b, h) do { _Pragma("unroll") for (int n = 0; n < 2; ++n) _Pragma("unroll") for (int k = 0; k < 2; ++k) dst[n][k] = *(const PG8_LAS bf16x8*)(lds + PG8_SB(b, h) + boff + n * 2048 + k * 1024); } while (0)
; #define PG8_MMA(ai, bj, At, Bt) do { __builtin_amdgcn_s_setprio(1); _Pragma("unroll") for (int m = 0; m < 4; ++m) _Pragma("unroll") for (int n = 0; n < 2; ++n) _Pragma("unroll") for (int k = 0; k < 2; ++k) \
;         acc[ai][bj][m][n] = __builtin_amdgcn_mfma_f32_16x16x32_bf16(Bt[n][k], At[m][k], acc[ai][bj][m][n], 0, 0, 0); __builtin_amdgcn_s_setprio(0); } while (0)
; #define PG8_WAIT_V(n) asm volatile("s_waitcnt vmcnt(" #n ")" ::: "memory")
; #define PG8_BAR __builtin_amdgcn_s_barrier()
; template <class Epi, class Sched, bool ALIGN_EPI = false, bool SP2 = false>
; __device__ __forceinline__ void gemm_phase(PG8_LAS unsigned char* lds, const Gemm g, const Sched& S, const Epi& E) {
;     ...
;         for (int t = 0; t < nt; t += 2) {
;             const bool last = (t == nt - 2);
;             const char* a1 = cA + (size_t)(t + 1) * kstep;
;             const char* a2 = last ? nA : cA + (size_t)(t + 2) * kstep; const char* b2 = last ? nB : cB + (size_t)(t + 2) * kstep;
;             const char* a3 = a2 + kstep; const char* b3 = b2 + kstep;
;             if (last && has_next) S.a_ready(nxt);
;             if constexpr (SP2) {
;             PG8_LDB(B0, 0, 0); PG8_LDB(B1, 0, 1); PG8_SCHED; PG8_LDA(At, 0, 0); PG8_STAGE(PG8_SA(1, 1), a1 + hstep, voffA);
;             PG8_WAIT_V(8); PG8_WAIT_L(0); PG8_BAR; PG8_MMA(0, 0, At, B0); PG8_MMA(0, 1, At, B1); PG8_BAR; PG8_SCHED;
;             PG8_LDA(At, 0, 1); PG8_STAGE(PG8_SB(0, 0), b2, voffB); PG8_STAGE(PG8_SB(0, 1), b2 + hstep, voffB); PG8_STAGE(PG8_SA(0, 0), a2, voffA);
;             PG8_WAIT_V(8); PG8_WAIT_L(0); PG8_BAR; PG8_MMA(1, 0, At, B0); PG8_MMA(1, 1, At, B1); PG8_BAR; PG8_SCHED;
.LBB0_2570:
	s_sleep 2
	ds_read_b128 v[128:131], v213
	ds_read_b128 v[132:135], v213 offset:1024
	ds_read_b128 v[136:139], v213 offset:2048
	ds_read_b128 v[140:143], v213 offset:3072
	ds_read_b128 v[144:147], v214
	ds_read_b128 v[148:151], v214 offset:1024
	ds_read_b128 v[152:155], v214 offset:2048
	ds_read_b128 v[156:159], v214 offset:3072
	s_add_i32 s51, s46, 2
	s_add_u32 s81, s4, 0x80
	s_addc_u32 s47, s5, 0
	s_cmp_eq_u32 s63, s46
	s_cselect_b32 s46, s40, s81
	s_cselect_b32 s47, s41, s47
	s_cselect_b32 s83, s43, s50
	s_cselect_b32 s82, s42, s7
	v_lshl_add_u64 v[208:209], s[4:5], 0, v[172:173]
	s_add_i32 m0, s58, 0xc000
	ds_read_b128 v[180:183], v215
	ds_read_b128 v[184:187], v215 offset:1024
	ds_read_b128 v[188:191], v215 offset:2048
	ds_read_b128 v[192:195], v215 offset:3072
	ds_read_b128 v[196:199], v215 offset:4096
	ds_read_b128 v[200:203], v215 offset:5120
	ds_read_b128 v[204:207], v215 offset:6144
	ds_read_b128 v[218:221], v215 offset:7168
	global_load_lds_dwordx4 v[208:209], off
	v_lshl_add_u64 v[208:209], s[4:5], 0, v[174:175]
	s_add_i32 m0, s58, 0xe000
	s_nop 0
	global_load_lds_dwordx4 v[208:209], off
	s_waitcnt vmcnt(8)
	s_waitcnt lgkmcnt(0)
	s_barrier
	s_setprio 1
	s_waitcnt lgkmcnt(0)
	v_mfma_f32_16x16x32_bf16 v[124:127], v[128:131], v[180:183], v[124:127]
	v_mfma_f32_16x16x32_bf16 v[120:123], v[136:139], v[180:183], v[120:123]
	v_mfma_f32_16x16x32_bf16 v[108:111], v[128:131], v[188:191], v[108:111]
	v_mfma_f32_16x16x32_bf16 v[104:107], v[136:139], v[188:191], v[104:107]
	v_mfma_f32_16x16x32_bf16 v[92:95], v[128:131], v[196:199], v[92:95]
	v_mfma_f32_16x16x32_bf16 v[88:91], v[136:139], v[196:199], v[88:91]
	v_mfma_f32_16x16x32_bf16 v[76:79], v[128:131], v[204:207], v[76:79]
	v_mfma_f32_16x16x32_bf16 v[72:75], v[136:139], v[204:207], v[72:75]
	v_mfma_f32_16x16x32_bf16 v[124:127], v[132:135], v[184:187], v[124:127]
	v_mfma_f32_16x16x32_bf16 v[120:123], v[140:143], v[184:187], v[120:123]
	v_mfma_f32_16x16x32_bf16 v[108:111], v[132:135], v[192:195], v[108:111]
	v_mfma_f32_16x16x32_bf16 v[104:107], v[140:143], v[192:195], v[104:107]
	v_mfma_f32_16x16x32_bf16 v[92:95], v[132:135], v[200:203], v[92:95]
	v_mfma_f32_16x16x32_bf16 v[88:91], v[140:143], v[200:203], v[88:91]
	v_mfma_f32_16x16x32_bf16 v[76:79], v[132:135], v[218:221], v[76:79]
	v_mfma_f32_16x16x32_bf16 v[72:75], v[140:143], v[218:221], v[72:75]
	s_setprio 0
	s_setprio 1
	v_mfma_f32_16x16x32_bf16 v[116:119], v[144:147], v[180:183], v[116:119]
	v_mfma_f32_16x16x32_bf16 v[112:115], v[152:155], v[180:183], v[112:115]
	v_mfma_f32_16x16x32_bf16 v[100:103], v[144:147], v[188:191], v[100:103]
	v_mfma_f32_16x16x32_bf16 v[96:99], v[152:155], v[188:191], v[96:99]
	v_mfma_f32_16x16x32_bf16 v[84:87], v[144:147], v[196:199], v[84:87]
	v_mfma_f32_16x16x32_bf16 v[80:83], v[152:155], v[196:199], v[80:83]
	v_mfma_f32_16x16x32_bf16 v[68:71], v[144:147], v[204:207], v[68:71]
	v_mfma_f32_16x16x32_bf16 v[64:67], v[152:155], v[204:207], v[64:67]
	v_mfma_f32_16x16x32_bf16 v[116:119], v[148:151], v[184:187], v[116:119]
	v_mfma_f32_16x16x32_bf16 v[112:115], v[156:159], v[184:187], v[112:115]
	v_mfma_f32_16x16x32_bf16 v[100:103], v[148:151], v[192:195], v[100:103]
	v_mfma_f32_16x16x32_bf16 v[96:99], v[156:159], v[192:195], v[96:99]
	v_mfma_f32_16x16x32_bf16 v[84:87], v[148:151], v[200:203], v[84:87]
	v_mfma_f32_16x16x32_bf16 v[80:83], v[156:159], v[200:203], v[80:83]
	v_mfma_f32_16x16x32_bf16 v[68:71], v[148:151], v[218:221], v[68:71]
	v_mfma_f32_16x16x32_bf16 v[64:67], v[156:159], v[218:221], v[64:67]
	s_setprio 0
	s_barrier
	s_add_i32 s81, s75, s53
	v_lshl_add_u64 v[208:209], s[82:83], 0, v[162:163]
	s_mov_b32 m0, s81
	ds_read_b128 v[180:183], v215 offset:16384
	ds_read_b128 v[184:187], v215 offset:17408
	ds_read_b128 v[188:191], v215 offset:18432
	ds_read_b128 v[192:195], v215 offset:19456
	ds_read_b128 v[196:199], v215 offset:20480
	ds_read_b128 v[200:203], v215 offset:21504
	ds_read_b128 v[204:207], v215 offset:22528
	ds_read_b128 v[218:221], v215 offset:23552
	global_load_lds_dwordx4 v[208:209], off
	s_add_i32 m0, s81, 0x2000
	v_lshl_add_u64 v[222:223], s[82:83], 0, v[166:167]
	s_add_u32 s82, s82, s8
	s_addc_u32 s83, s83, s9
	s_add_i32 s81, s76, s53
	global_load_lds_dwordx4 v[222:223], off
	v_lshl_add_u64 v[224:225], s[82:83], 0, v[162:163]
	s_mov_b32 m0, s81
	v_lshl_add_u64 v[226:227], s[82:83], 0, v[166:167]
	global_load_lds_dwordx4 v[224:225], off
	s_add_i32 m0, s81, 0x2000
	v_lshl_add_u64 v[228:229], s[46:47], 0, v[160:161]
	global_load_lds_dwordx4 v[226:227], off
	s_mov_b32 m0, s58
	v_lshl_add_u64 v[230:231], s[46:47], 0, v[164:165]
	global_load_lds_dwordx4 v[228:229], off
	s_mov_b32 m0, s59
	s_nop 0
	global_load_lds_dwordx4 v[230:231], off
	s_waitcnt vmcnt(8)
	s_waitcnt lgkmcnt(0)
	s_barrier
; #define PG8_STAGE(bufoff, gbase, voff) do { _Pragma("unroll") for (int _i = 0; _i < 2; ++_i) \
;         __builtin_amdgcn_global_load_lds((const unsigned*)((const char*)(gbase) + (voff)[_i]), (PG8_LAS unsigned*)(lds + (bufoff) + ldsw + _i * 8192), 16, 0, 0); } while (0)
; #define PG8_LDA(dst, b, h) do { _Pragma("unroll") for (int m = 0; m < 4; ++m) _Pragma("unroll") for (int k = 0; k < 2; ++k) dst[m][k] = *(const PG8_LAS bf16x8*)(lds + PG8_SA(b, h) + aoff + m * 2048 + k * 1024); } while (0)
; #define PG8_LDB(dst, b, h) do { _Pragma("unroll") for (int n = 0; n < 2; ++n) _Pragma("unroll") for (int k = 0; k < 2; ++k) dst[n][k] = *(const PG8_LAS bf16x8*)(lds + PG8_SB(b, h) + boff + n * 2048 + k * 1024); } while (0)
; #define PG8_MMA(ai, bj, At, Bt) do { __builtin_amdgcn_s_setprio(1); _Pragma("unroll") for (int m = 0; m < 4; ++m) _Pragma("unroll") for (int n = 0; n < 2; ++n) _Pragma("unroll") for (int k = 0; k < 2; ++k) \
;         acc[ai][bj][m][n] = __builtin_amdgcn_mfma_f32_16x16x32_bf16(Bt[n][k], At[m][k], acc[ai][bj][m][n], 0, 0, 0); __builtin_amdgcn_s_setprio(0); } while (0)
; #define PG8_WAIT_V(n) asm volatile("s_waitcnt vmcnt(" #n ")" ::: "memory")
; #define PG8_WAIT_L(n) asm volatile("s_waitcnt lgkmcnt(" #n ")" ::: "memory")
; #define PG8_BAR __builtin_amdgcn_s_barrier()
; #define PG8_SCHED __builtin_amdgcn_sched_barrier(0)
; template <class Epi, class Sched, bool ALIGN_EPI = false, bool SP2 = false>
; __device__ __forceinline__ void gemm_phase(PG8_LAS unsigned char* lds, const Gemm g, const Sched& S, const Epi& E) {
;     ...
;             PG8_WAIT_V(8); PG8_WAIT_L(0); PG8_BAR; PG8_MMA(1, 0, At, B0); PG8_MMA(1, 1, At, B1); PG8_BAR; PG8_SCHED;
;             PG8_LDB(B0, 1, 0); PG8_LDB(B1, 1, 1); PG8_SCHED; PG8_LDA(At, 1, 0); PG8_STAGE(PG8_SA(0, 1), a2 + hstep, voffA);
;             PG8_WAIT_V(8); PG8_WAIT_L(0); PG8_BAR; PG8_MMA(0, 0, At, B0); PG8_MMA(0, 1, At, B1); PG8_BAR; PG8_SCHED;
	s_setprio 1
	s_waitcnt lgkmcnt(0)
	v_mfma_f32_16x16x32_bf16 v[60:63], v[128:131], v[180:183], v[60:63]
	v_mfma_f32_16x16x32_bf16 v[56:59], v[136:139], v[180:183], v[56:59]
	v_mfma_f32_16x16x32_bf16 v[44:47], v[128:131], v[188:191], v[44:47]
	v_mfma_f32_16x16x32_bf16 v[40:43], v[136:139], v[188:191], v[40:43]
	v_mfma_f32_16x16x32_bf16 v[28:31], v[128:131], v[196:199], v[28:31]
	v_mfma_f32_16x16x32_bf16 v[24:27], v[136:139], v[196:199], v[24:27]
	v_mfma_f32_16x16x32_bf16 v[12:15], v[128:131], v[204:207], v[12:15]
	v_mfma_f32_16x16x32_bf16 v[8:11], v[136:139], v[204:207], v[8:11]
	v_mfma_f32_16x16x32_bf16 v[60:63], v[132:135], v[184:187], v[60:63]
	v_mfma_f32_16x16x32_bf16 v[56:59], v[140:143], v[184:187], v[56:59]
	v_mfma_f32_16x16x32_bf16 v[44:47], v[132:135], v[192:195], v[44:47]
	v_mfma_f32_16x16x32_bf16 v[40:43], v[140:143], v[192:195], v[40:43]
	v_mfma_f32_16x16x32_bf16 v[28:31], v[132:135], v[200:203], v[28:31]
	v_mfma_f32_16x16x32_bf16 v[24:27], v[140:143], v[200:203], v[24:27]
	v_mfma_f32_16x16x32_bf16 v[12:15], v[132:135], v[218:221], v[12:15]
	v_mfma_f32_16x16x32_bf16 v[8:11], v[140:143], v[218:221], v[8:11]
	s_setprio 0
	s_setprio 1
	v_mfma_f32_16x16x32_bf16 v[52:55], v[144:147], v[180:183], v[52:55]
	v_mfma_f32_16x16x32_bf16 v[48:51], v[152:155], v[180:183], v[48:51]
	v_mfma_f32_16x16x32_bf16 v[36:39], v[144:147], v[188:191], v[36:39]
	v_mfma_f32_16x16x32_bf16 v[32:35], v[152:155], v[188:191], v[32:35]
	v_mfma_f32_16x16x32_bf16 v[20:23], v[144:147], v[196:199], v[20:23]
	v_mfma_f32_16x16x32_bf16 v[16:19], v[152:155], v[196:199], v[16:19]
	v_mfma_f32_16x16x32_bf16 v[4:7], v[144:147], v[204:207], v[4:7]
	v_mfma_f32_16x16x32_bf16 v[0:3], v[152:155], v[204:207], v[0:3]
	v_mfma_f32_16x16x32_bf16 v[52:55], v[148:151], v[184:187], v[52:55]
	v_mfma_f32_16x16x32_bf16 v[48:51], v[156:159], v[184:187], v[48:51]
	v_mfma_f32_16x16x32_bf16 v[36:39], v[148:151], v[192:195], v[36:39]
	v_mfma_f32_16x16x32_bf16 v[32:35], v[156:159], v[192:195], v[32:35]
	v_mfma_f32_16x16x32_bf16 v[20:23], v[148:151], v[200:203], v[20:23]
	v_mfma_f32_16x16x32_bf16 v[16:19], v[156:159], v[200:203], v[16:19]
	v_mfma_f32_16x16x32_bf16 v[4:7], v[148:151], v[218:221], v[4:7]
	v_mfma_f32_16x16x32_bf16 v[0:3], v[156:159], v[218:221], v[0:3]
	s_setprio 0
	s_barrier
	s_add_i32 s81, 0, 0x18000
	s_add_i32 s82, 0, 0x1c000
	v_add_u32_e32 v140, s81, v211
	v_add_u32_e32 v156, s82, v211
	ds_read_b128 v[128:131], v140
	ds_read_b128 v[132:135], v140 offset:1024
	ds_read_b128 v[136:139], v140 offset:2048
	ds_read_b128 v[140:143], v140 offset:3072
	ds_read_b128 v[144:147], v156
	ds_read_b128 v[148:151], v156 offset:1024
	ds_read_b128 v[152:155], v156 offset:2048
	ds_read_b128 v[156:159], v156 offset:3072
	s_add_u32 s46, s46, s8
	s_addc_u32 s47, s47, s9
	s_mov_b32 m0, s60
	v_lshl_add_u64 v[232:233], s[46:47], 0, v[160:161]
	ds_read_b128 v[180:183], v215 offset:32768
	ds_read_b128 v[184:187], v215 offset:33792
	ds_read_b128 v[188:191], v215 offset:34816
	ds_read_b128 v[192:195], v215 offset:35840
	ds_read_b128 v[196:199], v215 offset:36864
	ds_read_b128 v[200:203], v215 offset:37888
	ds_read_b128 v[204:207], v215 offset:38912
	ds_read_b128 v[218:221], v215 offset:39936
	global_load_lds_dwordx4 v[232:233], off
	v_lshl_add_u64 v[232:233], s[46:47], 0, v[164:165]
	s_mov_b32 m0, s61
	s_nop 0
	global_load_lds_dwordx4 v[232:233], off
	s_waitcnt vmcnt(8)
	s_waitcnt lgkmcnt(0)
	s_barrier
	s_setprio 1
	s_waitcnt lgkmcnt(0)
	v_mfma_f32_16x16x32_bf16 v[124:127], v[128:131], v[180:183], v[124:127]
	v_mfma_f32_16x16x32_bf16 v[120:123], v[136:139], v[180:183], v[120:123]
	v_mfma_f32_16x16x32_bf16 v[108:111], v[128:131], v[188:191], v[108:111]
	v_mfma_f32_16x16x32_bf16 v[104:107], v[136:139], v[188:191], v[104:107]
	v_mfma_f32_16x16x32_bf16 v[92:95], v[128:131], v[196:199], v[92:95]
	v_mfma_f32_16x16x32_bf16 v[88:91], v[136:139], v[196:199], v[88:91]
	v_mfma_f32_16x16x32_bf16 v[76:79], v[128:131], v[204:207], v[76:79]
	v_mfma_f32_16x16x32_bf16 v[72:75], v[136:139], v[204:207], v[72:75]
	v_mfma_f32_16x16x32_bf16 v[124:127], v[132:135], v[184:187], v[124:127]
	v_mfma_f32_16x16x32_bf16 v[120:123], v[140:143], v[184:187], v[120:123]
	v_mfma_f32_16x16x32_bf16 v[108:111], v[132:135], v[192:195], v[108:111]
	v_mfma_f32_16x16x32_bf16 v[104:107], v[140:143], v[192:195], v[104:107]
	v_mfma_f32_16x16x32_bf16 v[92:95], v[132:135], v[200:203], v[92:95]
	v_mfma_f32_16x16x32_bf16 v[88:91], v[140:143], v[200:203], v[88:91]
	v_mfma_f32_16x16x32_bf16 v[76:79], v[132:135], v[218:221], v[76:79]
	v_mfma_f32_16x16x32_bf16 v[72:75], v[140:143], v[218:221], v[72:75]
	s_setprio 0
	s_setprio 1
	v_mfma_f32_16x16x32_bf16 v[116:119], v[144:147], v[180:183], v[116:119]
	v_mfma_f32_16x16x32_bf16 v[112:115], v[152:155], v[180:183], v[112:115]
	v_mfma_f32_16x16x32_bf16 v[100:103], v[144:147], v[188:191], v[100:103]
	v_mfma_f32_16x16x32_bf16 v[96:99], v[152:155], v[188:191], v[96:99]
	v_mfma_f32_16x16x32_bf16 v[84:87], v[144:147], v[196:199], v[84:87]
	v_mfma_f32_16x16x32_bf16 v[80:83], v[152:155], v[196:199], v[80:83]
	v_mfma_f32_16x16x32_bf16 v[68:71], v[144:147], v[204:207], v[68:71]
	v_mfma_f32_16x16x32_bf16 v[64:67], v[152:155], v[204:207], v[64:67]
	v_mfma_f32_16x16x32_bf16 v[116:119], v[148:151], v[184:187], v[116:119]
	v_mfma_f32_16x16x32_bf16 v[112:115], v[156:159], v[184:187], v[112:115]
	v_mfma_f32_16x16x32_bf16 v[100:103], v[148:151], v[192:195], v[100:103]
	v_mfma_f32_16x16x32_bf16 v[96:99], v[156:159], v[192:195], v[96:99]
	v_mfma_f32_16x16x32_bf16 v[84:87], v[148:151], v[200:203], v[84:87]
	v_mfma_f32_16x16x32_bf16 v[80:83], v[156:159], v[200:203], v[80:83]
	v_mfma_f32_16x16x32_bf16 v[68:71], v[148:151], v[218:221], v[68:71]
	v_mfma_f32_16x16x32_bf16 v[64:67], v[156:159], v[218:221], v[64:67]
	s_setprio 0
	s_barrier
; #define PG8_STAGE(bufoff, gbase, voff) do { _Pragma("unroll") for (int _i = 0; _i < 2; ++_i) \
;         __builtin_amdgcn_global_load_lds((const unsigned*)((const char*)(gbase) + (voff)[_i]), (PG8_LAS unsigned*)(lds + (bufoff) + ldsw + _i * 8192), 16, 0, 0); } while (0)
; #define PG8_LDA(dst, b, h) do { _Pragma("unroll") for (int m = 0; m < 4; ++m) _Pragma("unroll") for (int k = 0; k < 2; ++k) dst[m][k] = *(const PG8_LAS bf16x8*)(lds + PG8_SA(b, h) + aoff + m * 2048 + k * 1024); } while (0)
; #define PG8_MMA(ai, bj, At, Bt) do { __builtin_amdgcn_s_setprio(1); _Pragma("unroll") for (int m = 0; m < 4; ++m) _Pragma("unroll") for (int n = 0; n < 2; ++n) _Pragma("unroll") for (int k = 0; k < 2; ++k) \
;         acc[ai][bj][m][n] = __builtin_amdgcn_mfma_f32_16x16x32_bf16(Bt[n][k], At[m][k], acc[ai][bj][m][n], 0, 0, 0); __builtin_amdgcn_s_setprio(0); } while (0)
; #define PG8_WAIT_V(n) asm volatile("s_waitcnt vmcnt(" #n ")" ::: "memory")
; #define PG8_WAIT_L(n) asm volatile("s_waitcnt lgkmcnt(" #n ")" ::: "memory")
; #define PG8_BAR __builtin_amdgcn_s_barrier()
; #define PG8_SCHED __builtin_amdgcn_sched_barrier(0)
; template <class Epi, class Sched, bool ALIGN_EPI = false, bool SP2 = false>
; __device__ __forceinline__ void gemm_phase(PG8_LAS unsigned char* lds, const Gemm g, const Sched& S, const Epi& E) {
;     ...
;         for (int t = 0; t < nt; t += 2) {
;     ...
;             PG8_LDA(At, 1, 1); PG8_STAGE(PG8_SB(1, 0), b3, voffB); PG8_STAGE(PG8_SB(1, 1), b3 + hstep, voffB); PG8_STAGE(PG8_SA(1, 0), a3, voffA);
;             PG8_WAIT_V(8); PG8_WAIT_L(0); PG8_BAR; PG8_MMA(1, 0, At, B0); PG8_MMA(1, 1, At, B1); PG8_BAR; PG8_SCHED;
	s_add_i32 s46, s81, s53
	v_lshl_add_u64 v[208:209], v[208:209], 0, s[24:25]
	s_mov_b32 m0, s46
	ds_read_b128 v[180:183], v215 offset:49152
	ds_read_b128 v[184:187], v215 offset:50176
	ds_read_b128 v[188:191], v215 offset:51200
	ds_read_b128 v[192:195], v215 offset:52224
	ds_read_b128 v[196:199], v215 offset:53248
	ds_read_b128 v[200:203], v215 offset:54272
	ds_read_b128 v[204:207], v215 offset:55296
	ds_read_b128 v[218:221], v215 offset:56320
	global_load_lds_dwordx4 v[208:209], off
	v_lshl_add_u64 v[208:209], v[222:223], 0, s[24:25]
	s_add_i32 m0, s46, 0x2000
	s_add_i32 s46, s82, s53
	global_load_lds_dwordx4 v[208:209], off
	v_lshl_add_u64 v[208:209], v[224:225], 0, s[24:25]
	s_mov_b32 m0, s46
	s_nop 0
	global_load_lds_dwordx4 v[208:209], off
	v_lshl_add_u64 v[208:209], v[226:227], 0, s[24:25]
	s_add_i32 m0, s46, 0x2000
	s_nop 0
	global_load_lds_dwordx4 v[208:209], off
	v_lshl_add_u64 v[208:209], v[228:229], 0, s[24:25]
	s_mov_b32 m0, s56
	s_nop 0
	global_load_lds_dwordx4 v[208:209], off
	v_lshl_add_u64 v[208:209], v[230:231], 0, s[24:25]
	s_mov_b32 m0, s57
	s_nop 0
	global_load_lds_dwordx4 v[208:209], off
	s_waitcnt vmcnt(8)
	s_waitcnt lgkmcnt(0)
	s_barrier
	s_setprio 1
	s_waitcnt lgkmcnt(0)
	v_mfma_f32_16x16x32_bf16 v[60:63], v[128:131], v[180:183], v[60:63]
	v_mfma_f32_16x16x32_bf16 v[56:59], v[136:139], v[180:183], v[56:59]
	v_mfma_f32_16x16x32_bf16 v[44:47], v[128:131], v[188:191], v[44:47]
	v_mfma_f32_16x16x32_bf16 v[40:43], v[136:139], v[188:191], v[40:43]
	v_mfma_f32_16x16x32_bf16 v[28:31], v[128:131], v[196:199], v[28:31]
	v_mfma_f32_16x16x32_bf16 v[24:27], v[136:139], v[196:199], v[24:27]
	v_mfma_f32_16x16x32_bf16 v[12:15], v[128:131], v[204:207], v[12:15]
	v_mfma_f32_16x16x32_bf16 v[8:11], v[136:139], v[204:207], v[8:11]
	v_mfma_f32_16x16x32_bf16 v[60:63], v[132:135], v[184:187], v[60:63]
	v_mfma_f32_16x16x32_bf16 v[56:59], v[140:143], v[184:187], v[56:59]
	v_mfma_f32_16x16x32_bf16 v[44:47], v[132:135], v[192:195], v[44:47]
	v_mfma_f32_16x16x32_bf16 v[40:43], v[140:143], v[192:195], v[40:43]
	v_mfma_f32_16x16x32_bf16 v[28:31], v[132:135], v[200:203], v[28:31]
	v_mfma_f32_16x16x32_bf16 v[24:27], v[140:143], v[200:203], v[24:27]
	v_mfma_f32_16x16x32_bf16 v[12:15], v[132:135], v[218:221], v[12:15]
	v_mfma_f32_16x16x32_bf16 v[8:11], v[140:143], v[218:221], v[8:11]
	s_setprio 0
	s_setprio 1
	v_mfma_f32_16x16x32_bf16 v[52:55], v[144:147], v[180:183], v[52:55]
	v_mfma_f32_16x16x32_bf16 v[48:51], v[152:155], v[180:183], v[48:51]
	v_mfma_f32_16x16x32_bf16 v[36:39], v[144:147], v[188:191], v[36:39]
	v_mfma_f32_16x16x32_bf16 v[32:35], v[152:155], v[188:191], v[32:35]
	v_mfma_f32_16x16x32_bf16 v[20:23], v[144:147], v[196:199], v[20:23]
	v_mfma_f32_16x16x32_bf16 v[16:19], v[152:155], v[196:199], v[16:19]
	v_mfma_f32_16x16x32_bf16 v[4:7], v[144:147], v[204:207], v[4:7]
	v_mfma_f32_16x16x32_bf16 v[0:3], v[152:155], v[204:207], v[0:3]
	v_mfma_f32_16x16x32_bf16 v[52:55], v[148:151], v[184:187], v[52:55]
	v_mfma_f32_16x16x32_bf16 v[48:51], v[156:159], v[184:187], v[48:51]
	v_mfma_f32_16x16x32_bf16 v[36:39], v[148:151], v[192:195], v[36:39]
	v_mfma_f32_16x16x32_bf16 v[32:35], v[156:159], v[192:195], v[32:35]
	v_mfma_f32_16x16x32_bf16 v[20:23], v[148:151], v[200:203], v[20:23]
	v_mfma_f32_16x16x32_bf16 v[16:19], v[156:159], v[200:203], v[16:19]
	v_mfma_f32_16x16x32_bf16 v[4:7], v[148:151], v[218:221], v[4:7]
	v_mfma_f32_16x16x32_bf16 v[0:3], v[156:159], v[218:221], v[0:3]
	s_setprio 0
	s_barrier
	s_add_u32 s4, s4, 0x100
	s_addc_u32 s5, s5, 0
	s_add_u32 s7, s7, 0x100
	s_addc_u32 s50, s50, 0
	s_cmp_ge_i32 s51, s62
	s_mov_b32 s46, s51
	s_cbranch_scc0 .LBB0_2570
